# sc1 write-through stores for the P2b projection tiles (published by P2's internal grid barrier)
# baseline (speedup 1.0000x reference)
; __device__ __forceinline__ void hgrn_mfma(Frame& F, int b, int h) {
;     ...
;         auto hgrn_sgload = [&](int cc, int tb2) __attribute__((always_inline)) {
;             const bf16_t* sgb = SG + (rbase + 64 * cc) * 512 + colh + 32 * (w - 4);
; #pragma unroll
;             for (int j = 0; j < 2; ++j) { const int idx = lane + 64 * j, row = idx >> 2, c8 = idx & 3, t = 32 * tb2 + row; sgp[tb2][j] = *(const u32x4*)(sgb + (unsigned)(t * 512 + 8 * c8)); }
;         };
;         auto hgrn_finalize = [&](int cc, int tb2) __attribute__((always_inline)) {
;             const int vb = w - 4; const size_t row0 = rbase + 64 * cc;
;             bf16_t* mxb = MIX + row0 * 1024 + colh + 32 * vb;
;             const LAS float* rq = rowsq + (cc & 1) * 256; const LAS unsigned char* sb_ = stg + (cc & 1) * 20480 + tb2 * 2560;
; #pragma unroll
;             for (int j = 0; j < 2; ++j) { const int idx = lane + 64 * j, row = idx >> 2, c8 = idx & 3, t = 32 * tb2 + row;
;                 const u32x4 sg = sgp[tb2][j];
;                 const float rstd = frsq(((rq[t] + rq[64 + t]) + (rq[128 + t] + rq[192 + t])) * (1.0f / 128.0f) + EPS);
;                 const u32x4 a = *(const LAS u32x4*)(sb_ + row * 80 + c8 * 16);
;                 u32x4 ov; ov.x = cvtpk(bflo(a.x) * rstd * bflo(sg.x), bfhi(a.x) * rstd * bfhi(sg.x)); ov.y = cvtpk(bflo(a.y) * rstd * bflo(sg.y), bfhi(a.y) * rstd * bfhi(sg.y));
;                 ov.z = cvtpk(bflo(a.z) * rstd * bflo(sg.z), bfhi(a.z) * rstd * bfhi(sg.z)); ov.w = cvtpk(bflo(a.w) * rstd * bflo(sg.w), bfhi(a.w) * rstd * bfhi(sg.w));
;                 *(u32x4*)(mxb + (unsigned)(t * 1024 + 8 * c8)) = ov; }
;         };
;         for (int c = 0; c < 32; ++c) {
;             const LAS unsigned char* Qi = img + (c & 1) * 49152; const LAS unsigned char* Ki = Qi + 16384;
;             u32x4 tmp[12]; f32x4 etmp = {0.f, 0.f, 0.f, 0.f};
;             const size_t nrow0 = rbase + 64 * ((c + 1 < 32) ? c + 1 : c);
;             const unsigned ploff = (unsigned)(ht >> 4) * 512u + 8u * (unsigned)(ht & 15);
; #pragma unroll
;             for (int i = 0; i < 12; ++i) { const int tensor = i >> 2;
;                 const bf16_t* tb_ = (tensor == 0 ? QT : tensor == 1 ? KT : V) + nrow0 * 512 + colh + (i & 3) * 8192;
;                 tmp[i] = *(const u32x4*)(tb_ + ploff); }
;             if (ht < 32) etmp = *(const f32x4*)(ELAST + (nrow0 >> 6) * 512 + colh + (unsigned)(4 * ht));
.LBB0_283:
	s_or_b64 exec, exec, s[68:69]
	s_and_b32 s44, s71, 1
	s_lshl_b32 s68, s44, 10
	s_add_i32 s68, s68, 0
	s_add_i32 s68, s68, 0x19800
	v_lshl_add_u32 v138, v136, 2, s68
	ds_read2st64_b32 v[0:1], v138 offset1:1
	ds_read2st64_b32 v[2:3], v138 offset0:2 offset1:3
	s_mulk_i32 s44, 0x5000
	s_add_i32 s44, s56, s44
	s_waitcnt vmcnt(15)
	v_lshlrev_b32_e32 v12, 16, v24
	s_waitcnt lgkmcnt(1)
	v_mov_b32_e32 v4, v0
	s_waitcnt lgkmcnt(0)
	v_mov_b32_e32 v5, v2
	v_mov_b32_e32 v2, v1
	v_pk_add_f32 v[0:1], v[4:5], v[2:3]
	v_and_b32_e32 v13, 0xffff0000, v24
	v_add_f32_e32 v0, v0, v1
	v_fmamk_f32 v4, v0, 0x3c000000, v178
	v_add_u32_e32 v0, s44, v135
	v_add_u32_e32 v91, v0, v125
	ds_read_b128 v[0:3], v91
	v_rsq_f32_e32 v8, v4
	v_add_u32_e32 v4, s44, v126
	v_add_u32_e32 v89, v4, v125
	ds_read_b128 v[4:7], v89
	s_waitcnt lgkmcnt(1)
	v_lshlrev_b32_e32 v10, 16, v0
	v_and_b32_e32 v11, 0xffff0000, v0
	v_pk_mul_f32 v[10:11], v[8:9], v[10:11] op_sel_hi:[0,1]
	v_pk_mul_f32 v[10:11], v[10:11], v[12:13]
	v_lshlrev_b32_e32 v12, 16, v25
	v_cvt_pk_bf16_f32 v0, v10, v11
	v_lshlrev_b32_e32 v10, 16, v1
	v_and_b32_e32 v11, 0xffff0000, v1
	v_pk_mul_f32 v[10:11], v[8:9], v[10:11] op_sel_hi:[0,1]
	v_and_b32_e32 v13, 0xffff0000, v25
	v_pk_mul_f32 v[10:11], v[10:11], v[12:13]
	v_lshlrev_b32_e32 v12, 16, v26
	v_cvt_pk_bf16_f32 v1, v10, v11
	v_lshlrev_b32_e32 v10, 16, v2
	v_and_b32_e32 v11, 0xffff0000, v2
	v_pk_mul_f32 v[10:11], v[8:9], v[10:11] op_sel_hi:[0,1]
	v_and_b32_e32 v13, 0xffff0000, v26
	v_lshl_add_u32 v139, v127, 2, s68
	v_pk_mul_f32 v[10:11], v[10:11], v[12:13]
	ds_read2st64_b32 v[12:13], v139 offset1:1
	ds_read2st64_b32 v[14:15], v139 offset0:2 offset1:3
	v_cvt_pk_bf16_f32 v2, v10, v11
	v_lshlrev_b32_e32 v10, 16, v3
	v_and_b32_e32 v11, 0xffff0000, v3
	v_pk_mul_f32 v[8:9], v[8:9], v[10:11] op_sel_hi:[0,1]
	v_lshlrev_b32_e32 v10, 16, v27
	v_and_b32_e32 v11, 0xffff0000, v27
	v_pk_mul_f32 v[8:9], v[8:9], v[10:11]
	s_waitcnt lgkmcnt(1)
	v_mov_b32_e32 v10, v12
	s_waitcnt lgkmcnt(0)
	v_mov_b32_e32 v11, v14
	v_mov_b32_e32 v14, v13
	v_pk_add_f32 v[10:11], v[10:11], v[14:15]
	v_cvt_pk_bf16_f32 v3, v8, v9
	v_add_f32_e32 v10, v10, v11
	v_fmamk_f32 v10, v10, 0x3c000000, v178
	v_rsq_f32_e32 v10, v10
	v_lshl_add_u64 v[8:9], v[98:99], 0, s[42:43]
	global_store_dwordx4 v[8:9], v[0:3], off sc1
	s_and_b64 vcc, exec, s[36:37]
	s_add_i32 s44, s71, 1
	v_lshlrev_b32_e32 v0, 16, v4
	v_and_b32_e32 v1, 0xffff0000, v4
	v_pk_mul_f32 v[0:1], v[10:11], v[0:1] op_sel_hi:[0,1]
	s_waitcnt vmcnt(15)
	v_lshlrev_b32_e32 v2, 16, v20
	v_and_b32_e32 v3, 0xffff0000, v20
	v_pk_mul_f32 v[0:1], v[0:1], v[2:3]
	v_lshlrev_b32_e32 v2, 16, v5
	v_and_b32_e32 v3, 0xffff0000, v5
	v_pk_mul_f32 v[2:3], v[10:11], v[2:3] op_sel_hi:[0,1]
	v_lshlrev_b32_e32 v4, 16, v21
	v_and_b32_e32 v5, 0xffff0000, v21
	v_pk_mul_f32 v[2:3], v[2:3], v[4:5]
	v_cvt_pk_bf16_f32 v0, v0, v1
	v_cvt_pk_bf16_f32 v1, v2, v3
	v_lshlrev_b32_e32 v2, 16, v6
	v_and_b32_e32 v3, 0xffff0000, v6
	v_pk_mul_f32 v[2:3], v[10:11], v[2:3] op_sel_hi:[0,1]
	v_lshlrev_b32_e32 v4, 16, v22
	v_and_b32_e32 v5, 0xffff0000, v22
	v_pk_mul_f32 v[2:3], v[2:3], v[4:5]
	v_lshlrev_b32_e32 v4, 16, v7
	v_and_b32_e32 v5, 0xffff0000, v7
	v_pk_mul_f32 v[4:5], v[10:11], v[4:5] op_sel_hi:[0,1]
	v_lshlrev_b32_e32 v6, 16, v23
	v_and_b32_e32 v7, 0xffff0000, v23
	v_pk_mul_f32 v[4:5], v[4:5], v[6:7]
	v_cvt_pk_bf16_f32 v2, v2, v3
	v_cvt_pk_bf16_f32 v3, v4, v5
	v_lshl_add_u64 v[4:5], v[96:97], 0, s[42:43]
	global_store_dwordx4 v[4:5], v[0:3], off sc1
	s_nop 1
	v_lshl_add_u64 v[0:1], v[106:107], 0, s[42:43]
	global_load_dwordx4 v[24:27], v[0:1], off
	v_lshl_add_u64 v[0:1], v[104:105], 0, s[42:43]
	global_load_dwordx4 v[20:23], v[0:1], off
	s_cbranch_vccnz .LBB0_291
	s_bitcmp1_b32 s44, 0
	s_cselect_b32 s68, 0xc000, 0
	s_add_i32 s68, s68, 0
	s_add_i32 s69, s68, s57
	s_add_i32 s68, s68, s64
	v_add_u32_e32 v164, s69, v123
	v_add_u32_e32 v165, s68, v123
	v_add_u32_e32 v166, s69, v124
	v_add_u32_e32 v168, s68, v124
	ds_read_b128 v[0:3], v164 offset:16384
	ds_read_b128 v[140:143], v164 offset:16896
	ds_read_b128 v[4:7], v165
	ds_read_b128 v[144:147], v165 offset:512
	ds_read_b128 v[148:151], v166 offset:16384
	ds_read_b128 v[152:155], v166 offset:16896
	ds_read_b128 v[156:159], v168
	ds_read_b128 v[160:163], v168 offset:512
	s_waitcnt lgkmcnt(5)
	v_mfma_f32_32x32x16_bf16 v[0:15], v[0:3], v[4:7], 0
	s_waitcnt lgkmcnt(1)
	v_mfma_f32_32x32x16_bf16 v[0:15], v[148:151], v[156:159], v[0:15]
	v_mfma_f32_32x32x16_bf16 v[0:15], v[140:143], v[144:147], v[0:15]
	s_waitcnt lgkmcnt(0)
	v_mfma_f32_32x32x16_bf16 v[0:15], v[152:155], v[160:163], v[0:15]
	ds_read_b128 v[140:143], v164 offset:17408
	ds_read_b128 v[144:147], v164 offset:17920
	ds_read_b128 v[148:151], v165 offset:1024
	ds_read_b128 v[152:155], v165 offset:1536
	ds_read_b128 v[156:159], v166 offset:17408
	ds_read_b128 v[160:163], v166 offset:17920
	ds_read_b128 v[164:167], v168 offset:1024
	ds_read_b128 v[168:171], v168 offset:1536
	s_waitcnt lgkmcnt(5)
	v_mfma_f32_32x32x16_bf16 v[0:15], v[140:143], v[148:151], v[0:15]
	s_waitcnt lgkmcnt(1)
	v_mfma_f32_32x32x16_bf16 v[0:15], v[156:159], v[164:167], v[0:15]
	v_mfma_f32_32x32x16_bf16 v[0:15], v[144:147], v[152:155], v[0:15]
	s_waitcnt lgkmcnt(0)
	v_mfma_f32_32x32x16_bf16 v[0:15], v[160:163], v[168:171], v[0:15]
	s_cmp_lt_i32 s3, 6
	s_cbranch_scc1 .LBB0_286
	s_cmp_eq_u32 s3, 6
	s_cselect_b64 s[68:69], -1, 0
	s_cbranch_execz .LBB0_287
	s_branch .LBB0_288

; #define LAS __attribute__((address_space(3)))
; __device__ __forceinline__ float frsq(float x) { return __builtin_amdgcn_rsqf(x); }
; __device__ __forceinline__ unsigned cvtpk(float lo, float hi) { f32x2_t v = {lo, hi}; bf16x2_t b = __builtin_convertvector(v, bf16x2_t); return __builtin_bit_cast(unsigned, b); }
; #define HG_BAR() asm volatile("s_waitcnt lgkmcnt(0)\n\ts_barrier" ::: "memory")
; __device__ __forceinline__ void hgrn_mfma(Frame& F, int b, int h) {
;     ...
;         auto hgrn_finalize = [&](int cc, int tb2) __attribute__((always_inline)) {
;             const int vb = w - 4; const size_t row0 = rbase + 64 * cc;
;             bf16_t* mxb = MIX + row0 * 1024 + colh + 32 * vb;
;             const LAS float* rq = rowsq + (cc & 1) * 256; const LAS unsigned char* sb_ = stg + (cc & 1) * 20480 + tb2 * 2560;
; #pragma unroll
;             for (int j = 0; j < 2; ++j) { const int idx = lane + 64 * j, row = idx >> 2, c8 = idx & 3, t = 32 * tb2 + row;
;                 const u32x4 sg = sgp[tb2][j];
;                 const float rstd = frsq(((rq[t] + rq[64 + t]) + (rq[128 + t] + rq[192 + t])) * (1.0f / 128.0f) + EPS);
;                 const u32x4 a = *(const LAS u32x4*)(sb_ + row * 80 + c8 * 16);
;                 u32x4 ov; ov.x = cvtpk(bflo(a.x) * rstd * bflo(sg.x), bfhi(a.x) * rstd * bfhi(sg.x)); ov.y = cvtpk(bflo(a.y) * rstd * bflo(sg.y), bfhi(a.y) * rstd * bfhi(sg.y));
;                 ov.z = cvtpk(bflo(a.z) * rstd * bflo(sg.z), bfhi(a.z) * rstd * bfhi(sg.z)); ov.w = cvtpk(bflo(a.w) * rstd * bflo(sg.w), bfhi(a.w) * rstd * bfhi(sg.w));
;                 *(u32x4*)(mxb + (unsigned)(t * 1024 + 8 * c8)) = ov; }
;         };
;     ...
;             if (c > 0) hgrn_finalize(c - 1, 1);
;             hgrn_sgload(c, 1);
;             HG_BAR();
.LBB0_295:
	ds_read2_b32 v[0:1], v138 offset0:32 offset1:96
	ds_read2_b32 v[2:3], v138 offset0:160 offset1:224
	s_waitcnt vmcnt(17)
	v_lshlrev_b32_e32 v8, 16, v28
	v_and_b32_e32 v9, 0xffff0000, v28
	s_add_i32 s63, s63, 64
	s_waitcnt lgkmcnt(1)
	v_mov_b32_e32 v4, v0
	s_waitcnt lgkmcnt(0)
	v_mov_b32_e32 v5, v2
	v_mov_b32_e32 v2, v1
	v_pk_add_f32 v[0:1], v[4:5], v[2:3]
	v_lshl_add_u64 v[96:97], v[96:97], 0, s[86:87]
	v_add_f32_e32 v0, v0, v1
	v_fmamk_f32 v0, v0, 0x3c000000, v178
	v_rsq_f32_e32 v4, v0
	ds_read_b128 v[0:3], v91 offset:2560
	v_lshl_add_u64 v[98:99], v[98:99], 0, s[86:87]
	v_lshl_add_u64 v[104:105], v[104:105], 0, s[82:83]
	v_lshl_add_u64 v[106:107], v[106:107], 0, s[82:83]
	s_cmp_eq_u32 s44, 31
	s_waitcnt lgkmcnt(0)
	v_lshlrev_b32_e32 v6, 16, v0
	v_and_b32_e32 v7, 0xffff0000, v0
	v_pk_mul_f32 v[6:7], v[4:5], v[6:7] op_sel_hi:[0,1]
	v_pk_mul_f32 v[6:7], v[6:7], v[8:9]
	v_lshlrev_b32_e32 v8, 16, v29
	v_cvt_pk_bf16_f32 v0, v6, v7
	v_lshlrev_b32_e32 v6, 16, v1
	v_and_b32_e32 v7, 0xffff0000, v1
	v_pk_mul_f32 v[6:7], v[4:5], v[6:7] op_sel_hi:[0,1]
	v_and_b32_e32 v9, 0xffff0000, v29
	v_pk_mul_f32 v[6:7], v[6:7], v[8:9]
	v_lshlrev_b32_e32 v8, 16, v30
	v_cvt_pk_bf16_f32 v1, v6, v7
	v_lshlrev_b32_e32 v6, 16, v2
	v_and_b32_e32 v7, 0xffff0000, v2
	v_pk_mul_f32 v[6:7], v[4:5], v[6:7] op_sel_hi:[0,1]
	v_and_b32_e32 v9, 0xffff0000, v30
	v_pk_mul_f32 v[6:7], v[6:7], v[8:9]
	s_waitcnt vmcnt(16)
	v_lshlrev_b32_e32 v8, 16, v16
	v_cvt_pk_bf16_f32 v2, v6, v7
	v_lshlrev_b32_e32 v6, 16, v3
	v_and_b32_e32 v7, 0xffff0000, v3
	v_pk_mul_f32 v[4:5], v[4:5], v[6:7] op_sel_hi:[0,1]
	v_lshlrev_b32_e32 v6, 16, v31
	v_and_b32_e32 v7, 0xffff0000, v31
	v_pk_mul_f32 v[4:5], v[4:5], v[6:7]
	v_and_b32_e32 v9, 0xffff0000, v16
	v_cvt_pk_bf16_f32 v3, v4, v5
	v_lshl_add_u64 v[4:5], v[92:93], 0, s[42:43]
	global_store_dwordx4 v[4:5], v[0:3], off sc1
	ds_read2_b32 v[0:1], v139 offset0:32 offset1:96
	ds_read2_b32 v[2:3], v139 offset0:160 offset1:224
	v_lshl_add_u64 v[92:93], v[92:93], 0, s[86:87]
	s_waitcnt lgkmcnt(1)
	v_mov_b32_e32 v4, v0
	s_waitcnt lgkmcnt(0)
	v_mov_b32_e32 v5, v2
	v_mov_b32_e32 v2, v1
	v_pk_add_f32 v[0:1], v[4:5], v[2:3]
	ds_read_b128 v[2:5], v89 offset:2560
	v_add_f32_e32 v0, v0, v1
	v_fmamk_f32 v0, v0, 0x3c000000, v178
	v_rsq_f32_e32 v0, v0
	s_waitcnt lgkmcnt(0)
	v_lshlrev_b32_e32 v6, 16, v2
	v_and_b32_e32 v7, 0xffff0000, v2
	v_pk_mul_f32 v[6:7], v[0:1], v[6:7] op_sel_hi:[0,1]
	v_pk_mul_f32 v[6:7], v[6:7], v[8:9]
	v_lshlrev_b32_e32 v8, 16, v17
	v_cvt_pk_bf16_f32 v2, v6, v7
	v_lshlrev_b32_e32 v6, 16, v3
	v_and_b32_e32 v7, 0xffff0000, v3
	v_pk_mul_f32 v[6:7], v[0:1], v[6:7] op_sel_hi:[0,1]
	v_and_b32_e32 v9, 0xffff0000, v17
	v_pk_mul_f32 v[6:7], v[6:7], v[8:9]
	v_lshlrev_b32_e32 v8, 16, v18
	v_cvt_pk_bf16_f32 v3, v6, v7
	v_lshlrev_b32_e32 v6, 16, v4
	v_and_b32_e32 v7, 0xffff0000, v4
	v_pk_mul_f32 v[6:7], v[0:1], v[6:7] op_sel_hi:[0,1]
	v_and_b32_e32 v9, 0xffff0000, v18
	v_pk_mul_f32 v[6:7], v[6:7], v[8:9]
	s_nop 0
	v_cvt_pk_bf16_f32 v4, v6, v7
	v_lshlrev_b32_e32 v6, 16, v5
	v_and_b32_e32 v7, 0xffff0000, v5
	v_pk_mul_f32 v[0:1], v[0:1], v[6:7] op_sel_hi:[0,1]
	v_lshlrev_b32_e32 v6, 16, v19
	v_and_b32_e32 v7, 0xffff0000, v19
	v_pk_mul_f32 v[0:1], v[0:1], v[6:7]
	s_nop 0
	v_cvt_pk_bf16_f32 v5, v0, v1
	v_lshl_add_u64 v[0:1], v[94:95], 0, s[42:43]
	global_store_dwordx4 v[0:1], v[2:5], off sc1
	v_lshl_add_u64 v[0:1], v[102:103], 0, s[42:43]
	global_load_dwordx4 v[28:31], v[0:1], off
	v_lshl_add_u64 v[0:1], v[100:101], 0, s[42:43]
	global_load_dwordx4 v[16:19], v[0:1], off
	s_waitcnt lgkmcnt(0)
	s_barrier
	v_lshl_add_u64 v[94:95], v[94:95], 0, s[86:87]
	v_lshl_add_u64 v[100:101], v[100:101], 0, s[82:83]
	v_lshl_add_u64 v[102:103], v[102:103], 0, s[82:83]
	s_cbranch_scc1 .LBB0_297
	s_mov_b32 s71, s44
	s_branch .LBB0_281
; #define LAS __attribute__((address_space(3)))
; __device__ __forceinline__ float frsq(float x) { return __builtin_amdgcn_rsqf(x); }
; __device__ __forceinline__ unsigned cvtpk(float lo, float hi) { f32x2_t v = {lo, hi}; bf16x2_t b = __builtin_convertvector(v, bf16x2_t); return __builtin_bit_cast(unsigned, b); }
; __device__ __forceinline__ void hgrn_mfma(Frame& F, int b, int h) {
;     ...
;         auto hgrn_finalize = [&](int cc, int tb2) __attribute__((always_inline)) {
;             const int vb = w - 4; const size_t row0 = rbase + 64 * cc;
;             bf16_t* mxb = MIX + row0 * 1024 + colh + 32 * vb;
;             const LAS float* rq = rowsq + (cc & 1) * 256; const LAS unsigned char* sb_ = stg + (cc & 1) * 20480 + tb2 * 2560;
; #pragma unroll
;             for (int j = 0; j < 2; ++j) { const int idx = lane + 64 * j, row = idx >> 2, c8 = idx & 3, t = 32 * tb2 + row;
;                 const u32x4 sg = sgp[tb2][j];
;                 const float rstd = frsq(((rq[t] + rq[64 + t]) + (rq[128 + t] + rq[192 + t])) * (1.0f / 128.0f) + EPS);
;                 const u32x4 a = *(const LAS u32x4*)(sb_ + row * 80 + c8 * 16);
;                 u32x4 ov; ov.x = cvtpk(bflo(a.x) * rstd * bflo(sg.x), bfhi(a.x) * rstd * bfhi(sg.x)); ov.y = cvtpk(bflo(a.y) * rstd * bflo(sg.y), bfhi(a.y) * rstd * bfhi(sg.y));
;                 ov.z = cvtpk(bflo(a.z) * rstd * bflo(sg.z), bfhi(a.z) * rstd * bfhi(sg.z)); ov.w = cvtpk(bflo(a.w) * rstd * bflo(sg.w), bfhi(a.w) * rstd * bfhi(sg.w));
;                 *(u32x4*)(mxb + (unsigned)(t * 1024 + 8 * c8)) = ov; }
;         };
;     ...
;         hgrn_finalize(31, 0); hgrn_finalize(31, 1);
.LBB0_297:
	v_lshl_or_b32 v0, v136, 10, v137
	v_add_u32_e32 v176, 0x8000, v0
	v_lshl_or_b32 v0, v127, 10, v137
	v_add_u32_e32 v4, 0x8000, v0
	v_lshl_add_u32 v0, v136, 2, s52
	ds_read2_b32 v[14:15], v0 offset1:32
	s_waitcnt vmcnt(19)
	ds_read2_b32 v[32:33], v0 offset0:64 offset1:96
	ds_read2_b32 v[34:35], v0 offset0:128 offset1:160
	s_waitcnt vmcnt(18)
	ds_read2_b32 v[36:37], v0 offset0:192 offset1:224
	s_waitcnt vmcnt(5)
	v_lshlrev_b32_e32 v10, 16, v24
	s_waitcnt lgkmcnt(3)
	v_mov_b32_e32 v0, v14
	s_waitcnt lgkmcnt(2)
	v_mov_b32_e32 v2, v32
	s_waitcnt lgkmcnt(1)
	v_mov_b32_e32 v1, v34
	s_waitcnt lgkmcnt(0)
	v_mov_b32_e32 v3, v36
	v_pk_add_f32 v[0:1], v[0:1], v[2:3]
	v_add3_u32 v14, s56, v135, v125
	v_add_f32_e32 v0, v0, v1
	v_fmamk_f32 v0, v0, 0x3c000000, v178
	v_rsq_f32_e32 v6, v0
	ds_read_b128 v[0:3], v14 offset:20480
	v_and_b32_e32 v11, 0xffff0000, v24
	s_lshl_b32 s4, s54, 22
	v_readlane_b32 s5, v254, 63
	s_add_u32 s4, s5, s4
	s_waitcnt lgkmcnt(0)
	v_lshlrev_b32_e32 v8, 16, v0
	v_and_b32_e32 v9, 0xffff0000, v0
	v_pk_mul_f32 v[8:9], v[6:7], v[8:9] op_sel_hi:[0,1]
	v_pk_mul_f32 v[8:9], v[8:9], v[10:11]
	v_readlane_b32 s5, v255, 7
	v_cvt_pk_bf16_f32 v0, v8, v9
	v_lshlrev_b32_e32 v8, 16, v1
	v_and_b32_e32 v9, 0xffff0000, v1
	v_pk_mul_f32 v[8:9], v[6:7], v[8:9] op_sel_hi:[0,1]
	v_lshlrev_b32_e32 v10, 16, v25
	v_and_b32_e32 v11, 0xffff0000, v25
	s_addc_u32 s5, s5, 0
	v_pk_mul_f32 v[8:9], v[8:9], v[10:11]
	s_add_u32 s4, s4, s70
	v_cvt_pk_bf16_f32 v1, v8, v9
	v_lshlrev_b32_e32 v8, 16, v2
	v_and_b32_e32 v9, 0xffff0000, v2
	s_addc_u32 s5, s5, 0
	v_pk_mul_f32 v[8:9], v[6:7], v[8:9] op_sel_hi:[0,1]
	v_lshlrev_b32_e32 v10, 16, v26
	v_and_b32_e32 v11, 0xffff0000, v26
	s_add_u32 s4, s4, s51
	v_pk_mul_f32 v[8:9], v[8:9], v[10:11]
	s_addc_u32 s5, s5, 0
	v_cvt_pk_bf16_f32 v2, v8, v9
	v_lshlrev_b32_e32 v8, 16, v3
	v_and_b32_e32 v9, 0xffff0000, v3
	s_add_u32 s4, s4, 0x3e0000
	v_pk_mul_f32 v[6:7], v[6:7], v[8:9] op_sel_hi:[0,1]
	v_lshlrev_b32_e32 v8, 16, v27
	v_and_b32_e32 v9, 0xffff0000, v27
	v_mov_b32_e32 v91, v177
	s_addc_u32 s5, s5, 0
	v_pk_mul_f32 v[6:7], v[6:7], v[8:9]
	v_lshl_add_u32 v8, v127, 2, s52
	v_cvt_pk_bf16_f32 v3, v6, v7
	v_lshl_add_u64 v[6:7], v[90:91], 1, s[4:5]
	global_store_dwordx4 v[6:7], v[0:3], off offset:-256 sc1
	ds_read2_b32 v[2:3], v8 offset1:32
	ds_read2_b32 v[6:7], v8 offset0:64 offset1:96
	ds_read2_b32 v[0:1], v8 offset0:128 offset1:160
	ds_read2_b32 v[8:9], v8 offset0:192 offset1:224
	s_waitcnt vmcnt(5)
	v_lshlrev_b32_e32 v26, 16, v20
	s_waitcnt lgkmcnt(3)
	v_mov_b32_e32 v10, v2
	s_waitcnt lgkmcnt(2)
	v_mov_b32_e32 v12, v6
	s_waitcnt lgkmcnt(1)
	v_mov_b32_e32 v11, v0
	s_waitcnt lgkmcnt(0)
	v_mov_b32_e32 v13, v8
	v_pk_add_f32 v[10:11], v[10:11], v[12:13]
	v_add3_u32 v2, s56, v126, v125
	v_add_f32_e32 v0, v10, v11
	ds_read_b128 v[10:13], v2 offset:20480
	v_fmamk_f32 v0, v0, 0x3c000000, v178
	v_rsq_f32_e32 v0, v0
	v_and_b32_e32 v27, 0xffff0000, v20
	v_lshlrev_b32_e32 v20, 16, v21
	s_waitcnt lgkmcnt(0)
	v_lshlrev_b32_e32 v24, 16, v10
	v_and_b32_e32 v25, 0xffff0000, v10
	v_pk_mul_f32 v[24:25], v[0:1], v[24:25] op_sel_hi:[0,1]
	v_pk_mul_f32 v[24:25], v[24:25], v[26:27]
	v_and_b32_e32 v21, 0xffff0000, v21
	v_cvt_pk_bf16_f32 v10, v24, v25
	v_lshlrev_b32_e32 v24, 16, v11
	v_and_b32_e32 v25, 0xffff0000, v11
	v_pk_mul_f32 v[24:25], v[0:1], v[24:25] op_sel_hi:[0,1]
	v_pk_mul_f32 v[20:21], v[24:25], v[20:21]
	v_lshlrev_b32_e32 v24, 16, v22
	v_cvt_pk_bf16_f32 v11, v20, v21
	v_lshlrev_b32_e32 v20, 16, v12
	v_and_b32_e32 v21, 0xffff0000, v12
	v_pk_mul_f32 v[20:21], v[0:1], v[20:21] op_sel_hi:[0,1]
	v_and_b32_e32 v25, 0xffff0000, v22
	v_pk_mul_f32 v[20:21], v[20:21], v[24:25]
	v_lshlrev_b32_e32 v22, 16, v23
	v_cvt_pk_bf16_f32 v12, v20, v21
	v_lshlrev_b32_e32 v20, 16, v13
	v_and_b32_e32 v21, 0xffff0000, v13
	v_pk_mul_f32 v[20:21], v[0:1], v[20:21] op_sel_hi:[0,1]
	v_and_b32_e32 v23, 0xffff0000, v23
	v_mov_b32_e32 v89, v177
	v_pk_mul_f32 v[20:21], v[20:21], v[22:23]
	v_mov_b32_e32 v34, v15
	v_cvt_pk_bf16_f32 v13, v20, v21
	v_lshl_add_u64 v[20:21], v[88:89], 1, s[4:5]
	v_mov_b32_e32 v36, v33
	global_store_dwordx4 v[20:21], v[10:13], off offset:-256 sc1
	s_waitcnt vmcnt(3)
	v_lshlrev_b32_e32 v20, 16, v28
	v_and_b32_e32 v21, 0xffff0000, v28
	v_pk_add_f32 v[10:11], v[34:35], v[36:37]
	v_mov_b32_e32 v8, v7
	v_add_f32_e32 v0, v10, v11
	ds_read_b128 v[10:13], v14 offset:23040
	v_fmamk_f32 v0, v0, 0x3c000000, v178
	v_rsq_f32_e32 v0, v0
	v_mov_b32_e32 v5, v177
	v_lshl_add_u64 v[4:5], v[4:5], 1, s[4:5]
	s_waitcnt lgkmcnt(0)
	v_lshlrev_b32_e32 v14, 16, v10
	v_and_b32_e32 v15, 0xffff0000, v10
	v_pk_mul_f32 v[14:15], v[0:1], v[14:15] op_sel_hi:[0,1]
	v_pk_mul_f32 v[14:15], v[14:15], v[20:21]
	v_lshlrev_b32_e32 v20, 16, v29
	v_cvt_pk_bf16_f32 v10, v14, v15
	v_lshlrev_b32_e32 v14, 16, v11
	v_and_b32_e32 v15, 0xffff0000, v11
	v_pk_mul_f32 v[14:15], v[0:1], v[14:15] op_sel_hi:[0,1]
	v_and_b32_e32 v21, 0xffff0000, v29
	v_pk_mul_f32 v[14:15], v[14:15], v[20:21]
	v_lshlrev_b32_e32 v20, 16, v30
	v_cvt_pk_bf16_f32 v11, v14, v15
	v_lshlrev_b32_e32 v14, 16, v12
	v_and_b32_e32 v15, 0xffff0000, v12
	v_pk_mul_f32 v[14:15], v[0:1], v[14:15] op_sel_hi:[0,1]
	v_and_b32_e32 v21, 0xffff0000, v30
	v_pk_mul_f32 v[14:15], v[14:15], v[20:21]
	v_lshlrev_b32_e32 v20, 16, v31
	v_cvt_pk_bf16_f32 v12, v14, v15
	v_lshlrev_b32_e32 v14, 16, v13
	v_and_b32_e32 v15, 0xffff0000, v13
	v_pk_mul_f32 v[14:15], v[0:1], v[14:15] op_sel_hi:[0,1]
	v_mov_b32_e32 v0, v3
	v_pk_add_f32 v[0:1], v[0:1], v[8:9]
	v_and_b32_e32 v21, 0xffff0000, v31
	v_add_f32_e32 v0, v0, v1
	v_fmamk_f32 v0, v0, 0x3c000000, v178
	v_rsq_f32_e32 v6, v0
	ds_read_b128 v[0:3], v2 offset:23040
	v_pk_mul_f32 v[14:15], v[14:15], v[20:21]
	s_mov_b64 s[62:63], s[66:67]
	v_cvt_pk_bf16_f32 v13, v14, v15
	v_lshl_add_u64 v[14:15], v[176:177], 1, s[4:5]
	s_waitcnt lgkmcnt(0)
	v_lshlrev_b32_e32 v8, 16, v0
	v_and_b32_e32 v9, 0xffff0000, v0
	global_store_dwordx4 v[14:15], v[10:13], off offset:-256 sc1
	v_pk_mul_f32 v[8:9], v[6:7], v[8:9] op_sel_hi:[0,1]
	s_mov_b64 s[4:5], 0
	s_waitcnt vmcnt(3)
	v_lshlrev_b32_e32 v10, 16, v16
	v_and_b32_e32 v11, 0xffff0000, v16
	v_pk_mul_f32 v[8:9], v[8:9], v[10:11]
	v_lshlrev_b32_e32 v10, 16, v17
	v_cvt_pk_bf16_f32 v0, v8, v9
	v_lshlrev_b32_e32 v8, 16, v1
	v_and_b32_e32 v9, 0xffff0000, v1
	v_pk_mul_f32 v[8:9], v[6:7], v[8:9] op_sel_hi:[0,1]
	v_and_b32_e32 v11, 0xffff0000, v17
	v_pk_mul_f32 v[8:9], v[8:9], v[10:11]
	v_lshlrev_b32_e32 v10, 16, v18
	v_cvt_pk_bf16_f32 v1, v8, v9
	v_lshlrev_b32_e32 v8, 16, v2
	v_and_b32_e32 v9, 0xffff0000, v2
	v_pk_mul_f32 v[8:9], v[6:7], v[8:9] op_sel_hi:[0,1]
	v_and_b32_e32 v11, 0xffff0000, v18
	v_pk_mul_f32 v[8:9], v[8:9], v[10:11]
	s_mov_b32 s55, s81
	v_cvt_pk_bf16_f32 v2, v8, v9
	v_lshlrev_b32_e32 v8, 16, v3
	v_and_b32_e32 v9, 0xffff0000, v3
	v_pk_mul_f32 v[6:7], v[6:7], v[8:9] op_sel_hi:[0,1]
	v_lshlrev_b32_e32 v8, 16, v19
	v_and_b32_e32 v9, 0xffff0000, v19
	v_pk_mul_f32 v[6:7], v[6:7], v[8:9]
	s_mov_b32 s58, s50
	v_cvt_pk_bf16_f32 v3, v6, v7
	global_store_dwordx4 v[4:5], v[0:3], off offset:-256 sc1

; #define LAS __attribute__((address_space(3)))
; __device__ __forceinline__ float frcp(float x) { return __builtin_amdgcn_rcpf(x); }
; #define MFMA32(a, b, c) __builtin_amdgcn_mfma_f32_32x32x16_bf16((a), (b), (c), 0, 0, 0)
; __device__ __forceinline__ s16x4 ds_tr(const LAS unsigned char* p) { return __builtin_bit_cast(s16x4, __builtin_amdgcn_ds_read_tr16_b64_v4i16((LAS v4i16_t*)p)); }
; __device__ __forceinline__ void swa_compute(Frame& F, int u) {
;     ...
;         for (int j = 0; j < 5; ++j) {
;             const int kt = a + j;
;             if (n == 0 && kt < 4) continue;
;             const LAS unsigned char* Kt = Kimg + kt * 4096; const LAS unsigned char* Vt = Vimg + kt * 4096;
;             f32x16 acc;
; #pragma unroll
;             for (int r = 0; r < 16; ++r) acc[r] = -C2;
; #pragma unroll
;             for (int ks = 0; ks < 4; ++ks) { const bf16x8 kf = *(const LAS bf16x8*)(Kt + ((ks & 1) ? kbo : kbe) + 512 * (ks >> 1)); acc = MFMA32(kf, qf[ks], acc); }
; #pragma unroll
;             for (int r = 0; r < 16; ++r) { const int kl = (r & 3) + 8 * (r >> 2) + 4 * hi;
;                 const bool valid = (j == 0) ? (r32 < kl) : ((j == 4) ? (kl <= r32) : true);
;                 const float p = valid ? __builtin_amdgcn_exp2f(acc[r]) : 0.f; acc[r] = p; lsum += p; }
;             const bf16x8 pa0 = pack_step(acc, 0), pa1 = pack_step(acc, 1);
; #pragma unroll
;             for (int s = 0; s < 2; ++s)
; #pragma unroll
;                 for (int c = 0; c < 2; ++c) { const bf16x8 vf = cat8(ds_tr(Vt + s * 2048 + c * 512 + vb0), ds_tr(Vt + s * 2048 + c * 512 + vb1)); o[c] = MFMA32(vf, s ? pa1 : pa0, o[c]); }
;         }
;         lsum += __shfl_xor(lsum, 32);
;         const float inv = frcp(lsum + __builtin_amdgcn_exp2f(sinkv * 1.4426950408889634f - C2));
; #pragma unroll
;         for (int c = 0; c < 2; ++c)
; #pragma unroll
;             for (int g = 0; g < 4; ++g) { u32x2 w; w.x = cvtpk(o[c][4 * g] * inv, o[c][4 * g + 1] * inv); w.y = cvtpk(o[c][4 * g + 2] * inv, o[c][4 * g + 3] * inv);
;                 *(LAS u32x2*)(stg + r32 * 144 + (32 * c + 8 * g + 4 * hi) * 2) = w; }
; #pragma unroll
;         for (int jj = 0; jj < 4; ++jj) { const int idx = lane + 64 * jj, row = idx >> 3, c8 = idx & 7;
;             const u32x4 v = *(const LAS u32x4*)(stg + row * 144 + 16 * c8);
;             *(u32x4*)(MIX + (size_t)(R0 + row) * 1024 + 512 + hq * 64 + 8 * c8) = v; }
.LBB0_318:
	v_add_u32_e32 v9, s51, v170
	v_add_u32_e32 v48, v9, v174
	ds_read_b128 v[10:13], v48
	v_add_u32_e32 v9, v9, v175
	v_fma_f32 v0, v167, s52, -v151
	v_exp_f32_e32 v168, v0
	v_mov_b32_e32 v0, s69
	v_mad_u32_u24 v7, v169, s5, v0
	v_and_b32_e32 v176, 7, v152
	v_ashrrev_i32_e32 v167, 3, v152
	v_lshlrev_b32_e32 v0, 4, v176
	s_waitcnt vmcnt(3) lgkmcnt(0)
	v_mfma_f32_32x32x16_bf16 v[32:47], v[10:13], v[136:139], v[16:31]
	ds_read_b128 v[10:13], v9
	v_add_u32_e32 v2, s69, v0
	v_mul_lo_u32 v6, v167, s5
	s_lshl_b32 s84, s50, 1
	v_add_u32_e32 v3, 64, v152
	v_ashrrev_i32_e32 v151, 3, v3
	v_mul_lo_u32 v5, v151, s5
	v_add_u32_e32 v3, 0x80, v152
	s_waitcnt vmcnt(2) lgkmcnt(0)
	v_mfma_f32_32x32x16_bf16 v[32:47], v[10:13], v[140:143], v[32:47]
	ds_read_b128 v[10:13], v48 offset:512
	v_ashrrev_i32_e32 v15, 3, v3
	v_mul_lo_u32 v4, v15, s5
	v_add_u32_e32 v3, 0xc0, v152
	v_ashrrev_i32_e32 v14, 3, v3
	v_mul_lo_u32 v3, v14, s5
	v_add_u32_e32 v136, v2, v3
	s_waitcnt vmcnt(1) lgkmcnt(0)
	v_mfma_f32_32x32x16_bf16 v[32:47], v[10:13], v[132:135], v[32:47]
	ds_read_b128 v[10:13], v9 offset:512
	v_add_u32_e32 v132, v7, v150
	v_add_u32_e32 v133, v2, v6
	v_add_u32_e32 v134, v2, v5
	v_add_u32_e32 v135, v2, v4
	s_or_b32 s48, s97, s48
	s_waitcnt vmcnt(0) lgkmcnt(0)
	v_mfma_f32_32x32x16_bf16 v[32:47], v[10:13], v[128:131], v[32:47]
	s_nop 11
	v_exp_f32_e32 v9, v32
	v_exp_f32_e32 v10, v33
	v_exp_f32_e32 v11, v34
	v_exp_f32_e32 v12, v35
	v_cndmask_b32_e64 v9, v9, 0, s[42:43]
	v_exp_f32_e32 v13, v36
	v_add_f32_e32 v8, v8, v9
	v_cndmask_b32_e64 v10, 0, v10, s[40:41]
	v_exp_f32_e32 v32, v37
	v_add_f32_e32 v8, v10, v8
	v_cndmask_b32_e64 v11, v11, 0, s[38:39]
	v_exp_f32_e32 v33, v38
	v_add_f32_e32 v8, v11, v8
	v_cndmask_b32_e64 v12, v12, 0, s[36:37]
	v_exp_f32_e32 v34, v39
	v_add_f32_e32 v8, v12, v8
	v_cndmask_b32_e64 v13, v13, 0, s[34:35]
	v_exp_f32_e32 v35, v40
	v_add_f32_e32 v8, v13, v8
	v_cndmask_b32_e64 v32, v32, 0, s[30:31]
	v_exp_f32_e32 v36, v41
	v_add_f32_e32 v8, v32, v8
	v_cndmask_b32_e64 v33, v33, 0, s[28:29]
	v_exp_f32_e32 v37, v42
	v_add_f32_e32 v8, v33, v8
	v_cndmask_b32_e64 v34, v34, 0, s[26:27]
	v_exp_f32_e32 v38, v43
	v_add_f32_e32 v8, v34, v8
	v_cndmask_b32_e64 v35, v35, 0, s[24:25]
	v_exp_f32_e32 v39, v44
	v_add_f32_e32 v8, v35, v8
	v_cndmask_b32_e64 v36, v36, 0, s[22:23]
	v_exp_f32_e32 v40, v45
	v_add_f32_e32 v8, v36, v8
	v_cndmask_b32_e64 v37, v37, 0, s[20:21]
	v_exp_f32_e32 v41, v46
	v_add_f32_e32 v8, v37, v8
	v_cndmask_b32_e64 v38, v38, 0, s[18:19]
	v_add_f32_e32 v8, v38, v8
	v_cndmask_b32_e64 v39, v39, 0, s[16:17]
	v_add_f32_e32 v8, v39, v8
	v_cndmask_b32_e64 v40, v40, 0, s[14:15]
	v_add_f32_e32 v8, v40, v8
	v_cndmask_b32_e64 v41, v41, 0, s[12:13]
	v_add_f32_e32 v42, v41, v8
	v_exp_f32_e32 v8, v47
	s_nop 0
	v_cndmask_b32_e64 v43, v8, 0, s[10:11]
	v_cvt_pk_bf16_f32 v8, v9, v10
	v_cvt_pk_bf16_f32 v9, v11, v12
	v_add_u32_e32 v12, s51, v173
	v_cvt_pk_bf16_f32 v10, v13, v32
	v_add_u32_e32 v13, v12, v171
	v_add_u32_e32 v12, v12, v172
	v_cvt_pk_bf16_f32 v11, v33, v34
	v_cvt_pk_bf16_f32 v32, v35, v36
	v_cvt_pk_bf16_f32 v33, v37, v38
	v_cvt_pk_bf16_f32 v34, v39, v40
	ds_read_b64_tr_b16 v[36:37], v13 offset:32768
	ds_read_b64_tr_b16 v[38:39], v12 offset:33792
	s_waitcnt lgkmcnt(0)
	v_mfma_f32_32x32x16_bf16 v[80:95], v[36:39], v[8:11], v[80:95]
	ds_read_b64_tr_b16 v[36:37], v13 offset:33280
	ds_read_b64_tr_b16 v[38:39], v12 offset:34304
	v_cvt_pk_bf16_f32 v35, v41, v43
	s_waitcnt lgkmcnt(0)
	v_mfma_f32_32x32x16_bf16 v[64:79], v[36:39], v[8:11], v[64:79]
	ds_read_b64_tr_b16 v[8:9], v13 offset:34816
	ds_read_b64_tr_b16 v[10:11], v12 offset:35840
	s_waitcnt lgkmcnt(0)
	v_mfma_f32_32x32x16_bf16 v[80:95], v[8:11], v[32:35], v[80:95]
	ds_read_b64_tr_b16 v[8:9], v13 offset:35328
	ds_read_b64_tr_b16 v[10:11], v12 offset:36352
	s_waitcnt lgkmcnt(0)
	v_mfma_f32_32x32x16_bf16 v[64:79], v[8:11], v[32:35], v[64:79]
	v_add_f32_e32 v8, v43, v42
	ds_bpermute_b32 v9, v153, v8
	s_waitcnt lgkmcnt(0)
	v_add_f32_e32 v8, v8, v9
	v_add_f32_e32 v8, v168, v8
	v_rcp_f32_e32 v8, v8
	s_nop 1
	v_pk_mul_f32 v[10:11], v[80:81], v[8:9] op_sel_hi:[1,0]
	v_pk_mul_f32 v[12:13], v[82:83], v[8:9] op_sel_hi:[1,0]
	v_cvt_pk_bf16_f32 v10, v10, v11
	v_cvt_pk_bf16_f32 v11, v12, v13
	v_pk_mul_f32 v[12:13], v[84:85], v[8:9] op_sel_hi:[1,0]
	v_pk_mul_f32 v[32:33], v[86:87], v[8:9] op_sel_hi:[1,0]
	v_cvt_pk_bf16_f32 v12, v12, v13
	v_cvt_pk_bf16_f32 v13, v32, v33
	ds_write2_b64 v132, v[10:11], v[12:13] offset1:2
	v_pk_mul_f32 v[10:11], v[88:89], v[8:9] op_sel_hi:[1,0]
	v_pk_mul_f32 v[12:13], v[90:91], v[8:9] op_sel_hi:[1,0]
	v_cvt_pk_bf16_f32 v10, v10, v11
	v_cvt_pk_bf16_f32 v11, v12, v13
	v_pk_mul_f32 v[12:13], v[92:93], v[8:9] op_sel_hi:[1,0]
	v_pk_mul_f32 v[32:33], v[94:95], v[8:9] op_sel_hi:[1,0]
	v_cvt_pk_bf16_f32 v12, v12, v13
	v_cvt_pk_bf16_f32 v13, v32, v33
	ds_write2_b64 v132, v[10:11], v[12:13] offset0:4 offset1:6
	v_pk_mul_f32 v[10:11], v[64:65], v[8:9] op_sel_hi:[1,0]
	v_pk_mul_f32 v[12:13], v[66:67], v[8:9] op_sel_hi:[1,0]
	v_cvt_pk_bf16_f32 v10, v10, v11
	v_cvt_pk_bf16_f32 v11, v12, v13
	v_pk_mul_f32 v[12:13], v[68:69], v[8:9] op_sel_hi:[1,0]
	v_pk_mul_f32 v[32:33], v[70:71], v[8:9] op_sel_hi:[1,0]
	v_cvt_pk_bf16_f32 v12, v12, v13
	v_cvt_pk_bf16_f32 v13, v32, v33
	ds_write2_b64 v132, v[10:11], v[12:13] offset0:8 offset1:10
	v_pk_mul_f32 v[10:11], v[72:73], v[8:9] op_sel_hi:[1,0]
	v_pk_mul_f32 v[12:13], v[74:75], v[8:9] op_sel_hi:[1,0]
	v_cvt_pk_bf16_f32 v10, v10, v11
	v_cvt_pk_bf16_f32 v11, v12, v13
	v_pk_mul_f32 v[12:13], v[76:77], v[8:9] op_sel_hi:[1,0]
	v_pk_mul_f32 v[8:9], v[78:79], v[8:9] op_sel_hi:[1,0]
	v_cvt_pk_bf16_f32 v12, v12, v13
	v_cvt_pk_bf16_f32 v13, v8, v9
	ds_write2_b64 v132, v[10:11], v[12:13] offset0:12 offset1:14
	v_add_u32_e32 v10, s49, v167
	v_ashrrev_i32_e32 v11, 31, v10
	v_lshlrev_b64 v[10:11], 11, v[10:11]
	ds_read_b128 v[6:9], v133
	v_lshl_add_u64 v[10:11], s[92:93], 0, v[10:11]
	v_lshl_add_u64 v[10:11], v[10:11], 0, s[84:85]
	v_lshl_add_u64 v[10:11], v[10:11], 0, v[0:1]
	v_add_co_u32_e32 v10, vcc, s6, v10
	v_add_u32_e32 v32, s46, v173
	s_nop 0
	v_addc_co_u32_e32 v11, vcc, 0, v11, vcc
	s_waitcnt lgkmcnt(0)
; #define LAS __attribute__((address_space(3)))
; __device__ __forceinline__ void swa_compute(Frame& F, int u) {
;     ...
;     for (int aa = 0; aa < 2; ++aa) {
;         const int a = (F.wave & 1) * 2 + aa;
;         const int R0 = b * SEQ + n * 128 + 32 * a;
;         const bf16_t* qp = SQ + (size_t)(R0 + r32) * 512 + hq * 64 + 8 * hi;
;         bf16x8 qf[4];
; #pragma unroll
;         for (int ks = 0; ks < 4; ++ks) qf[ks] = *(const bf16x8*)(qp + 16 * ks);
;         f32x16 o[2]; float lsum = 0.f;
; #pragma unroll
;         for (int c = 0; c < 2; ++c)
; #pragma unroll
;             for (int r = 0; r < 16; ++r) o[c][r] = 0.f;
;         for (int j = 0; j < 5; ++j) {
;             const int kt = a + j;
;             if (n == 0 && kt < 4) continue;
;             const LAS unsigned char* Kt = Kimg + kt * 4096; const LAS unsigned char* Vt = Vimg + kt * 4096;
;             f32x16 acc;
; #pragma unroll
;             for (int r = 0; r < 16; ++r) acc[r] = -C2;
; #pragma unroll
;             for (int ks = 0; ks < 4; ++ks) { const bf16x8 kf = *(const LAS bf16x8*)(Kt + ((ks & 1) ? kbo : kbe) + 512 * (ks >> 1)); acc = MFMA32(kf, qf[ks], acc); }
; #pragma unroll
;             for (int r = 0; r < 16; ++r) { const int kl = (r & 3) + 8 * (r >> 2) + 4 * hi;
;                 const bool valid = (j == 0) ? (r32 < kl) : ((j == 4) ? (kl <= r32) : true);
;                 const float p = valid ? __builtin_amdgcn_exp2f(acc[r]) : 0.f; acc[r] = p; lsum += p; }
;             const bf16x8 pa0 = pack_step(acc, 0), pa1 = pack_step(acc, 1);
; #pragma unroll
;             for (int s = 0; s < 2; ++s)
; #pragma unroll
;                 for (int c = 0; c < 2; ++c) { const bf16x8 vf = cat8(ds_tr(Vt + s * 2048 + c * 512 + vb0), ds_tr(Vt + s * 2048 + c * 512 + vb1)); o[c] = MFMA32(vf, s ? pa1 : pa0, o[c]); }
;         }
;         lsum += __shfl_xor(lsum, 32);
;         const float inv = frcp(lsum + __builtin_amdgcn_exp2f(sinkv * 1.4426950408889634f - C2));
; #pragma unroll
;         for (int c = 0; c < 2; ++c)
; #pragma unroll
;             for (int g = 0; g < 4; ++g) { u32x2 w; w.x = cvtpk(o[c][4 * g] * inv, o[c][4 * g + 1] * inv); w.y = cvtpk(o[c][4 * g + 2] * inv, o[c][4 * g + 3] * inv);
;                 *(LAS u32x2*)(stg + r32 * 144 + (32 * c + 8 * g + 4 * hi) * 2) = w; }
; #pragma unroll
;         for (int jj = 0; jj < 4; ++jj) { const int idx = lane + 64 * jj, row = idx >> 3, c8 = idx & 7;
	global_store_dwordx4 v[10:11], v[6:9], off offset:1024 sc1
	v_add_u32_e32 v10, s49, v151
	v_ashrrev_i32_e32 v11, 31, v10
	v_lshlrev_b64 v[10:11], 11, v[10:11]
	ds_read_b128 v[6:9], v134
	v_lshl_add_u64 v[10:11], s[92:93], 0, v[10:11]
	v_lshl_add_u64 v[10:11], v[10:11], 0, s[84:85]
	v_lshl_add_u64 v[10:11], v[10:11], 0, v[0:1]
	v_add_co_u32_e32 v10, vcc, s6, v10
	v_add_u32_e32 v137, v32, v171
	s_nop 0
	v_addc_co_u32_e32 v11, vcc, 0, v11, vcc
	s_waitcnt lgkmcnt(0)
	global_store_dwordx4 v[10:11], v[6:9], off offset:1024 sc1
	ds_read_b128 v[4:7], v135
	s_nop 0
	v_add_u32_e32 v8, s49, v15
	v_ashrrev_i32_e32 v9, 31, v8
	v_lshlrev_b64 v[8:9], 11, v[8:9]
	v_lshl_add_u64 v[8:9], s[92:93], 0, v[8:9]
	v_lshl_add_u64 v[8:9], v[8:9], 0, s[84:85]
	v_lshl_add_u64 v[8:9], v[8:9], 0, v[0:1]
	v_add_co_u32_e32 v8, vcc, s6, v8
	s_nop 1
	v_addc_co_u32_e32 v9, vcc, 0, v9, vcc
	s_waitcnt lgkmcnt(0)
	global_store_dwordx4 v[8:9], v[4:7], off offset:1024 sc1
	ds_read_b128 v[2:5], v136
	s_nop 0
	v_add_u32_e32 v6, s49, v14
	v_ashrrev_i32_e32 v7, 31, v6
	v_lshlrev_b64 v[6:7], 11, v[6:7]
	v_lshl_add_u64 v[6:7], s[92:93], 0, v[6:7]
	v_lshl_add_u64 v[6:7], v[6:7], 0, s[84:85]
	v_lshl_add_u64 v[6:7], v[6:7], 0, v[0:1]
	v_add_co_u32_e32 v6, vcc, 0xb000000, v6
	v_add_u32_e32 v0, s46, v170
	s_nop 0
	v_addc_co_u32_e32 v7, vcc, 0, v7, vcc
	s_waitcnt lgkmcnt(0)
	global_store_dwordx4 v[6:7], v[2:5], off offset:1024 sc1
	s_and_b64 vcc, exec, s[44:45]
	v_add_u32_e32 v139, v0, v174
	v_or_b32_e32 v2, s48, v169
	v_ashrrev_i32_e32 v3, 31, v2
	v_lshlrev_b64 v[2:3], 10, v[2:3]
	v_lshl_add_u64 v[2:3], v[148:149], 0, v[2:3]
	global_load_dwordx4 v[128:131], v[2:3], off
	global_load_dwordx4 v[10:13], v[2:3], off offset:32
	global_load_dwordx4 v[6:9], v[2:3], off offset:64
	s_nop 0
	global_load_dwordx4 v[2:5], v[2:3], off offset:96
	v_add_u32_e32 v138, v0, v175
	v_add_u32_e32 v0, v32, v172
	s_cbranch_vccnz .LBB0_328
	ds_read_b128 v[48:51], v139
	s_waitcnt vmcnt(3) lgkmcnt(0)
	v_mfma_f32_32x32x16_bf16 v[32:47], v[48:51], v[128:131], v[16:31]
	ds_read_b128 v[48:51], v138
	s_waitcnt vmcnt(2) lgkmcnt(0)
	v_mfma_f32_32x32x16_bf16 v[32:47], v[48:51], v[10:13], v[32:47]
	ds_read_b128 v[48:51], v139 offset:512
	s_waitcnt vmcnt(1) lgkmcnt(0)
	v_mfma_f32_32x32x16_bf16 v[32:47], v[48:51], v[6:9], v[32:47]
	ds_read_b128 v[48:51], v138 offset:512
	s_waitcnt vmcnt(0) lgkmcnt(0)
	v_mfma_f32_32x32x16_bf16 v[32:47], v[48:51], v[2:5], v[32:47]
	s_nop 11
	v_exp_f32_e32 v32, v32
	v_exp_f32_e32 v33, v33
	v_exp_f32_e32 v34, v34
	v_exp_f32_e32 v35, v35
	v_cndmask_b32_e64 v32, 0, v32, s[42:43]
	v_exp_f32_e32 v36, v36
	v_add_f32_e32 v48, 0, v32
	v_cndmask_b32_e64 v33, v33, 0, s[40:41]
	v_exp_f32_e32 v37, v37
	v_add_f32_e32 v48, v33, v48
	v_cndmask_b32_e64 v34, 0, v34, s[38:39]
	v_add_f32_e32 v48, v34, v48
	v_cndmask_b32_e64 v35, 0, v35, s[36:37]
	v_add_f32_e32 v48, v35, v48
	v_cndmask_b32_e64 v49, 0, v36, s[34:35]
	v_add_f32_e32 v36, v49, v48
	v_cndmask_b32_e64 v48, 0, v37, s[30:31]
	v_exp_f32_e32 v37, v38
	v_add_f32_e32 v36, v48, v36
	v_cvt_pk_bf16_f32 v38, v49, v48
	v_cndmask_b32_e64 v50, 0, v37, s[28:29]
	v_exp_f32_e32 v37, v39
	v_add_f32_e32 v36, v50, v36
	v_cndmask_b32_e64 v39, 0, v37, s[26:27]
	v_exp_f32_e32 v37, v40
	v_add_f32_e32 v36, v39, v36
	v_cvt_pk_bf16_f32 v39, v50, v39
	v_cndmask_b32_e64 v51, 0, v37, s[24:25]
	v_exp_f32_e32 v37, v41
	v_add_f32_e32 v36, v51, v36
	v_cndmask_b32_e64 v52, 0, v37, s[22:23]
	v_exp_f32_e32 v37, v42
	v_add_f32_e32 v36, v52, v36
	v_cndmask_b32_e64 v42, 0, v37, s[20:21]
	v_exp_f32_e32 v37, v43
	v_add_f32_e32 v36, v42, v36
	v_cndmask_b32_e64 v43, 0, v37, s[18:19]
	v_exp_f32_e32 v37, v44
	v_add_f32_e32 v36, v43, v36
	v_cndmask_b32_e64 v44, 0, v37, s[16:17]
	v_exp_f32_e32 v37, v45
	v_add_f32_e32 v36, v44, v36
	v_cndmask_b32_e64 v45, 0, v37, s[14:15]
	v_exp_f32_e32 v37, v46
	v_add_f32_e32 v36, v45, v36
	v_cndmask_b32_e64 v46, 0, v37, s[12:13]
	v_add_f32_e32 v40, v46, v36
	v_exp_f32_e32 v36, v47
	v_cvt_pk_bf16_f32 v37, v34, v35
	v_cvt_pk_bf16_f32 v34, v44, v45
	v_cndmask_b32_e64 v41, 0, v36, s[10:11]
	v_cvt_pk_bf16_f32 v36, v32, v33
	v_cvt_pk_bf16_f32 v33, v42, v43
	ds_read_b64_tr_b16 v[42:43], v137 offset:32768
	ds_read_b64_tr_b16 v[44:45], v0 offset:33792
	s_waitcnt lgkmcnt(0)
	v_mfma_f32_32x32x16_bf16 v[64:79], v[42:45], v[36:39], 0
	ds_read_b64_tr_b16 v[42:43], v137 offset:33280
	ds_read_b64_tr_b16 v[44:45], v0 offset:34304
	v_cvt_pk_bf16_f32 v32, v51, v52
	v_cvt_pk_bf16_f32 v35, v46, v41
	v_add_f32_e32 v140, v41, v40
	s_waitcnt lgkmcnt(0)
	v_mfma_f32_32x32x16_bf16 v[48:63], v[42:45], v[36:39], 0
	ds_read_b64_tr_b16 v[36:37], v137 offset:34816
	ds_read_b64_tr_b16 v[38:39], v0 offset:35840
	s_waitcnt lgkmcnt(0)
	v_mfma_f32_32x32x16_bf16 v[64:79], v[36:39], v[32:35], v[64:79]
	ds_read_b64_tr_b16 v[36:37], v137 offset:35328
	ds_read_b64_tr_b16 v[38:39], v0 offset:36352
	s_waitcnt lgkmcnt(0)
	v_mfma_f32_32x32x16_bf16 v[48:63], v[36:39], v[32:35], v[48:63]
	s_andn2_b64 vcc, exec, s[82:83]
	s_cbranch_vccnz .LBB0_321

; #define LAS __attribute__((address_space(3)))
; #define MFMA32(a, b, c) __builtin_amdgcn_mfma_f32_32x32x16_bf16((a), (b), (c), 0, 0, 0)
; __device__ __forceinline__ s16x4 ds_tr(const LAS unsigned char* p) { return __builtin_bit_cast(s16x4, __builtin_amdgcn_ds_read_tr16_b64_v4i16((LAS v4i16_t*)p)); }
; __device__ __forceinline__ bf16x8 cat8(s16x4 lo, s16x4 hi) { return (bf16x8){lo[0], lo[1], lo[2], lo[3], hi[0], hi[1], hi[2], hi[3]}; }
; __device__ __forceinline__ void swa_compute(Frame& F, int u) {
;     ...
;         for (int j = 0; j < 5; ++j) {
;             const int kt = a + j;
;             if (n == 0 && kt < 4) continue;
;             const LAS unsigned char* Kt = Kimg + kt * 4096; const LAS unsigned char* Vt = Vimg + kt * 4096;
;             f32x16 acc;
; #pragma unroll
;             for (int r = 0; r < 16; ++r) acc[r] = -C2;
; #pragma unroll
;             for (int ks = 0; ks < 4; ++ks) { const bf16x8 kf = *(const LAS bf16x8*)(Kt + ((ks & 1) ? kbo : kbe) + 512 * (ks >> 1)); acc = MFMA32(kf, qf[ks], acc); }
; #pragma unroll
;             for (int r = 0; r < 16; ++r) { const int kl = (r & 3) + 8 * (r >> 2) + 4 * hi;
;                 const bool valid = (j == 0) ? (r32 < kl) : ((j == 4) ? (kl <= r32) : true);
;                 const float p = valid ? __builtin_amdgcn_exp2f(acc[r]) : 0.f; acc[r] = p; lsum += p; }
;             const bf16x8 pa0 = pack_step(acc, 0), pa1 = pack_step(acc, 1);
; #pragma unroll
;             for (int s = 0; s < 2; ++s)
; #pragma unroll
;                 for (int c = 0; c < 2; ++c) { const bf16x8 vf = cat8(ds_tr(Vt + s * 2048 + c * 512 + vb0), ds_tr(Vt + s * 2048 + c * 512 + vb1)); o[c] = MFMA32(vf, s ? pa1 : pa0, o[c]); }
.LBB0_324:
	ds_read_b128 v[66:69], v139 offset:12288
	v_lshlrev_b32_e32 v64, 3, v176
	s_waitcnt vmcnt(3) lgkmcnt(0)
	v_mfma_f32_32x32x16_bf16 v[48:63], v[66:69], v[128:131], v[16:31]
	ds_read_b128 v[66:69], v138 offset:12288
	s_waitcnt vmcnt(2) lgkmcnt(0)
	v_mfma_f32_32x32x16_bf16 v[48:63], v[66:69], v[10:13], v[48:63]
	ds_read_b128 v[66:69], v139 offset:12800
	s_waitcnt vmcnt(1) lgkmcnt(0)
	v_mfma_f32_32x32x16_bf16 v[48:63], v[66:69], v[6:9], v[48:63]
	ds_read_b128 v[66:69], v138 offset:12800
	s_waitcnt vmcnt(0) lgkmcnt(0)
	v_mfma_f32_32x32x16_bf16 v[48:63], v[66:69], v[2:5], v[48:63]
	s_nop 11
	v_exp_f32_e32 v48, v48
	v_exp_f32_e32 v49, v49
	v_exp_f32_e32 v50, v50
	v_exp_f32_e32 v51, v51
	v_add_f32_e32 v65, v141, v48
	v_exp_f32_e32 v52, v52
	v_add_f32_e32 v65, v49, v65
	v_exp_f32_e32 v53, v53
	v_add_f32_e32 v65, v50, v65
	v_exp_f32_e32 v54, v54
	v_add_f32_e32 v65, v51, v65
	v_exp_f32_e32 v55, v55
	v_add_f32_e32 v65, v52, v65
	v_exp_f32_e32 v56, v56
	v_add_f32_e32 v65, v53, v65
	v_exp_f32_e32 v57, v57
	v_add_f32_e32 v65, v54, v65
	v_exp_f32_e32 v58, v58
	v_add_f32_e32 v65, v55, v65
	v_exp_f32_e32 v59, v59
	v_add_f32_e32 v65, v56, v65
	v_add_f32_e32 v65, v57, v65
	v_add_f32_e32 v65, v58, v65
	v_add_f32_e32 v65, v59, v65
	v_cvt_pk_bf16_f32 v48, v48, v49
	v_cvt_pk_bf16_f32 v49, v50, v51
	v_cvt_pk_bf16_f32 v50, v52, v53
	v_cvt_pk_bf16_f32 v52, v56, v57
	v_cvt_pk_bf16_f32 v53, v58, v59
	ds_read_b64_tr_b16 v[56:57], v137 offset:45056
	ds_read_b64_tr_b16 v[58:59], v0 offset:46080
	v_cvt_pk_bf16_f32 v51, v54, v55
	v_exp_f32_e32 v60, v60
	v_exp_f32_e32 v61, v61
	s_waitcnt lgkmcnt(0)
	v_mfma_f32_32x32x16_bf16 v[80:95], v[56:59], v[48:51], v[80:95]
	ds_read_b64_tr_b16 v[56:57], v137 offset:45568
	ds_read_b64_tr_b16 v[58:59], v0 offset:46592
	v_exp_f32_e32 v62, v62
	v_exp_f32_e32 v63, v63
	v_cvt_pk_bf16_f32 v54, v60, v61
	v_add_f32_e32 v65, v60, v65
	v_add_f32_e32 v65, v61, v65
	v_cvt_pk_bf16_f32 v55, v62, v63
	s_waitcnt lgkmcnt(0)
	v_mfma_f32_32x32x16_bf16 v[32:47], v[56:59], v[48:51], v[32:47]
	ds_read_b64_tr_b16 v[48:49], v137 offset:47104
	ds_read_b64_tr_b16 v[50:51], v0 offset:48128
	v_add_f32_e32 v65, v62, v65
	s_waitcnt lgkmcnt(0)
	v_mfma_f32_32x32x16_bf16 v[80:95], v[48:51], v[52:55], v[80:95]
	ds_read_b64_tr_b16 v[48:49], v137 offset:47616
	ds_read_b64_tr_b16 v[50:51], v0 offset:48640
	s_waitcnt lgkmcnt(0)
	v_mfma_f32_32x32x16_bf16 v[32:47], v[48:51], v[52:55], v[32:47]
	ds_read_b128 v[48:51], v139 offset:16384
	v_add_f32_e32 v52, v63, v65
	s_waitcnt lgkmcnt(0)
	v_mfma_f32_32x32x16_bf16 v[16:31], v[48:51], v[128:131], v[16:31]
	ds_read_b128 v[48:51], v138 offset:16384
	s_waitcnt lgkmcnt(0)
	v_mfma_f32_32x32x16_bf16 v[16:31], v[48:51], v[10:13], v[16:31]
	ds_read_b128 v[10:13], v139 offset:16896
	s_waitcnt lgkmcnt(0)
	v_mfma_f32_32x32x16_bf16 v[16:31], v[10:13], v[6:9], v[16:31]
	ds_read_b128 v[6:9], v138 offset:16896
	s_waitcnt lgkmcnt(0)
	v_mfma_f32_32x32x16_bf16 v[16:31], v[6:9], v[2:5], v[16:31]
	s_nop 11
	v_exp_f32_e32 v2, v16
	v_exp_f32_e32 v4, v17
	v_exp_f32_e32 v5, v18
	v_exp_f32_e32 v6, v19
	v_cndmask_b32_e64 v2, v2, 0, s[42:43]
	v_exp_f32_e32 v7, v20
	v_add_f32_e32 v3, v52, v2
	v_cndmask_b32_e64 v4, 0, v4, s[40:41]
	v_exp_f32_e32 v8, v21
	v_add_f32_e32 v3, v4, v3
	v_cndmask_b32_e64 v5, v5, 0, s[38:39]
	v_exp_f32_e32 v9, v22
	v_add_f32_e32 v3, v5, v3
	v_cndmask_b32_e64 v6, v6, 0, s[36:37]
	v_exp_f32_e32 v10, v23
	v_add_f32_e32 v3, v6, v3
	v_cndmask_b32_e64 v7, v7, 0, s[34:35]
	v_exp_f32_e32 v11, v24
	v_add_f32_e32 v3, v7, v3
	v_cndmask_b32_e64 v8, v8, 0, s[30:31]
	v_exp_f32_e32 v12, v25
	v_add_f32_e32 v3, v8, v3
	v_cndmask_b32_e64 v9, v9, 0, s[28:29]
	v_exp_f32_e32 v13, v26
	v_add_f32_e32 v3, v9, v3
	v_cndmask_b32_e64 v10, v10, 0, s[26:27]
	v_exp_f32_e32 v16, v27
	v_add_f32_e32 v3, v10, v3
	v_cndmask_b32_e64 v11, v11, 0, s[24:25]
	v_exp_f32_e32 v17, v28
	v_add_f32_e32 v3, v11, v3
	v_cndmask_b32_e64 v12, v12, 0, s[22:23]
	v_exp_f32_e32 v18, v29
	v_add_f32_e32 v3, v12, v3
	v_cndmask_b32_e64 v13, v13, 0, s[20:21]
	v_exp_f32_e32 v19, v30
	v_add_f32_e32 v3, v13, v3
	v_cndmask_b32_e64 v16, v16, 0, s[18:19]
	v_add_f32_e32 v3, v16, v3
	v_cndmask_b32_e64 v17, v17, 0, s[16:17]
	v_add_f32_e32 v3, v17, v3
	v_cndmask_b32_e64 v18, v18, 0, s[14:15]
	v_add_f32_e32 v3, v18, v3
	v_cndmask_b32_e64 v19, v19, 0, s[12:13]
	v_add_f32_e32 v20, v19, v3
	v_exp_f32_e32 v3, v31
	v_cvt_pk_bf16_f32 v2, v2, v4
	v_cvt_pk_bf16_f32 v4, v7, v8
	v_cvt_pk_bf16_f32 v7, v13, v16
	v_cndmask_b32_e64 v21, v3, 0, s[10:11]
	v_cvt_pk_bf16_f32 v3, v5, v6
	v_cvt_pk_bf16_f32 v5, v9, v10
	v_cvt_pk_bf16_f32 v6, v11, v12
	ds_read_b64_tr_b16 v[10:11], v137 offset:49152
	ds_read_b64_tr_b16 v[12:13], v0 offset:50176
	s_waitcnt lgkmcnt(0)
; #define LAS __attribute__((address_space(3)))
; __device__ __forceinline__ float frcp(float x) { return __builtin_amdgcn_rcpf(x); }
; #define MFMA32(a, b, c) __builtin_amdgcn_mfma_f32_32x32x16_bf16((a), (b), (c), 0, 0, 0)
; __device__ __forceinline__ unsigned cvtpk(float lo, float hi) { f32x2_t v = {lo, hi}; bf16x2_t b = __builtin_convertvector(v, bf16x2_t); return __builtin_bit_cast(unsigned, b); }
; __device__ __forceinline__ s16x4 ds_tr(const LAS unsigned char* p) { return __builtin_bit_cast(s16x4, __builtin_amdgcn_ds_read_tr16_b64_v4i16((LAS v4i16_t*)p)); }
; __device__ __forceinline__ bf16x8 cat8(s16x4 lo, s16x4 hi) { return (bf16x8){lo[0], lo[1], lo[2], lo[3], hi[0], hi[1], hi[2], hi[3]}; }
; __device__ __forceinline__ void swa_compute(Frame& F, int u) {
;     ...
;             for (int r = 0; r < 16; ++r) { const int kl = (r & 3) + 8 * (r >> 2) + 4 * hi;
;                 const bool valid = (j == 0) ? (r32 < kl) : ((j == 4) ? (kl <= r32) : true);
;                 const float p = valid ? __builtin_amdgcn_exp2f(acc[r]) : 0.f; acc[r] = p; lsum += p; }
;             const bf16x8 pa0 = pack_step(acc, 0), pa1 = pack_step(acc, 1);
; #pragma unroll
;             for (int s = 0; s < 2; ++s)
; #pragma unroll
;                 for (int c = 0; c < 2; ++c) { const bf16x8 vf = cat8(ds_tr(Vt + s * 2048 + c * 512 + vb0), ds_tr(Vt + s * 2048 + c * 512 + vb1)); o[c] = MFMA32(vf, s ? pa1 : pa0, o[c]); }
;         }
;         lsum += __shfl_xor(lsum, 32);
;         const float inv = frcp(lsum + __builtin_amdgcn_exp2f(sinkv * 1.4426950408889634f - C2));
; #pragma unroll
;         for (int c = 0; c < 2; ++c)
; #pragma unroll
;             for (int g = 0; g < 4; ++g) { u32x2 w; w.x = cvtpk(o[c][4 * g] * inv, o[c][4 * g + 1] * inv); w.y = cvtpk(o[c][4 * g + 2] * inv, o[c][4 * g + 3] * inv);
;                 *(LAS u32x2*)(stg + r32 * 144 + (32 * c + 8 * g + 4 * hi) * 2) = w; }
; #pragma unroll
;         for (int jj = 0; jj < 4; ++jj) { const int idx = lane + 64 * jj, row = idx >> 3, c8 = idx & 7;
;             const u32x4 v = *(const LAS u32x4*)(stg + row * 144 + 16 * c8);
;             *(u32x4*)(MIX + (size_t)(R0 + row) * 1024 + 512 + hq * 64 + 8 * c8) = v; }
; __device__ __forceinline__ void swa_units(Frame& F, int u0, int stride) {
;     ...
;         __syncthreads();
;         swa_stage(F, kt_, vt_);
;         __syncthreads();
	v_mfma_f32_32x32x16_bf16 v[80:95], v[10:13], v[2:5], v[80:95]
	ds_read_b64_tr_b16 v[10:11], v137 offset:49664
	ds_read_b64_tr_b16 v[12:13], v0 offset:50688
	v_cvt_pk_bf16_f32 v8, v17, v18
	v_cvt_pk_bf16_f32 v9, v19, v21
	s_mov_b64 s[10:11], -1
	s_waitcnt lgkmcnt(0)
	v_mfma_f32_32x32x16_bf16 v[32:47], v[10:13], v[2:5], v[32:47]
	ds_read_b64_tr_b16 v[2:3], v137 offset:51200
	ds_read_b64_tr_b16 v[4:5], v0 offset:52224
	s_waitcnt lgkmcnt(0)
	v_mfma_f32_32x32x16_bf16 v[80:95], v[2:5], v[6:9], v[80:95]
	ds_read_b64_tr_b16 v[2:3], v137 offset:51712
	ds_read_b64_tr_b16 v[4:5], v0 offset:52736
	v_add_f32_e32 v0, v21, v20
	s_waitcnt lgkmcnt(0)
	v_mfma_f32_32x32x16_bf16 v[32:47], v[2:5], v[6:9], v[32:47]
	ds_bpermute_b32 v2, v153, v0
	s_waitcnt lgkmcnt(0)
	v_add_f32_e32 v0, v0, v2
	v_add_f32_e32 v0, v168, v0
	v_rcp_f32_e32 v0, v0
	s_nop 1
	v_pk_mul_f32 v[2:3], v[80:81], v[0:1] op_sel_hi:[1,0]
	v_pk_mul_f32 v[4:5], v[82:83], v[0:1] op_sel_hi:[1,0]
	v_cvt_pk_bf16_f32 v2, v2, v3
	v_cvt_pk_bf16_f32 v3, v4, v5
	v_pk_mul_f32 v[4:5], v[84:85], v[0:1] op_sel_hi:[1,0]
	v_pk_mul_f32 v[6:7], v[86:87], v[0:1] op_sel_hi:[1,0]
	v_cvt_pk_bf16_f32 v4, v4, v5
	v_cvt_pk_bf16_f32 v5, v6, v7
	ds_write2_b64 v132, v[2:3], v[4:5] offset1:2
	v_pk_mul_f32 v[2:3], v[88:89], v[0:1] op_sel_hi:[1,0]
	v_pk_mul_f32 v[4:5], v[90:91], v[0:1] op_sel_hi:[1,0]
	v_cvt_pk_bf16_f32 v2, v2, v3
	v_cvt_pk_bf16_f32 v3, v4, v5
	v_pk_mul_f32 v[4:5], v[92:93], v[0:1] op_sel_hi:[1,0]
	v_pk_mul_f32 v[6:7], v[94:95], v[0:1] op_sel_hi:[1,0]
	v_cvt_pk_bf16_f32 v4, v4, v5
	v_cvt_pk_bf16_f32 v5, v6, v7
	ds_write2_b64 v132, v[2:3], v[4:5] offset0:4 offset1:6
	v_pk_mul_f32 v[2:3], v[32:33], v[0:1] op_sel_hi:[1,0]
	v_pk_mul_f32 v[4:5], v[34:35], v[0:1] op_sel_hi:[1,0]
	v_cvt_pk_bf16_f32 v2, v2, v3
	v_cvt_pk_bf16_f32 v3, v4, v5
	v_pk_mul_f32 v[4:5], v[36:37], v[0:1] op_sel_hi:[1,0]
	v_pk_mul_f32 v[6:7], v[38:39], v[0:1] op_sel_hi:[1,0]
	v_cvt_pk_bf16_f32 v4, v4, v5
	v_cvt_pk_bf16_f32 v5, v6, v7
	ds_write2_b64 v132, v[2:3], v[4:5] offset0:8 offset1:10
	v_pk_mul_f32 v[2:3], v[40:41], v[0:1] op_sel_hi:[1,0]
	v_pk_mul_f32 v[4:5], v[42:43], v[0:1] op_sel_hi:[1,0]
	v_cvt_pk_bf16_f32 v2, v2, v3
	v_cvt_pk_bf16_f32 v3, v4, v5
	v_pk_mul_f32 v[4:5], v[44:45], v[0:1] op_sel_hi:[1,0]
	v_pk_mul_f32 v[6:7], v[46:47], v[0:1] op_sel_hi:[1,0]
	v_cvt_pk_bf16_f32 v4, v4, v5
	v_cvt_pk_bf16_f32 v5, v6, v7
	v_add_u32_e32 v6, s48, v167
	v_ashrrev_i32_e32 v7, 31, v6
	ds_write2_b64 v132, v[2:3], v[4:5] offset0:12 offset1:14
	v_lshlrev_b64 v[6:7], 11, v[6:7]
	ds_read_b128 v[2:5], v133
	v_lshl_add_u64 v[6:7], s[92:93], 0, v[6:7]
	v_lshl_add_u64 v[6:7], v[6:7], 0, s[84:85]
	v_lshlrev_b32_e32 v0, 1, v64
	v_lshl_add_u64 v[6:7], v[6:7], 0, v[0:1]
	v_add_co_u32_e32 v6, vcc, s6, v6
	s_nop 1
	v_addc_co_u32_e32 v7, vcc, 0, v7, vcc
	s_waitcnt lgkmcnt(0)
	global_store_dwordx4 v[6:7], v[2:5], off offset:1024 sc1
	v_add_u32_e32 v6, s48, v151
	v_ashrrev_i32_e32 v7, 31, v6
	v_lshlrev_b64 v[6:7], 11, v[6:7]
	ds_read_b128 v[2:5], v134
	v_lshl_add_u64 v[6:7], s[92:93], 0, v[6:7]
	v_lshl_add_u64 v[6:7], v[6:7], 0, s[84:85]
	v_lshl_add_u64 v[6:7], v[6:7], 0, v[0:1]
	v_add_co_u32_e32 v6, vcc, s6, v6
	s_nop 1
	v_addc_co_u32_e32 v7, vcc, 0, v7, vcc
	s_waitcnt lgkmcnt(0)
	global_store_dwordx4 v[6:7], v[2:5], off offset:1024 sc1
	v_add_u32_e32 v6, s48, v15
	v_ashrrev_i32_e32 v7, 31, v6
	v_lshlrev_b64 v[6:7], 11, v[6:7]
	ds_read_b128 v[2:5], v135
	v_lshl_add_u64 v[6:7], s[92:93], 0, v[6:7]
	v_lshl_add_u64 v[6:7], v[6:7], 0, s[84:85]
	v_lshl_add_u64 v[6:7], v[6:7], 0, v[0:1]
	v_add_co_u32_e32 v6, vcc, s6, v6
	s_nop 1
	v_addc_co_u32_e32 v7, vcc, 0, v7, vcc
	s_waitcnt lgkmcnt(0)
	global_store_dwordx4 v[6:7], v[2:5], off offset:1024 sc1
	v_add_u32_e32 v6, s48, v14
	v_ashrrev_i32_e32 v7, 31, v6
	v_lshlrev_b64 v[6:7], 11, v[6:7]
	v_lshl_add_u64 v[6:7], s[92:93], 0, v[6:7]
	ds_read_b128 v[2:5], v136
	v_lshl_add_u64 v[6:7], v[6:7], 0, s[84:85]
	v_lshl_add_u64 v[6:7], v[6:7], 0, v[0:1]
	v_add_co_u32_e32 v6, vcc, 0xb000000, v6
	s_nop 1
	v_addc_co_u32_e32 v7, vcc, 0, v7, vcc
	s_andn2_b64 vcc, exec, s[86:87]
	s_waitcnt lgkmcnt(0)
	global_store_dwordx4 v[6:7], v[2:5], off offset:1024 sc1
	s_cbranch_vccnz .LBB0_307
	s_add_i32 s68, s68, s47
	s_add_i32 s4, s4, s53
	s_mov_b64 s[10:11], 0
	s_barrier
	ds_write_b128 v162, v[96:99]
	ds_write_b128 v162, v[100:103] offset:32768
	ds_write_b128 v163, v[104:107]
	ds_write_b128 v163, v[108:111] offset:32768
	ds_write_b128 v164, v[112:115]
	ds_write_b128 v164, v[116:119] offset:32768
	ds_write_b128 v165, v[120:123]
	ds_write_b128 v165, v[124:127] offset:32768
	s_waitcnt lgkmcnt(0)
	s_barrier
	s_branch .LBB0_307

; __device__ __forceinline__ float frsq(float x) { return __builtin_amdgcn_rsqf(x); }
;     __device__ __forceinline__ void operator()(Acc& acc, const Unit& u, int wr, int wc, int fr, int fq) const {
;     ...
;                 const bool isk = (pn == 10);
;                 const float* gp = isk ? kng : qng; const float osc = isk ? 1.0f : 0.125f * 1.4426950408889634f;
;                 f32x4 g[2][2];
; #pragma unroll
;                 for (int bj = 0; bj < 2; ++bj)
; #pragma unroll
;                     for (int n = 0; n < 2; ++n) g[bj][n] = *(const f32x4*)(gp + bj * 32 + 8 * fq + 4 * n) * osc;
;                 bf16_t* ob = isk ? (SK + wc * 64 + 8 * fq) : (SQ + (pn - 8) * 256 + wc * 64 + 8 * fq); const int ld = isk ? 128 : 512;
; #pragma unroll
;                 for (int ai = 0; ai < 2; ++ai) {
; #pragma unroll
;                   for (int mh = 0; mh < 2; ++mh) {
;                     f32x4 rc[2][2], rs[2][2];
; #pragma unroll
;                     for (int m2 = 0; m2 < 2; ++m2) { const float* rp = rope + (size_t)(row0 + ai * HALF + (2 * mh + m2) * 16) * 16;
; #pragma unroll
;                         for (int n = 0; n < 2; ++n) { rc[m2][n] = *(const f32x4*)(rp + 4 * n); rs[m2][n] = *(const f32x4*)(rp + 8 + 4 * n); } }
;                     __builtin_amdgcn_sched_barrier(0);
; #pragma unroll
;                     for (int m2 = 0; m2 < 2; ++m2) { const int m = 2 * mh + m2;
;                         const int row = row0 + ai * HALF + m * 16;
;                         float ss = 0.f;
; #pragma unroll
;                         for (int bj = 0; bj < 2; ++bj)
; #pragma unroll
;                             for (int n = 0; n < 2; ++n) { const f32x4 v = acc[ai][bj][m][n]; ss += (v[0] * v[0] + v[1] * v[1]) + (v[2] * v[2] + v[3] * v[3]); }
;                         ss += __shfl_xor(ss, 16); ss += __shfl_xor(ss, 32);
;                         const float rstd = frsq(ss * (1.0f / 64.0f) + EPS);
.LBB0_360:
	v_mov_b32_e32 v219, v209
	v_mov_b32_e32 v128, v210
	s_lshl_b32 s4, s84, 8
	s_add_i32 s4, s4, s22
	v_lshlrev_b32_e32 v176, 3, v128
	v_add_u32_e32 v174, s4, v219
	v_add_u32_e32 v172, s23, v176
	s_cmp_lg_u32 s12, 1
	s_mov_b64 s[4:5], -1
	s_cbranch_scc0 .LBB0_383
	s_cmp_gt_i32 s40, 3
	s_cbranch_scc0 .LBB0_375
	s_cmp_gt_u32 s40, 5
	s_cbranch_scc0 .LBB0_372
	s_cmp_gt_u32 s40, 7
	s_cbranch_scc0 .LBB0_369
	s_cmp_eq_u32 s40, 10
	s_cselect_b64 s[70:71], -1, 0
	s_and_b64 s[48:49], s[70:71], s[52:53]
	s_andn2_b64 vcc, exec, s[48:49]
	v_ashrrev_i32_e32 v177, 31, v176
	s_cbranch_vccz .LBB0_366
	s_and_b64 s[4:5], s[70:71], exec
	s_mov_b64 s[4:5], s[62:63]
	s_mov_b32 s12, s55
	s_mov_b32 s35, s58
	s_mov_b64 s[80:81], s[52:53]
	v_readlane_b32 s48, v254, 24
	v_readlane_b32 s52, v254, 28
	v_readlane_b32 s53, v254, 29
	v_readlane_b32 s54, v254, 30
	v_readlane_b32 s55, v254, 31
	v_readlane_b32 s56, v254, 32
	v_readlane_b32 s57, v254, 33
	v_readlane_b32 s58, v254, 34
	v_readlane_b32 s59, v254, 35
	v_readlane_b32 s60, v254, 36
	v_readlane_b32 s61, v254, 37
	v_readlane_b32 s62, v254, 38
	v_readlane_b32 s63, v254, 39
	v_readlane_b32 s52, v254, 8
	v_readlane_b32 s49, v254, 25
	v_readlane_b32 s62, v254, 18
	v_readlane_b32 s63, v254, 19
	v_readlane_b32 s66, v254, 22
	v_readlane_b32 s67, v254, 23
	s_mov_b64 s[62:63], s[4:5]
	s_cselect_b32 s4, s49, s67
	s_cselect_b32 s5, s48, s66
	v_mov_b32_e32 v130, s5
	v_mov_b32_e32 v131, s4
	v_lshl_add_u64 v[140:141], v[176:177], 2, v[130:131]
	global_load_dwordx4 v[130:133], v[140:141], off offset:16
	global_load_dwordx4 v[134:137], v[140:141], off
	v_cndmask_b32_e64 v138, v216, 1.0, s[70:71]
	v_readlane_b32 s55, v254, 11
	s_lshl_b32 s4, s40, 8
	s_mov_b32 s55, s12
	s_add_i32 s12, s4, 0xfffff800
	s_lshl_b64 s[4:5], s[12:13], 1
	v_readlane_b32 s12, v254, 47
	v_readlane_b32 s58, v254, 14
	s_add_u32 s12, s12, s4
	v_readlane_b32 s4, v254, 48
	s_mov_b32 s58, s35
	s_addc_u32 s35, s4, s5
	v_xor_b32_e32 v129, 16, v217
	s_and_b64 s[4:5], s[70:71], exec
	v_readlane_b32 s4, v254, 49
	v_readlane_b32 s5, v254, 50
	s_cselect_b32 s4, s4, s12
	v_readlane_b32 s12, v254, 63
	v_readlane_b32 s50, v254, 26
	v_readlane_b32 s51, v254, 27
	s_cselect_b32 s5, s5, s35
	s_add_u32 s4, s4, s12
	s_addc_u32 s5, s5, 0
	v_ashrrev_i32_e32 v175, 31, v174
	v_readlane_b32 s50, v254, 57
	v_lshl_add_u64 v[178:179], v[176:177], 1, s[4:5]
	v_cmp_eq_u32_e64 s[4:5], 0, v128
	v_readlane_b32 s51, v254, 58
	v_add_u32_e32 v196, 16, v174
	v_ashrrev_i32_e32 v197, 31, v196
	v_readlane_b32 s53, v254, 9
	v_readlane_b32 s56, v254, 12
	v_readlane_b32 s57, v254, 13
	v_readlane_b32 s60, v254, 16
	v_readlane_b32 s61, v254, 17
	v_readlane_b32 s64, v254, 20
	v_readlane_b32 s65, v254, 21
	s_mov_b64 s[56:57], 0x4000
	s_mov_b64 s[64:65], 0x20000
	s_mov_b64 s[60:61], 0xc000
	s_mov_b64 s[52:53], s[80:81]
	s_mov_b64 s[66:67], 0x24000
	v_readlane_b32 s54, v254, 10
	v_readlane_b32 s59, v254, 15
	s_waitcnt vmcnt(0)
	v_pk_mul_f32 v[180:181], v[138:139], v[132:133] op_sel_hi:[0,1]
	v_pk_mul_f32 v[184:185], v[138:139], v[136:137] op_sel_hi:[0,1]
	v_pk_mul_f32 v[186:187], v[138:139], v[134:135] op_sel_hi:[0,1]
	v_pk_mul_f32 v[182:183], v[138:139], v[130:131] op_sel_hi:[0,1]
	global_load_dwordx4 v[130:133], v[140:141], off offset:144
	global_load_dwordx4 v[134:137], v[140:141], off offset:128
	s_waitcnt vmcnt(1)
	v_pk_mul_f32 v[190:191], v[138:139], v[130:131] op_sel_hi:[0,1]
	v_and_b32_e32 v130, 64, v217
	v_add_u32_e32 v130, 64, v130
	v_cmp_lt_i32_e32 vcc, v129, v130
	s_waitcnt vmcnt(0)
	v_pk_mul_f32 v[192:193], v[138:139], v[136:137] op_sel_hi:[0,1]
	v_pk_mul_f32 v[194:195], v[138:139], v[134:135] op_sel_hi:[0,1]
	v_cndmask_b32_e32 v129, v217, v129, vcc
	v_lshlrev_b32_e32 v173, 2, v129
	v_xor_b32_e32 v129, 32, v217
	v_cmp_lt_i32_e32 vcc, v129, v130
	v_pk_mul_f32 v[188:189], v[138:139], v[132:133] op_sel_hi:[0,1]
	s_nop 0
	v_cndmask_b32_e32 v129, v217, v129, vcc
	v_lshlrev_b32_e32 v220, 2, v129
	v_cmp_gt_i32_e32 vcc, 2, v128
	v_lshlrev_b64 v[128:129], 6, v[174:175]
	v_lshl_add_u64 v[128:129], s[50:51], 0, v[128:129]
	global_load_dwordx4 v[144:147], v[128:129], off offset:16
	global_load_dwordx4 v[148:151], v[128:129], off offset:48
	global_load_dwordx4 v[152:155], v[128:129], off
	global_load_dwordx4 v[156:159], v[128:129], off offset:32
	v_lshlrev_b64 v[128:129], 6, v[196:197]
	v_lshl_add_u64 v[140:141], s[50:51], 0, v[128:129]
	global_load_dwordx4 v[128:131], v[140:141], off offset:16
	global_load_dwordx4 v[132:135], v[140:141], off offset:48
	global_load_dwordx4 v[136:139], v[140:141], off
	s_nop 0
	global_load_dwordx4 v[140:143], v[140:141], off offset:32
	v_pk_mul_f32 v[198:199], v[126:127], v[126:127]
	v_pk_mul_f32 v[200:201], v[124:125], v[124:125]
	s_and_b64 s[48:49], s[70:71], exec
	v_pk_mov_b32 v[202:203], v[200:201], v[198:199] op_sel:[1,0]
	v_mov_b32_e32 v201, v199
	v_pk_add_f32 v[198:199], v[202:203], v[200:201]
	v_pk_mul_f32 v[200:201], v[122:123], v[122:123]
	v_pk_mul_f32 v[202:203], v[120:121], v[120:121]
	v_pk_add_f32 v[198:199], v[198:199], v[198:199] op_sel:[0,1] op_sel_hi:[1,0]
	v_pk_mov_b32 v[204:205], v[202:203], v[200:201] op_sel:[1,0]
	v_mov_b32_e32 v203, v201
	v_pk_add_f32 v[200:201], v[204:205], v[202:203]
	v_mul_f32_e32 v202, v104, v104
	v_mul_f32_e32 v203, v105, v105
	v_pk_add_f32 v[200:201], v[200:201], v[200:201] op_sel:[0,1] op_sel_hi:[1,0]
	v_mov_b32_e32 v199, v202
	v_mov_b32_e32 v201, v203
	v_pk_add_f32 v[198:199], v[198:199], v[200:201]
	v_mul_f32_e32 v200, v113, v113
	v_mul_f32_e32 v202, v115, v115
	v_mul_f32_e32 v204, v106, v106
	v_mul_f32_e32 v205, v107, v107
	v_pk_fma_f32 v[200:201], v[112:113], v[112:113], v[200:201] op_sel_hi:[1,1,0]
	v_pk_fma_f32 v[202:203], v[114:115], v[114:115], v[202:203] op_sel_hi:[1,1,0]
	v_mov_b32_e32 v201, v204
	v_mov_b32_e32 v203, v205
	v_pk_add_f32 v[200:201], v[200:201], v[202:203]
	s_cselect_b32 s12, 7, 9
	v_pk_add_f32 v[198:199], v[198:199], v[200:201]
	s_nop 0
	v_add_f32_e32 v198, v198, v199
	ds_bpermute_b32 v199, v173, v198
	s_waitcnt lgkmcnt(0)
; __device__ __forceinline__ u32x4 pack8(const f32x4& a, const f32x4& b) { u32x4 w; w.x = cvt_pk_bf16(a[0], a[1]); w.y = cvt_pk_bf16(a[2], a[3]); w.z = cvt_pk_bf16(b[0], b[1]); w.w = cvt_pk_bf16(b[2], b[3]); return w; }
; __device__ __forceinline__ float frsq(float x) { return __builtin_amdgcn_rsqf(x); }
;     __device__ __forceinline__ void operator()(Acc& acc, const Unit& u, int wr, int wc, int fr, int fq) const {
;     ...
;                     for (int m2 = 0; m2 < 2; ++m2) { const float* rp = rope + (size_t)(row0 + ai * HALF + (2 * mh + m2) * 16) * 16;
; #pragma unroll
;                         for (int n = 0; n < 2; ++n) { rc[m2][n] = *(const f32x4*)(rp + 4 * n); rs[m2][n] = *(const f32x4*)(rp + 8 + 4 * n); } }
;                     __builtin_amdgcn_sched_barrier(0);
; #pragma unroll
;                     for (int m2 = 0; m2 < 2; ++m2) { const int m = 2 * mh + m2;
;                         const int row = row0 + ai * HALF + m * 16;
;                         float ss = 0.f;
; #pragma unroll
;                         for (int bj = 0; bj < 2; ++bj)
; #pragma unroll
;                             for (int n = 0; n < 2; ++n) { const f32x4 v = acc[ai][bj][m][n]; ss += (v[0] * v[0] + v[1] * v[1]) + (v[2] * v[2] + v[3] * v[3]); }
;                         ss += __shfl_xor(ss, 16); ss += __shfl_xor(ss, 32);
;                         const float rstd = frsq(ss * (1.0f / 64.0f) + EPS);
;                         f32x4 y[2][2];
; #pragma unroll
;                         for (int bj = 0; bj < 2; ++bj)
; #pragma unroll
;                             for (int n = 0; n < 2; ++n) y[bj][n] = acc[ai][bj][m][n] * rstd * g[bj][n];
; #pragma unroll
;                         for (int n = 0; n < 2; ++n) {
;                             const f32x4 cs = rc[m2][n], sn = rs[m2][n];
;                             f32x4 o;
; #pragma unroll
;                             for (int i = 0; i < 4; ++i) { const float mine = y[0][n][i], oth = __shfl_xor(mine, 16);
;                                 const float r = (fq == 0) ? (mine * cs[i] - oth * sn[i]) : (mine * cs[i] + oth * sn[i]);
;                                 o[i] = (fq < 2) ? r : mine; }
;                             y[0][n] = o;
;                         }
; #pragma unroll
;                         for (int bj = 0; bj < 2; ++bj) *(u32x4*)(ob + (size_t)row * ld + bj * 32) = pack8(y[bj][0], y[bj][1]);
	v_add_f32_e32 v198, v198, v199
	ds_bpermute_b32 v199, v220, v198
	s_waitcnt lgkmcnt(0)
	v_add_f32_e32 v198, v198, v199
	v_fmamk_f32 v198, v198, 0x3c800000, v215
	v_rsq_f32_e32 v202, v198
	s_nop 0
	v_pk_mul_f32 v[198:199], v[124:125], v[202:203] op_sel_hi:[1,0]
	s_nop 0
	v_pk_mul_f32 v[224:225], v[186:187], v[198:199]
	ds_bpermute_b32 v221, v173, v224
	v_pk_mul_f32 v[200:201], v[126:127], v[202:203] op_sel_hi:[1,0]
	v_pk_mul_f32 v[198:199], v[120:121], v[202:203] op_sel_hi:[1,0]
	v_pk_mul_f32 v[222:223], v[184:185], v[200:201]
	v_pk_mul_f32 v[226:227], v[182:183], v[198:199]
	s_waitcnt vmcnt(4) lgkmcnt(0)
	v_mul_f32_e32 v156, v156, v221
	v_cndmask_b32_e64 v156, v156, -v156, s[4:5]
	v_fmac_f32_e32 v156, v152, v224
	v_cndmask_b32_e32 v152, v224, v156, vcc
	ds_bpermute_b32 v156, v173, v225
	v_pk_mul_f32 v[200:201], v[122:123], v[202:203] op_sel_hi:[1,0]
	v_pk_mul_f32 v[198:199], v[114:115], v[202:203] op_sel_hi:[1,0]
	v_pk_mul_f32 v[206:207], v[180:181], v[200:201]
	v_pk_mul_f32 v[200:201], v[112:113], v[202:203] op_sel_hi:[1,0]
	s_waitcnt lgkmcnt(0)
	v_mul_f32_e32 v156, v157, v156
	v_cndmask_b32_e64 v156, v156, -v156, s[4:5]
	v_fmac_f32_e32 v156, v153, v225
	v_cndmask_b32_e32 v153, v225, v156, vcc
	ds_bpermute_b32 v156, v173, v222
	v_pk_mul_f32 v[204:205], v[104:105], v[202:203] op_sel_hi:[1,0]
	v_pk_mul_f32 v[202:203], v[106:107], v[202:203] op_sel_hi:[1,0]
	v_pk_mul_f32 v[198:199], v[192:193], v[198:199]
	v_pk_mul_f32 v[200:201], v[194:195], v[200:201]
	s_waitcnt lgkmcnt(0)
	v_mul_f32_e32 v156, v158, v156
	v_cndmask_b32_e64 v156, v156, -v156, s[4:5]
	v_fmac_f32_e32 v156, v154, v222
	v_cndmask_b32_e32 v154, v222, v156, vcc
	ds_bpermute_b32 v156, v173, v223
	v_pk_mul_f32 v[202:203], v[188:189], v[202:203]
	v_pk_mul_f32 v[204:205], v[190:191], v[204:205]
	s_waitcnt lgkmcnt(0)
	v_mul_f32_e32 v156, v159, v156
	v_cndmask_b32_e64 v156, v156, -v156, s[4:5]
	v_fmac_f32_e32 v156, v155, v223
	v_cndmask_b32_e32 v155, v223, v156, vcc
	ds_bpermute_b32 v156, v173, v226
	s_waitcnt lgkmcnt(0)
	v_mul_f32_e32 v148, v148, v156
	v_cndmask_b32_e64 v148, v148, -v148, s[4:5]
	v_fmac_f32_e32 v148, v144, v226
	ds_bpermute_b32 v144, v173, v227
	v_cndmask_b32_e32 v156, v226, v148, vcc
	s_waitcnt lgkmcnt(0)
	v_mul_f32_e32 v144, v149, v144
	v_cndmask_b32_e64 v144, v144, -v144, s[4:5]
	v_fmac_f32_e32 v144, v145, v227
	v_cndmask_b32_e32 v157, v227, v144, vcc
	ds_bpermute_b32 v144, v173, v206
	s_waitcnt lgkmcnt(0)
	v_mul_f32_e32 v144, v150, v144
	v_cndmask_b32_e64 v144, v144, -v144, s[4:5]
	v_fmac_f32_e32 v144, v146, v206
	v_cndmask_b32_e32 v150, v206, v144, vcc
	ds_bpermute_b32 v144, v173, v207
	s_waitcnt lgkmcnt(0)
	v_mul_f32_e32 v144, v151, v144
	v_cndmask_b32_e64 v144, v144, -v144, s[4:5]
	v_fmac_f32_e32 v144, v147, v207
	v_cndmask_b32_e32 v147, v207, v144, vcc
	v_lshlrev_b64 v[144:145], s12, v[174:175]
	v_lshl_add_u64 v[148:149], v[144:145], 1, v[178:179]
	v_cvt_pk_bf16_f32 v144, v152, v153
	v_cvt_pk_bf16_f32 v145, v154, v155
	v_cvt_pk_bf16_f32 v146, v156, v157
	v_cvt_pk_bf16_f32 v147, v150, v147
	global_store_dwordx4 v[148:149], v[144:147], off sc1
	s_nop 1
	v_cvt_pk_bf16_f32 v144, v200, v201
	v_cvt_pk_bf16_f32 v145, v198, v199
	v_cvt_pk_bf16_f32 v146, v204, v205
	v_cvt_pk_bf16_f32 v147, v202, v203
	global_store_dwordx4 v[148:149], v[144:147], off offset:64 sc1
	s_nop 1
	v_pk_mul_f32 v[144:145], v[118:119], v[118:119]
	v_pk_mul_f32 v[146:147], v[116:117], v[116:117]
	s_nop 0
	v_pk_mov_b32 v[148:149], v[146:147], v[144:145] op_sel:[1,0]
	v_mov_b32_e32 v147, v145
	v_pk_add_f32 v[144:145], v[148:149], v[146:147]
	v_pk_mul_f32 v[146:147], v[110:111], v[110:111]
	v_pk_mul_f32 v[148:149], v[108:109], v[108:109]
	v_pk_add_f32 v[144:145], v[144:145], v[144:145] op_sel:[0,1] op_sel_hi:[1,0]
	v_pk_mov_b32 v[150:151], v[148:149], v[146:147] op_sel:[1,0]
	v_mov_b32_e32 v149, v147
	v_pk_add_f32 v[146:147], v[150:151], v[148:149]
	v_mul_f32_e32 v148, v88, v88
	v_mul_f32_e32 v149, v89, v89
	v_pk_add_f32 v[146:147], v[146:147], v[146:147] op_sel:[0,1] op_sel_hi:[1,0]
	v_mov_b32_e32 v145, v148
	v_mov_b32_e32 v147, v149
	v_pk_add_f32 v[144:145], v[144:145], v[146:147]
	v_mul_f32_e32 v146, v97, v97
	v_mul_f32_e32 v148, v99, v99
	v_mul_f32_e32 v150, v90, v90
	v_mul_f32_e32 v151, v91, v91
	v_pk_fma_f32 v[146:147], v[96:97], v[96:97], v[146:147] op_sel_hi:[1,1,0]
	v_pk_fma_f32 v[148:149], v[98:99], v[98:99], v[148:149] op_sel_hi:[1,1,0]
	v_mov_b32_e32 v147, v150
	v_mov_b32_e32 v149, v151
	v_pk_add_f32 v[146:147], v[146:147], v[148:149]
	s_nop 0
	v_pk_add_f32 v[144:145], v[144:145], v[146:147]
	s_nop 0
	v_add_f32_e32 v144, v144, v145
	ds_bpermute_b32 v145, v173, v144
	s_waitcnt lgkmcnt(0)
	v_add_f32_e32 v144, v144, v145
	ds_bpermute_b32 v145, v220, v144
	s_waitcnt lgkmcnt(0)
	v_add_f32_e32 v144, v144, v145
	v_fmamk_f32 v144, v144, 0x3c800000, v215
	v_rsq_f32_e32 v144, v144
	s_nop 0
	v_pk_mul_f32 v[146:147], v[116:117], v[144:145] op_sel_hi:[1,0]
	s_nop 0
	v_pk_mul_f32 v[156:157], v[186:187], v[146:147]
	ds_bpermute_b32 v175, v173, v156
	v_pk_mul_f32 v[148:149], v[118:119], v[144:145] op_sel_hi:[1,0]
	v_pk_mul_f32 v[146:147], v[108:109], v[144:145] op_sel_hi:[1,0]
	v_pk_mul_f32 v[154:155], v[184:185], v[148:149]
	v_pk_mul_f32 v[158:159], v[182:183], v[146:147]
	s_waitcnt vmcnt(2) lgkmcnt(0)
	v_mul_f32_e32 v140, v140, v175
	v_cndmask_b32_e64 v140, v140, -v140, s[4:5]
	v_fmac_f32_e32 v140, v136, v156
	v_cndmask_b32_e32 v136, v156, v140, vcc
	ds_bpermute_b32 v140, v173, v157
	v_pk_mul_f32 v[148:149], v[110:111], v[144:145] op_sel_hi:[1,0]
	v_pk_mul_f32 v[146:147], v[98:99], v[144:145] op_sel_hi:[1,0]
	v_pk_mul_f32 v[152:153], v[180:181], v[148:149]
	v_pk_mul_f32 v[148:149], v[96:97], v[144:145] op_sel_hi:[1,0]
	s_waitcnt lgkmcnt(0)
; __device__ __forceinline__ u32x4 pack8(const f32x4& a, const f32x4& b) { u32x4 w; w.x = cvt_pk_bf16(a[0], a[1]); w.y = cvt_pk_bf16(a[2], a[3]); w.z = cvt_pk_bf16(b[0], b[1]); w.w = cvt_pk_bf16(b[2], b[3]); return w; }
; __device__ __forceinline__ float frsq(float x) { return __builtin_amdgcn_rsqf(x); }
;     __device__ __forceinline__ void operator()(Acc& acc, const Unit& u, int wr, int wc, int fr, int fq) const {
;     ...
;                     for (int m2 = 0; m2 < 2; ++m2) { const float* rp = rope + (size_t)(row0 + ai * HALF + (2 * mh + m2) * 16) * 16;
; #pragma unroll
;                         for (int n = 0; n < 2; ++n) { rc[m2][n] = *(const f32x4*)(rp + 4 * n); rs[m2][n] = *(const f32x4*)(rp + 8 + 4 * n); } }
;                     __builtin_amdgcn_sched_barrier(0);
; #pragma unroll
;                     for (int m2 = 0; m2 < 2; ++m2) { const int m = 2 * mh + m2;
;                         const int row = row0 + ai * HALF + m * 16;
;                         float ss = 0.f;
; #pragma unroll
;                         for (int bj = 0; bj < 2; ++bj)
; #pragma unroll
;                             for (int n = 0; n < 2; ++n) { const f32x4 v = acc[ai][bj][m][n]; ss += (v[0] * v[0] + v[1] * v[1]) + (v[2] * v[2] + v[3] * v[3]); }
;                         ss += __shfl_xor(ss, 16); ss += __shfl_xor(ss, 32);
;                         const float rstd = frsq(ss * (1.0f / 64.0f) + EPS);
;                         f32x4 y[2][2];
; #pragma unroll
;                         for (int bj = 0; bj < 2; ++bj)
; #pragma unroll
;                             for (int n = 0; n < 2; ++n) y[bj][n] = acc[ai][bj][m][n] * rstd * g[bj][n];
; #pragma unroll
;                         for (int n = 0; n < 2; ++n) {
;                             const f32x4 cs = rc[m2][n], sn = rs[m2][n];
;                             f32x4 o;
; #pragma unroll
;                             for (int i = 0; i < 4; ++i) { const float mine = y[0][n][i], oth = __shfl_xor(mine, 16);
;                                 const float r = (fq == 0) ? (mine * cs[i] - oth * sn[i]) : (mine * cs[i] + oth * sn[i]);
;                                 o[i] = (fq < 2) ? r : mine; }
;                             y[0][n] = o;
;                         }
; #pragma unroll
;                         for (int bj = 0; bj < 2; ++bj) *(u32x4*)(ob + (size_t)row * ld + bj * 32) = pack8(y[bj][0], y[bj][1]);
	v_mul_f32_e32 v140, v141, v140
	v_cndmask_b32_e64 v140, v140, -v140, s[4:5]
	v_fmac_f32_e32 v140, v137, v157
	v_cndmask_b32_e32 v137, v157, v140, vcc
	ds_bpermute_b32 v140, v173, v154
	v_pk_mul_f32 v[146:147], v[192:193], v[146:147]
	v_pk_mul_f32 v[150:151], v[194:195], v[148:149]
	v_pk_mul_f32 v[148:149], v[88:89], v[144:145] op_sel_hi:[1,0]
	v_pk_mul_f32 v[144:145], v[90:91], v[144:145] op_sel_hi:[1,0]
	s_waitcnt lgkmcnt(0)
	v_mul_f32_e32 v140, v142, v140
	v_cndmask_b32_e64 v140, v140, -v140, s[4:5]
	v_fmac_f32_e32 v140, v138, v154
	v_cndmask_b32_e32 v138, v154, v140, vcc
	ds_bpermute_b32 v140, v173, v155
	v_add_u32_e32 v154, 32, v174
	v_pk_mul_f32 v[144:145], v[188:189], v[144:145]
	v_pk_mul_f32 v[148:149], v[190:191], v[148:149]
	s_waitcnt lgkmcnt(0)
	v_mul_f32_e32 v140, v143, v140
	v_cndmask_b32_e64 v140, v140, -v140, s[4:5]
	v_fmac_f32_e32 v140, v139, v155
	v_cndmask_b32_e32 v139, v155, v140, vcc
	ds_bpermute_b32 v140, v173, v158
	v_ashrrev_i32_e32 v155, 31, v154
	s_waitcnt lgkmcnt(0)
	v_mul_f32_e32 v132, v132, v140
	v_cndmask_b32_e64 v132, v132, -v132, s[4:5]
	v_fmac_f32_e32 v132, v128, v158
	ds_bpermute_b32 v128, v173, v159
	v_cndmask_b32_e32 v140, v158, v132, vcc
	s_waitcnt lgkmcnt(0)
	v_mul_f32_e32 v128, v133, v128
	v_cndmask_b32_e64 v128, v128, -v128, s[4:5]
	v_fmac_f32_e32 v128, v129, v159
	v_cndmask_b32_e32 v141, v159, v128, vcc
	ds_bpermute_b32 v128, v173, v152
	s_waitcnt lgkmcnt(0)
	v_mul_f32_e32 v128, v134, v128
	v_cndmask_b32_e64 v128, v128, -v128, s[4:5]
	v_fmac_f32_e32 v128, v130, v152
	v_cndmask_b32_e32 v134, v152, v128, vcc
	ds_bpermute_b32 v128, v173, v153
	v_add_u32_e32 v152, 48, v174
	s_waitcnt lgkmcnt(0)
	v_mul_f32_e32 v128, v135, v128
	v_cndmask_b32_e64 v128, v128, -v128, s[4:5]
	v_fmac_f32_e32 v128, v131, v153
	v_cndmask_b32_e32 v131, v153, v128, vcc
	v_lshlrev_b64 v[128:129], s12, v[196:197]
	v_lshl_add_u64 v[132:133], v[128:129], 1, v[178:179]
	v_cvt_pk_bf16_f32 v128, v136, v137
	v_cvt_pk_bf16_f32 v129, v138, v139
	v_cvt_pk_bf16_f32 v130, v140, v141
	v_cvt_pk_bf16_f32 v131, v134, v131
	global_store_dwordx4 v[132:133], v[128:131], off sc1
	v_ashrrev_i32_e32 v153, 31, v152
	s_nop 0
	v_cvt_pk_bf16_f32 v128, v150, v151
	v_cvt_pk_bf16_f32 v129, v146, v147
	v_cvt_pk_bf16_f32 v130, v148, v149
	v_cvt_pk_bf16_f32 v131, v144, v145
	global_store_dwordx4 v[132:133], v[128:131], off offset:64 sc1
	s_nop 1
	v_lshlrev_b64 v[128:129], 6, v[154:155]
	v_lshl_add_u64 v[128:129], s[50:51], 0, v[128:129]
	global_load_dwordx4 v[144:147], v[128:129], off offset:16
	global_load_dwordx4 v[148:151], v[128:129], off offset:48
	global_load_dwordx4 v[202:205], v[128:129], off
	global_load_dwordx4 v[222:225], v[128:129], off offset:32
	v_lshlrev_b64 v[128:129], 6, v[152:153]
	v_lshl_add_u64 v[140:141], s[50:51], 0, v[128:129]
	global_load_dwordx4 v[128:131], v[140:141], off offset:16
	global_load_dwordx4 v[132:135], v[140:141], off offset:48
	global_load_dwordx4 v[136:139], v[140:141], off
	s_nop 0
	global_load_dwordx4 v[140:143], v[140:141], off offset:32
	v_pk_mul_f32 v[156:157], v[102:103], v[102:103]
	v_pk_mul_f32 v[158:159], v[100:101], v[100:101]
	v_mul_f32_e32 v175, v72, v72
	v_pk_mov_b32 v[196:197], v[158:159], v[156:157] op_sel:[1,0]
	v_mov_b32_e32 v159, v157
	v_pk_add_f32 v[156:157], v[196:197], v[158:159]
	v_pk_mul_f32 v[158:159], v[94:95], v[94:95]
	v_pk_mul_f32 v[196:197], v[92:93], v[92:93]
	v_pk_add_f32 v[156:157], v[156:157], v[156:157] op_sel:[0,1] op_sel_hi:[1,0]
	v_pk_mov_b32 v[198:199], v[196:197], v[158:159] op_sel:[1,0]
	v_mov_b32_e32 v197, v159
	v_pk_add_f32 v[158:159], v[198:199], v[196:197]
	v_mul_f32_e32 v196, v73, v73
	v_pk_add_f32 v[158:159], v[158:159], v[158:159] op_sel:[0,1] op_sel_hi:[1,0]
	v_mov_b32_e32 v157, v175
	v_mov_b32_e32 v159, v196
	v_pk_add_f32 v[156:157], v[156:157], v[158:159]
	v_mul_f32_e32 v158, v81, v81
	v_mul_f32_e32 v197, v74, v74
	v_pk_fma_f32 v[158:159], v[80:81], v[80:81], v[158:159] op_sel_hi:[1,1,0]
	v_mul_f32_e32 v196, v83, v83
	v_mul_f32_e32 v198, v75, v75
	v_mov_b32_e32 v159, v197
	v_pk_fma_f32 v[196:197], v[82:83], v[82:83], v[196:197] op_sel_hi:[1,1,0]
	s_nop 0
	v_mov_b32_e32 v197, v198
	v_pk_add_f32 v[158:159], v[158:159], v[196:197]
	s_nop 0
	v_pk_add_f32 v[156:157], v[156:157], v[158:159]
	s_nop 0
	v_add_f32_e32 v156, v156, v157
	ds_bpermute_b32 v157, v173, v156
	s_waitcnt lgkmcnt(0)
	v_add_f32_e32 v156, v156, v157
	ds_bpermute_b32 v157, v220, v156
	s_waitcnt lgkmcnt(0)
	v_add_f32_e32 v156, v156, v157
	v_fmamk_f32 v156, v156, 0x3c800000, v215
	v_rsq_f32_e32 v196, v156
	s_nop 0
	v_pk_mul_f32 v[156:157], v[100:101], v[196:197] op_sel_hi:[1,0]
	s_nop 0
	v_pk_mul_f32 v[226:227], v[186:187], v[156:157]
	ds_bpermute_b32 v175, v173, v226
	v_pk_mul_f32 v[158:159], v[102:103], v[196:197] op_sel_hi:[1,0]
	v_pk_mul_f32 v[156:157], v[92:93], v[196:197] op_sel_hi:[1,0]
	v_pk_mul_f32 v[206:207], v[184:185], v[158:159]
	v_pk_mul_f32 v[230:231], v[182:183], v[156:157]
	s_waitcnt vmcnt(4) lgkmcnt(0)
	v_mul_f32_e32 v175, v222, v175
	v_cndmask_b32_e64 v175, v175, -v175, s[4:5]
	v_fmac_f32_e32 v175, v202, v226
	ds_bpermute_b32 v202, v173, v227
	v_pk_mul_f32 v[158:159], v[94:95], v[196:197] op_sel_hi:[1,0]
	v_pk_mul_f32 v[156:157], v[82:83], v[196:197] op_sel_hi:[1,0]
	v_pk_mul_f32 v[200:201], v[180:181], v[158:159]
	v_pk_mul_f32 v[158:159], v[80:81], v[196:197] op_sel_hi:[1,0]
	s_waitcnt lgkmcnt(0)
	v_mul_f32_e32 v202, v223, v202
	v_cndmask_b32_e64 v202, v202, -v202, s[4:5]
	v_fmac_f32_e32 v202, v203, v227
	ds_bpermute_b32 v203, v173, v206
	v_pk_mul_f32 v[198:199], v[72:73], v[196:197] op_sel_hi:[1,0]
	v_pk_mul_f32 v[196:197], v[74:75], v[196:197] op_sel_hi:[1,0]
	v_cndmask_b32_e32 v175, v226, v175, vcc
	v_cndmask_b32_e32 v202, v227, v202, vcc
	s_waitcnt lgkmcnt(0)
; __device__ __forceinline__ u32x4 pack8(const f32x4& a, const f32x4& b) { u32x4 w; w.x = cvt_pk_bf16(a[0], a[1]); w.y = cvt_pk_bf16(a[2], a[3]); w.z = cvt_pk_bf16(b[0], b[1]); w.w = cvt_pk_bf16(b[2], b[3]); return w; }
; __device__ __forceinline__ float frsq(float x) { return __builtin_amdgcn_rsqf(x); }
;     __device__ __forceinline__ void operator()(Acc& acc, const Unit& u, int wr, int wc, int fr, int fq) const {
;     ...
;                     for (int m2 = 0; m2 < 2; ++m2) { const float* rp = rope + (size_t)(row0 + ai * HALF + (2 * mh + m2) * 16) * 16;
; #pragma unroll
;                         for (int n = 0; n < 2; ++n) { rc[m2][n] = *(const f32x4*)(rp + 4 * n); rs[m2][n] = *(const f32x4*)(rp + 8 + 4 * n); } }
;                     __builtin_amdgcn_sched_barrier(0);
; #pragma unroll
;                     for (int m2 = 0; m2 < 2; ++m2) { const int m = 2 * mh + m2;
;                         const int row = row0 + ai * HALF + m * 16;
;                         float ss = 0.f;
; #pragma unroll
;                         for (int bj = 0; bj < 2; ++bj)
; #pragma unroll
;                             for (int n = 0; n < 2; ++n) { const f32x4 v = acc[ai][bj][m][n]; ss += (v[0] * v[0] + v[1] * v[1]) + (v[2] * v[2] + v[3] * v[3]); }
;                         ss += __shfl_xor(ss, 16); ss += __shfl_xor(ss, 32);
;                         const float rstd = frsq(ss * (1.0f / 64.0f) + EPS);
;                         f32x4 y[2][2];
; #pragma unroll
;                         for (int bj = 0; bj < 2; ++bj)
; #pragma unroll
;                             for (int n = 0; n < 2; ++n) y[bj][n] = acc[ai][bj][m][n] * rstd * g[bj][n];
; #pragma unroll
;                         for (int n = 0; n < 2; ++n) {
;                             const f32x4 cs = rc[m2][n], sn = rs[m2][n];
;                             f32x4 o;
; #pragma unroll
;                             for (int i = 0; i < 4; ++i) { const float mine = y[0][n][i], oth = __shfl_xor(mine, 16);
;                                 const float r = (fq == 0) ? (mine * cs[i] - oth * sn[i]) : (mine * cs[i] + oth * sn[i]);
;                                 o[i] = (fq < 2) ? r : mine; }
;                             y[0][n] = o;
;                         }
; #pragma unroll
;                         for (int bj = 0; bj < 2; ++bj) *(u32x4*)(ob + (size_t)row * ld + bj * 32) = pack8(y[bj][0], y[bj][1]);
	v_mul_f32_e32 v203, v224, v203
	v_cndmask_b32_e64 v203, v203, -v203, s[4:5]
	v_fmac_f32_e32 v203, v204, v206
	ds_bpermute_b32 v204, v173, v207
	v_cndmask_b32_e32 v203, v206, v203, vcc
	v_pk_mul_f32 v[156:157], v[192:193], v[156:157]
	v_pk_mul_f32 v[158:159], v[194:195], v[158:159]
	v_pk_mul_f32 v[196:197], v[188:189], v[196:197]
	s_waitcnt lgkmcnt(0)
	v_mul_f32_e32 v204, v225, v204
	v_cndmask_b32_e64 v204, v204, -v204, s[4:5]
	v_fmac_f32_e32 v204, v205, v207
	ds_bpermute_b32 v205, v173, v230
	v_cndmask_b32_e32 v204, v207, v204, vcc
	v_pk_mul_f32 v[198:199], v[190:191], v[198:199]
	s_waitcnt lgkmcnt(0)
	v_mul_f32_e32 v148, v148, v205
	v_cndmask_b32_e64 v148, v148, -v148, s[4:5]
	v_fmac_f32_e32 v148, v144, v230
	ds_bpermute_b32 v144, v173, v231
	v_cndmask_b32_e32 v205, v230, v148, vcc
	s_waitcnt lgkmcnt(0)
	v_mul_f32_e32 v144, v149, v144
	v_cndmask_b32_e64 v144, v144, -v144, s[4:5]
	v_fmac_f32_e32 v144, v145, v231
	v_cndmask_b32_e32 v206, v231, v144, vcc
	ds_bpermute_b32 v144, v173, v200
	s_waitcnt lgkmcnt(0)
	v_mul_f32_e32 v144, v150, v144
	v_cndmask_b32_e64 v144, v144, -v144, s[4:5]
	v_fmac_f32_e32 v144, v146, v200
	v_cndmask_b32_e32 v150, v200, v144, vcc
	ds_bpermute_b32 v144, v173, v201
	s_waitcnt lgkmcnt(0)
	v_mul_f32_e32 v144, v151, v144
	v_cndmask_b32_e64 v144, v144, -v144, s[4:5]
	v_fmac_f32_e32 v144, v147, v201
	v_cndmask_b32_e32 v147, v201, v144, vcc
	v_lshlrev_b64 v[144:145], s12, v[154:155]
	v_lshl_add_u64 v[148:149], v[144:145], 1, v[178:179]
	v_cvt_pk_bf16_f32 v144, v175, v202
	v_cvt_pk_bf16_f32 v145, v203, v204
	v_cvt_pk_bf16_f32 v146, v205, v206
	v_cvt_pk_bf16_f32 v147, v150, v147
	global_store_dwordx4 v[148:149], v[144:147], off sc1
	s_nop 1
	v_cvt_pk_bf16_f32 v144, v158, v159
	v_cvt_pk_bf16_f32 v145, v156, v157
	v_cvt_pk_bf16_f32 v146, v198, v199
	v_cvt_pk_bf16_f32 v147, v196, v197
	global_store_dwordx4 v[148:149], v[144:147], off offset:64 sc1
	s_nop 1
	v_pk_mul_f32 v[144:145], v[86:87], v[86:87]
	v_pk_mul_f32 v[146:147], v[84:85], v[84:85]
	s_nop 0
	v_pk_mov_b32 v[148:149], v[146:147], v[144:145] op_sel:[1,0]
	v_mov_b32_e32 v147, v145
	v_pk_add_f32 v[144:145], v[148:149], v[146:147]
	v_pk_mul_f32 v[146:147], v[78:79], v[78:79]
	v_pk_mul_f32 v[148:149], v[76:77], v[76:77]
	v_pk_add_f32 v[144:145], v[144:145], v[144:145] op_sel:[0,1] op_sel_hi:[1,0]
	v_pk_mov_b32 v[150:151], v[148:149], v[146:147] op_sel:[1,0]
	v_mov_b32_e32 v149, v147
	v_pk_add_f32 v[146:147], v[150:151], v[148:149]
	v_mul_f32_e32 v148, v64, v64
	v_mul_f32_e32 v149, v65, v65
	v_pk_add_f32 v[146:147], v[146:147], v[146:147] op_sel:[0,1] op_sel_hi:[1,0]
	v_mov_b32_e32 v145, v148
	v_mov_b32_e32 v147, v149
	v_pk_add_f32 v[144:145], v[144:145], v[146:147]
	v_mul_f32_e32 v146, v69, v69
	v_mul_f32_e32 v148, v71, v71
	v_mul_f32_e32 v150, v66, v66
	v_mul_f32_e32 v151, v67, v67
	v_pk_fma_f32 v[146:147], v[68:69], v[68:69], v[146:147] op_sel_hi:[1,1,0]
	v_pk_fma_f32 v[148:149], v[70:71], v[70:71], v[148:149] op_sel_hi:[1,1,0]
	v_mov_b32_e32 v147, v150
	v_mov_b32_e32 v149, v151
	v_pk_add_f32 v[146:147], v[146:147], v[148:149]
	s_nop 0
	v_pk_add_f32 v[144:145], v[144:145], v[146:147]
	s_nop 0
	v_add_f32_e32 v144, v144, v145
	ds_bpermute_b32 v145, v173, v144
	s_waitcnt lgkmcnt(0)
	v_add_f32_e32 v144, v144, v145
	ds_bpermute_b32 v145, v220, v144
	s_waitcnt lgkmcnt(0)
	v_add_f32_e32 v144, v144, v145
	v_fmamk_f32 v144, v144, 0x3c800000, v215
	v_rsq_f32_e32 v144, v144
	s_nop 0
	v_pk_mul_f32 v[146:147], v[84:85], v[144:145] op_sel_hi:[1,0]
	s_nop 0
	v_pk_mul_f32 v[158:159], v[186:187], v[146:147]
	ds_bpermute_b32 v175, v173, v158
	v_pk_mul_f32 v[148:149], v[86:87], v[144:145] op_sel_hi:[1,0]
	v_pk_mul_f32 v[146:147], v[76:77], v[144:145] op_sel_hi:[1,0]
	v_pk_mul_f32 v[156:157], v[184:185], v[148:149]
	v_pk_mul_f32 v[196:197], v[182:183], v[146:147]
	s_waitcnt vmcnt(2) lgkmcnt(0)
	v_mul_f32_e32 v140, v140, v175
	v_cndmask_b32_e64 v140, v140, -v140, s[4:5]
	v_fmac_f32_e32 v140, v136, v158
	v_cndmask_b32_e32 v136, v158, v140, vcc
	ds_bpermute_b32 v140, v173, v159
	v_pk_mul_f32 v[148:149], v[78:79], v[144:145] op_sel_hi:[1,0]
	v_pk_mul_f32 v[146:147], v[70:71], v[144:145] op_sel_hi:[1,0]
	v_pk_mul_f32 v[154:155], v[180:181], v[148:149]
	v_pk_mul_f32 v[148:149], v[68:69], v[144:145] op_sel_hi:[1,0]
	s_waitcnt lgkmcnt(0)
	v_mul_f32_e32 v140, v141, v140
	v_cndmask_b32_e64 v140, v140, -v140, s[4:5]
	v_fmac_f32_e32 v140, v137, v159
	v_cndmask_b32_e32 v137, v159, v140, vcc
	ds_bpermute_b32 v140, v173, v156
	v_pk_mul_f32 v[146:147], v[192:193], v[146:147]
	v_pk_mul_f32 v[150:151], v[194:195], v[148:149]
	v_pk_mul_f32 v[148:149], v[64:65], v[144:145] op_sel_hi:[1,0]
	v_pk_mul_f32 v[144:145], v[66:67], v[144:145] op_sel_hi:[1,0]
	s_waitcnt lgkmcnt(0)
	v_mul_f32_e32 v140, v142, v140
	v_cndmask_b32_e64 v140, v140, -v140, s[4:5]
	v_fmac_f32_e32 v140, v138, v156
	v_cndmask_b32_e32 v138, v156, v140, vcc
	ds_bpermute_b32 v140, v173, v157
	v_pk_mul_f32 v[144:145], v[188:189], v[144:145]
	v_pk_mul_f32 v[148:149], v[190:191], v[148:149]
	s_waitcnt lgkmcnt(0)
	v_mul_f32_e32 v140, v143, v140
	v_cndmask_b32_e64 v140, v140, -v140, s[4:5]
	v_fmac_f32_e32 v140, v139, v157
	v_cndmask_b32_e32 v139, v157, v140, vcc
	ds_bpermute_b32 v140, v173, v196
	s_waitcnt lgkmcnt(0)
	v_mul_f32_e32 v132, v132, v140
	v_cndmask_b32_e64 v132, v132, -v132, s[4:5]
	v_fmac_f32_e32 v132, v128, v196
	ds_bpermute_b32 v128, v173, v197
	v_cndmask_b32_e32 v140, v196, v132, vcc
	s_waitcnt lgkmcnt(0)
	v_mul_f32_e32 v128, v133, v128
	v_cndmask_b32_e64 v128, v128, -v128, s[4:5]
	v_fmac_f32_e32 v128, v129, v197
	v_cndmask_b32_e32 v141, v197, v128, vcc
	ds_bpermute_b32 v128, v173, v154
	s_waitcnt lgkmcnt(0)
; __device__ __forceinline__ u32x4 pack8(const f32x4& a, const f32x4& b) { u32x4 w; w.x = cvt_pk_bf16(a[0], a[1]); w.y = cvt_pk_bf16(a[2], a[3]); w.z = cvt_pk_bf16(b[0], b[1]); w.w = cvt_pk_bf16(b[2], b[3]); return w; }
; __device__ __forceinline__ float frsq(float x) { return __builtin_amdgcn_rsqf(x); }
;     __device__ __forceinline__ void operator()(Acc& acc, const Unit& u, int wr, int wc, int fr, int fq) const {
;     ...
;                     for (int m2 = 0; m2 < 2; ++m2) { const float* rp = rope + (size_t)(row0 + ai * HALF + (2 * mh + m2) * 16) * 16;
; #pragma unroll
;                         for (int n = 0; n < 2; ++n) { rc[m2][n] = *(const f32x4*)(rp + 4 * n); rs[m2][n] = *(const f32x4*)(rp + 8 + 4 * n); } }
;                     __builtin_amdgcn_sched_barrier(0);
; #pragma unroll
;                     for (int m2 = 0; m2 < 2; ++m2) { const int m = 2 * mh + m2;
;                         const int row = row0 + ai * HALF + m * 16;
;                         float ss = 0.f;
; #pragma unroll
;                         for (int bj = 0; bj < 2; ++bj)
; #pragma unroll
;                             for (int n = 0; n < 2; ++n) { const f32x4 v = acc[ai][bj][m][n]; ss += (v[0] * v[0] + v[1] * v[1]) + (v[2] * v[2] + v[3] * v[3]); }
;                         ss += __shfl_xor(ss, 16); ss += __shfl_xor(ss, 32);
;                         const float rstd = frsq(ss * (1.0f / 64.0f) + EPS);
;                         f32x4 y[2][2];
; #pragma unroll
;                         for (int bj = 0; bj < 2; ++bj)
; #pragma unroll
;                             for (int n = 0; n < 2; ++n) y[bj][n] = acc[ai][bj][m][n] * rstd * g[bj][n];
; #pragma unroll
;                         for (int n = 0; n < 2; ++n) {
;                             const f32x4 cs = rc[m2][n], sn = rs[m2][n];
;                             f32x4 o;
; #pragma unroll
;                             for (int i = 0; i < 4; ++i) { const float mine = y[0][n][i], oth = __shfl_xor(mine, 16);
;                                 const float r = (fq == 0) ? (mine * cs[i] - oth * sn[i]) : (mine * cs[i] + oth * sn[i]);
;                                 o[i] = (fq < 2) ? r : mine; }
;                             y[0][n] = o;
;                         }
; #pragma unroll
;                         for (int bj = 0; bj < 2; ++bj) *(u32x4*)(ob + (size_t)row * ld + bj * 32) = pack8(y[bj][0], y[bj][1]);
	v_mul_f32_e32 v128, v134, v128
	v_cndmask_b32_e64 v128, v128, -v128, s[4:5]
	v_fmac_f32_e32 v128, v130, v154
	v_cndmask_b32_e32 v134, v154, v128, vcc
	ds_bpermute_b32 v128, v173, v155
	v_add_u32_e32 v154, 0x80, v174
	s_waitcnt lgkmcnt(0)
	v_mul_f32_e32 v128, v135, v128
	v_cndmask_b32_e64 v128, v128, -v128, s[4:5]
	v_fmac_f32_e32 v128, v131, v155
	v_cndmask_b32_e32 v131, v155, v128, vcc
	v_lshlrev_b64 v[128:129], s12, v[152:153]
	v_lshl_add_u64 v[132:133], v[128:129], 1, v[178:179]
	v_cvt_pk_bf16_f32 v128, v136, v137
	v_cvt_pk_bf16_f32 v129, v138, v139
	v_cvt_pk_bf16_f32 v130, v140, v141
	v_cvt_pk_bf16_f32 v131, v134, v131
	global_store_dwordx4 v[132:133], v[128:131], off sc1
	v_ashrrev_i32_e32 v155, 31, v154
	v_add_u32_e32 v152, 0x90, v174
	v_cvt_pk_bf16_f32 v128, v150, v151
	v_cvt_pk_bf16_f32 v129, v146, v147
	v_cvt_pk_bf16_f32 v130, v148, v149
	v_cvt_pk_bf16_f32 v131, v144, v145
	global_store_dwordx4 v[132:133], v[128:131], off offset:64 sc1
	v_ashrrev_i32_e32 v153, 31, v152
	s_nop 0
	v_lshlrev_b64 v[128:129], 6, v[154:155]
	v_lshl_add_u64 v[128:129], s[50:51], 0, v[128:129]
	global_load_dwordx4 v[144:147], v[128:129], off offset:16
	global_load_dwordx4 v[148:151], v[128:129], off offset:48
	global_load_dwordx4 v[202:205], v[128:129], off
	global_load_dwordx4 v[222:225], v[128:129], off offset:32
	v_lshlrev_b64 v[128:129], 6, v[152:153]
	v_lshl_add_u64 v[140:141], s[50:51], 0, v[128:129]
	global_load_dwordx4 v[128:131], v[140:141], off offset:16
	global_load_dwordx4 v[132:135], v[140:141], off offset:48
	global_load_dwordx4 v[136:139], v[140:141], off
	s_nop 0
	global_load_dwordx4 v[140:143], v[140:141], off offset:32
	v_pk_mul_f32 v[156:157], v[62:63], v[62:63]
	v_pk_mul_f32 v[158:159], v[60:61], v[60:61]
	v_mul_f32_e32 v175, v40, v40
	v_pk_mov_b32 v[196:197], v[158:159], v[156:157] op_sel:[1,0]
	v_mov_b32_e32 v159, v157
	v_pk_add_f32 v[156:157], v[196:197], v[158:159]
	v_pk_mul_f32 v[158:159], v[58:59], v[58:59]
	v_pk_mul_f32 v[196:197], v[56:57], v[56:57]
	v_pk_add_f32 v[156:157], v[156:157], v[156:157] op_sel:[0,1] op_sel_hi:[1,0]
	v_pk_mov_b32 v[198:199], v[196:197], v[158:159] op_sel:[1,0]
	v_mov_b32_e32 v197, v159
	v_pk_add_f32 v[158:159], v[198:199], v[196:197]
	v_mul_f32_e32 v196, v41, v41
	v_pk_add_f32 v[158:159], v[158:159], v[158:159] op_sel:[0,1] op_sel_hi:[1,0]
	v_mov_b32_e32 v157, v175
	v_mov_b32_e32 v159, v196
	v_pk_add_f32 v[156:157], v[156:157], v[158:159]
	v_mul_f32_e32 v158, v49, v49
	v_mul_f32_e32 v197, v42, v42
	v_pk_fma_f32 v[158:159], v[48:49], v[48:49], v[158:159] op_sel_hi:[1,1,0]
	v_mul_f32_e32 v196, v51, v51
	v_mul_f32_e32 v198, v43, v43
	v_mov_b32_e32 v159, v197
	v_pk_fma_f32 v[196:197], v[50:51], v[50:51], v[196:197] op_sel_hi:[1,1,0]
	s_nop 0
	v_mov_b32_e32 v197, v198
	v_pk_add_f32 v[158:159], v[158:159], v[196:197]
	s_nop 0
	v_pk_add_f32 v[156:157], v[156:157], v[158:159]
	s_nop 0
	v_add_f32_e32 v156, v156, v157
	ds_bpermute_b32 v157, v173, v156
	s_waitcnt lgkmcnt(0)
	v_add_f32_e32 v156, v156, v157
	ds_bpermute_b32 v157, v220, v156
	s_waitcnt lgkmcnt(0)
	v_add_f32_e32 v156, v156, v157
	v_fmamk_f32 v156, v156, 0x3c800000, v215
	v_rsq_f32_e32 v196, v156
	s_nop 0
	v_pk_mul_f32 v[156:157], v[60:61], v[196:197] op_sel_hi:[1,0]
	s_nop 0
	v_pk_mul_f32 v[226:227], v[186:187], v[156:157]
	ds_bpermute_b32 v175, v173, v226
	v_pk_mul_f32 v[158:159], v[62:63], v[196:197] op_sel_hi:[1,0]
	v_pk_mul_f32 v[156:157], v[56:57], v[196:197] op_sel_hi:[1,0]
	v_pk_mul_f32 v[206:207], v[184:185], v[158:159]
	v_pk_mul_f32 v[230:231], v[182:183], v[156:157]
	s_waitcnt vmcnt(4) lgkmcnt(0)
	v_mul_f32_e32 v175, v222, v175
	v_cndmask_b32_e64 v175, v175, -v175, s[4:5]
	v_fmac_f32_e32 v175, v202, v226
	ds_bpermute_b32 v202, v173, v227
	v_pk_mul_f32 v[158:159], v[58:59], v[196:197] op_sel_hi:[1,0]
	v_pk_mul_f32 v[156:157], v[50:51], v[196:197] op_sel_hi:[1,0]
	v_pk_mul_f32 v[200:201], v[180:181], v[158:159]
	v_pk_mul_f32 v[158:159], v[48:49], v[196:197] op_sel_hi:[1,0]
	s_waitcnt lgkmcnt(0)
	v_mul_f32_e32 v202, v223, v202
	v_cndmask_b32_e64 v202, v202, -v202, s[4:5]
	v_fmac_f32_e32 v202, v203, v227
	ds_bpermute_b32 v203, v173, v206
	v_pk_mul_f32 v[198:199], v[40:41], v[196:197] op_sel_hi:[1,0]
	v_pk_mul_f32 v[196:197], v[42:43], v[196:197] op_sel_hi:[1,0]
	v_cndmask_b32_e32 v175, v226, v175, vcc
	v_cndmask_b32_e32 v202, v227, v202, vcc
	s_waitcnt lgkmcnt(0)
	v_mul_f32_e32 v203, v224, v203
	v_cndmask_b32_e64 v203, v203, -v203, s[4:5]
	v_fmac_f32_e32 v203, v204, v206
	ds_bpermute_b32 v204, v173, v207
	v_cndmask_b32_e32 v203, v206, v203, vcc
	v_pk_mul_f32 v[156:157], v[192:193], v[156:157]
	v_pk_mul_f32 v[158:159], v[194:195], v[158:159]
	v_pk_mul_f32 v[196:197], v[188:189], v[196:197]
	s_waitcnt lgkmcnt(0)
	v_mul_f32_e32 v204, v225, v204
	v_cndmask_b32_e64 v204, v204, -v204, s[4:5]
	v_fmac_f32_e32 v204, v205, v207
	ds_bpermute_b32 v205, v173, v230
	v_cndmask_b32_e32 v204, v207, v204, vcc
	v_pk_mul_f32 v[198:199], v[190:191], v[198:199]
	s_waitcnt lgkmcnt(0)
	v_mul_f32_e32 v148, v148, v205
	v_cndmask_b32_e64 v148, v148, -v148, s[4:5]
	v_fmac_f32_e32 v148, v144, v230
	ds_bpermute_b32 v144, v173, v231
	v_cndmask_b32_e32 v205, v230, v148, vcc
	s_waitcnt lgkmcnt(0)
	v_mul_f32_e32 v144, v149, v144
	v_cndmask_b32_e64 v144, v144, -v144, s[4:5]
	v_fmac_f32_e32 v144, v145, v231
	v_cndmask_b32_e32 v206, v231, v144, vcc
	ds_bpermute_b32 v144, v173, v200
	s_waitcnt lgkmcnt(0)
	v_mul_f32_e32 v144, v150, v144
	v_cndmask_b32_e64 v144, v144, -v144, s[4:5]
	v_fmac_f32_e32 v144, v146, v200
	v_cndmask_b32_e32 v150, v200, v144, vcc
	ds_bpermute_b32 v144, v173, v201
	s_waitcnt lgkmcnt(0)
; __device__ __forceinline__ u32x4 pack8(const f32x4& a, const f32x4& b) { u32x4 w; w.x = cvt_pk_bf16(a[0], a[1]); w.y = cvt_pk_bf16(a[2], a[3]); w.z = cvt_pk_bf16(b[0], b[1]); w.w = cvt_pk_bf16(b[2], b[3]); return w; }
; __device__ __forceinline__ float frsq(float x) { return __builtin_amdgcn_rsqf(x); }
;     __device__ __forceinline__ void operator()(Acc& acc, const Unit& u, int wr, int wc, int fr, int fq) const {
;     ...
;                     for (int m2 = 0; m2 < 2; ++m2) { const float* rp = rope + (size_t)(row0 + ai * HALF + (2 * mh + m2) * 16) * 16;
; #pragma unroll
;                         for (int n = 0; n < 2; ++n) { rc[m2][n] = *(const f32x4*)(rp + 4 * n); rs[m2][n] = *(const f32x4*)(rp + 8 + 4 * n); } }
;                     __builtin_amdgcn_sched_barrier(0);
; #pragma unroll
;                     for (int m2 = 0; m2 < 2; ++m2) { const int m = 2 * mh + m2;
;                         const int row = row0 + ai * HALF + m * 16;
;                         float ss = 0.f;
; #pragma unroll
;                         for (int bj = 0; bj < 2; ++bj)
; #pragma unroll
;                             for (int n = 0; n < 2; ++n) { const f32x4 v = acc[ai][bj][m][n]; ss += (v[0] * v[0] + v[1] * v[1]) + (v[2] * v[2] + v[3] * v[3]); }
;                         ss += __shfl_xor(ss, 16); ss += __shfl_xor(ss, 32);
;                         const float rstd = frsq(ss * (1.0f / 64.0f) + EPS);
;                         f32x4 y[2][2];
; #pragma unroll
;                         for (int bj = 0; bj < 2; ++bj)
; #pragma unroll
;                             for (int n = 0; n < 2; ++n) y[bj][n] = acc[ai][bj][m][n] * rstd * g[bj][n];
; #pragma unroll
;                         for (int n = 0; n < 2; ++n) {
;                             const f32x4 cs = rc[m2][n], sn = rs[m2][n];
;                             f32x4 o;
; #pragma unroll
;                             for (int i = 0; i < 4; ++i) { const float mine = y[0][n][i], oth = __shfl_xor(mine, 16);
;                                 const float r = (fq == 0) ? (mine * cs[i] - oth * sn[i]) : (mine * cs[i] + oth * sn[i]);
;                                 o[i] = (fq < 2) ? r : mine; }
;                             y[0][n] = o;
;                         }
; #pragma unroll
;                         for (int bj = 0; bj < 2; ++bj) *(u32x4*)(ob + (size_t)row * ld + bj * 32) = pack8(y[bj][0], y[bj][1]);
	v_mul_f32_e32 v144, v151, v144
	v_cndmask_b32_e64 v144, v144, -v144, s[4:5]
	v_fmac_f32_e32 v144, v147, v201
	v_cndmask_b32_e32 v147, v201, v144, vcc
	v_lshlrev_b64 v[144:145], s12, v[154:155]
	v_lshl_add_u64 v[148:149], v[144:145], 1, v[178:179]
	v_cvt_pk_bf16_f32 v144, v175, v202
	v_cvt_pk_bf16_f32 v145, v203, v204
	v_cvt_pk_bf16_f32 v146, v205, v206
	v_cvt_pk_bf16_f32 v147, v150, v147
	global_store_dwordx4 v[148:149], v[144:147], off sc1
	s_nop 1
	v_cvt_pk_bf16_f32 v144, v158, v159
	v_cvt_pk_bf16_f32 v145, v156, v157
	v_cvt_pk_bf16_f32 v146, v198, v199
	v_cvt_pk_bf16_f32 v147, v196, v197
	global_store_dwordx4 v[148:149], v[144:147], off offset:64 sc1
	s_nop 1
	v_pk_mul_f32 v[144:145], v[54:55], v[54:55]
	v_pk_mul_f32 v[146:147], v[52:53], v[52:53]
	s_nop 0
	v_pk_mov_b32 v[148:149], v[146:147], v[144:145] op_sel:[1,0]
	v_mov_b32_e32 v147, v145
	v_pk_add_f32 v[144:145], v[148:149], v[146:147]
	v_pk_mul_f32 v[146:147], v[46:47], v[46:47]
	v_pk_mul_f32 v[148:149], v[44:45], v[44:45]
	v_pk_add_f32 v[144:145], v[144:145], v[144:145] op_sel:[0,1] op_sel_hi:[1,0]
	v_pk_mov_b32 v[150:151], v[148:149], v[146:147] op_sel:[1,0]
	v_mov_b32_e32 v149, v147
	v_pk_add_f32 v[146:147], v[150:151], v[148:149]
	v_mul_f32_e32 v148, v24, v24
	v_mul_f32_e32 v149, v25, v25
	v_pk_add_f32 v[146:147], v[146:147], v[146:147] op_sel:[0,1] op_sel_hi:[1,0]
	v_mov_b32_e32 v145, v148
	v_mov_b32_e32 v147, v149
	v_pk_add_f32 v[144:145], v[144:145], v[146:147]
	v_mul_f32_e32 v146, v33, v33
	v_mul_f32_e32 v148, v35, v35
	v_mul_f32_e32 v150, v26, v26
	v_mul_f32_e32 v151, v27, v27
	v_pk_fma_f32 v[146:147], v[32:33], v[32:33], v[146:147] op_sel_hi:[1,1,0]
	v_pk_fma_f32 v[148:149], v[34:35], v[34:35], v[148:149] op_sel_hi:[1,1,0]
	v_mov_b32_e32 v147, v150
	v_mov_b32_e32 v149, v151
	v_pk_add_f32 v[146:147], v[146:147], v[148:149]
	s_nop 0
	v_pk_add_f32 v[144:145], v[144:145], v[146:147]
	s_nop 0
	v_add_f32_e32 v144, v144, v145
	ds_bpermute_b32 v145, v173, v144
	s_waitcnt lgkmcnt(0)
	v_add_f32_e32 v144, v144, v145
	ds_bpermute_b32 v145, v220, v144
	s_waitcnt lgkmcnt(0)
	v_add_f32_e32 v144, v144, v145
	v_fmamk_f32 v144, v144, 0x3c800000, v215
	v_rsq_f32_e32 v144, v144
	s_nop 0
	v_pk_mul_f32 v[146:147], v[52:53], v[144:145] op_sel_hi:[1,0]
	s_nop 0
	v_pk_mul_f32 v[158:159], v[186:187], v[146:147]
	ds_bpermute_b32 v175, v173, v158
	v_pk_mul_f32 v[148:149], v[54:55], v[144:145] op_sel_hi:[1,0]
	v_pk_mul_f32 v[146:147], v[44:45], v[144:145] op_sel_hi:[1,0]
	v_pk_mul_f32 v[156:157], v[184:185], v[148:149]
	v_pk_mul_f32 v[196:197], v[182:183], v[146:147]
	s_waitcnt vmcnt(2) lgkmcnt(0)
	v_mul_f32_e32 v140, v140, v175
	v_cndmask_b32_e64 v140, v140, -v140, s[4:5]
	v_fmac_f32_e32 v140, v136, v158
	v_cndmask_b32_e32 v136, v158, v140, vcc
	ds_bpermute_b32 v140, v173, v159
	v_pk_mul_f32 v[148:149], v[46:47], v[144:145] op_sel_hi:[1,0]
	v_pk_mul_f32 v[146:147], v[34:35], v[144:145] op_sel_hi:[1,0]
	v_pk_mul_f32 v[154:155], v[180:181], v[148:149]
	v_pk_mul_f32 v[148:149], v[32:33], v[144:145] op_sel_hi:[1,0]
	s_waitcnt lgkmcnt(0)
	v_mul_f32_e32 v140, v141, v140
	v_cndmask_b32_e64 v140, v140, -v140, s[4:5]
	v_fmac_f32_e32 v140, v137, v159
	v_cndmask_b32_e32 v137, v159, v140, vcc
	ds_bpermute_b32 v140, v173, v156
	v_pk_mul_f32 v[146:147], v[192:193], v[146:147]
	v_pk_mul_f32 v[150:151], v[194:195], v[148:149]
	v_pk_mul_f32 v[148:149], v[24:25], v[144:145] op_sel_hi:[1,0]
	v_pk_mul_f32 v[144:145], v[26:27], v[144:145] op_sel_hi:[1,0]
	s_waitcnt lgkmcnt(0)
	v_mul_f32_e32 v140, v142, v140
	v_cndmask_b32_e64 v140, v140, -v140, s[4:5]
	v_fmac_f32_e32 v140, v138, v156
	v_cndmask_b32_e32 v138, v156, v140, vcc
	ds_bpermute_b32 v140, v173, v157
	v_pk_mul_f32 v[144:145], v[188:189], v[144:145]
	v_pk_mul_f32 v[148:149], v[190:191], v[148:149]
	s_waitcnt lgkmcnt(0)
	v_mul_f32_e32 v140, v143, v140
	v_cndmask_b32_e64 v140, v140, -v140, s[4:5]
	v_fmac_f32_e32 v140, v139, v157
	v_cndmask_b32_e32 v139, v157, v140, vcc
	ds_bpermute_b32 v140, v173, v196
	s_waitcnt lgkmcnt(0)
	v_mul_f32_e32 v132, v132, v140
	v_cndmask_b32_e64 v132, v132, -v132, s[4:5]
	v_fmac_f32_e32 v132, v128, v196
	ds_bpermute_b32 v128, v173, v197
	v_cndmask_b32_e32 v140, v196, v132, vcc
	s_waitcnt lgkmcnt(0)
	v_mul_f32_e32 v128, v133, v128
	v_cndmask_b32_e64 v128, v128, -v128, s[4:5]
	v_fmac_f32_e32 v128, v129, v197
	v_cndmask_b32_e32 v141, v197, v128, vcc
	ds_bpermute_b32 v128, v173, v154
	s_waitcnt lgkmcnt(0)
	v_mul_f32_e32 v128, v134, v128
	v_cndmask_b32_e64 v128, v128, -v128, s[4:5]
	v_fmac_f32_e32 v128, v130, v154
	v_cndmask_b32_e32 v134, v154, v128, vcc
	ds_bpermute_b32 v128, v173, v155
	v_add_u32_e32 v154, 0xa0, v174
	s_waitcnt lgkmcnt(0)
; __device__ __forceinline__ u32x4 pack8(const f32x4& a, const f32x4& b) { u32x4 w; w.x = cvt_pk_bf16(a[0], a[1]); w.y = cvt_pk_bf16(a[2], a[3]); w.z = cvt_pk_bf16(b[0], b[1]); w.w = cvt_pk_bf16(b[2], b[3]); return w; }
; __device__ __forceinline__ float frsq(float x) { return __builtin_amdgcn_rsqf(x); }
;     __device__ __forceinline__ void operator()(Acc& acc, const Unit& u, int wr, int wc, int fr, int fq) const {
;     ...
;                     for (int m2 = 0; m2 < 2; ++m2) { const float* rp = rope + (size_t)(row0 + ai * HALF + (2 * mh + m2) * 16) * 16;
; #pragma unroll
;                         for (int n = 0; n < 2; ++n) { rc[m2][n] = *(const f32x4*)(rp + 4 * n); rs[m2][n] = *(const f32x4*)(rp + 8 + 4 * n); } }
;                     __builtin_amdgcn_sched_barrier(0);
; #pragma unroll
;                     for (int m2 = 0; m2 < 2; ++m2) { const int m = 2 * mh + m2;
;                         const int row = row0 + ai * HALF + m * 16;
;                         float ss = 0.f;
; #pragma unroll
;                         for (int bj = 0; bj < 2; ++bj)
; #pragma unroll
;                             for (int n = 0; n < 2; ++n) { const f32x4 v = acc[ai][bj][m][n]; ss += (v[0] * v[0] + v[1] * v[1]) + (v[2] * v[2] + v[3] * v[3]); }
;                         ss += __shfl_xor(ss, 16); ss += __shfl_xor(ss, 32);
;                         const float rstd = frsq(ss * (1.0f / 64.0f) + EPS);
;                         f32x4 y[2][2];
; #pragma unroll
;                         for (int bj = 0; bj < 2; ++bj)
; #pragma unroll
;                             for (int n = 0; n < 2; ++n) y[bj][n] = acc[ai][bj][m][n] * rstd * g[bj][n];
; #pragma unroll
;                         for (int n = 0; n < 2; ++n) {
;                             const f32x4 cs = rc[m2][n], sn = rs[m2][n];
;                             f32x4 o;
; #pragma unroll
;                             for (int i = 0; i < 4; ++i) { const float mine = y[0][n][i], oth = __shfl_xor(mine, 16);
;                                 const float r = (fq == 0) ? (mine * cs[i] - oth * sn[i]) : (mine * cs[i] + oth * sn[i]);
;                                 o[i] = (fq < 2) ? r : mine; }
;                             y[0][n] = o;
;                         }
; #pragma unroll
;                         for (int bj = 0; bj < 2; ++bj) *(u32x4*)(ob + (size_t)row * ld + bj * 32) = pack8(y[bj][0], y[bj][1]);
	v_mul_f32_e32 v128, v135, v128
	v_cndmask_b32_e64 v128, v128, -v128, s[4:5]
	v_fmac_f32_e32 v128, v131, v155
	v_cndmask_b32_e32 v131, v155, v128, vcc
	v_lshlrev_b64 v[128:129], s12, v[152:153]
	v_lshl_add_u64 v[132:133], v[128:129], 1, v[178:179]
	v_cvt_pk_bf16_f32 v128, v136, v137
	v_cvt_pk_bf16_f32 v129, v138, v139
	v_cvt_pk_bf16_f32 v130, v140, v141
	v_cvt_pk_bf16_f32 v131, v134, v131
	global_store_dwordx4 v[132:133], v[128:131], off sc1
	v_ashrrev_i32_e32 v155, 31, v154
	v_add_u32_e32 v152, 0xb0, v174
	v_cvt_pk_bf16_f32 v128, v150, v151
	v_cvt_pk_bf16_f32 v129, v146, v147
	v_cvt_pk_bf16_f32 v130, v148, v149
	v_cvt_pk_bf16_f32 v131, v144, v145
	global_store_dwordx4 v[132:133], v[128:131], off offset:64 sc1
	v_ashrrev_i32_e32 v153, 31, v152
	s_nop 0
	v_lshlrev_b64 v[128:129], 6, v[154:155]
	v_lshl_add_u64 v[128:129], s[50:51], 0, v[128:129]
	global_load_dwordx4 v[144:147], v[128:129], off offset:16
	global_load_dwordx4 v[148:151], v[128:129], off offset:48
	global_load_dwordx4 v[202:205], v[128:129], off
	global_load_dwordx4 v[222:225], v[128:129], off offset:32
	v_lshlrev_b64 v[128:129], 6, v[152:153]
	v_lshl_add_u64 v[140:141], s[50:51], 0, v[128:129]
	global_load_dwordx4 v[128:131], v[140:141], off offset:16
	global_load_dwordx4 v[132:135], v[140:141], off offset:48
	global_load_dwordx4 v[136:139], v[140:141], off
	s_nop 0
	global_load_dwordx4 v[140:143], v[140:141], off offset:32
	v_pk_mul_f32 v[156:157], v[38:39], v[38:39]
	v_pk_mul_f32 v[158:159], v[36:37], v[36:37]
	v_mul_f32_e32 v175, v8, v8
	v_pk_mov_b32 v[196:197], v[158:159], v[156:157] op_sel:[1,0]
	v_mov_b32_e32 v159, v157
	v_pk_add_f32 v[156:157], v[196:197], v[158:159]
	v_pk_mul_f32 v[158:159], v[30:31], v[30:31]
	v_pk_mul_f32 v[196:197], v[28:29], v[28:29]
	v_pk_add_f32 v[156:157], v[156:157], v[156:157] op_sel:[0,1] op_sel_hi:[1,0]
	v_pk_mov_b32 v[198:199], v[196:197], v[158:159] op_sel:[1,0]
	v_mov_b32_e32 v197, v159
	v_pk_add_f32 v[158:159], v[198:199], v[196:197]
	v_mul_f32_e32 v196, v9, v9
	v_pk_add_f32 v[158:159], v[158:159], v[158:159] op_sel:[0,1] op_sel_hi:[1,0]
	v_mov_b32_e32 v157, v175
	v_mov_b32_e32 v159, v196
	v_pk_add_f32 v[156:157], v[156:157], v[158:159]
	v_mul_f32_e32 v158, v17, v17
	v_mul_f32_e32 v197, v10, v10
	v_pk_fma_f32 v[158:159], v[16:17], v[16:17], v[158:159] op_sel_hi:[1,1,0]
	v_mul_f32_e32 v196, v19, v19
	v_mul_f32_e32 v198, v11, v11
	v_mov_b32_e32 v159, v197
	v_pk_fma_f32 v[196:197], v[18:19], v[18:19], v[196:197] op_sel_hi:[1,1,0]
	s_nop 0
	v_mov_b32_e32 v197, v198
	v_pk_add_f32 v[158:159], v[158:159], v[196:197]
	s_nop 0
	v_pk_add_f32 v[156:157], v[156:157], v[158:159]
	s_nop 0
	v_add_f32_e32 v156, v156, v157
	ds_bpermute_b32 v157, v173, v156
	s_waitcnt lgkmcnt(0)
	v_add_f32_e32 v156, v156, v157
	ds_bpermute_b32 v157, v220, v156
	s_waitcnt lgkmcnt(0)
	v_add_f32_e32 v156, v156, v157
	v_fmamk_f32 v156, v156, 0x3c800000, v215
	v_rsq_f32_e32 v196, v156
	s_nop 0
	v_pk_mul_f32 v[156:157], v[36:37], v[196:197] op_sel_hi:[1,0]
	s_nop 0
	v_pk_mul_f32 v[226:227], v[186:187], v[156:157]
	ds_bpermute_b32 v175, v173, v226
	v_pk_mul_f32 v[158:159], v[38:39], v[196:197] op_sel_hi:[1,0]
	v_pk_mul_f32 v[156:157], v[28:29], v[196:197] op_sel_hi:[1,0]
	v_pk_mul_f32 v[206:207], v[184:185], v[158:159]
	v_pk_mul_f32 v[230:231], v[182:183], v[156:157]
	s_waitcnt vmcnt(4) lgkmcnt(0)
	v_mul_f32_e32 v175, v222, v175
	v_cndmask_b32_e64 v175, v175, -v175, s[4:5]
	v_fmac_f32_e32 v175, v202, v226
	ds_bpermute_b32 v202, v173, v227
	v_pk_mul_f32 v[158:159], v[30:31], v[196:197] op_sel_hi:[1,0]
	v_pk_mul_f32 v[156:157], v[18:19], v[196:197] op_sel_hi:[1,0]
	v_pk_mul_f32 v[200:201], v[180:181], v[158:159]
	v_pk_mul_f32 v[158:159], v[16:17], v[196:197] op_sel_hi:[1,0]
	s_waitcnt lgkmcnt(0)
	v_mul_f32_e32 v202, v223, v202
	v_cndmask_b32_e64 v202, v202, -v202, s[4:5]
	v_fmac_f32_e32 v202, v203, v227
	ds_bpermute_b32 v203, v173, v206
	v_pk_mul_f32 v[198:199], v[8:9], v[196:197] op_sel_hi:[1,0]
	v_pk_mul_f32 v[196:197], v[10:11], v[196:197] op_sel_hi:[1,0]
	v_cndmask_b32_e32 v175, v226, v175, vcc
	v_cndmask_b32_e32 v202, v227, v202, vcc
	s_waitcnt lgkmcnt(0)
	v_mul_f32_e32 v203, v224, v203
	v_cndmask_b32_e64 v203, v203, -v203, s[4:5]
	v_fmac_f32_e32 v203, v204, v206
	ds_bpermute_b32 v204, v173, v207
	v_cndmask_b32_e32 v203, v206, v203, vcc
	v_pk_mul_f32 v[156:157], v[192:193], v[156:157]
	v_pk_mul_f32 v[158:159], v[194:195], v[158:159]
	v_pk_mul_f32 v[196:197], v[188:189], v[196:197]
	s_waitcnt lgkmcnt(0)
	v_mul_f32_e32 v204, v225, v204
	v_cndmask_b32_e64 v204, v204, -v204, s[4:5]
	v_fmac_f32_e32 v204, v205, v207
	ds_bpermute_b32 v205, v173, v230
	v_cndmask_b32_e32 v204, v207, v204, vcc
	v_pk_mul_f32 v[198:199], v[190:191], v[198:199]
	s_waitcnt lgkmcnt(0)
	v_mul_f32_e32 v148, v148, v205
	v_cndmask_b32_e64 v148, v148, -v148, s[4:5]
	v_fmac_f32_e32 v148, v144, v230
	ds_bpermute_b32 v144, v173, v231
	v_cndmask_b32_e32 v205, v230, v148, vcc
	s_waitcnt lgkmcnt(0)
	v_mul_f32_e32 v144, v149, v144
	v_cndmask_b32_e64 v144, v144, -v144, s[4:5]
	v_fmac_f32_e32 v144, v145, v231
	v_cndmask_b32_e32 v206, v231, v144, vcc
	ds_bpermute_b32 v144, v173, v200
	s_waitcnt lgkmcnt(0)
	v_mul_f32_e32 v144, v150, v144
	v_cndmask_b32_e64 v144, v144, -v144, s[4:5]
	v_fmac_f32_e32 v144, v146, v200
	v_cndmask_b32_e32 v150, v200, v144, vcc
	ds_bpermute_b32 v144, v173, v201
	s_waitcnt lgkmcnt(0)
; __device__ __forceinline__ u32x4 pack8(const f32x4& a, const f32x4& b) { u32x4 w; w.x = cvt_pk_bf16(a[0], a[1]); w.y = cvt_pk_bf16(a[2], a[3]); w.z = cvt_pk_bf16(b[0], b[1]); w.w = cvt_pk_bf16(b[2], b[3]); return w; }
; __device__ __forceinline__ float frsq(float x) { return __builtin_amdgcn_rsqf(x); }
;     __device__ __forceinline__ void operator()(Acc& acc, const Unit& u, int wr, int wc, int fr, int fq) const {
;     ...
;                         float ss = 0.f;
; #pragma unroll
;                         for (int bj = 0; bj < 2; ++bj)
; #pragma unroll
;                             for (int n = 0; n < 2; ++n) { const f32x4 v = acc[ai][bj][m][n]; ss += (v[0] * v[0] + v[1] * v[1]) + (v[2] * v[2] + v[3] * v[3]); }
;                         ss += __shfl_xor(ss, 16); ss += __shfl_xor(ss, 32);
;                         const float rstd = frsq(ss * (1.0f / 64.0f) + EPS);
;                         f32x4 y[2][2];
; #pragma unroll
;                         for (int bj = 0; bj < 2; ++bj)
; #pragma unroll
;                             for (int n = 0; n < 2; ++n) y[bj][n] = acc[ai][bj][m][n] * rstd * g[bj][n];
; #pragma unroll
;                         for (int n = 0; n < 2; ++n) {
;                             const f32x4 cs = rc[m2][n], sn = rs[m2][n];
;                             f32x4 o;
; #pragma unroll
;                             for (int i = 0; i < 4; ++i) { const float mine = y[0][n][i], oth = __shfl_xor(mine, 16);
;                                 const float r = (fq == 0) ? (mine * cs[i] - oth * sn[i]) : (mine * cs[i] + oth * sn[i]);
;                                 o[i] = (fq < 2) ? r : mine; }
;                             y[0][n] = o;
;                         }
; #pragma unroll
;                         for (int bj = 0; bj < 2; ++bj) *(u32x4*)(ob + (size_t)row * ld + bj * 32) = pack8(y[bj][0], y[bj][1]);
	v_mul_f32_e32 v144, v151, v144
	v_cndmask_b32_e64 v144, v144, -v144, s[4:5]
	v_fmac_f32_e32 v144, v147, v201
	v_cndmask_b32_e32 v147, v201, v144, vcc
	v_lshlrev_b64 v[144:145], s12, v[154:155]
	v_lshl_add_u64 v[148:149], v[144:145], 1, v[178:179]
	v_cvt_pk_bf16_f32 v144, v175, v202
	v_cvt_pk_bf16_f32 v145, v203, v204
	v_cvt_pk_bf16_f32 v146, v205, v206
	v_cvt_pk_bf16_f32 v147, v150, v147
	global_store_dwordx4 v[148:149], v[144:147], off sc1
	s_nop 1
	v_cvt_pk_bf16_f32 v144, v158, v159
	v_cvt_pk_bf16_f32 v145, v156, v157
	v_cvt_pk_bf16_f32 v146, v198, v199
	v_cvt_pk_bf16_f32 v147, v196, v197
	global_store_dwordx4 v[148:149], v[144:147], off offset:64 sc1
	s_nop 1
	v_pk_mul_f32 v[144:145], v[22:23], v[22:23]
	v_pk_mul_f32 v[146:147], v[20:21], v[20:21]
	s_nop 0
	v_pk_mov_b32 v[148:149], v[146:147], v[144:145] op_sel:[1,0]
	v_mov_b32_e32 v147, v145
	v_pk_add_f32 v[144:145], v[148:149], v[146:147]
	v_pk_mul_f32 v[146:147], v[14:15], v[14:15]
	v_pk_mul_f32 v[148:149], v[12:13], v[12:13]
	v_pk_add_f32 v[144:145], v[144:145], v[144:145] op_sel:[0,1] op_sel_hi:[1,0]
	v_pk_mov_b32 v[150:151], v[148:149], v[146:147] op_sel:[1,0]
	v_mov_b32_e32 v149, v147
	v_pk_add_f32 v[146:147], v[150:151], v[148:149]
	v_mul_f32_e32 v148, v0, v0
	v_mul_f32_e32 v149, v1, v1
	v_pk_add_f32 v[146:147], v[146:147], v[146:147] op_sel:[0,1] op_sel_hi:[1,0]
	v_mov_b32_e32 v145, v148
	v_mov_b32_e32 v147, v149
	v_pk_add_f32 v[144:145], v[144:145], v[146:147]
	v_mul_f32_e32 v146, v5, v5
	v_mul_f32_e32 v148, v7, v7
	v_mul_f32_e32 v150, v2, v2
	v_mul_f32_e32 v151, v3, v3
	v_pk_fma_f32 v[146:147], v[4:5], v[4:5], v[146:147] op_sel_hi:[1,1,0]
	v_pk_fma_f32 v[148:149], v[6:7], v[6:7], v[148:149] op_sel_hi:[1,1,0]
	v_mov_b32_e32 v147, v150
	v_mov_b32_e32 v149, v151
	v_pk_add_f32 v[146:147], v[146:147], v[148:149]
	s_nop 0
	v_pk_add_f32 v[144:145], v[144:145], v[146:147]
	s_nop 0
	v_add_f32_e32 v144, v144, v145
	ds_bpermute_b32 v145, v173, v144
	s_waitcnt lgkmcnt(0)
	v_add_f32_e32 v144, v144, v145
	ds_bpermute_b32 v145, v220, v144
	s_waitcnt lgkmcnt(0)
	v_add_f32_e32 v144, v144, v145
	v_fmamk_f32 v144, v144, 0x3c800000, v215
	v_rsq_f32_e32 v144, v144
	s_nop 0
	v_pk_mul_f32 v[146:147], v[20:21], v[144:145] op_sel_hi:[1,0]
	s_nop 0
	v_pk_mul_f32 v[158:159], v[186:187], v[146:147]
	ds_bpermute_b32 v175, v173, v158
	v_pk_mul_f32 v[148:149], v[22:23], v[144:145] op_sel_hi:[1,0]
	v_pk_mul_f32 v[146:147], v[12:13], v[144:145] op_sel_hi:[1,0]
	v_pk_mul_f32 v[156:157], v[184:185], v[148:149]
	v_pk_mul_f32 v[148:149], v[14:15], v[144:145] op_sel_hi:[1,0]
	s_waitcnt vmcnt(2) lgkmcnt(0)
	v_mul_f32_e32 v140, v140, v175
	v_cndmask_b32_e64 v140, v140, -v140, s[4:5]
	v_fmac_f32_e32 v140, v136, v158
	v_cndmask_b32_e32 v136, v158, v140, vcc
	ds_bpermute_b32 v140, v173, v159
	v_pk_mul_f32 v[154:155], v[180:181], v[148:149]
	v_pk_mul_f32 v[180:181], v[182:183], v[146:147]
	v_pk_mul_f32 v[148:149], v[4:5], v[144:145] op_sel_hi:[1,0]
	v_pk_mul_f32 v[146:147], v[6:7], v[144:145] op_sel_hi:[1,0]
	s_waitcnt lgkmcnt(0)
	v_mul_f32_e32 v140, v141, v140
	v_cndmask_b32_e64 v140, v140, -v140, s[4:5]
	v_fmac_f32_e32 v140, v137, v159
	v_cndmask_b32_e32 v137, v159, v140, vcc
	ds_bpermute_b32 v140, v173, v156
	v_pk_mul_f32 v[150:151], v[194:195], v[148:149]
	v_pk_mul_f32 v[148:149], v[0:1], v[144:145] op_sel_hi:[1,0]
	v_pk_mul_f32 v[144:145], v[2:3], v[144:145] op_sel_hi:[1,0]
	v_pk_mul_f32 v[146:147], v[192:193], v[146:147]
	s_waitcnt lgkmcnt(0)
	v_mul_f32_e32 v140, v142, v140
	v_cndmask_b32_e64 v140, v140, -v140, s[4:5]
	v_fmac_f32_e32 v140, v138, v156
	v_cndmask_b32_e32 v138, v156, v140, vcc
	ds_bpermute_b32 v140, v173, v157
	v_pk_mul_f32 v[144:145], v[188:189], v[144:145]
	v_pk_mul_f32 v[148:149], v[190:191], v[148:149]
	s_waitcnt lgkmcnt(0)
	v_mul_f32_e32 v140, v143, v140
	v_cndmask_b32_e64 v140, v140, -v140, s[4:5]
	v_fmac_f32_e32 v140, v139, v157
	v_cndmask_b32_e32 v139, v157, v140, vcc
	ds_bpermute_b32 v140, v173, v180
	s_waitcnt lgkmcnt(0)
	v_mul_f32_e32 v132, v132, v140
	v_cndmask_b32_e64 v132, v132, -v132, s[4:5]
	v_fmac_f32_e32 v132, v128, v180
	ds_bpermute_b32 v128, v173, v181
	v_cndmask_b32_e32 v140, v180, v132, vcc
	s_waitcnt lgkmcnt(0)
	v_mul_f32_e32 v128, v133, v128
	v_cndmask_b32_e64 v128, v128, -v128, s[4:5]
	v_fmac_f32_e32 v128, v129, v181
	v_cndmask_b32_e32 v141, v181, v128, vcc
	ds_bpermute_b32 v128, v173, v154
	s_waitcnt lgkmcnt(0)
	v_mul_f32_e32 v128, v134, v128
	v_cndmask_b32_e64 v128, v128, -v128, s[4:5]
	v_fmac_f32_e32 v128, v130, v154
	v_cndmask_b32_e32 v134, v154, v128, vcc
	ds_bpermute_b32 v128, v173, v155
	s_waitcnt lgkmcnt(0)
	v_mul_f32_e32 v128, v135, v128
	v_cndmask_b32_e64 v128, v128, -v128, s[4:5]
	v_fmac_f32_e32 v128, v131, v155
	v_cndmask_b32_e32 v131, v155, v128, vcc
	v_lshlrev_b64 v[128:129], s12, v[152:153]
	v_lshl_add_u64 v[132:133], v[128:129], 1, v[178:179]
	v_cvt_pk_bf16_f32 v128, v136, v137
	v_cvt_pk_bf16_f32 v129, v138, v139
	v_cvt_pk_bf16_f32 v130, v140, v141
	v_cvt_pk_bf16_f32 v131, v134, v131
	global_store_dwordx4 v[132:133], v[128:131], off sc1
	s_mov_b64 s[4:5], 0
	s_nop 0
	v_cvt_pk_bf16_f32 v128, v150, v151
	v_cvt_pk_bf16_f32 v129, v146, v147
	v_cvt_pk_bf16_f32 v130, v148, v149
	v_cvt_pk_bf16_f32 v131, v144, v145
	global_store_dwordx4 v[132:133], v[128:131], off offset:64 sc1

; __device__ __forceinline__ u32x4 pack8(const f32x4& a, const f32x4& b) { u32x4 w; w.x = cvt_pk_bf16(a[0], a[1]); w.y = cvt_pk_bf16(a[2], a[3]); w.z = cvt_pk_bf16(b[0], b[1]); w.w = cvt_pk_bf16(b[2], b[3]); return w; }
; __device__ __forceinline__ float fexp(float x) { return __builtin_amdgcn_exp2f(x * 1.4426950408889634f); }
; __device__ __forceinline__ float frcp(float x) { return __builtin_amdgcn_rcpf(x); }
;     __device__ __forceinline__ void operator()(Acc& acc, const Unit& u, int wr, int wc, int fr, int fq) const {
;     ...
;         } else if (pn < 8 && !(DIS_MASK & 2)) {
; #pragma unroll
;             for (int ai = 0; ai < 2; ++ai)
; #pragma unroll
;                 for (int m = 0; m < 4; ++m)
; #pragma unroll
;                     for (int bj = 0; bj < 2; ++bj) { f32x4 a = acc[ai][bj][m][0], b = acc[ai][bj][m][1];
; #pragma unroll
;                         for (int i = 0; i < 4; ++i) { a[i] = a[i] * frcp(1.0f + fexp(-a[i])); b[i] = b[i] * frcp(1.0f + fexp(-b[i])); }
;                         *(u32x4*)(SG + (size_t)(row0 + ai * HALF + m * 16) * 512 + (pn - 6) * 256 + bj * HALF + cw) = pack8(a, b); }
.LBB0_369:
	s_andn2_b64 vcc, exec, s[4:5]
	s_cbranch_vccnz .LBB0_371
	v_mul_f32_e32 v131, 0xbfb8aa3b, v120
	v_mul_f32_e32 v132, 0xbfb8aa3b, v125
	v_exp_f32_e32 v131, v131
	v_exp_f32_e32 v132, v132
	v_mul_f32_e32 v133, 0xbfb8aa3b, v121
	v_exp_f32_e32 v133, v133
	v_add_f32_e32 v131, 1.0, v131
	v_add_f32_e32 v132, 1.0, v132
	v_rcp_f32_e32 v131, v131
	v_rcp_f32_e32 v132, v132
	v_mul_f32_e32 v128, 0xbfb8aa3b, v124
	v_exp_f32_e32 v130, v128
	v_mul_f32_e32 v134, v120, v131
	v_mul_f32_e32 v131, v125, v132
	v_add_f32_e32 v132, 1.0, v133
	v_mul_f32_e32 v133, 0xbfb8aa3b, v126
	v_mul_f32_e32 v136, 0xbfb8aa3b, v127
	v_exp_f32_e32 v133, v133
	v_mul_f32_e32 v135, 0xbfb8aa3b, v122
	v_exp_f32_e32 v136, v136
	v_mul_f32_e32 v137, 0xbfb8aa3b, v123
	v_exp_f32_e32 v135, v135
	v_exp_f32_e32 v137, v137
	v_add_f32_e32 v130, 1.0, v130
	v_rcp_f32_e32 v130, v130
	v_rcp_f32_e32 v132, v132
	v_add_f32_e32 v133, 1.0, v133
	v_add_f32_e32 v136, 1.0, v136
	v_ashrrev_i32_e32 v175, 31, v174
	v_rcp_f32_e32 v133, v133
	v_add_f32_e32 v135, 1.0, v135
	v_rcp_f32_e32 v136, v136
	v_add_f32_e32 v137, 1.0, v137
	v_readlane_b32 s4, v254, 45
	v_lshlrev_b64 v[128:129], 10, v[174:175]
	v_rcp_f32_e32 v135, v135
	v_rcp_f32_e32 v137, v137
	v_readlane_b32 s5, v254, 46
	s_lshl_b32 s12, s40, 9
	v_ashrrev_i32_e32 v173, 31, v172
	v_lshl_add_u64 v[128:129], s[4:5], 0, v[128:129]
	v_mul_f32_e32 v130, v124, v130
	v_mul_f32_e32 v132, v121, v132
	v_lshl_add_u64 v[128:129], v[128:129], 0, s[12:13]
	v_mul_f32_e32 v133, v126, v133
	v_mul_f32_e32 v136, v127, v136
	v_cvt_pk_bf16_f32 v130, v130, v131
	v_cvt_pk_bf16_f32 v131, v133, v136
	v_cvt_pk_bf16_f32 v132, v134, v132
	v_lshl_add_u64 v[128:129], v[172:173], 1, v[128:129]
	v_mul_f32_e32 v135, v122, v135
	v_mul_f32_e32 v137, v123, v137
	v_cvt_pk_bf16_f32 v133, v135, v137
	global_store_dwordx4 v[128:129], v[130:133], off offset:-3072 sc1
	v_mul_f32_e32 v134, 0xbfb8aa3b, v112
	v_exp_f32_e32 v134, v134
	v_mul_f32_e32 v131, 0xbfb8aa3b, v104
	v_mul_f32_e32 v132, 0xbfb8aa3b, v113
	v_exp_f32_e32 v131, v131
	v_exp_f32_e32 v132, v132
	v_mul_f32_e32 v133, 0xbfb8aa3b, v105
	v_exp_f32_e32 v133, v133
	v_add_f32_e32 v131, 1.0, v131
	v_add_f32_e32 v132, 1.0, v132
	v_rcp_f32_e32 v131, v131
	v_rcp_f32_e32 v132, v132
	v_add_f32_e32 v130, 1.0, v134
	v_mul_f32_e32 v136, 0xbfb8aa3b, v115
	v_mul_f32_e32 v134, v104, v131
	v_mul_f32_e32 v131, v113, v132
	v_add_f32_e32 v132, 1.0, v133
	v_mul_f32_e32 v133, 0xbfb8aa3b, v114
	v_exp_f32_e32 v133, v133
	v_mul_f32_e32 v135, 0xbfb8aa3b, v106
	v_exp_f32_e32 v136, v136
	v_mul_f32_e32 v137, 0xbfb8aa3b, v107
	v_exp_f32_e32 v135, v135
	v_exp_f32_e32 v137, v137
	v_add_f32_e32 v133, 1.0, v133
	v_rcp_f32_e32 v130, v130
	v_rcp_f32_e32 v132, v132
	v_rcp_f32_e32 v133, v133
	v_add_f32_e32 v136, 1.0, v136
	v_add_f32_e32 v135, 1.0, v135
	v_rcp_f32_e32 v136, v136
	v_add_f32_e32 v137, 1.0, v137
	v_rcp_f32_e32 v135, v135
	v_rcp_f32_e32 v137, v137
	v_mul_f32_e32 v130, v112, v130
	v_mul_f32_e32 v132, v105, v132
	v_mul_f32_e32 v133, v114, v133
	v_mul_f32_e32 v136, v115, v136
	v_cvt_pk_bf16_f32 v130, v130, v131
	v_cvt_pk_bf16_f32 v131, v133, v136
	v_mul_f32_e32 v133, 0xbfb8aa3b, v116
	v_cvt_pk_bf16_f32 v132, v134, v132
	v_mul_f32_e32 v135, v106, v135
	v_mul_f32_e32 v137, v107, v137
	v_exp_f32_e32 v136, v133
	v_cvt_pk_bf16_f32 v133, v135, v137
	global_store_dwordx4 v[128:129], v[130:133], off offset:-2816 sc1
	v_mul_f32_e32 v135, 0xbfb8aa3b, v110
	v_exp_f32_e32 v135, v135
	v_mul_f32_e32 v131, 0xbfb8aa3b, v108
	v_mul_f32_e32 v132, 0xbfb8aa3b, v117
	v_exp_f32_e32 v131, v131
	v_exp_f32_e32 v132, v132
	v_mul_f32_e32 v133, 0xbfb8aa3b, v109
	v_exp_f32_e32 v133, v133
	v_add_f32_e32 v131, 1.0, v131
	v_add_f32_e32 v132, 1.0, v132
	v_rcp_f32_e32 v131, v131
	v_rcp_f32_e32 v132, v132
	v_add_f32_e32 v130, 1.0, v136
	v_mul_f32_e32 v136, 0xbfb8aa3b, v119
	v_mul_f32_e32 v134, v108, v131
	v_mul_f32_e32 v131, v117, v132
	v_add_f32_e32 v132, 1.0, v133
	v_mul_f32_e32 v133, 0xbfb8aa3b, v118
	v_exp_f32_e32 v133, v133
	v_exp_f32_e32 v136, v136
	v_mul_f32_e32 v137, 0xbfb8aa3b, v111
	v_exp_f32_e32 v137, v137
	v_add_f32_e32 v133, 1.0, v133
	v_rcp_f32_e32 v130, v130
	v_rcp_f32_e32 v133, v133
	v_add_f32_e32 v135, 1.0, v135
	v_add_f32_e32 v136, 1.0, v136
	v_rcp_f32_e32 v132, v132
	v_rcp_f32_e32 v135, v135
	v_rcp_f32_e32 v136, v136
	v_add_f32_e32 v137, 1.0, v137
	v_rcp_f32_e32 v137, v137
	v_mul_f32_e32 v130, v116, v130
	v_mul_f32_e32 v133, v118, v133
	v_mul_f32_e32 v132, v109, v132
	v_mul_f32_e32 v135, v110, v135
	v_mul_f32_e32 v136, v119, v136
	v_cvt_pk_bf16_f32 v130, v130, v131
	v_cvt_pk_bf16_f32 v131, v133, v136
	v_mul_f32_e32 v133, 0xbfb8aa3b, v96
	v_mul_f32_e32 v137, v111, v137
	v_cvt_pk_bf16_f32 v132, v134, v132
	v_exp_f32_e32 v136, v133
	v_cvt_pk_bf16_f32 v133, v135, v137
	v_lshl_add_u64 v[134:135], v[128:129], 0, s[56:57]
	global_store_dwordx4 v[134:135], v[130:133], off offset:-3072 sc1
	v_mul_f32_e32 v138, 0xbfb8aa3b, v99
	v_mul_f32_e32 v137, 0xbfb8aa3b, v90
	v_mul_f32_e32 v131, 0xbfb8aa3b, v88
	v_mul_f32_e32 v132, 0xbfb8aa3b, v97
	v_exp_f32_e32 v131, v131
	v_exp_f32_e32 v132, v132
	v_mul_f32_e32 v133, 0xbfb8aa3b, v89
	v_exp_f32_e32 v133, v133
	v_add_f32_e32 v131, 1.0, v131
	v_add_f32_e32 v132, 1.0, v132
	v_rcp_f32_e32 v131, v131
	v_rcp_f32_e32 v132, v132
	v_add_f32_e32 v130, 1.0, v136
	v_exp_f32_e32 v138, v138
	v_mul_f32_e32 v136, v88, v131
	v_mul_f32_e32 v131, v97, v132
	v_add_f32_e32 v132, 1.0, v133
	v_mul_f32_e32 v133, 0xbfb8aa3b, v98
	v_exp_f32_e32 v133, v133
	v_mul_f32_e32 v139, 0xbfb8aa3b, v91
	v_exp_f32_e32 v137, v137
	v_exp_f32_e32 v139, v139
	v_add_f32_e32 v133, 1.0, v133
	v_rcp_f32_e32 v130, v130
	v_rcp_f32_e32 v132, v132
	v_rcp_f32_e32 v133, v133
; __device__ __forceinline__ u32x4 pack8(const f32x4& a, const f32x4& b) { u32x4 w; w.x = cvt_pk_bf16(a[0], a[1]); w.y = cvt_pk_bf16(a[2], a[3]); w.z = cvt_pk_bf16(b[0], b[1]); w.w = cvt_pk_bf16(b[2], b[3]); return w; }
; __device__ __forceinline__ float fexp(float x) { return __builtin_amdgcn_exp2f(x * 1.4426950408889634f); }
; __device__ __forceinline__ float frcp(float x) { return __builtin_amdgcn_rcpf(x); }
;     __device__ __forceinline__ void operator()(Acc& acc, const Unit& u, int wr, int wc, int fr, int fq) const {
;     ...
;         } else if (pn < 8 && !(DIS_MASK & 2)) {
; #pragma unroll
;             for (int ai = 0; ai < 2; ++ai)
; #pragma unroll
;                 for (int m = 0; m < 4; ++m)
; #pragma unroll
;                     for (int bj = 0; bj < 2; ++bj) { f32x4 a = acc[ai][bj][m][0], b = acc[ai][bj][m][1];
; #pragma unroll
;                         for (int i = 0; i < 4; ++i) { a[i] = a[i] * frcp(1.0f + fexp(-a[i])); b[i] = b[i] * frcp(1.0f + fexp(-b[i])); }
;                         *(u32x4*)(SG + (size_t)(row0 + ai * HALF + m * 16) * 512 + (pn - 6) * 256 + bj * HALF + cw) = pack8(a, b); }
	v_add_f32_e32 v138, 1.0, v138
	v_add_f32_e32 v137, 1.0, v137
	v_rcp_f32_e32 v138, v138
	v_add_f32_e32 v139, 1.0, v139
	v_rcp_f32_e32 v137, v137
	v_rcp_f32_e32 v139, v139
	v_mul_f32_e32 v130, v96, v130
	v_mul_f32_e32 v132, v89, v132
	v_mul_f32_e32 v133, v98, v133
	v_mul_f32_e32 v138, v99, v138
	v_cvt_pk_bf16_f32 v130, v130, v131
	v_cvt_pk_bf16_f32 v131, v133, v138
	v_mul_f32_e32 v133, 0xbfb8aa3b, v100
	v_cvt_pk_bf16_f32 v132, v136, v132
	v_mul_f32_e32 v137, v90, v137
	v_mul_f32_e32 v139, v91, v139
	v_exp_f32_e32 v138, v133
	v_cvt_pk_bf16_f32 v133, v137, v139
	global_store_dwordx4 v[134:135], v[130:133], off offset:-2816 sc1
	v_mul_f32_e32 v135, 0xbfb8aa3b, v94
	v_mul_f32_e32 v136, 0xbfb8aa3b, v103
	v_mul_f32_e32 v131, 0xbfb8aa3b, v92
	v_mul_f32_e32 v132, 0xbfb8aa3b, v101
	v_exp_f32_e32 v131, v131
	v_exp_f32_e32 v132, v132
	v_mul_f32_e32 v133, 0xbfb8aa3b, v93
	v_exp_f32_e32 v133, v133
	v_add_f32_e32 v131, 1.0, v131
	v_add_f32_e32 v132, 1.0, v132
	v_rcp_f32_e32 v131, v131
	v_rcp_f32_e32 v132, v132
	v_exp_f32_e32 v135, v135
	v_exp_f32_e32 v136, v136
	v_mul_f32_e32 v134, v92, v131
	v_mul_f32_e32 v131, v101, v132
	v_add_f32_e32 v132, 1.0, v133
	v_mul_f32_e32 v133, 0xbfb8aa3b, v102
	v_exp_f32_e32 v133, v133
	v_mul_f32_e32 v137, 0xbfb8aa3b, v95
	v_exp_f32_e32 v137, v137
	v_add_f32_e32 v130, 1.0, v138
	v_add_f32_e32 v133, 1.0, v133
	v_rcp_f32_e32 v130, v130
	v_rcp_f32_e32 v133, v133
	v_add_f32_e32 v135, 1.0, v135
	v_add_f32_e32 v136, 1.0, v136
	v_rcp_f32_e32 v132, v132
	v_rcp_f32_e32 v135, v135
	v_rcp_f32_e32 v136, v136
	v_add_f32_e32 v137, 1.0, v137
	v_rcp_f32_e32 v137, v137
	v_mul_f32_e32 v130, v100, v130
	v_mul_f32_e32 v133, v102, v133
	v_mul_f32_e32 v132, v93, v132
	v_mul_f32_e32 v135, v94, v135
	v_mul_f32_e32 v136, v103, v136
	v_cvt_pk_bf16_f32 v130, v130, v131
	v_cvt_pk_bf16_f32 v131, v133, v136
	v_mul_f32_e32 v133, 0xbfb8aa3b, v80
	v_mul_f32_e32 v137, v95, v137
	v_cvt_pk_bf16_f32 v132, v134, v132
	v_exp_f32_e32 v136, v133
	v_cvt_pk_bf16_f32 v133, v135, v137
	v_lshl_add_u64 v[134:135], v[128:129], 0, s[24:25]
	global_store_dwordx4 v[134:135], v[130:133], off offset:-3072 sc1
	v_mul_f32_e32 v138, 0xbfb8aa3b, v83
	v_mul_f32_e32 v137, 0xbfb8aa3b, v74
	v_mul_f32_e32 v131, 0xbfb8aa3b, v72
	v_mul_f32_e32 v132, 0xbfb8aa3b, v81
	v_exp_f32_e32 v131, v131
	v_exp_f32_e32 v132, v132
	v_mul_f32_e32 v133, 0xbfb8aa3b, v73
	v_exp_f32_e32 v133, v133
	v_add_f32_e32 v131, 1.0, v131
	v_add_f32_e32 v132, 1.0, v132
	v_rcp_f32_e32 v131, v131
	v_rcp_f32_e32 v132, v132
	v_add_f32_e32 v130, 1.0, v136
	v_exp_f32_e32 v138, v138
	v_mul_f32_e32 v136, v72, v131
	v_mul_f32_e32 v131, v81, v132
	v_add_f32_e32 v132, 1.0, v133
	v_mul_f32_e32 v133, 0xbfb8aa3b, v82
	v_exp_f32_e32 v133, v133
	v_mul_f32_e32 v139, 0xbfb8aa3b, v75
	v_exp_f32_e32 v137, v137
	v_exp_f32_e32 v139, v139
	v_add_f32_e32 v133, 1.0, v133
	v_rcp_f32_e32 v130, v130
	v_rcp_f32_e32 v132, v132
	v_rcp_f32_e32 v133, v133
	v_add_f32_e32 v138, 1.0, v138
	v_add_f32_e32 v137, 1.0, v137
	v_rcp_f32_e32 v138, v138
	v_add_f32_e32 v139, 1.0, v139
	v_rcp_f32_e32 v137, v137
	v_rcp_f32_e32 v139, v139
	v_mul_f32_e32 v130, v80, v130
	v_mul_f32_e32 v132, v73, v132
	v_mul_f32_e32 v133, v82, v133
	v_mul_f32_e32 v138, v83, v138
	v_cvt_pk_bf16_f32 v130, v130, v131
	v_cvt_pk_bf16_f32 v131, v133, v138
	v_mul_f32_e32 v133, 0xbfb8aa3b, v84
	v_cvt_pk_bf16_f32 v132, v136, v132
	v_mul_f32_e32 v137, v74, v137
	v_mul_f32_e32 v139, v75, v139
	v_exp_f32_e32 v138, v133
	v_cvt_pk_bf16_f32 v133, v137, v139
	global_store_dwordx4 v[134:135], v[130:133], off offset:-2816 sc1
	v_mul_f32_e32 v135, 0xbfb8aa3b, v78
	v_mul_f32_e32 v136, 0xbfb8aa3b, v87
	v_mul_f32_e32 v131, 0xbfb8aa3b, v76
	v_mul_f32_e32 v132, 0xbfb8aa3b, v85
	v_exp_f32_e32 v131, v131
	v_exp_f32_e32 v132, v132
	v_mul_f32_e32 v133, 0xbfb8aa3b, v77
	v_exp_f32_e32 v133, v133
	v_add_f32_e32 v131, 1.0, v131
	v_add_f32_e32 v132, 1.0, v132
	v_rcp_f32_e32 v131, v131
	v_rcp_f32_e32 v132, v132
	v_exp_f32_e32 v135, v135
	v_exp_f32_e32 v136, v136
	v_mul_f32_e32 v134, v76, v131
	v_mul_f32_e32 v131, v85, v132
	v_add_f32_e32 v132, 1.0, v133
	v_mul_f32_e32 v133, 0xbfb8aa3b, v86
	v_exp_f32_e32 v133, v133
	v_mul_f32_e32 v137, 0xbfb8aa3b, v79
	v_exp_f32_e32 v137, v137
	v_add_f32_e32 v130, 1.0, v138
	v_add_f32_e32 v133, 1.0, v133
	v_rcp_f32_e32 v130, v130
	v_rcp_f32_e32 v133, v133
	v_add_f32_e32 v135, 1.0, v135
	v_add_f32_e32 v136, 1.0, v136
	v_rcp_f32_e32 v132, v132
	v_rcp_f32_e32 v135, v135
	v_rcp_f32_e32 v136, v136
	v_add_f32_e32 v137, 1.0, v137
	v_rcp_f32_e32 v137, v137
	v_mul_f32_e32 v130, v84, v130
	v_mul_f32_e32 v133, v86, v133
	v_mul_f32_e32 v132, v77, v132
	v_mul_f32_e32 v135, v78, v135
	v_mul_f32_e32 v136, v87, v136
	v_cvt_pk_bf16_f32 v130, v130, v131
	v_cvt_pk_bf16_f32 v131, v133, v136
	v_mul_f32_e32 v133, 0xbfb8aa3b, v68
	v_mul_f32_e32 v137, v79, v137
	v_cvt_pk_bf16_f32 v132, v134, v132
	v_exp_f32_e32 v136, v133
	v_cvt_pk_bf16_f32 v133, v135, v137
	v_lshl_add_u64 v[134:135], v[128:129], 0, s[60:61]
	global_store_dwordx4 v[134:135], v[130:133], off offset:-3072 sc1
	v_mul_f32_e32 v138, 0xbfb8aa3b, v71
	v_mul_f32_e32 v137, 0xbfb8aa3b, v66
	v_mul_f32_e32 v131, 0xbfb8aa3b, v64
	v_mul_f32_e32 v132, 0xbfb8aa3b, v69
	v_exp_f32_e32 v131, v131
	v_exp_f32_e32 v132, v132
	v_mul_f32_e32 v133, 0xbfb8aa3b, v65
	v_exp_f32_e32 v133, v133
	v_add_f32_e32 v131, 1.0, v131
	v_add_f32_e32 v132, 1.0, v132
	v_rcp_f32_e32 v131, v131
	v_rcp_f32_e32 v132, v132
	v_add_f32_e32 v130, 1.0, v136
	v_exp_f32_e32 v138, v138
	v_mul_f32_e32 v136, v64, v131
	v_mul_f32_e32 v131, v69, v132
	v_add_f32_e32 v132, 1.0, v133
	v_mul_f32_e32 v133, 0xbfb8aa3b, v70
	v_exp_f32_e32 v133, v133
	v_mul_f32_e32 v139, 0xbfb8aa3b, v67
; __device__ __forceinline__ u32x4 pack8(const f32x4& a, const f32x4& b) { u32x4 w; w.x = cvt_pk_bf16(a[0], a[1]); w.y = cvt_pk_bf16(a[2], a[3]); w.z = cvt_pk_bf16(b[0], b[1]); w.w = cvt_pk_bf16(b[2], b[3]); return w; }
; __device__ __forceinline__ float fexp(float x) { return __builtin_amdgcn_exp2f(x * 1.4426950408889634f); }
; __device__ __forceinline__ float frcp(float x) { return __builtin_amdgcn_rcpf(x); }
;     __device__ __forceinline__ void operator()(Acc& acc, const Unit& u, int wr, int wc, int fr, int fq) const {
;     ...
;         } else if (pn < 8 && !(DIS_MASK & 2)) {
; #pragma unroll
;             for (int ai = 0; ai < 2; ++ai)
; #pragma unroll
;                 for (int m = 0; m < 4; ++m)
; #pragma unroll
;                     for (int bj = 0; bj < 2; ++bj) { f32x4 a = acc[ai][bj][m][0], b = acc[ai][bj][m][1];
; #pragma unroll
;                         for (int i = 0; i < 4; ++i) { a[i] = a[i] * frcp(1.0f + fexp(-a[i])); b[i] = b[i] * frcp(1.0f + fexp(-b[i])); }
;                         *(u32x4*)(SG + (size_t)(row0 + ai * HALF + m * 16) * 512 + (pn - 6) * 256 + bj * HALF + cw) = pack8(a, b); }
	v_exp_f32_e32 v137, v137
	v_exp_f32_e32 v139, v139
	v_add_f32_e32 v133, 1.0, v133
	v_rcp_f32_e32 v130, v130
	v_rcp_f32_e32 v132, v132
	v_rcp_f32_e32 v133, v133
	v_add_f32_e32 v138, 1.0, v138
	v_add_f32_e32 v137, 1.0, v137
	v_rcp_f32_e32 v138, v138
	v_add_f32_e32 v139, 1.0, v139
	v_rcp_f32_e32 v137, v137
	v_rcp_f32_e32 v139, v139
	v_mul_f32_e32 v130, v68, v130
	v_mul_f32_e32 v132, v65, v132
	v_mul_f32_e32 v133, v70, v133
	v_mul_f32_e32 v138, v71, v138
	v_cvt_pk_bf16_f32 v130, v130, v131
	v_cvt_pk_bf16_f32 v131, v133, v138
	v_mul_f32_e32 v133, 0xbfb8aa3b, v60
	v_cvt_pk_bf16_f32 v132, v136, v132
	v_mul_f32_e32 v137, v66, v137
	v_mul_f32_e32 v139, v67, v139
	v_exp_f32_e32 v138, v133
	v_cvt_pk_bf16_f32 v133, v137, v139
	global_store_dwordx4 v[134:135], v[130:133], off offset:-2816 sc1
	v_mul_f32_e32 v135, 0xbfb8aa3b, v58
	v_mul_f32_e32 v136, 0xbfb8aa3b, v63
	v_mul_f32_e32 v131, 0xbfb8aa3b, v56
	v_mul_f32_e32 v132, 0xbfb8aa3b, v61
	v_exp_f32_e32 v131, v131
	v_exp_f32_e32 v132, v132
	v_mul_f32_e32 v133, 0xbfb8aa3b, v57
	v_exp_f32_e32 v133, v133
	v_add_f32_e32 v131, 1.0, v131
	v_add_f32_e32 v132, 1.0, v132
	v_rcp_f32_e32 v131, v131
	v_rcp_f32_e32 v132, v132
	v_exp_f32_e32 v135, v135
	v_exp_f32_e32 v136, v136
	v_mul_f32_e32 v134, v56, v131
	v_mul_f32_e32 v131, v61, v132
	v_add_f32_e32 v132, 1.0, v133
	v_mul_f32_e32 v133, 0xbfb8aa3b, v62
	v_exp_f32_e32 v133, v133
	v_mul_f32_e32 v137, 0xbfb8aa3b, v59
	v_exp_f32_e32 v137, v137
	v_add_f32_e32 v130, 1.0, v138
	v_add_f32_e32 v133, 1.0, v133
	v_rcp_f32_e32 v130, v130
	v_rcp_f32_e32 v133, v133
	v_add_f32_e32 v135, 1.0, v135
	v_add_f32_e32 v136, 1.0, v136
	v_rcp_f32_e32 v132, v132
	v_rcp_f32_e32 v135, v135
	v_rcp_f32_e32 v136, v136
	v_add_f32_e32 v137, 1.0, v137
	v_rcp_f32_e32 v137, v137
	v_mul_f32_e32 v130, v60, v130
	v_mul_f32_e32 v133, v62, v133
	v_mul_f32_e32 v132, v57, v132
	v_mul_f32_e32 v135, v58, v135
	v_mul_f32_e32 v136, v63, v136
	v_cvt_pk_bf16_f32 v130, v130, v131
	v_cvt_pk_bf16_f32 v131, v133, v136
	v_mul_f32_e32 v133, 0xbfb8aa3b, v48
	v_mul_f32_e32 v137, v59, v137
	v_cvt_pk_bf16_f32 v132, v134, v132
	v_exp_f32_e32 v136, v133
	v_cvt_pk_bf16_f32 v133, v135, v137
	v_lshl_add_u64 v[134:135], v[128:129], 0, s[64:65]
	global_store_dwordx4 v[134:135], v[130:133], off offset:-3072 sc1
	v_mul_f32_e32 v138, 0xbfb8aa3b, v51
	v_mul_f32_e32 v137, 0xbfb8aa3b, v42
	v_mul_f32_e32 v131, 0xbfb8aa3b, v40
	v_mul_f32_e32 v132, 0xbfb8aa3b, v49
	v_exp_f32_e32 v131, v131
	v_exp_f32_e32 v132, v132
	v_mul_f32_e32 v133, 0xbfb8aa3b, v41
	v_exp_f32_e32 v133, v133
	v_add_f32_e32 v131, 1.0, v131
	v_add_f32_e32 v132, 1.0, v132
	v_rcp_f32_e32 v131, v131
	v_rcp_f32_e32 v132, v132
	v_add_f32_e32 v130, 1.0, v136
	v_exp_f32_e32 v138, v138
	v_mul_f32_e32 v136, v40, v131
	v_mul_f32_e32 v131, v49, v132
	v_add_f32_e32 v132, 1.0, v133
	v_mul_f32_e32 v133, 0xbfb8aa3b, v50
	v_exp_f32_e32 v133, v133
	v_mul_f32_e32 v139, 0xbfb8aa3b, v43
	v_exp_f32_e32 v137, v137
	v_exp_f32_e32 v139, v139
	v_add_f32_e32 v133, 1.0, v133
	v_rcp_f32_e32 v130, v130
	v_rcp_f32_e32 v132, v132
	v_rcp_f32_e32 v133, v133
	v_add_f32_e32 v138, 1.0, v138
	v_add_f32_e32 v137, 1.0, v137
	v_rcp_f32_e32 v138, v138
	v_add_f32_e32 v139, 1.0, v139
	v_rcp_f32_e32 v137, v137
	v_rcp_f32_e32 v139, v139
	v_mul_f32_e32 v130, v48, v130
	v_mul_f32_e32 v132, v41, v132
	v_mul_f32_e32 v133, v50, v133
	v_mul_f32_e32 v138, v51, v138
	v_cvt_pk_bf16_f32 v130, v130, v131
	v_cvt_pk_bf16_f32 v131, v133, v138
	v_mul_f32_e32 v133, 0xbfb8aa3b, v52
	v_cvt_pk_bf16_f32 v132, v136, v132
	v_mul_f32_e32 v137, v42, v137
	v_mul_f32_e32 v139, v43, v139
	v_exp_f32_e32 v138, v133
	v_cvt_pk_bf16_f32 v133, v137, v139
	global_store_dwordx4 v[134:135], v[130:133], off offset:-2816 sc1
	v_mul_f32_e32 v135, 0xbfb8aa3b, v46
	v_mul_f32_e32 v136, 0xbfb8aa3b, v55
	v_mul_f32_e32 v131, 0xbfb8aa3b, v44
	v_mul_f32_e32 v132, 0xbfb8aa3b, v53
	v_exp_f32_e32 v131, v131
	v_exp_f32_e32 v132, v132
	v_mul_f32_e32 v133, 0xbfb8aa3b, v45
	v_exp_f32_e32 v133, v133
	v_add_f32_e32 v131, 1.0, v131
	v_add_f32_e32 v132, 1.0, v132
	v_rcp_f32_e32 v131, v131
	v_rcp_f32_e32 v132, v132
	v_exp_f32_e32 v135, v135
	v_exp_f32_e32 v136, v136
	v_mul_f32_e32 v134, v44, v131
	v_mul_f32_e32 v131, v53, v132
	v_add_f32_e32 v132, 1.0, v133
	v_mul_f32_e32 v133, 0xbfb8aa3b, v54
	v_exp_f32_e32 v133, v133
	v_mul_f32_e32 v137, 0xbfb8aa3b, v47
	v_exp_f32_e32 v137, v137
	v_add_f32_e32 v130, 1.0, v138
	v_add_f32_e32 v133, 1.0, v133
	v_rcp_f32_e32 v130, v130
	v_rcp_f32_e32 v133, v133
	v_add_f32_e32 v135, 1.0, v135
	v_add_f32_e32 v136, 1.0, v136
	v_rcp_f32_e32 v132, v132
	v_rcp_f32_e32 v135, v135
	v_rcp_f32_e32 v136, v136
	v_add_f32_e32 v137, 1.0, v137
	v_rcp_f32_e32 v137, v137
	v_mul_f32_e32 v130, v52, v130
	v_mul_f32_e32 v133, v54, v133
	v_mul_f32_e32 v132, v45, v132
	v_mul_f32_e32 v135, v46, v135
	v_mul_f32_e32 v136, v55, v136
	v_cvt_pk_bf16_f32 v130, v130, v131
	v_cvt_pk_bf16_f32 v131, v133, v136
	v_mul_f32_e32 v133, 0xbfb8aa3b, v32
	v_mul_f32_e32 v137, v47, v137
	v_cvt_pk_bf16_f32 v132, v134, v132
	v_exp_f32_e32 v136, v133
	v_cvt_pk_bf16_f32 v133, v135, v137
	v_lshl_add_u64 v[134:135], v[128:129], 0, s[66:67]
	global_store_dwordx4 v[134:135], v[130:133], off offset:-3072 sc1
	v_mul_f32_e32 v138, 0xbfb8aa3b, v35
	v_mul_f32_e32 v137, 0xbfb8aa3b, v26
	v_mul_f32_e32 v131, 0xbfb8aa3b, v24
	v_mul_f32_e32 v132, 0xbfb8aa3b, v33
	v_exp_f32_e32 v131, v131
	v_exp_f32_e32 v132, v132
	v_mul_f32_e32 v133, 0xbfb8aa3b, v25
	v_exp_f32_e32 v133, v133
	v_add_f32_e32 v131, 1.0, v131
	v_add_f32_e32 v132, 1.0, v132
	v_rcp_f32_e32 v131, v131
	v_rcp_f32_e32 v132, v132
	v_add_f32_e32 v130, 1.0, v136
	v_exp_f32_e32 v138, v138
	v_mul_f32_e32 v136, v24, v131
	v_mul_f32_e32 v131, v33, v132
; __device__ __forceinline__ u32x4 pack8(const f32x4& a, const f32x4& b) { u32x4 w; w.x = cvt_pk_bf16(a[0], a[1]); w.y = cvt_pk_bf16(a[2], a[3]); w.z = cvt_pk_bf16(b[0], b[1]); w.w = cvt_pk_bf16(b[2], b[3]); return w; }
; __device__ __forceinline__ float fexp(float x) { return __builtin_amdgcn_exp2f(x * 1.4426950408889634f); }
; __device__ __forceinline__ float frcp(float x) { return __builtin_amdgcn_rcpf(x); }
;     __device__ __forceinline__ void operator()(Acc& acc, const Unit& u, int wr, int wc, int fr, int fq) const {
;     ...
;         } else if (pn < 8 && !(DIS_MASK & 2)) {
; #pragma unroll
;             for (int ai = 0; ai < 2; ++ai)
; #pragma unroll
;                 for (int m = 0; m < 4; ++m)
; #pragma unroll
;                     for (int bj = 0; bj < 2; ++bj) { f32x4 a = acc[ai][bj][m][0], b = acc[ai][bj][m][1];
; #pragma unroll
;                         for (int i = 0; i < 4; ++i) { a[i] = a[i] * frcp(1.0f + fexp(-a[i])); b[i] = b[i] * frcp(1.0f + fexp(-b[i])); }
;                         *(u32x4*)(SG + (size_t)(row0 + ai * HALF + m * 16) * 512 + (pn - 6) * 256 + bj * HALF + cw) = pack8(a, b); }
	v_add_f32_e32 v132, 1.0, v133
	v_mul_f32_e32 v133, 0xbfb8aa3b, v34
	v_exp_f32_e32 v133, v133
	v_mul_f32_e32 v139, 0xbfb8aa3b, v27
	v_exp_f32_e32 v137, v137
	v_exp_f32_e32 v139, v139
	v_add_f32_e32 v133, 1.0, v133
	v_rcp_f32_e32 v130, v130
	v_rcp_f32_e32 v132, v132
	v_rcp_f32_e32 v133, v133
	v_add_f32_e32 v138, 1.0, v138
	v_add_f32_e32 v137, 1.0, v137
	v_rcp_f32_e32 v138, v138
	v_add_f32_e32 v139, 1.0, v139
	v_rcp_f32_e32 v137, v137
	v_rcp_f32_e32 v139, v139
	v_mul_f32_e32 v130, v32, v130
	v_mul_f32_e32 v132, v25, v132
	v_mul_f32_e32 v133, v34, v133
	v_mul_f32_e32 v138, v35, v138
	v_cvt_pk_bf16_f32 v130, v130, v131
	v_cvt_pk_bf16_f32 v131, v133, v138
	v_mul_f32_e32 v133, 0xbfb8aa3b, v36
	v_cvt_pk_bf16_f32 v132, v136, v132
	v_mul_f32_e32 v137, v26, v137
	v_mul_f32_e32 v139, v27, v139
	v_exp_f32_e32 v138, v133
	v_cvt_pk_bf16_f32 v133, v137, v139
	global_store_dwordx4 v[134:135], v[130:133], off offset:-2816 sc1
	v_mul_f32_e32 v135, 0xbfb8aa3b, v30
	v_mul_f32_e32 v136, 0xbfb8aa3b, v39
	v_mul_f32_e32 v131, 0xbfb8aa3b, v28
	v_mul_f32_e32 v132, 0xbfb8aa3b, v37
	v_exp_f32_e32 v131, v131
	v_exp_f32_e32 v132, v132
	v_mul_f32_e32 v133, 0xbfb8aa3b, v29
	v_exp_f32_e32 v133, v133
	v_add_f32_e32 v131, 1.0, v131
	v_add_f32_e32 v132, 1.0, v132
	v_rcp_f32_e32 v131, v131
	v_rcp_f32_e32 v132, v132
	v_exp_f32_e32 v135, v135
	v_exp_f32_e32 v136, v136
	v_mul_f32_e32 v134, v28, v131
	v_mul_f32_e32 v131, v37, v132
	v_add_f32_e32 v132, 1.0, v133
	v_mul_f32_e32 v133, 0xbfb8aa3b, v38
	v_exp_f32_e32 v133, v133
	v_mul_f32_e32 v137, 0xbfb8aa3b, v31
	v_exp_f32_e32 v137, v137
	v_add_f32_e32 v130, 1.0, v138
	v_add_f32_e32 v133, 1.0, v133
	v_rcp_f32_e32 v130, v130
	v_rcp_f32_e32 v133, v133
	v_add_f32_e32 v135, 1.0, v135
	v_add_f32_e32 v136, 1.0, v136
	v_rcp_f32_e32 v132, v132
	v_rcp_f32_e32 v135, v135
	v_rcp_f32_e32 v136, v136
	v_add_f32_e32 v137, 1.0, v137
	v_rcp_f32_e32 v137, v137
	v_mul_f32_e32 v130, v36, v130
	v_mul_f32_e32 v133, v38, v133
	v_mul_f32_e32 v132, v29, v132
	v_mul_f32_e32 v135, v30, v135
	v_mul_f32_e32 v136, v39, v136
	v_cvt_pk_bf16_f32 v130, v130, v131
	v_cvt_pk_bf16_f32 v131, v133, v136
	v_mul_f32_e32 v133, 0xbfb8aa3b, v16
	v_mul_f32_e32 v137, v31, v137
	v_cvt_pk_bf16_f32 v132, v134, v132
	v_exp_f32_e32 v136, v133
	v_cvt_pk_bf16_f32 v133, v135, v137
	v_lshl_add_u64 v[134:135], v[128:129], 0, s[36:37]
	global_store_dwordx4 v[134:135], v[130:133], off offset:-3072 sc1
	v_mul_f32_e32 v138, 0xbfb8aa3b, v19
	v_mul_f32_e32 v137, 0xbfb8aa3b, v10
	v_mul_f32_e32 v131, 0xbfb8aa3b, v8
	v_mul_f32_e32 v132, 0xbfb8aa3b, v17
	v_exp_f32_e32 v131, v131
	v_exp_f32_e32 v132, v132
	v_mul_f32_e32 v133, 0xbfb8aa3b, v9
	v_exp_f32_e32 v133, v133
	v_add_f32_e32 v131, 1.0, v131
	v_add_f32_e32 v132, 1.0, v132
	v_rcp_f32_e32 v131, v131
	v_rcp_f32_e32 v132, v132
	v_add_f32_e32 v130, 1.0, v136
	v_exp_f32_e32 v138, v138
	v_mul_f32_e32 v136, v8, v131
	v_mul_f32_e32 v131, v17, v132
	v_add_f32_e32 v132, 1.0, v133
	v_mul_f32_e32 v133, 0xbfb8aa3b, v18
	v_exp_f32_e32 v133, v133
	v_mul_f32_e32 v139, 0xbfb8aa3b, v11
	v_exp_f32_e32 v137, v137
	v_exp_f32_e32 v139, v139
	v_add_f32_e32 v133, 1.0, v133
	v_rcp_f32_e32 v130, v130
	v_rcp_f32_e32 v132, v132
	v_rcp_f32_e32 v133, v133
	v_add_f32_e32 v138, 1.0, v138
	v_add_f32_e32 v137, 1.0, v137
	v_rcp_f32_e32 v138, v138
	v_add_f32_e32 v139, 1.0, v139
	v_rcp_f32_e32 v137, v137
	v_rcp_f32_e32 v139, v139
	v_mul_f32_e32 v130, v16, v130
	v_mul_f32_e32 v132, v9, v132
	v_mul_f32_e32 v133, v18, v133
	v_mul_f32_e32 v138, v19, v138
	v_cvt_pk_bf16_f32 v130, v130, v131
	v_cvt_pk_bf16_f32 v131, v133, v138
	v_mul_f32_e32 v133, 0xbfb8aa3b, v20
	v_cvt_pk_bf16_f32 v132, v136, v132
	v_mul_f32_e32 v137, v10, v137
	v_mul_f32_e32 v139, v11, v139
	v_exp_f32_e32 v138, v133
	v_cvt_pk_bf16_f32 v133, v137, v139
	global_store_dwordx4 v[134:135], v[130:133], off offset:-2816 sc1
	v_mul_f32_e32 v135, 0xbfb8aa3b, v14
	v_mul_f32_e32 v136, 0xbfb8aa3b, v23
	v_mul_f32_e32 v131, 0xbfb8aa3b, v12
	v_mul_f32_e32 v132, 0xbfb8aa3b, v21
	v_exp_f32_e32 v131, v131
	v_exp_f32_e32 v132, v132
	v_mul_f32_e32 v133, 0xbfb8aa3b, v13
	v_exp_f32_e32 v133, v133
	v_add_f32_e32 v131, 1.0, v131
	v_add_f32_e32 v132, 1.0, v132
	v_rcp_f32_e32 v131, v131
	v_rcp_f32_e32 v132, v132
	v_exp_f32_e32 v135, v135
	v_exp_f32_e32 v136, v136
	v_mul_f32_e32 v134, v12, v131
	v_mul_f32_e32 v131, v21, v132
	v_add_f32_e32 v132, 1.0, v133
	v_mul_f32_e32 v133, 0xbfb8aa3b, v22
	v_exp_f32_e32 v133, v133
	v_mul_f32_e32 v137, 0xbfb8aa3b, v15
	v_exp_f32_e32 v137, v137
	v_add_f32_e32 v130, 1.0, v138
	v_add_f32_e32 v133, 1.0, v133
	v_rcp_f32_e32 v130, v130
	v_rcp_f32_e32 v133, v133
	v_add_f32_e32 v135, 1.0, v135
	v_add_f32_e32 v136, 1.0, v136
	v_rcp_f32_e32 v132, v132
	v_rcp_f32_e32 v135, v135
	v_rcp_f32_e32 v136, v136
	v_add_f32_e32 v137, 1.0, v137
	v_rcp_f32_e32 v137, v137
	v_mul_f32_e32 v130, v20, v130
	v_mul_f32_e32 v133, v22, v133
	v_mul_f32_e32 v132, v13, v132
	v_mul_f32_e32 v135, v14, v135
	v_mul_f32_e32 v136, v23, v136
	v_cvt_pk_bf16_f32 v130, v130, v131
	v_cvt_pk_bf16_f32 v131, v133, v136
	v_mul_f32_e32 v133, 0xbfb8aa3b, v4
	v_mul_f32_e32 v137, v15, v137
	v_cvt_pk_bf16_f32 v132, v134, v132
	v_exp_f32_e32 v136, v133
	v_cvt_pk_bf16_f32 v133, v135, v137
	v_lshl_add_u64 v[134:135], v[128:129], 0, s[38:39]
	global_store_dwordx4 v[134:135], v[130:133], off offset:-3072 sc1
	v_mul_f32_e32 v129, 0xbfb8aa3b, v0
	v_exp_f32_e32 v129, v129
	v_mul_f32_e32 v130, 0xbfb8aa3b, v5
	v_exp_f32_e32 v130, v130
	v_mul_f32_e32 v131, 0xbfb8aa3b, v1
	v_add_f32_e32 v129, 1.0, v129
	v_rcp_f32_e32 v129, v129
	v_add_f32_e32 v130, 1.0, v130
	v_rcp_f32_e32 v130, v130
	v_exp_f32_e32 v131, v131
	v_mul_f32_e32 v132, v0, v129
	v_add_f32_e32 v128, 1.0, v136
	v_mul_f32_e32 v129, v5, v130
	v_add_f32_e32 v130, 1.0, v131
	v_mul_f32_e32 v131, 0xbfb8aa3b, v6
	v_exp_f32_e32 v131, v131
	v_mul_f32_e32 v133, 0xbfb8aa3b, v2
	v_mul_f32_e32 v136, 0xbfb8aa3b, v7
	v_mul_f32_e32 v137, 0xbfb8aa3b, v3
	v_exp_f32_e32 v133, v133
	v_exp_f32_e32 v136, v136
	v_exp_f32_e32 v137, v137
	v_add_f32_e32 v131, 1.0, v131
	v_rcp_f32_e32 v128, v128
	v_rcp_f32_e32 v130, v130
	v_rcp_f32_e32 v131, v131
	v_add_f32_e32 v133, 1.0, v133
	v_add_f32_e32 v136, 1.0, v136
	v_add_f32_e32 v137, 1.0, v137
	v_rcp_f32_e32 v133, v133
	v_rcp_f32_e32 v136, v136
	v_rcp_f32_e32 v137, v137
	v_mul_f32_e32 v128, v4, v128
	v_mul_f32_e32 v130, v1, v130
	v_mul_f32_e32 v131, v6, v131
	v_mul_f32_e32 v133, v2, v133
	v_mul_f32_e32 v136, v7, v136
	v_mul_f32_e32 v137, v3, v137
	v_cvt_pk_bf16_f32 v128, v128, v129
	v_cvt_pk_bf16_f32 v129, v131, v136
	v_cvt_pk_bf16_f32 v130, v132, v130
	v_cvt_pk_bf16_f32 v131, v133, v137
	global_store_dwordx4 v[134:135], v[128:131], off offset:-2816 sc1

; __device__ __forceinline__ u32x4 pack8(const f32x4& a, const f32x4& b) { u32x4 w; w.x = cvt_pk_bf16(a[0], a[1]); w.y = cvt_pk_bf16(a[2], a[3]); w.z = cvt_pk_bf16(b[0], b[1]); w.w = cvt_pk_bf16(b[2], b[3]); return w; }
;     __device__ __forceinline__ void operator()(Acc& acc, const Unit& u, int wr, int wc, int fr, int fq) const {
;     ...
;         } else if (pn < 6) {
; #pragma unroll
;             for (int ai = 0; ai < 2; ++ai)
; #pragma unroll
;                 for (int m = 0; m < 4; ++m)
; #pragma unroll
;                     for (int bj = 0; bj < 2; ++bj) *(u32x4*)(V + (size_t)(row0 + ai * HALF + m * 16) * 512 + (pn - 4) * 256 + bj * HALF + cw) = pack8(acc[ai][bj][m][0], acc[ai][bj][m][1]);
.LBB0_372:
	s_andn2_b64 vcc, exec, s[4:5]
	s_cbranch_vccnz .LBB0_374
	v_ashrrev_i32_e32 v175, 31, v174
	v_lshlrev_b64 v[132:133], 10, v[174:175]
	v_lshl_add_u64 v[132:133], s[62:63], 0, v[132:133]
	s_lshl_b32 s12, s40, 9
	v_ashrrev_i32_e32 v173, 31, v172
	v_lshl_add_u64 v[132:133], v[132:133], 0, s[12:13]
	v_cvt_pk_bf16_f32 v128, v124, v125
	v_cvt_pk_bf16_f32 v129, v126, v127
	v_cvt_pk_bf16_f32 v130, v120, v121
	v_cvt_pk_bf16_f32 v131, v122, v123
	v_lshl_add_u64 v[132:133], v[172:173], 1, v[132:133]
	global_store_dwordx4 v[132:133], v[128:131], off offset:-2048 sc1
	v_lshl_add_u64 v[134:135], v[132:133], 0, s[56:57]
	s_nop 0
	v_cvt_pk_bf16_f32 v128, v112, v113
	v_cvt_pk_bf16_f32 v129, v114, v115
	v_cvt_pk_bf16_f32 v130, v104, v105
	v_cvt_pk_bf16_f32 v131, v106, v107
	global_store_dwordx4 v[132:133], v[128:131], off offset:-1792 sc1
	s_nop 1
	v_cvt_pk_bf16_f32 v128, v116, v117
	v_cvt_pk_bf16_f32 v129, v118, v119
	v_cvt_pk_bf16_f32 v130, v108, v109
	v_cvt_pk_bf16_f32 v131, v110, v111
	global_store_dwordx4 v[134:135], v[128:131], off offset:-2048 sc1
	s_nop 1
	v_cvt_pk_bf16_f32 v128, v96, v97
	v_cvt_pk_bf16_f32 v129, v98, v99
	v_cvt_pk_bf16_f32 v130, v88, v89
	v_cvt_pk_bf16_f32 v131, v90, v91
	global_store_dwordx4 v[134:135], v[128:131], off offset:-1792 sc1
	v_lshl_add_u64 v[134:135], v[132:133], 0, s[24:25]
	s_nop 0
	v_cvt_pk_bf16_f32 v128, v100, v101
	v_cvt_pk_bf16_f32 v129, v102, v103
	v_cvt_pk_bf16_f32 v130, v92, v93
	v_cvt_pk_bf16_f32 v131, v94, v95
	global_store_dwordx4 v[134:135], v[128:131], off offset:-2048 sc1
	s_nop 1
	v_cvt_pk_bf16_f32 v128, v80, v81
	v_cvt_pk_bf16_f32 v129, v82, v83
	v_cvt_pk_bf16_f32 v130, v72, v73
	v_cvt_pk_bf16_f32 v131, v74, v75
	global_store_dwordx4 v[134:135], v[128:131], off offset:-1792 sc1
	v_lshl_add_u64 v[134:135], v[132:133], 0, s[60:61]
	s_nop 0
	v_cvt_pk_bf16_f32 v128, v84, v85
	v_cvt_pk_bf16_f32 v129, v86, v87
	v_cvt_pk_bf16_f32 v130, v76, v77
	v_cvt_pk_bf16_f32 v131, v78, v79
	global_store_dwordx4 v[134:135], v[128:131], off offset:-2048 sc1
	s_nop 1
	v_cvt_pk_bf16_f32 v128, v68, v69
	v_cvt_pk_bf16_f32 v129, v70, v71
	v_cvt_pk_bf16_f32 v130, v64, v65
	v_cvt_pk_bf16_f32 v131, v66, v67
	global_store_dwordx4 v[134:135], v[128:131], off offset:-1792 sc1
	v_lshl_add_u64 v[134:135], v[132:133], 0, s[64:65]
	s_nop 0
	v_cvt_pk_bf16_f32 v128, v60, v61
	v_cvt_pk_bf16_f32 v129, v62, v63
	v_cvt_pk_bf16_f32 v130, v56, v57
	v_cvt_pk_bf16_f32 v131, v58, v59
	global_store_dwordx4 v[134:135], v[128:131], off offset:-2048 sc1
	s_nop 1
	v_cvt_pk_bf16_f32 v128, v48, v49
	v_cvt_pk_bf16_f32 v129, v50, v51
	v_cvt_pk_bf16_f32 v130, v40, v41
	v_cvt_pk_bf16_f32 v131, v42, v43
	global_store_dwordx4 v[134:135], v[128:131], off offset:-1792 sc1
	v_lshl_add_u64 v[134:135], v[132:133], 0, s[66:67]
	s_nop 0
	v_cvt_pk_bf16_f32 v128, v52, v53
	v_cvt_pk_bf16_f32 v129, v54, v55
	v_cvt_pk_bf16_f32 v130, v44, v45
	v_cvt_pk_bf16_f32 v131, v46, v47
	global_store_dwordx4 v[134:135], v[128:131], off offset:-2048 sc1
	s_nop 1
	v_cvt_pk_bf16_f32 v128, v32, v33
	v_cvt_pk_bf16_f32 v129, v34, v35
	v_cvt_pk_bf16_f32 v130, v24, v25
	v_cvt_pk_bf16_f32 v131, v26, v27
	global_store_dwordx4 v[134:135], v[128:131], off offset:-1792 sc1
	v_lshl_add_u64 v[134:135], v[132:133], 0, s[36:37]
	v_lshl_add_u64 v[132:133], v[132:133], 0, s[38:39]
	v_cvt_pk_bf16_f32 v128, v36, v37
	v_cvt_pk_bf16_f32 v129, v38, v39
	v_cvt_pk_bf16_f32 v130, v28, v29
	v_cvt_pk_bf16_f32 v131, v30, v31
	global_store_dwordx4 v[134:135], v[128:131], off offset:-2048 sc1
	s_nop 1
	v_cvt_pk_bf16_f32 v128, v16, v17
	v_cvt_pk_bf16_f32 v129, v18, v19
	v_cvt_pk_bf16_f32 v130, v8, v9
	v_cvt_pk_bf16_f32 v131, v10, v11
	global_store_dwordx4 v[134:135], v[128:131], off offset:-1792 sc1
	s_nop 1
	v_cvt_pk_bf16_f32 v128, v20, v21
	v_cvt_pk_bf16_f32 v129, v22, v23
	v_cvt_pk_bf16_f32 v130, v12, v13
	v_cvt_pk_bf16_f32 v131, v14, v15
	global_store_dwordx4 v[132:133], v[128:131], off offset:-2048 sc1
	s_nop 1
	v_cvt_pk_bf16_f32 v128, v4, v5
	v_cvt_pk_bf16_f32 v129, v6, v7
	v_cvt_pk_bf16_f32 v130, v0, v1
	v_cvt_pk_bf16_f32 v131, v2, v3
	global_store_dwordx4 v[132:133], v[128:131], off offset:-1792 sc1

; __device__ __forceinline__ float fexp(float x) { return __builtin_amdgcn_exp2f(x * 1.4426950408889634f); }
; __device__ __forceinline__ float frcp(float x) { return __builtin_amdgcn_rcpf(x); }
;     __device__ __forceinline__ void operator()(Acc& acc, const Unit& u, int wr, int wc, int fr, int fq) const {
;     ...
;         if (pn < 4 && !(DIS_MASK & 1)) {
;             const int hk0 = pn * 128 + cw;
;             const f32x4 lb4[2] = {*(const f32x4*)(LB + hk0), *(const f32x4*)(LB + hk0 + 4)};
; #pragma unroll
;             for (int ai = 0; ai < 2; ++ai) {
;                 f32x4 el[2];
; #pragma unroll
;                 for (int n = 0; n < 2; ++n)
; #pragma unroll
;                     for (int i = 0; i < 4; ++i) {
;                         const float lbv = lb4[n][i], oml = 1.0f - lbv;
;                         float carry = 1.f;
; #pragma unroll
;                         for (int m = 0; m < 4; ++m) {
;                             float x = acc[ai][1][m][n][i]; x = fminf(fmaxf(x, -30.f), 30.f);
;                             const float ex = fexp(-x), s = frcp(1.0f + ex);
;                             const float f = lbv + oml * s, kk = oml * ex * s;
;                             const float p = row16_prefix_mul(f);
;                             const float eb = carry * p;
;                             carry *= __shfl(p, 15, 16);
;                             float qv = acc[ai][0][m][n][i] * eb, kv = kk * frcp(eb);
;                             asm volatile("" : "+v"(qv), "+v"(kv));
;                             acc[ai][0][m][n][i] = qv; acc[ai][1][m][n][i] = kv;
;                         }
;                         el[n][i] = carry;
;                         __builtin_amdgcn_sched_barrier(0);
;                     }
.LBB0_375:
	s_andn2_b64 vcc, exec, s[4:5]
	s_cbranch_vccnz .LBB0_381
	v_lshl_add_u32 v136, s40, 7, v172
	v_readlane_b32 s4, v254, 55
	v_ashrrev_i32_e32 v137, 31, v136
	v_readlane_b32 s5, v254, 56
	v_max_f32_e32 v138, v112, v112
	v_med3_f32 v138, v138, s30, v218
	v_lshl_add_u64 v[132:133], v[136:137], 2, s[4:5]
	global_load_dwordx4 v[128:131], v[132:133], off offset:16
	s_nop 0
	global_load_dwordx4 v[132:135], v[132:133], off
	v_mul_f32_e32 v138, 0xbfb8aa3b, v138
	v_exp_f32_e32 v138, v138
	v_lshl_or_b32 v154, v217, 2, 60
	v_max_f32_e32 v143, v113, v113
	v_med3_f32 v143, v143, s30, v218
	v_add_f32_e32 v139, 1.0, v138
	v_rcp_f32_e32 v139, v139
	v_mul_f32_e32 v143, 0xbfb8aa3b, v143
	v_exp_f32_e32 v143, v143
	v_cmp_eq_u32_e32 vcc, 0, v219
	v_add_f32_e32 v144, 1.0, v143
	v_rcp_f32_e32 v144, v144
	s_waitcnt vmcnt(0)
	v_sub_f32_e32 v155, 1.0, v132
	v_mul_f32_e32 v138, v138, v155
	v_fma_f32 v140, v139, v155, v132
	v_mul_f32_e32 v138, v139, v138
	v_mov_b32_e32 v139, 1.0
	v_sub_f32_e32 v173, 1.0, v133
	v_mul_f32_e32 v143, v143, v173
	v_mov_b32_dpp v139, v140 row_shr:1 row_mask:0xf bank_mask:0xf
	v_mul_f32_e32 v139, v140, v139
	v_mov_b32_e32 v140, 1.0
	v_fma_f32 v145, v144, v173, v133
	v_mul_f32_e32 v143, v144, v143
	v_mov_b32_dpp v140, v139 row_shr:2 row_mask:0xf bank_mask:0xf
	v_mul_f32_e32 v139, v139, v140
	v_mov_b32_e32 v140, 1.0
	v_max_f32_e32 v144, v97, v97
	v_med3_f32 v144, v144, s30, v218
	v_mov_b32_dpp v140, v139 row_shr:4 row_mask:0xf bank_mask:0xf
	v_mul_f32_e32 v139, v139, v140
	v_mov_b32_e32 v140, 1.0
	v_mul_f32_e32 v144, 0xbfb8aa3b, v144
	v_exp_f32_e32 v144, v144
	v_mov_b32_dpp v140, v139 row_shr:8 row_mask:0xf bank_mask:0xf
	v_mul_f32_e32 v139, v139, v140
	ds_bpermute_b32 v140, v154, v139
	v_mul_f32_e32 v157, v124, v139
	v_rcp_f32_e32 v139, v139
	v_add_f32_e32 v146, 1.0, v144
	v_rcp_f32_e32 v146, v146
	v_mul_f32_e32 v144, v144, v173
	v_mul_f32_e32 v156, v138, v139
	v_max_f32_e32 v138, v96, v96
	v_med3_f32 v138, v138, s30, v218
	v_mul_f32_e32 v138, 0xbfb8aa3b, v138
	v_exp_f32_e32 v138, v138
	v_fma_f32 v147, v146, v173, v133
	v_mul_f32_e32 v144, v146, v144
	v_max_f32_e32 v146, v81, v81
	v_add_f32_e32 v139, 1.0, v138
	v_rcp_f32_e32 v139, v139
	v_mul_f32_e32 v138, v138, v155
	v_med3_f32 v146, v146, s30, v218
	v_mul_f32_e32 v146, 0xbfb8aa3b, v146
	v_fma_f32 v141, v139, v155, v132
	v_mul_f32_e32 v138, v139, v138
	v_mov_b32_e32 v139, 1.0
	v_exp_f32_e32 v146, v146
	s_nop 0
	v_mov_b32_dpp v139, v141 row_shr:1 row_mask:0xf bank_mask:0xf
	v_mul_f32_e32 v139, v141, v139
	v_mov_b32_e32 v141, 1.0
	v_add_f32_e32 v148, 1.0, v146
	v_rcp_f32_e32 v148, v148
	v_mov_b32_dpp v141, v139 row_shr:2 row_mask:0xf bank_mask:0xf
	v_mul_f32_e32 v139, v139, v141
	v_mov_b32_e32 v141, 1.0
	v_mul_f32_e32 v146, v146, v173
	v_fma_f32 v149, v148, v173, v133
	v_mov_b32_dpp v141, v139 row_shr:4 row_mask:0xf bank_mask:0xf
	v_mul_f32_e32 v139, v139, v141
	v_mov_b32_e32 v141, 1.0
	v_mul_f32_e32 v146, v148, v146
	s_nop 0
	v_mov_b32_dpp v141, v139 row_shr:8 row_mask:0xf bank_mask:0xf
	v_mul_f32_e32 v139, v139, v141
	s_waitcnt lgkmcnt(0)
	v_mul_f32_e32 v141, v139, v140
	ds_bpermute_b32 v139, v154, v139
	v_mul_f32_e32 v159, v116, v141
	s_waitcnt lgkmcnt(0)
	v_mul_f32_e32 v139, v140, v139
	v_rcp_f32_e32 v140, v141
	s_nop 0
	v_mul_f32_e32 v158, v138, v140
	v_max_f32_e32 v138, v80, v80
	v_med3_f32 v138, v138, s30, v218
	v_mul_f32_e32 v138, 0xbfb8aa3b, v138
	v_exp_f32_e32 v138, v138
	s_nop 0
	v_add_f32_e32 v140, 1.0, v138
	v_rcp_f32_e32 v140, v140
	v_mul_f32_e32 v138, v138, v155
	v_fma_f32 v141, v140, v155, v132
	v_mul_f32_e32 v138, v140, v138
	v_mov_b32_e32 v140, 1.0
	s_nop 1
	v_mov_b32_dpp v140, v141 row_shr:1 row_mask:0xf bank_mask:0xf
	v_mul_f32_e32 v140, v141, v140
	v_mov_b32_e32 v141, 1.0
	s_nop 1
	v_mov_b32_dpp v141, v140 row_shr:2 row_mask:0xf bank_mask:0xf
	v_mul_f32_e32 v140, v140, v141
	v_mov_b32_e32 v141, 1.0
	s_nop 1
	v_mov_b32_dpp v141, v140 row_shr:4 row_mask:0xf bank_mask:0xf
	v_mul_f32_e32 v140, v140, v141
	v_mov_b32_e32 v141, 1.0
	s_nop 1
	v_mov_b32_dpp v141, v140 row_shr:8 row_mask:0xf bank_mask:0xf
	v_mul_f32_e32 v140, v140, v141
	v_mul_f32_e32 v141, v139, v140
	v_mul_f32_e32 v177, v100, v141
	v_rcp_f32_e32 v141, v141
	ds_bpermute_b32 v140, v154, v140
	v_mul_f32_e32 v176, v138, v141
	v_max_f32_e32 v138, v68, v68
	v_med3_f32 v138, v138, s30, v218
	v_mul_f32_e32 v138, 0xbfb8aa3b, v138
	v_exp_f32_e32 v138, v138
	s_waitcnt lgkmcnt(0)
	v_mul_f32_e32 v140, v139, v140
	v_add_f32_e32 v141, 1.0, v138
	v_rcp_f32_e32 v141, v141
	v_mul_f32_e32 v138, v138, v155
	v_fma_f32 v142, v141, v155, v132
	v_mul_f32_e32 v141, v141, v138
	v_mov_b32_e32 v138, 1.0
	s_nop 1
	v_mov_b32_dpp v138, v142 row_shr:1 row_mask:0xf bank_mask:0xf
	v_mul_f32_e32 v138, v142, v138
	v_mov_b32_e32 v142, 1.0
	s_nop 1
	v_mov_b32_dpp v142, v138 row_shr:2 row_mask:0xf bank_mask:0xf
	v_mul_f32_e32 v138, v138, v142
	v_mov_b32_e32 v142, 1.0
	s_nop 1
	v_mov_b32_dpp v142, v138 row_shr:4 row_mask:0xf bank_mask:0xf
	v_mul_f32_e32 v138, v138, v142
	v_mov_b32_e32 v142, 1.0
	s_nop 1
	v_mov_b32_dpp v142, v138 row_shr:8 row_mask:0xf bank_mask:0xf
	v_mul_f32_e32 v142, v138, v142
	v_mul_f32_e32 v139, v140, v142
	ds_bpermute_b32 v138, v154, v142
	v_mul_f32_e32 v185, v84, v139
	v_rcp_f32_e32 v139, v139
	s_nop 0
	v_mul_f32_e32 v184, v141, v139
	v_mov_b32_e32 v139, 1.0
	v_mov_b32_e32 v141, 1.0
	v_mov_b32_e32 v142, 1.0
	v_mov_b32_dpp v139, v145 row_shr:1 row_mask:0xf bank_mask:0xf
	v_mul_f32_e32 v139, v145, v139
	s_nop 1
	v_mov_b32_dpp v141, v139 row_shr:2 row_mask:0xf bank_mask:0xf
	v_mul_f32_e32 v139, v139, v141
	v_mov_b32_e32 v141, 1.0
	s_nop 1
	v_mov_b32_dpp v141, v139 row_shr:4 row_mask:0xf bank_mask:0xf
	v_mul_f32_e32 v139, v139, v141
	v_mov_b32_e32 v141, 1.0
	s_nop 1
	v_mov_b32_dpp v141, v139 row_shr:8 row_mask:0xf bank_mask:0xf
	v_mul_f32_e32 v139, v139, v141
	ds_bpermute_b32 v141, v154, v139
	v_mul_f32_e32 v187, v125, v139
	v_rcp_f32_e32 v139, v139
	s_nop 0
	v_mul_f32_e32 v186, v143, v139
	v_mov_b32_e32 v139, 1.0
	s_nop 1
	v_mov_b32_dpp v139, v147 row_shr:1 row_mask:0xf bank_mask:0xf
	v_mul_f32_e32 v139, v147, v139
	s_nop 1
	v_mov_b32_dpp v142, v139 row_shr:2 row_mask:0xf bank_mask:0xf
	v_mul_f32_e32 v139, v139, v142
	v_mov_b32_e32 v142, 1.0
	s_nop 1
	v_mov_b32_dpp v142, v139 row_shr:4 row_mask:0xf bank_mask:0xf
	v_mul_f32_e32 v139, v139, v142
	v_mov_b32_e32 v142, 1.0
	s_nop 1
	v_mov_b32_dpp v142, v139 row_shr:8 row_mask:0xf bank_mask:0xf
	v_mul_f32_e32 v139, v139, v142
	s_waitcnt lgkmcnt(0)
; __device__ __forceinline__ float fexp(float x) { return __builtin_amdgcn_exp2f(x * 1.4426950408889634f); }
; __device__ __forceinline__ float frcp(float x) { return __builtin_amdgcn_rcpf(x); }
;     __device__ __forceinline__ void operator()(Acc& acc, const Unit& u, int wr, int wc, int fr, int fq) const {
;     ...
;                     for (int i = 0; i < 4; ++i) {
;                         const float lbv = lb4[n][i], oml = 1.0f - lbv;
;                         float carry = 1.f;
; #pragma unroll
;                         for (int m = 0; m < 4; ++m) {
;                             float x = acc[ai][1][m][n][i]; x = fminf(fmaxf(x, -30.f), 30.f);
;                             const float ex = fexp(-x), s = frcp(1.0f + ex);
;                             const float f = lbv + oml * s, kk = oml * ex * s;
;                             const float p = row16_prefix_mul(f);
;                             const float eb = carry * p;
;                             carry *= __shfl(p, 15, 16);
;                             float qv = acc[ai][0][m][n][i] * eb, kv = kk * frcp(eb);
;                             asm volatile("" : "+v"(qv), "+v"(kv));
;                             acc[ai][0][m][n][i] = qv; acc[ai][1][m][n][i] = kv;
;                         }
	v_mul_f32_e32 v142, v139, v141
	ds_bpermute_b32 v139, v154, v139
	v_mul_f32_e32 v188, v117, v142
	s_waitcnt lgkmcnt(0)
	v_mul_f32_e32 v139, v141, v139
	v_rcp_f32_e32 v141, v142
	v_mov_b32_e32 v142, 1.0
	v_mul_f32_e32 v189, v144, v141
	v_mov_b32_e32 v141, 1.0
	s_nop 1
	v_mov_b32_dpp v141, v149 row_shr:1 row_mask:0xf bank_mask:0xf
	v_mul_f32_e32 v141, v149, v141
	s_nop 1
	v_mov_b32_dpp v142, v141 row_shr:2 row_mask:0xf bank_mask:0xf
	v_mul_f32_e32 v141, v141, v142
	v_mov_b32_e32 v142, 1.0
	s_nop 1
	v_mov_b32_dpp v142, v141 row_shr:4 row_mask:0xf bank_mask:0xf
	v_mul_f32_e32 v141, v141, v142
	v_mov_b32_e32 v142, 1.0
	s_nop 1
	v_mov_b32_dpp v142, v141 row_shr:8 row_mask:0xf bank_mask:0xf
	v_mul_f32_e32 v141, v141, v142
	v_mul_f32_e32 v142, v139, v141
	ds_bpermute_b32 v141, v154, v141
	v_mul_f32_e32 v191, v101, v142
	s_waitcnt lgkmcnt(0)
	v_mul_f32_e32 v141, v139, v141
	v_rcp_f32_e32 v139, v142
	s_nop 0
	v_mul_f32_e32 v190, v146, v139
	v_max_f32_e32 v139, v69, v69
	v_med3_f32 v139, v139, s30, v218
	v_mul_f32_e32 v139, 0xbfb8aa3b, v139
	v_exp_f32_e32 v139, v139
	s_nop 0
	v_add_f32_e32 v142, 1.0, v139
	v_rcp_f32_e32 v142, v142
	v_mul_f32_e32 v139, v139, v173
	v_fma_f32 v143, v142, v173, v133
	v_mul_f32_e32 v142, v142, v139
	v_mov_b32_e32 v139, 1.0
	s_nop 1
	v_mov_b32_dpp v139, v143 row_shr:1 row_mask:0xf bank_mask:0xf
	v_mul_f32_e32 v139, v143, v139
	v_mov_b32_e32 v143, 1.0
	s_nop 1
	v_mov_b32_dpp v143, v139 row_shr:2 row_mask:0xf bank_mask:0xf
	v_mul_f32_e32 v139, v139, v143
	v_mov_b32_e32 v143, 1.0
	s_nop 1
	v_mov_b32_dpp v143, v139 row_shr:4 row_mask:0xf bank_mask:0xf
	v_mul_f32_e32 v139, v139, v143
	v_mov_b32_e32 v143, 1.0
	s_nop 1
	v_mov_b32_dpp v143, v139 row_shr:8 row_mask:0xf bank_mask:0xf
	v_mul_f32_e32 v139, v139, v143
	v_mul_f32_e32 v143, v141, v139
	ds_bpermute_b32 v139, v154, v139
	v_mul_f32_e32 v193, v85, v143
	v_rcp_f32_e32 v143, v143
	s_nop 0
	v_mul_f32_e32 v192, v142, v143
	v_max_f32_e32 v142, v114, v114
	v_med3_f32 v142, v142, s30, v218
	v_mul_f32_e32 v142, 0xbfb8aa3b, v142
	v_exp_f32_e32 v142, v142
	v_sub_f32_e32 v181, 1.0, v134
	v_mov_b32_e32 v143, 1.0
	v_mov_b32_e32 v145, 1.0
	v_add_f32_e32 v144, 1.0, v142
	v_rcp_f32_e32 v144, v144
	v_mov_b32_e32 v146, 1.0
	v_mul_f32_e32 v142, v142, v181
	v_max_f32_e32 v150, v99, v99
	v_fma_f32 v147, v144, v181, v134
	v_mul_f32_e32 v142, v144, v142
	v_mov_b32_e32 v144, 1.0
	v_mov_b32_dpp v143, v147 row_shr:1 row_mask:0xf bank_mask:0xf
	v_mul_f32_e32 v143, v147, v143
	v_max_f32_e32 v151, v83, v83
	v_med3_f32 v150, v150, s30, v218
	v_mov_b32_dpp v145, v143 row_shr:2 row_mask:0xf bank_mask:0xf
	v_mul_f32_e32 v143, v143, v145
	v_max_f32_e32 v145, v98, v98
	v_med3_f32 v145, v145, s30, v218
	v_mul_f32_e32 v145, 0xbfb8aa3b, v145
	v_exp_f32_e32 v145, v145
	v_mov_b32_dpp v146, v143 row_shr:4 row_mask:0xf bank_mask:0xf
	v_mul_f32_e32 v143, v143, v146
	v_med3_f32 v151, v151, s30, v218
	v_add_f32_e32 v147, 1.0, v145
	v_mov_b32_dpp v144, v143 row_shr:8 row_mask:0xf bank_mask:0xf
	v_mul_f32_e32 v143, v143, v144
	v_rcp_f32_e32 v146, v143
	v_rcp_f32_e32 v147, v147
	ds_bpermute_b32 v144, v154, v143
	v_mul_f32_e32 v195, v126, v143
	v_mul_f32_e32 v194, v142, v146
	v_fma_f32 v142, v147, v181, v134
	v_mul_f32_e32 v143, v145, v181
	v_mov_b32_e32 v145, 1.0
	v_max_f32_e32 v146, v82, v82
	v_med3_f32 v146, v146, s30, v218
	v_mov_b32_dpp v145, v142 row_shr:1 row_mask:0xf bank_mask:0xf
	v_mul_f32_e32 v142, v142, v145
	v_mov_b32_e32 v145, 1.0
	v_mul_f32_e32 v146, 0xbfb8aa3b, v146
	v_exp_f32_e32 v146, v146
	v_mov_b32_dpp v145, v142 row_shr:2 row_mask:0xf bank_mask:0xf
	v_mul_f32_e32 v142, v142, v145
	v_mov_b32_e32 v145, 1.0
	v_mul_f32_e32 v143, v147, v143
	v_add_f32_e32 v147, 1.0, v146
	v_mov_b32_dpp v145, v142 row_shr:4 row_mask:0xf bank_mask:0xf
	v_mul_f32_e32 v142, v142, v145
	v_mov_b32_e32 v145, 1.0
	v_rcp_f32_e32 v147, v147
	v_mul_f32_e32 v150, 0xbfb8aa3b, v150
	v_mov_b32_dpp v145, v142 row_shr:8 row_mask:0xf bank_mask:0xf
	v_mul_f32_e32 v142, v142, v145
	ds_bpermute_b32 v145, v154, v142
	s_waitcnt lgkmcnt(1)
	v_mul_f32_e32 v142, v142, v144
	v_mul_f32_e32 v197, v118, v142
	v_mul_f32_e32 v151, 0xbfb8aa3b, v151
	v_exp_f32_e32 v150, v150
	s_waitcnt lgkmcnt(0)
	v_mul_f32_e32 v144, v144, v145
	v_rcp_f32_e32 v145, v142
	v_fma_f32 v142, v147, v181, v134
	v_exp_f32_e32 v151, v151
	v_sub_f32_e32 v178, 1.0, v135
	v_mul_f32_e32 v196, v143, v145
	v_mov_b32_e32 v145, 1.0
	v_mul_f32_e32 v143, v146, v181
	v_mul_f32_e32 v143, v147, v143
	v_mov_b32_dpp v145, v142 row_shr:1 row_mask:0xf bank_mask:0xf
	v_mul_f32_e32 v142, v142, v145
	v_mov_b32_e32 v145, 1.0
	v_add_f32_e32 v152, 1.0, v150
	v_rcp_f32_e32 v152, v152
	v_mov_b32_dpp v145, v142 row_shr:2 row_mask:0xf bank_mask:0xf
	v_mul_f32_e32 v142, v142, v145
	v_mov_b32_e32 v145, 1.0
	v_mul_f32_e32 v150, v150, v178
	v_fma_f32 v153, v152, v178, v135
	v_mov_b32_dpp v145, v142 row_shr:4 row_mask:0xf bank_mask:0xf
	v_mul_f32_e32 v142, v142, v145
	v_mov_b32_e32 v145, 1.0
	v_mul_f32_e32 v150, v152, v150
	s_nop 0
	v_mov_b32_dpp v145, v142 row_shr:8 row_mask:0xf bank_mask:0xf
	v_mul_f32_e32 v142, v142, v145
	v_max_f32_e32 v145, v70, v70
	v_med3_f32 v145, v145, s30, v218
	v_mul_f32_e32 v145, 0xbfb8aa3b, v145
	v_exp_f32_e32 v145, v145
	v_mul_f32_e32 v146, v144, v142
	ds_bpermute_b32 v147, v154, v142
	v_rcp_f32_e32 v142, v146
	v_add_f32_e32 v148, 1.0, v145
	v_rcp_f32_e32 v148, v148
	v_mul_f32_e32 v199, v102, v146
	v_max_f32_e32 v146, v115, v115
	v_med3_f32 v146, v146, s30, v218
	v_mul_f32_e32 v146, 0xbfb8aa3b, v146
	v_mul_f32_e32 v198, v143, v142
	v_fma_f32 v142, v148, v181, v134
	v_mul_f32_e32 v143, v145, v181
	v_mov_b32_e32 v145, 1.0
	v_exp_f32_e32 v146, v146
	v_mul_f32_e32 v143, v148, v143
	v_mov_b32_dpp v145, v142 row_shr:1 row_mask:0xf bank_mask:0xf
	v_mul_f32_e32 v142, v142, v145
	v_mov_b32_e32 v145, 1.0
	v_add_f32_e32 v148, 1.0, v146
	v_rcp_f32_e32 v148, v148
	v_mov_b32_dpp v145, v142 row_shr:2 row_mask:0xf bank_mask:0xf
	v_mul_f32_e32 v142, v142, v145
	v_mov_b32_e32 v145, 1.0
	v_mul_f32_e32 v146, v146, v178
	s_waitcnt lgkmcnt(0)
; __device__ __forceinline__ float fexp(float x) { return __builtin_amdgcn_exp2f(x * 1.4426950408889634f); }
; __device__ __forceinline__ float frcp(float x) { return __builtin_amdgcn_rcpf(x); }
;     __device__ __forceinline__ void operator()(Acc& acc, const Unit& u, int wr, int wc, int fr, int fq) const {
;     ...
;                     for (int i = 0; i < 4; ++i) {
;                         const float lbv = lb4[n][i], oml = 1.0f - lbv;
;                         float carry = 1.f;
; #pragma unroll
;                         for (int m = 0; m < 4; ++m) {
;                             float x = acc[ai][1][m][n][i]; x = fminf(fmaxf(x, -30.f), 30.f);
;                             const float ex = fexp(-x), s = frcp(1.0f + ex);
;                             const float f = lbv + oml * s, kk = oml * ex * s;
;                             const float p = row16_prefix_mul(f);
;                             const float eb = carry * p;
;                             carry *= __shfl(p, 15, 16);
;                             float qv = acc[ai][0][m][n][i] * eb, kv = kk * frcp(eb);
;                             asm volatile("" : "+v"(qv), "+v"(kv));
;                             acc[ai][0][m][n][i] = qv; acc[ai][1][m][n][i] = kv;
;                         }
	v_mul_f32_e32 v144, v144, v147
	v_mov_b32_dpp v145, v142 row_shr:4 row_mask:0xf bank_mask:0xf
	v_mul_f32_e32 v142, v142, v145
	v_mov_b32_e32 v145, 1.0
	v_fma_f32 v149, v148, v178, v135
	v_mul_f32_e32 v146, v148, v146
	v_mov_b32_dpp v145, v142 row_shr:8 row_mask:0xf bank_mask:0xf
	v_mul_f32_e32 v145, v142, v145
	ds_bpermute_b32 v142, v154, v145
	v_add_f32_e32 v148, 1.0, v151
	v_mul_f32_e32 v145, v144, v145
	v_rcp_f32_e32 v148, v148
	v_rcp_f32_e32 v147, v145
	v_mul_f32_e32 v151, v151, v178
	v_mul_f32_e32 v201, v86, v145
	v_fma_f32 v152, v148, v178, v135
	v_mul_f32_e32 v148, v148, v151
	v_mul_f32_e32 v200, v143, v147
	v_mov_b32_e32 v143, 1.0
	v_mov_b32_e32 v145, 1.0
	s_nop 0
	v_mov_b32_dpp v143, v149 row_shr:1 row_mask:0xf bank_mask:0xf
	v_mul_f32_e32 v143, v149, v143
	s_nop 1
	v_mov_b32_dpp v145, v143 row_shr:2 row_mask:0xf bank_mask:0xf
	v_mul_f32_e32 v143, v143, v145
	v_mov_b32_e32 v145, 1.0
	s_nop 1
	v_mov_b32_dpp v145, v143 row_shr:4 row_mask:0xf bank_mask:0xf
	v_mul_f32_e32 v143, v143, v145
	v_mov_b32_e32 v145, 1.0
	s_nop 1
	v_mov_b32_dpp v145, v143 row_shr:8 row_mask:0xf bank_mask:0xf
	v_mul_f32_e32 v143, v143, v145
	ds_bpermute_b32 v145, v154, v143
	v_mul_f32_e32 v203, v127, v143
	v_rcp_f32_e32 v143, v143
	s_nop 0
	v_mul_f32_e32 v202, v146, v143
	v_mov_b32_e32 v143, 1.0
	v_mov_b32_e32 v146, 1.0
	s_nop 0
	v_mov_b32_dpp v143, v153 row_shr:1 row_mask:0xf bank_mask:0xf
	v_mul_f32_e32 v143, v153, v143
	s_nop 1
	v_mov_b32_dpp v146, v143 row_shr:2 row_mask:0xf bank_mask:0xf
	v_mul_f32_e32 v143, v143, v146
	v_mov_b32_e32 v146, 1.0
	s_nop 1
	v_mov_b32_dpp v146, v143 row_shr:4 row_mask:0xf bank_mask:0xf
	v_mul_f32_e32 v143, v143, v146
	v_mov_b32_e32 v146, 1.0
	s_nop 1
	v_mov_b32_dpp v146, v143 row_shr:8 row_mask:0xf bank_mask:0xf
	v_mul_f32_e32 v143, v143, v146
	s_waitcnt lgkmcnt(0)
	v_mul_f32_e32 v146, v143, v145
	ds_bpermute_b32 v143, v154, v143
	v_mul_f32_e32 v204, v119, v146
	s_waitcnt lgkmcnt(0)
	v_mul_f32_e32 v143, v145, v143
	v_rcp_f32_e32 v145, v146
	v_mov_b32_e32 v146, 1.0
	v_mul_f32_e32 v205, v150, v145
	v_mov_b32_e32 v145, 1.0
	s_nop 1
	v_mov_b32_dpp v145, v152 row_shr:1 row_mask:0xf bank_mask:0xf
	v_mul_f32_e32 v145, v152, v145
	s_nop 1
	v_mov_b32_dpp v146, v145 row_shr:2 row_mask:0xf bank_mask:0xf
	v_mul_f32_e32 v145, v145, v146
	v_mov_b32_e32 v146, 1.0
	s_nop 1
	v_mov_b32_dpp v146, v145 row_shr:4 row_mask:0xf bank_mask:0xf
	v_mul_f32_e32 v145, v145, v146
	v_mov_b32_e32 v146, 1.0
	s_nop 1
	v_mov_b32_dpp v146, v145 row_shr:8 row_mask:0xf bank_mask:0xf
	v_mul_f32_e32 v145, v145, v146
	v_mul_f32_e32 v146, v143, v145
	ds_bpermute_b32 v145, v154, v145
	v_mul_f32_e32 v207, v103, v146
	s_waitcnt lgkmcnt(0)
	v_mul_f32_e32 v145, v143, v145
	v_rcp_f32_e32 v143, v146
	s_nop 0
	v_mul_f32_e32 v206, v148, v143
	v_max_f32_e32 v143, v71, v71
	v_med3_f32 v143, v143, s30, v218
	v_mul_f32_e32 v143, 0xbfb8aa3b, v143
	v_exp_f32_e32 v143, v143
	s_nop 0
	v_add_f32_e32 v146, 1.0, v143
	v_rcp_f32_e32 v146, v146
	v_mul_f32_e32 v143, v143, v178
	v_fma_f32 v147, v146, v178, v135
	v_mul_f32_e32 v146, v146, v143
	v_mov_b32_e32 v143, 1.0
	s_nop 1
	v_mov_b32_dpp v143, v147 row_shr:1 row_mask:0xf bank_mask:0xf
	v_mul_f32_e32 v143, v147, v143
	v_mov_b32_e32 v147, 1.0
	s_nop 1
	v_mov_b32_dpp v147, v143 row_shr:2 row_mask:0xf bank_mask:0xf
	v_mul_f32_e32 v143, v143, v147
	v_mov_b32_e32 v147, 1.0
	s_nop 1
	v_mov_b32_dpp v147, v143 row_shr:4 row_mask:0xf bank_mask:0xf
	v_mul_f32_e32 v143, v143, v147
	v_mov_b32_e32 v147, 1.0
	s_nop 1
	v_mov_b32_dpp v147, v143 row_shr:8 row_mask:0xf bank_mask:0xf
	v_mul_f32_e32 v143, v143, v147
	v_mul_f32_e32 v147, v145, v143
	ds_bpermute_b32 v143, v154, v143
	v_mul_f32_e32 v220, v87, v147
	v_rcp_f32_e32 v147, v147
	s_nop 0
	v_mul_f32_e32 v219, v146, v147
	v_max_f32_e32 v146, v104, v104
	v_med3_f32 v146, v146, s30, v218
	v_mul_f32_e32 v146, 0xbfb8aa3b, v146
	v_exp_f32_e32 v146, v146
	v_sub_f32_e32 v182, 1.0, v128
	v_mov_b32_e32 v147, 1.0
	v_mov_b32_e32 v149, 1.0
	v_add_f32_e32 v148, 1.0, v146
	v_rcp_f32_e32 v148, v148
	v_mov_b32_e32 v150, 1.0
	v_mul_f32_e32 v146, v146, v182
	v_max_f32_e32 v175, v89, v89
	v_fma_f32 v151, v148, v182, v128
	v_mul_f32_e32 v146, v148, v146
	v_mov_b32_e32 v148, 1.0
	v_mov_b32_dpp v147, v151 row_shr:1 row_mask:0xf bank_mask:0xf
	v_mul_f32_e32 v147, v151, v147
	v_max_f32_e32 v180, v73, v73
	v_med3_f32 v175, v175, s30, v218
	v_mov_b32_dpp v149, v147 row_shr:2 row_mask:0xf bank_mask:0xf
	v_mul_f32_e32 v147, v147, v149
	v_max_f32_e32 v149, v88, v88
	v_med3_f32 v149, v149, s30, v218
	v_mul_f32_e32 v149, 0xbfb8aa3b, v149
	v_exp_f32_e32 v149, v149
	v_mov_b32_dpp v150, v147 row_shr:4 row_mask:0xf bank_mask:0xf
	v_mul_f32_e32 v147, v147, v150
	v_med3_f32 v180, v180, s30, v218
	v_add_f32_e32 v151, 1.0, v149
	v_mov_b32_dpp v148, v147 row_shr:8 row_mask:0xf bank_mask:0xf
	v_mul_f32_e32 v147, v147, v148
	v_rcp_f32_e32 v150, v147
	v_rcp_f32_e32 v151, v151
	ds_bpermute_b32 v148, v154, v147
	v_mul_f32_e32 v222, v120, v147
	v_mul_f32_e32 v221, v146, v150
	v_fma_f32 v146, v151, v182, v128
	v_mul_f32_e32 v147, v149, v182
	v_mov_b32_e32 v149, 1.0
	v_max_f32_e32 v150, v72, v72
	v_med3_f32 v150, v150, s30, v218
	v_mov_b32_dpp v149, v146 row_shr:1 row_mask:0xf bank_mask:0xf
	v_mul_f32_e32 v146, v146, v149
	v_mov_b32_e32 v149, 1.0
	v_mul_f32_e32 v150, 0xbfb8aa3b, v150
	v_exp_f32_e32 v150, v150
	v_mov_b32_dpp v149, v146 row_shr:2 row_mask:0xf bank_mask:0xf
	v_mul_f32_e32 v146, v146, v149
	v_mov_b32_e32 v149, 1.0
	v_mul_f32_e32 v147, v151, v147
	v_add_f32_e32 v151, 1.0, v150
	v_mov_b32_dpp v149, v146 row_shr:4 row_mask:0xf bank_mask:0xf
	v_mul_f32_e32 v146, v146, v149
	v_mov_b32_e32 v149, 1.0
	v_rcp_f32_e32 v151, v151
	v_mul_f32_e32 v175, 0xbfb8aa3b, v175
	v_mov_b32_dpp v149, v146 row_shr:8 row_mask:0xf bank_mask:0xf
	v_mul_f32_e32 v146, v146, v149
	ds_bpermute_b32 v149, v154, v146
	s_waitcnt lgkmcnt(1)
; __device__ __forceinline__ float fexp(float x) { return __builtin_amdgcn_exp2f(x * 1.4426950408889634f); }
; __device__ __forceinline__ float frcp(float x) { return __builtin_amdgcn_rcpf(x); }
;     __device__ __forceinline__ void operator()(Acc& acc, const Unit& u, int wr, int wc, int fr, int fq) const {
;     ...
;                     for (int i = 0; i < 4; ++i) {
;                         const float lbv = lb4[n][i], oml = 1.0f - lbv;
;                         float carry = 1.f;
; #pragma unroll
;                         for (int m = 0; m < 4; ++m) {
;                             float x = acc[ai][1][m][n][i]; x = fminf(fmaxf(x, -30.f), 30.f);
;                             const float ex = fexp(-x), s = frcp(1.0f + ex);
;                             const float f = lbv + oml * s, kk = oml * ex * s;
;                             const float p = row16_prefix_mul(f);
;                             const float eb = carry * p;
;                             carry *= __shfl(p, 15, 16);
;                             float qv = acc[ai][0][m][n][i] * eb, kv = kk * frcp(eb);
;                             asm volatile("" : "+v"(qv), "+v"(kv));
;                             acc[ai][0][m][n][i] = qv; acc[ai][1][m][n][i] = kv;
;                         }
	v_mul_f32_e32 v146, v146, v148
	v_mul_f32_e32 v224, v108, v146
	v_mul_f32_e32 v180, 0xbfb8aa3b, v180
	v_exp_f32_e32 v175, v175
	s_waitcnt lgkmcnt(0)
	v_mul_f32_e32 v148, v148, v149
	v_rcp_f32_e32 v149, v146
	v_fma_f32 v146, v151, v182, v128
	v_exp_f32_e32 v180, v180
	v_sub_f32_e32 v179, 1.0, v129
	v_mul_f32_e32 v223, v147, v149
	v_mov_b32_e32 v149, 1.0
	v_mul_f32_e32 v147, v150, v182
	v_mul_f32_e32 v147, v151, v147
	v_mov_b32_dpp v149, v146 row_shr:1 row_mask:0xf bank_mask:0xf
	v_mul_f32_e32 v146, v146, v149
	v_mov_b32_e32 v149, 1.0
	v_add_f32_e32 v183, 1.0, v175
	v_rcp_f32_e32 v183, v183
	v_mov_b32_dpp v149, v146 row_shr:2 row_mask:0xf bank_mask:0xf
	v_mul_f32_e32 v146, v146, v149
	v_mov_b32_e32 v149, 1.0
	v_mul_f32_e32 v175, v175, v179
	v_fma_f32 v232, v183, v179, v129
	v_mov_b32_dpp v149, v146 row_shr:4 row_mask:0xf bank_mask:0xf
	v_mul_f32_e32 v146, v146, v149
	v_mov_b32_e32 v149, 1.0
	v_mul_f32_e32 v175, v183, v175
	s_nop 0
	v_mov_b32_dpp v149, v146 row_shr:8 row_mask:0xf bank_mask:0xf
	v_mul_f32_e32 v146, v146, v149
	v_max_f32_e32 v149, v64, v64
	v_med3_f32 v149, v149, s30, v218
	v_mul_f32_e32 v149, 0xbfb8aa3b, v149
	v_exp_f32_e32 v149, v149
	v_mul_f32_e32 v150, v148, v146
	ds_bpermute_b32 v151, v154, v146
	v_rcp_f32_e32 v146, v150
	v_add_f32_e32 v152, 1.0, v149
	v_rcp_f32_e32 v152, v152
	v_mul_f32_e32 v226, v92, v150
	v_max_f32_e32 v150, v105, v105
	v_med3_f32 v150, v150, s30, v218
	v_mul_f32_e32 v150, 0xbfb8aa3b, v150
	v_mul_f32_e32 v225, v147, v146
	v_fma_f32 v146, v152, v182, v128
	v_mul_f32_e32 v147, v149, v182
	v_mov_b32_e32 v149, 1.0
	v_exp_f32_e32 v150, v150
	v_mul_f32_e32 v147, v152, v147
	v_mov_b32_dpp v149, v146 row_shr:1 row_mask:0xf bank_mask:0xf
	v_mul_f32_e32 v146, v146, v149
	v_mov_b32_e32 v149, 1.0
	v_add_f32_e32 v152, 1.0, v150
	v_rcp_f32_e32 v152, v152
	v_mov_b32_dpp v149, v146 row_shr:2 row_mask:0xf bank_mask:0xf
	v_mul_f32_e32 v146, v146, v149
	v_mov_b32_e32 v149, 1.0
	v_mul_f32_e32 v150, v150, v179
	s_waitcnt lgkmcnt(0)
	v_mul_f32_e32 v148, v148, v151
	v_mov_b32_dpp v149, v146 row_shr:4 row_mask:0xf bank_mask:0xf
	v_mul_f32_e32 v146, v146, v149
	v_mov_b32_e32 v149, 1.0
	v_fma_f32 v153, v152, v179, v129
	v_mul_f32_e32 v150, v152, v150
	v_mov_b32_dpp v149, v146 row_shr:8 row_mask:0xf bank_mask:0xf
	v_mul_f32_e32 v149, v146, v149
	ds_bpermute_b32 v146, v154, v149
	v_add_f32_e32 v152, 1.0, v180
	v_mul_f32_e32 v149, v148, v149
	v_rcp_f32_e32 v152, v152
	v_rcp_f32_e32 v151, v149
	v_mul_f32_e32 v180, v180, v179
	v_mul_f32_e32 v229, v76, v149
	v_fma_f32 v183, v152, v179, v129
	v_mul_f32_e32 v152, v152, v180
	v_mul_f32_e32 v227, v147, v151
	v_mov_b32_e32 v147, 1.0
	v_mov_b32_e32 v149, 1.0
	s_nop 0
	v_mov_b32_dpp v147, v153 row_shr:1 row_mask:0xf bank_mask:0xf
	v_mul_f32_e32 v147, v153, v147
	s_nop 1
	v_mov_b32_dpp v149, v147 row_shr:2 row_mask:0xf bank_mask:0xf
	v_mul_f32_e32 v147, v147, v149
	v_mov_b32_e32 v149, 1.0
	s_nop 1
	v_mov_b32_dpp v149, v147 row_shr:4 row_mask:0xf bank_mask:0xf
	v_mul_f32_e32 v147, v147, v149
	v_mov_b32_e32 v149, 1.0
	s_nop 1
	v_mov_b32_dpp v149, v147 row_shr:8 row_mask:0xf bank_mask:0xf
	v_mul_f32_e32 v147, v147, v149
	ds_bpermute_b32 v149, v154, v147
	v_mul_f32_e32 v231, v121, v147
	v_rcp_f32_e32 v147, v147
	s_nop 0
	v_mul_f32_e32 v230, v150, v147
	v_mov_b32_e32 v147, 1.0
	v_mov_b32_e32 v150, 1.0
	s_nop 0
	v_mov_b32_dpp v147, v232 row_shr:1 row_mask:0xf bank_mask:0xf
	v_mul_f32_e32 v147, v232, v147
	s_nop 1
	v_mov_b32_dpp v150, v147 row_shr:2 row_mask:0xf bank_mask:0xf
	v_mul_f32_e32 v147, v147, v150
	v_mov_b32_e32 v150, 1.0
	s_nop 1
	v_mov_b32_dpp v150, v147 row_shr:4 row_mask:0xf bank_mask:0xf
	v_mul_f32_e32 v147, v147, v150
	v_mov_b32_e32 v150, 1.0
	s_nop 1
	v_mov_b32_dpp v150, v147 row_shr:8 row_mask:0xf bank_mask:0xf
	v_mul_f32_e32 v147, v147, v150
	s_waitcnt lgkmcnt(0)
	v_mul_f32_e32 v150, v147, v149
	ds_bpermute_b32 v147, v154, v147
	v_mul_f32_e32 v232, v109, v150
	s_waitcnt lgkmcnt(0)
	v_mul_f32_e32 v147, v149, v147
	v_rcp_f32_e32 v149, v150
	v_mov_b32_e32 v150, 1.0
	v_mul_f32_e32 v233, v175, v149
	v_mov_b32_e32 v149, 1.0
	s_nop 1
	v_mov_b32_dpp v149, v183 row_shr:1 row_mask:0xf bank_mask:0xf
	v_mul_f32_e32 v149, v183, v149
	s_nop 1
	v_mov_b32_dpp v150, v149 row_shr:2 row_mask:0xf bank_mask:0xf
	v_mul_f32_e32 v149, v149, v150
	v_mov_b32_e32 v150, 1.0
	s_nop 1
	v_mov_b32_dpp v150, v149 row_shr:4 row_mask:0xf bank_mask:0xf
	v_mul_f32_e32 v149, v149, v150
	v_mov_b32_e32 v150, 1.0
	s_nop 1
	v_mov_b32_dpp v150, v149 row_shr:8 row_mask:0xf bank_mask:0xf
	v_mul_f32_e32 v149, v149, v150
	v_mul_f32_e32 v150, v147, v149
	ds_bpermute_b32 v149, v154, v149
	v_mul_f32_e32 v235, v93, v150
	s_waitcnt lgkmcnt(0)
; __device__ __forceinline__ float fexp(float x) { return __builtin_amdgcn_exp2f(x * 1.4426950408889634f); }
; __device__ __forceinline__ float frcp(float x) { return __builtin_amdgcn_rcpf(x); }
;     __device__ __forceinline__ void operator()(Acc& acc, const Unit& u, int wr, int wc, int fr, int fq) const {
;     ...
;                     for (int i = 0; i < 4; ++i) {
;                         const float lbv = lb4[n][i], oml = 1.0f - lbv;
;                         float carry = 1.f;
; #pragma unroll
;                         for (int m = 0; m < 4; ++m) {
;                             float x = acc[ai][1][m][n][i]; x = fminf(fmaxf(x, -30.f), 30.f);
;                             const float ex = fexp(-x), s = frcp(1.0f + ex);
;                             const float f = lbv + oml * s, kk = oml * ex * s;
;                             const float p = row16_prefix_mul(f);
;                             const float eb = carry * p;
;                             carry *= __shfl(p, 15, 16);
;                             float qv = acc[ai][0][m][n][i] * eb, kv = kk * frcp(eb);
;                             asm volatile("" : "+v"(qv), "+v"(kv));
;                             acc[ai][0][m][n][i] = qv; acc[ai][1][m][n][i] = kv;
;                         }
	v_mul_f32_e32 v149, v147, v149
	v_rcp_f32_e32 v147, v150
	s_nop 0
	v_mul_f32_e32 v234, v152, v147
	v_max_f32_e32 v147, v65, v65
	v_med3_f32 v147, v147, s30, v218
	v_mul_f32_e32 v147, 0xbfb8aa3b, v147
	v_exp_f32_e32 v147, v147
	s_nop 0
	v_add_f32_e32 v150, 1.0, v147
	v_rcp_f32_e32 v150, v150
	v_mul_f32_e32 v147, v147, v179
	v_fma_f32 v151, v150, v179, v129
	v_mul_f32_e32 v150, v150, v147
	v_mov_b32_e32 v147, 1.0
	s_nop 1
	v_mov_b32_dpp v147, v151 row_shr:1 row_mask:0xf bank_mask:0xf
	v_mul_f32_e32 v147, v151, v147
	v_mov_b32_e32 v151, 1.0
	s_nop 1
	v_mov_b32_dpp v151, v147 row_shr:2 row_mask:0xf bank_mask:0xf
	v_mul_f32_e32 v147, v147, v151
	v_mov_b32_e32 v151, 1.0
	s_nop 1
	v_mov_b32_dpp v151, v147 row_shr:4 row_mask:0xf bank_mask:0xf
	v_mul_f32_e32 v147, v147, v151
	v_mov_b32_e32 v151, 1.0
	s_nop 1
	v_mov_b32_dpp v151, v147 row_shr:8 row_mask:0xf bank_mask:0xf
	v_mul_f32_e32 v147, v147, v151
	v_mul_f32_e32 v151, v149, v147
	ds_bpermute_b32 v147, v154, v147
	v_mul_f32_e32 v237, v77, v151
	v_rcp_f32_e32 v151, v151
	s_nop 0
	v_mul_f32_e32 v236, v150, v151
	v_max_f32_e32 v150, v106, v106
	v_med3_f32 v150, v150, s30, v218
	v_mul_f32_e32 v150, 0xbfb8aa3b, v150
	v_exp_f32_e32 v150, v150
	v_sub_f32_e32 v183, 1.0, v130
	v_mov_b32_e32 v151, 1.0
	v_mov_b32_e32 v153, 1.0
	v_add_f32_e32 v152, 1.0, v150
	v_rcp_f32_e32 v152, v152
	v_mov_b32_e32 v175, 1.0
	v_mul_f32_e32 v150, v150, v183
	v_max_f32_e32 v247, v91, v91
	v_fma_f32 v180, v152, v183, v130
	v_mul_f32_e32 v150, v152, v150
	v_mov_b32_e32 v152, 1.0
	v_mov_b32_dpp v151, v180 row_shr:1 row_mask:0xf bank_mask:0xf
	v_mul_f32_e32 v151, v180, v151
	v_med3_f32 v247, v247, s30, v218
	v_max_f32_e32 v248, v75, v75
	v_mov_b32_dpp v153, v151 row_shr:2 row_mask:0xf bank_mask:0xf
	v_mul_f32_e32 v151, v151, v153
	v_max_f32_e32 v153, v90, v90
	v_med3_f32 v153, v153, s30, v218
	v_mul_f32_e32 v153, 0xbfb8aa3b, v153
	v_exp_f32_e32 v153, v153
	v_mov_b32_dpp v175, v151 row_shr:4 row_mask:0xf bank_mask:0xf
	v_mul_f32_e32 v151, v151, v175
	v_mul_f32_e32 v247, 0xbfb8aa3b, v247
	v_add_f32_e32 v180, 1.0, v153
	v_mov_b32_dpp v152, v151 row_shr:8 row_mask:0xf bank_mask:0xf
	v_mul_f32_e32 v151, v151, v152
	v_rcp_f32_e32 v175, v151
	v_rcp_f32_e32 v180, v180
	ds_bpermute_b32 v152, v154, v151
	v_mul_f32_e32 v239, v122, v151
	v_mul_f32_e32 v238, v150, v175
	v_fma_f32 v150, v180, v183, v130
	v_mul_f32_e32 v151, v153, v183
	v_mov_b32_e32 v153, 1.0
	v_max_f32_e32 v175, v74, v74
	v_med3_f32 v175, v175, s30, v218
	v_mov_b32_dpp v153, v150 row_shr:1 row_mask:0xf bank_mask:0xf
	v_mul_f32_e32 v150, v150, v153
	v_mov_b32_e32 v153, 1.0
	v_mul_f32_e32 v175, 0xbfb8aa3b, v175
	v_exp_f32_e32 v175, v175
	v_mov_b32_dpp v153, v150 row_shr:2 row_mask:0xf bank_mask:0xf
	v_mul_f32_e32 v150, v150, v153
	v_mov_b32_e32 v153, 1.0
	v_mul_f32_e32 v151, v180, v151
	v_add_f32_e32 v180, 1.0, v175
	v_mov_b32_dpp v153, v150 row_shr:4 row_mask:0xf bank_mask:0xf
	v_mul_f32_e32 v150, v150, v153
	v_mov_b32_e32 v153, 1.0
	v_rcp_f32_e32 v180, v180
	v_med3_f32 v248, v248, s30, v218
	v_mov_b32_dpp v153, v150 row_shr:8 row_mask:0xf bank_mask:0xf
	v_mul_f32_e32 v150, v150, v153
	ds_bpermute_b32 v153, v154, v150
	s_waitcnt lgkmcnt(1)
	v_mul_f32_e32 v150, v150, v152
	v_mul_f32_e32 v241, v110, v150
	v_exp_f32_e32 v247, v247
	v_mul_f32_e32 v248, 0xbfb8aa3b, v248
	s_waitcnt lgkmcnt(0)
	v_mul_f32_e32 v152, v152, v153
	v_rcp_f32_e32 v153, v150
	v_fma_f32 v150, v180, v183, v130
	v_exp_f32_e32 v248, v248
	v_add_f32_e32 v249, 1.0, v247
	v_mul_f32_e32 v240, v151, v153
	v_mov_b32_e32 v153, 1.0
	v_mul_f32_e32 v151, v175, v183
	v_mul_f32_e32 v151, v180, v151
	v_mov_b32_dpp v153, v150 row_shr:1 row_mask:0xf bank_mask:0xf
	v_mul_f32_e32 v150, v150, v153
	v_mov_b32_e32 v153, 1.0
	v_rcp_f32_e32 v249, v249
	s_nop 0
	v_mov_b32_dpp v153, v150 row_shr:2 row_mask:0xf bank_mask:0xf
	v_mul_f32_e32 v150, v150, v153
	v_mov_b32_e32 v153, 1.0
	s_nop 1
	v_mov_b32_dpp v153, v150 row_shr:4 row_mask:0xf bank_mask:0xf
	v_mul_f32_e32 v150, v150, v153
	v_mov_b32_e32 v153, 1.0
	s_nop 1
	v_mov_b32_dpp v153, v150 row_shr:8 row_mask:0xf bank_mask:0xf
	v_mul_f32_e32 v150, v150, v153
	v_max_f32_e32 v153, v66, v66
	v_med3_f32 v153, v153, s30, v218
	v_mul_f32_e32 v153, 0xbfb8aa3b, v153
	v_exp_f32_e32 v153, v153
	v_mul_f32_e32 v175, v152, v150
	ds_bpermute_b32 v244, v154, v150
	v_rcp_f32_e32 v150, v175
	v_add_f32_e32 v180, 1.0, v153
	v_rcp_f32_e32 v180, v180
	v_mul_f32_e32 v243, v94, v175
	v_max_f32_e32 v175, v107, v107
	v_med3_f32 v175, v175, s30, v218
	v_mul_f32_e32 v175, 0xbfb8aa3b, v175
	v_mul_f32_e32 v242, v151, v150
	v_fma_f32 v150, v180, v183, v130
	v_mul_f32_e32 v151, v153, v183
	v_mov_b32_e32 v153, 1.0
	v_exp_f32_e32 v175, v175
	v_mul_f32_e32 v151, v180, v151
	v_mov_b32_dpp v153, v150 row_shr:1 row_mask:0xf bank_mask:0xf
	v_mul_f32_e32 v150, v150, v153
	v_mov_b32_e32 v153, 1.0
	v_add_f32_e32 v180, 1.0, v175
	v_rcp_f32_e32 v245, v180
	v_mov_b32_dpp v153, v150 row_shr:2 row_mask:0xf bank_mask:0xf
	v_mul_f32_e32 v150, v150, v153
	v_mov_b32_e32 v153, 1.0
	v_sub_f32_e32 v180, 1.0, v131
	v_mul_f32_e32 v175, v175, v180
	v_mov_b32_dpp v153, v150 row_shr:4 row_mask:0xf bank_mask:0xf
	v_mul_f32_e32 v150, v150, v153
	v_mov_b32_e32 v153, 1.0
	s_waitcnt lgkmcnt(0)
; __device__ __forceinline__ float fexp(float x) { return __builtin_amdgcn_exp2f(x * 1.4426950408889634f); }
; __device__ __forceinline__ float frcp(float x) { return __builtin_amdgcn_rcpf(x); }
;     __device__ __forceinline__ void operator()(Acc& acc, const Unit& u, int wr, int wc, int fr, int fq) const {
;     ...
;                     for (int i = 0; i < 4; ++i) {
;                         const float lbv = lb4[n][i], oml = 1.0f - lbv;
;                         float carry = 1.f;
; #pragma unroll
;                         for (int m = 0; m < 4; ++m) {
;                             float x = acc[ai][1][m][n][i]; x = fminf(fmaxf(x, -30.f), 30.f);
;                             const float ex = fexp(-x), s = frcp(1.0f + ex);
;                             const float f = lbv + oml * s, kk = oml * ex * s;
;                             const float p = row16_prefix_mul(f);
;                             const float eb = carry * p;
;                             carry *= __shfl(p, 15, 16);
;                             float qv = acc[ai][0][m][n][i] * eb, kv = kk * frcp(eb);
;                             asm volatile("" : "+v"(qv), "+v"(kv));
;                             acc[ai][0][m][n][i] = qv; acc[ai][1][m][n][i] = kv;
;                         }
;                         el[n][i] = carry;
;                         __builtin_amdgcn_sched_barrier(0);
;                     }
;                 if (fr == 0) { float* ep = ELAST + (size_t)(u.pm * 4 + ai * 2 + wr) * 512 + hk0; *(f32x4*)ep = el[0]; *(f32x4*)(ep + 4) = el[1]; }
	v_mul_f32_e32 v152, v152, v244
	v_fma_f32 v246, v245, v180, v131
	v_mov_b32_dpp v153, v150 row_shr:8 row_mask:0xf bank_mask:0xf
	v_mul_f32_e32 v153, v150, v153
	ds_bpermute_b32 v150, v154, v153
	v_mul_f32_e32 v175, v245, v175
	v_add_f32_e32 v245, 1.0, v248
	v_mul_f32_e32 v153, v152, v153
	v_rcp_f32_e32 v245, v245
	v_rcp_f32_e32 v244, v153
	v_mul_f32_e32 v247, v247, v180
	v_fma_f32 v250, v249, v180, v131
	v_mul_f32_e32 v249, v249, v247
	v_mul_f32_e32 v247, v248, v180
	v_fma_f32 v251, v245, v180, v131
	v_mul_f32_e32 v252, v245, v247
	v_mul_f32_e32 v245, v78, v153
	v_mul_f32_e32 v244, v151, v244
	v_mov_b32_e32 v151, 1.0
	v_mov_b32_e32 v153, 1.0
	s_nop 0
	v_mov_b32_dpp v151, v246 row_shr:1 row_mask:0xf bank_mask:0xf
	v_mul_f32_e32 v151, v246, v151
	s_nop 1
	v_mov_b32_dpp v153, v151 row_shr:2 row_mask:0xf bank_mask:0xf
	v_mul_f32_e32 v151, v151, v153
	v_mov_b32_e32 v153, 1.0
	s_nop 1
	v_mov_b32_dpp v153, v151 row_shr:4 row_mask:0xf bank_mask:0xf
	v_mul_f32_e32 v151, v151, v153
	v_mov_b32_e32 v153, 1.0
	s_nop 1
	v_mov_b32_dpp v153, v151 row_shr:8 row_mask:0xf bank_mask:0xf
	v_mul_f32_e32 v151, v151, v153
	ds_bpermute_b32 v153, v154, v151
	v_mul_f32_e32 v247, v123, v151
	v_rcp_f32_e32 v151, v151
	s_nop 0
	v_mul_f32_e32 v246, v175, v151
	v_mov_b32_e32 v151, 1.0
	v_mov_b32_e32 v175, 1.0
	s_nop 0
	v_mov_b32_dpp v151, v250 row_shr:1 row_mask:0xf bank_mask:0xf
	v_mul_f32_e32 v151, v250, v151
	s_nop 1
	v_mov_b32_dpp v175, v151 row_shr:2 row_mask:0xf bank_mask:0xf
	v_mul_f32_e32 v151, v151, v175
	v_mov_b32_e32 v175, 1.0
	s_nop 1
	v_mov_b32_dpp v175, v151 row_shr:4 row_mask:0xf bank_mask:0xf
	v_mul_f32_e32 v151, v151, v175
	v_mov_b32_e32 v175, 1.0
	s_nop 1
	v_mov_b32_dpp v175, v151 row_shr:8 row_mask:0xf bank_mask:0xf
	v_mul_f32_e32 v151, v151, v175
	s_waitcnt lgkmcnt(0)
	v_mul_f32_e32 v175, v151, v153
	ds_bpermute_b32 v151, v154, v151
	v_mul_f32_e32 v248, v111, v175
	s_waitcnt lgkmcnt(0)
	v_mul_f32_e32 v151, v153, v151
	v_rcp_f32_e32 v153, v175
	v_mov_b32_e32 v175, 1.0
	v_mul_f32_e32 v249, v249, v153
	v_mov_b32_e32 v153, 1.0
	s_nop 1
	v_mov_b32_dpp v153, v251 row_shr:1 row_mask:0xf bank_mask:0xf
	v_mul_f32_e32 v153, v251, v153
	s_nop 1
	v_mov_b32_dpp v175, v153 row_shr:2 row_mask:0xf bank_mask:0xf
	v_mul_f32_e32 v153, v153, v175
	v_mov_b32_e32 v175, 1.0
	s_nop 1
	v_mov_b32_dpp v175, v153 row_shr:4 row_mask:0xf bank_mask:0xf
	v_mul_f32_e32 v153, v153, v175
	v_mov_b32_e32 v175, 1.0
	s_nop 1
	v_mov_b32_dpp v175, v153 row_shr:8 row_mask:0xf bank_mask:0xf
	v_mul_f32_e32 v153, v153, v175
	v_mul_f32_e32 v175, v151, v153
	ds_bpermute_b32 v153, v154, v153
	v_mul_f32_e32 v251, v95, v175
	s_waitcnt lgkmcnt(0)
	v_mul_f32_e32 v153, v151, v153
	v_rcp_f32_e32 v151, v175
	s_nop 0
	v_mul_f32_e32 v250, v252, v151
	v_max_f32_e32 v151, v67, v67
	v_med3_f32 v151, v151, s30, v218
	v_mul_f32_e32 v151, 0xbfb8aa3b, v151
	v_exp_f32_e32 v151, v151
	s_nop 0
	v_add_f32_e32 v175, 1.0, v151
	v_rcp_f32_e32 v175, v175
	v_mul_f32_e32 v151, v151, v180
	v_fma_f32 v252, v175, v180, v131
	v_mul_f32_e32 v175, v175, v151
	v_mov_b32_e32 v151, 1.0
	s_nop 1
	v_mov_b32_dpp v151, v252 row_shr:1 row_mask:0xf bank_mask:0xf
	v_mul_f32_e32 v151, v252, v151
	v_mov_b32_e32 v252, 1.0
	s_nop 1
	v_mov_b32_dpp v252, v151 row_shr:2 row_mask:0xf bank_mask:0xf
	v_mul_f32_e32 v151, v151, v252
	v_mov_b32_e32 v252, 1.0
	s_nop 1
	v_mov_b32_dpp v252, v151 row_shr:4 row_mask:0xf bank_mask:0xf
	v_mul_f32_e32 v151, v151, v252
	v_mov_b32_e32 v252, 1.0
	s_nop 1
	v_mov_b32_dpp v252, v151 row_shr:8 row_mask:0xf bank_mask:0xf
	v_mul_f32_e32 v151, v151, v252
	v_mul_f32_e32 v252, v153, v151
	ds_bpermute_b32 v151, v154, v151
	v_mul_f32_e32 v253, v79, v252
	v_rcp_f32_e32 v252, v252
	s_nop 0
	v_mul_f32_e32 v252, v175, v252
	s_and_saveexec_b64 s[4:5], vcc
	s_cbranch_execz .LBB0_378
	s_lshl_b32 s12, s84, 2
	s_add_i32 s48, s12, s96
	s_ashr_i32 s49, s48, 31
	s_lshl_b64 s[48:49], s[48:49], 11
	s_add_u32 s48, s55, s48
	s_addc_u32 s49, s58, s49
	v_pk_mul_f32 v[142:143], v[144:145], v[142:143]
	v_pk_mul_f32 v[140:141], v[140:141], v[138:139]
	v_lshl_add_u64 v[138:139], v[136:137], 2, s[48:49]
	s_waitcnt lgkmcnt(0)
	v_pk_mul_f32 v[150:151], v[152:153], v[150:151]
	v_pk_mul_f32 v[148:149], v[148:149], v[146:147]
	global_store_dwordx4 v[138:139], v[140:143], off sc1
	global_store_dwordx4 v[138:139], v[148:151], off offset:16 sc1
; __device__ __forceinline__ u32x4 pack8(const f32x4& a, const f32x4& b) { u32x4 w; w.x = cvt_pk_bf16(a[0], a[1]); w.y = cvt_pk_bf16(a[2], a[3]); w.z = cvt_pk_bf16(b[0], b[1]); w.w = cvt_pk_bf16(b[2], b[3]); return w; }
; __device__ __forceinline__ float fexp(float x) { return __builtin_amdgcn_exp2f(x * 1.4426950408889634f); }
; __device__ __forceinline__ float frcp(float x) { return __builtin_amdgcn_rcpf(x); }
;     __device__ __forceinline__ void operator()(Acc& acc, const Unit& u, int wr, int wc, int fr, int fq) const {
;     ...
;                     for (int i = 0; i < 4; ++i) {
;                         const float lbv = lb4[n][i], oml = 1.0f - lbv;
;                         float carry = 1.f;
; #pragma unroll
;                         for (int m = 0; m < 4; ++m) {
;                             float x = acc[ai][1][m][n][i]; x = fminf(fmaxf(x, -30.f), 30.f);
;                             const float ex = fexp(-x), s = frcp(1.0f + ex);
;                             const float f = lbv + oml * s, kk = oml * ex * s;
;                             const float p = row16_prefix_mul(f);
;                             const float eb = carry * p;
;                             carry *= __shfl(p, 15, 16);
;                             float qv = acc[ai][0][m][n][i] * eb, kv = kk * frcp(eb);
;                             asm volatile("" : "+v"(qv), "+v"(kv));
;                             acc[ai][0][m][n][i] = qv; acc[ai][1][m][n][i] = kv;
;                         }
;     ...
; #pragma unroll
;                 for (int m = 0; m < 4; ++m) { const size_t o = (size_t)(row0 + ai * HALF + m * 16) * 512 + hk0;
;                     *(u32x4*)(QT + o) = pack8(acc[ai][0][m][0], acc[ai][0][m][1]); *(u32x4*)(KT + o) = pack8(acc[ai][1][m][0], acc[ai][1][m][1]); }
.LBB0_378:
	s_or_b64 exec, exec, s[4:5]
	v_ashrrev_i32_e32 v175, 31, v174
	v_lshlrev_b64 v[138:139], 9, v[174:175]
	v_lshl_add_u64 v[138:139], v[138:139], 0, v[136:137]
	v_lshlrev_b64 v[138:139], 1, v[138:139]
	v_lshl_add_u64 v[144:145], s[74:75], 0, v[138:139]
	v_cvt_pk_bf16_f32 v140, v157, v187
	v_cvt_pk_bf16_f32 v141, v195, v203
	v_cvt_pk_bf16_f32 v142, v222, v231
	v_cvt_pk_bf16_f32 v143, v239, v247
	global_store_dwordx4 v[144:145], v[140:143], off sc1
	v_lshl_add_u64 v[144:145], s[0:1], 0, v[138:139]
	s_nop 0
	v_cvt_pk_bf16_f32 v140, v156, v186
	v_cvt_pk_bf16_f32 v141, v194, v202
	v_cvt_pk_bf16_f32 v142, v221, v230
	v_cvt_pk_bf16_f32 v143, v238, v246
	global_store_dwordx4 v[144:145], v[140:143], off sc1
	v_lshl_add_u64 v[144:145], v[138:139], 0, s[56:57]
	v_lshl_add_u64 v[146:147], s[74:75], 0, v[144:145]
	v_cvt_pk_bf16_f32 v140, v159, v188
	v_cvt_pk_bf16_f32 v141, v197, v204
	v_cvt_pk_bf16_f32 v142, v224, v232
	v_cvt_pk_bf16_f32 v143, v241, v248
	v_lshl_add_u64 v[144:145], s[0:1], 0, v[144:145]
	global_store_dwordx4 v[146:147], v[140:143], off sc1
	s_nop 1
	v_cvt_pk_bf16_f32 v140, v158, v189
	v_cvt_pk_bf16_f32 v141, v196, v205
	v_cvt_pk_bf16_f32 v142, v223, v233
	v_cvt_pk_bf16_f32 v143, v240, v249
	global_store_dwordx4 v[144:145], v[140:143], off sc1
	v_lshl_add_u64 v[144:145], v[138:139], 0, s[24:25]
	v_lshl_add_u64 v[146:147], s[74:75], 0, v[144:145]
	v_cvt_pk_bf16_f32 v140, v177, v191
	v_cvt_pk_bf16_f32 v141, v199, v207
	v_cvt_pk_bf16_f32 v142, v226, v235
	v_cvt_pk_bf16_f32 v143, v243, v251
	v_lshl_add_u64 v[144:145], s[0:1], 0, v[144:145]
	global_store_dwordx4 v[146:147], v[140:143], off sc1
	s_nop 1
	v_cvt_pk_bf16_f32 v140, v176, v190
	v_cvt_pk_bf16_f32 v141, v198, v206
	v_cvt_pk_bf16_f32 v142, v225, v234
	v_cvt_pk_bf16_f32 v143, v242, v250
	global_store_dwordx4 v[144:145], v[140:143], off sc1
	v_lshl_add_u64 v[144:145], v[138:139], 0, s[60:61]
	v_lshl_add_u64 v[146:147], s[74:75], 0, v[144:145]
	v_cvt_pk_bf16_f32 v140, v185, v193
	v_cvt_pk_bf16_f32 v141, v201, v220
	v_cvt_pk_bf16_f32 v142, v229, v237
	v_cvt_pk_bf16_f32 v143, v245, v253
	global_store_dwordx4 v[146:147], v[140:143], off sc1
	v_lshl_add_u64 v[144:145], s[0:1], 0, v[144:145]
	s_nop 0
	v_max_f32_e32 v140, v48, v48
	v_med3_f32 v140, v140, s30, v218
	v_mul_f32_e32 v140, 0xbfb8aa3b, v140
	v_exp_f32_e32 v146, v140
	v_cvt_pk_bf16_f32 v140, v184, v192
	v_cvt_pk_bf16_f32 v141, v200, v219
	v_cvt_pk_bf16_f32 v142, v227, v236
	s_nop 0
	v_add_f32_e32 v143, 1.0, v146
	v_rcp_f32_e32 v147, v143
	v_cvt_pk_bf16_f32 v143, v244, v252
	global_store_dwordx4 v[144:145], v[140:143], off sc1
	s_nop 1
	v_fma_f32 v140, v147, v155, v132
	v_mov_b32_e32 v142, 1.0
	v_max_f32_e32 v143, v32, v32
	v_med3_f32 v143, v143, s30, v218
	v_mov_b32_dpp v142, v140 row_shr:1 row_mask:0xf bank_mask:0xf
	v_mul_f32_e32 v140, v140, v142
	v_mov_b32_e32 v142, 1.0
	v_mul_f32_e32 v143, 0xbfb8aa3b, v143
	v_exp_f32_e32 v143, v143
	v_mov_b32_dpp v142, v140 row_shr:2 row_mask:0xf bank_mask:0xf
	v_mul_f32_e32 v140, v140, v142
	v_mov_b32_e32 v142, 1.0
	v_add_f32_e32 v145, 1.0, v143
	v_rcp_f32_e32 v145, v145
	v_mov_b32_dpp v142, v140 row_shr:4 row_mask:0xf bank_mask:0xf
	v_mul_f32_e32 v140, v140, v142
	v_mov_b32_e32 v142, 1.0
	v_mul_f32_e32 v141, v146, v155
	v_mul_f32_e32 v141, v147, v141
	v_mov_b32_dpp v142, v140 row_shr:8 row_mask:0xf bank_mask:0xf
	v_mul_f32_e32 v140, v140, v142
	v_rcp_f32_e32 v144, v140
	ds_bpermute_b32 v142, v154, v140
	v_mul_f32_e32 v153, v60, v140
	v_fma_f32 v140, v145, v155, v132
	v_mul_f32_e32 v150, v141, v144
	v_mul_f32_e32 v141, v143, v155
	v_mov_b32_e32 v143, 1.0
	v_max_f32_e32 v144, v16, v16
	v_med3_f32 v144, v144, s30, v218
	v_mov_b32_dpp v143, v140 row_shr:1 row_mask:0xf bank_mask:0xf
	v_mul_f32_e32 v140, v140, v143
	v_mov_b32_e32 v143, 1.0
	v_mul_f32_e32 v144, 0xbfb8aa3b, v144
	v_exp_f32_e32 v144, v144
	v_mov_b32_dpp v143, v140 row_shr:2 row_mask:0xf bank_mask:0xf
	v_mul_f32_e32 v140, v140, v143
	v_mov_b32_e32 v143, 1.0
	v_mul_f32_e32 v141, v145, v141
	v_add_f32_e32 v145, 1.0, v144
	v_mov_b32_dpp v143, v140 row_shr:4 row_mask:0xf bank_mask:0xf
	v_mul_f32_e32 v140, v140, v143
	v_mov_b32_e32 v143, 1.0
	v_rcp_f32_e32 v145, v145
	v_max_f32_e32 v147, v33, v33
	v_mov_b32_dpp v143, v140 row_shr:8 row_mask:0xf bank_mask:0xf
	v_mul_f32_e32 v140, v140, v143
	ds_bpermute_b32 v143, v154, v140
	s_waitcnt lgkmcnt(1)
	v_mul_f32_e32 v140, v140, v142
	v_mul_f32_e32 v152, v52, v140
	v_med3_f32 v147, v147, s30, v218
	v_mul_f32_e32 v147, 0xbfb8aa3b, v147
	s_waitcnt lgkmcnt(0)
	v_mul_f32_e32 v142, v142, v143
	v_rcp_f32_e32 v143, v140
	v_fma_f32 v140, v145, v155, v132
	v_exp_f32_e32 v147, v147
	v_mul_f32_e32 v149, v141, v143
	v_mov_b32_e32 v143, 1.0
	v_mul_f32_e32 v141, v144, v155
	v_mul_f32_e32 v141, v145, v141
	v_mov_b32_dpp v143, v140 row_shr:1 row_mask:0xf bank_mask:0xf
	v_mul_f32_e32 v140, v140, v143
	v_mov_b32_e32 v143, 1.0
	v_add_f32_e32 v156, 1.0, v147
	v_rcp_f32_e32 v156, v156
	v_mov_b32_dpp v143, v140 row_shr:2 row_mask:0xf bank_mask:0xf
	v_mul_f32_e32 v140, v140, v143
	v_mov_b32_e32 v143, 1.0
	v_mul_f32_e32 v147, v147, v173
	v_fma_f32 v158, v156, v173, v133
	v_mov_b32_dpp v143, v140 row_shr:4 row_mask:0xf bank_mask:0xf
	v_mul_f32_e32 v140, v140, v143
	v_mov_b32_e32 v143, 1.0
	v_mul_f32_e32 v147, v156, v147
	s_nop 0
	v_mov_b32_dpp v143, v140 row_shr:8 row_mask:0xf bank_mask:0xf
	v_mul_f32_e32 v140, v140, v143
	v_max_f32_e32 v143, v4, v4
	v_med3_f32 v143, v143, s30, v218
	v_mul_f32_e32 v143, 0xbfb8aa3b, v143
	v_exp_f32_e32 v143, v143
	v_mul_f32_e32 v144, v142, v140
	v_rcp_f32_e32 v145, v144
	v_mul_f32_e32 v151, v36, v144
	v_add_f32_e32 v146, 1.0, v143
	v_rcp_f32_e32 v146, v146
	v_max_f32_e32 v144, v49, v49
	v_med3_f32 v144, v144, s30, v218
	v_mul_f32_e32 v144, 0xbfb8aa3b, v144
	v_mul_f32_e32 v148, v141, v145
	v_fma_f32 v132, v146, v155, v132
	v_mul_f32_e32 v141, v143, v155
	v_mov_b32_e32 v143, 1.0
	v_exp_f32_e32 v144, v144
	v_max_f32_e32 v155, v17, v17
	v_mov_b32_dpp v143, v132 row_shr:1 row_mask:0xf bank_mask:0xf
	v_mul_f32_e32 v132, v132, v143
	v_mov_b32_e32 v143, 1.0
	ds_bpermute_b32 v140, v154, v140
	v_med3_f32 v155, v155, s30, v218
	v_mov_b32_dpp v143, v132 row_shr:2 row_mask:0xf bank_mask:0xf
	v_mul_f32_e32 v132, v132, v143
	v_mov_b32_e32 v143, 1.0
	v_add_f32_e32 v145, 1.0, v144
	v_mul_f32_e32 v155, 0xbfb8aa3b, v155
	v_mov_b32_dpp v143, v132 row_shr:4 row_mask:0xf bank_mask:0xf
	v_rcp_f32_e32 v145, v145
	v_exp_f32_e32 v155, v155
	v_mul_f32_e32 v132, v132, v143
	v_mov_b32_e32 v143, 1.0
	v_mul_f32_e32 v144, v144, v173
	s_waitcnt lgkmcnt(0)
; __device__ __forceinline__ float fexp(float x) { return __builtin_amdgcn_exp2f(x * 1.4426950408889634f); }
; __device__ __forceinline__ float frcp(float x) { return __builtin_amdgcn_rcpf(x); }
;     __device__ __forceinline__ void operator()(Acc& acc, const Unit& u, int wr, int wc, int fr, int fq) const {
;     ...
;                     for (int i = 0; i < 4; ++i) {
;                         const float lbv = lb4[n][i], oml = 1.0f - lbv;
;                         float carry = 1.f;
; #pragma unroll
;                         for (int m = 0; m < 4; ++m) {
;                             float x = acc[ai][1][m][n][i]; x = fminf(fmaxf(x, -30.f), 30.f);
;                             const float ex = fexp(-x), s = frcp(1.0f + ex);
;                             const float f = lbv + oml * s, kk = oml * ex * s;
;                             const float p = row16_prefix_mul(f);
;                             const float eb = carry * p;
;                             carry *= __shfl(p, 15, 16);
;                             float qv = acc[ai][0][m][n][i] * eb, kv = kk * frcp(eb);
;                             asm volatile("" : "+v"(qv), "+v"(kv));
;                             acc[ai][0][m][n][i] = qv; acc[ai][1][m][n][i] = kv;
;                         }
	v_mul_f32_e32 v140, v142, v140
	v_mov_b32_dpp v143, v132 row_shr:8 row_mask:0xf bank_mask:0xf
	v_mul_f32_e32 v143, v132, v143
	v_mul_f32_e32 v141, v146, v141
	v_fma_f32 v146, v145, v173, v133
	v_mul_f32_e32 v144, v145, v144
	v_add_f32_e32 v145, 1.0, v155
	v_mul_f32_e32 v142, v140, v143
	ds_bpermute_b32 v132, v154, v143
	v_rcp_f32_e32 v145, v145
	v_rcp_f32_e32 v143, v142
	v_mul_f32_e32 v155, v155, v173
	v_mul_f32_e32 v156, v20, v142
	v_fma_f32 v177, v145, v173, v133
	v_mul_f32_e32 v145, v145, v155
	v_mul_f32_e32 v155, v141, v143
	v_mov_b32_e32 v141, 1.0
	v_mov_b32_e32 v142, 1.0
	v_mov_b32_e32 v143, 1.0
	v_mov_b32_dpp v141, v146 row_shr:1 row_mask:0xf bank_mask:0xf
	v_mul_f32_e32 v141, v146, v141
	s_nop 1
	v_mov_b32_dpp v142, v141 row_shr:2 row_mask:0xf bank_mask:0xf
	v_mul_f32_e32 v141, v141, v142
	v_mov_b32_e32 v142, 1.0
	s_nop 1
	v_mov_b32_dpp v142, v141 row_shr:4 row_mask:0xf bank_mask:0xf
	v_mul_f32_e32 v141, v141, v142
	v_mov_b32_e32 v142, 1.0
	s_nop 1
	v_mov_b32_dpp v142, v141 row_shr:8 row_mask:0xf bank_mask:0xf
	v_mul_f32_e32 v141, v141, v142
	ds_bpermute_b32 v142, v154, v141
	v_mul_f32_e32 v175, v61, v141
	v_rcp_f32_e32 v141, v141
	s_nop 0
	v_mul_f32_e32 v157, v144, v141
	v_mov_b32_e32 v141, 1.0
	s_nop 1
	v_mov_b32_dpp v141, v158 row_shr:1 row_mask:0xf bank_mask:0xf
	v_mul_f32_e32 v141, v158, v141
	s_nop 1
	v_mov_b32_dpp v143, v141 row_shr:2 row_mask:0xf bank_mask:0xf
	v_mul_f32_e32 v141, v141, v143
	v_mov_b32_e32 v143, 1.0
	s_nop 1
	v_mov_b32_dpp v143, v141 row_shr:4 row_mask:0xf bank_mask:0xf
	v_mul_f32_e32 v141, v141, v143
	v_mov_b32_e32 v143, 1.0
	s_nop 1
	v_mov_b32_dpp v143, v141 row_shr:8 row_mask:0xf bank_mask:0xf
	v_mul_f32_e32 v141, v141, v143
	s_waitcnt lgkmcnt(0)
	v_mul_f32_e32 v143, v141, v142
	ds_bpermute_b32 v141, v154, v141
	v_mul_f32_e32 v159, v53, v143
	s_waitcnt lgkmcnt(0)
	v_mul_f32_e32 v141, v142, v141
	v_rcp_f32_e32 v142, v143
	v_mov_b32_e32 v143, 1.0
	v_mul_f32_e32 v176, v147, v142
	v_mov_b32_e32 v142, 1.0
	s_nop 1
	v_mov_b32_dpp v142, v177 row_shr:1 row_mask:0xf bank_mask:0xf
	v_mul_f32_e32 v142, v177, v142
	s_nop 1
	v_mov_b32_dpp v143, v142 row_shr:2 row_mask:0xf bank_mask:0xf
	v_mul_f32_e32 v142, v142, v143
	v_mov_b32_e32 v143, 1.0
	s_nop 1
	v_mov_b32_dpp v143, v142 row_shr:4 row_mask:0xf bank_mask:0xf
	v_mul_f32_e32 v142, v142, v143
	v_mov_b32_e32 v143, 1.0
	s_nop 1
	v_mov_b32_dpp v143, v142 row_shr:8 row_mask:0xf bank_mask:0xf
	v_mul_f32_e32 v142, v142, v143
	v_mul_f32_e32 v143, v141, v142
	ds_bpermute_b32 v142, v154, v142
	v_mul_f32_e32 v177, v37, v143
	s_waitcnt lgkmcnt(0)
	v_mul_f32_e32 v141, v141, v142
	v_rcp_f32_e32 v142, v143
	s_nop 0
	v_mul_f32_e32 v158, v145, v142
	v_max_f32_e32 v142, v5, v5
	v_med3_f32 v142, v142, s30, v218
	v_mul_f32_e32 v142, 0xbfb8aa3b, v142
	v_exp_f32_e32 v142, v142
	s_nop 0
	v_add_f32_e32 v143, 1.0, v142
	v_rcp_f32_e32 v143, v143
	v_mul_f32_e32 v142, v142, v173
	v_fma_f32 v133, v143, v173, v133
	v_mul_f32_e32 v142, v143, v142
	v_mov_b32_e32 v143, 1.0
	s_nop 1
	v_mov_b32_dpp v143, v133 row_shr:1 row_mask:0xf bank_mask:0xf
	v_mul_f32_e32 v133, v133, v143
	v_mov_b32_e32 v143, 1.0
	s_nop 1
	v_mov_b32_dpp v143, v133 row_shr:2 row_mask:0xf bank_mask:0xf
	v_mul_f32_e32 v133, v133, v143
	v_mov_b32_e32 v143, 1.0
	s_nop 1
	v_mov_b32_dpp v143, v133 row_shr:4 row_mask:0xf bank_mask:0xf
	v_mul_f32_e32 v133, v133, v143
	v_mov_b32_e32 v143, 1.0
	s_nop 1
	v_mov_b32_dpp v143, v133 row_shr:8 row_mask:0xf bank_mask:0xf
	v_mul_f32_e32 v133, v133, v143
	v_mul_f32_e32 v143, v141, v133
	ds_bpermute_b32 v133, v154, v133
	v_mul_f32_e32 v173, v21, v143
	v_rcp_f32_e32 v143, v143
	s_nop 0
	v_mul_f32_e32 v184, v142, v143
	v_max_f32_e32 v142, v50, v50
	v_med3_f32 v142, v142, s30, v218
	v_mul_f32_e32 v142, 0xbfb8aa3b, v142
	v_exp_f32_e32 v142, v142
	v_mov_b32_e32 v143, 1.0
	v_mov_b32_e32 v144, 1.0
	v_mov_b32_e32 v146, 1.0
	v_add_f32_e32 v145, 1.0, v142
	v_rcp_f32_e32 v145, v145
	v_mov_b32_e32 v147, 1.0
	v_mul_f32_e32 v142, v142, v181
	v_fma_f32 v185, v145, v181, v134
	v_mul_f32_e32 v142, v145, v142
	s_nop 0
	v_mov_b32_dpp v143, v185 row_shr:1 row_mask:0xf bank_mask:0xf
	v_mul_f32_e32 v143, v185, v143
	s_nop 1
	v_mov_b32_dpp v144, v143 row_shr:2 row_mask:0xf bank_mask:0xf
	v_mul_f32_e32 v143, v143, v144
	v_max_f32_e32 v144, v34, v34
	v_med3_f32 v144, v144, s30, v218
	v_mul_f32_e32 v144, 0xbfb8aa3b, v144
	v_exp_f32_e32 v144, v144
	v_mov_b32_dpp v146, v143 row_shr:4 row_mask:0xf bank_mask:0xf
	v_mul_f32_e32 v143, v143, v146
	s_nop 1
	v_mov_b32_dpp v147, v143 row_shr:8 row_mask:0xf bank_mask:0xf
	v_mul_f32_e32 v143, v143, v147
	v_add_f32_e32 v147, 1.0, v144
	v_rcp_f32_e32 v146, v143
	v_rcp_f32_e32 v147, v147
	ds_bpermute_b32 v145, v154, v143
	v_mul_f32_e32 v190, v62, v143
	v_mul_f32_e32 v187, v142, v146
	v_fma_f32 v142, v147, v181, v134
	v_mul_f32_e32 v143, v144, v181
	v_mov_b32_e32 v144, 1.0
	v_max_f32_e32 v146, v18, v18
	v_med3_f32 v146, v146, s30, v218
	v_mov_b32_dpp v144, v142 row_shr:1 row_mask:0xf bank_mask:0xf
	v_mul_f32_e32 v142, v142, v144
	v_mov_b32_e32 v144, 1.0
	v_mul_f32_e32 v146, 0xbfb8aa3b, v146
	v_exp_f32_e32 v146, v146
	v_mov_b32_dpp v144, v142 row_shr:2 row_mask:0xf bank_mask:0xf
	v_mul_f32_e32 v142, v142, v144
	v_mov_b32_e32 v144, 1.0
	v_mul_f32_e32 v143, v147, v143
	v_add_f32_e32 v147, 1.0, v146
	v_mov_b32_dpp v144, v142 row_shr:4 row_mask:0xf bank_mask:0xf
	v_mul_f32_e32 v142, v142, v144
	v_mov_b32_e32 v144, 1.0
	v_rcp_f32_e32 v147, v147
	s_nop 0
	v_mov_b32_dpp v144, v142 row_shr:8 row_mask:0xf bank_mask:0xf
	v_mul_f32_e32 v142, v142, v144
	ds_bpermute_b32 v144, v154, v142
	s_waitcnt lgkmcnt(1)
	v_mul_f32_e32 v142, v142, v145
	v_mul_f32_e32 v189, v54, v142
	s_waitcnt lgkmcnt(0)
; __device__ __forceinline__ float fexp(float x) { return __builtin_amdgcn_exp2f(x * 1.4426950408889634f); }
; __device__ __forceinline__ float frcp(float x) { return __builtin_amdgcn_rcpf(x); }
;     __device__ __forceinline__ void operator()(Acc& acc, const Unit& u, int wr, int wc, int fr, int fq) const {
;     ...
;                     for (int i = 0; i < 4; ++i) {
;                         const float lbv = lb4[n][i], oml = 1.0f - lbv;
;                         float carry = 1.f;
; #pragma unroll
;                         for (int m = 0; m < 4; ++m) {
;                             float x = acc[ai][1][m][n][i]; x = fminf(fmaxf(x, -30.f), 30.f);
;                             const float ex = fexp(-x), s = frcp(1.0f + ex);
;                             const float f = lbv + oml * s, kk = oml * ex * s;
;                             const float p = row16_prefix_mul(f);
;                             const float eb = carry * p;
;                             carry *= __shfl(p, 15, 16);
;                             float qv = acc[ai][0][m][n][i] * eb, kv = kk * frcp(eb);
;                             asm volatile("" : "+v"(qv), "+v"(kv));
;                             acc[ai][0][m][n][i] = qv; acc[ai][1][m][n][i] = kv;
;                         }
	v_mul_f32_e32 v144, v145, v144
	v_rcp_f32_e32 v145, v142
	v_fma_f32 v142, v147, v181, v134
	v_mul_f32_e32 v186, v143, v145
	v_mov_b32_e32 v145, 1.0
	v_mul_f32_e32 v143, v146, v181
	v_mul_f32_e32 v143, v147, v143
	v_mov_b32_dpp v145, v142 row_shr:1 row_mask:0xf bank_mask:0xf
	v_mul_f32_e32 v142, v142, v145
	v_mov_b32_e32 v145, 1.0
	s_nop 1
	v_mov_b32_dpp v145, v142 row_shr:2 row_mask:0xf bank_mask:0xf
	v_mul_f32_e32 v142, v142, v145
	v_mov_b32_e32 v145, 1.0
	s_nop 1
	v_mov_b32_dpp v145, v142 row_shr:4 row_mask:0xf bank_mask:0xf
	v_mul_f32_e32 v142, v142, v145
	v_mov_b32_e32 v145, 1.0
	s_nop 1
	v_mov_b32_dpp v145, v142 row_shr:8 row_mask:0xf bank_mask:0xf
	v_mul_f32_e32 v142, v142, v145
	v_max_f32_e32 v145, v6, v6
	v_med3_f32 v145, v145, s30, v218
	v_mul_f32_e32 v145, 0xbfb8aa3b, v145
	v_exp_f32_e32 v145, v145
	v_mul_f32_e32 v146, v144, v142
	v_rcp_f32_e32 v147, v146
	v_mul_f32_e32 v188, v38, v146
	v_add_f32_e32 v185, 1.0, v145
	v_rcp_f32_e32 v191, v185
	v_max_f32_e32 v146, v51, v51
	v_med3_f32 v146, v146, s30, v218
	v_mul_f32_e32 v146, 0xbfb8aa3b, v146
	v_mul_f32_e32 v185, v143, v147
	v_fma_f32 v134, v191, v181, v134
	v_mul_f32_e32 v143, v145, v181
	v_mov_b32_e32 v145, 1.0
	v_exp_f32_e32 v146, v146
	v_max_f32_e32 v181, v35, v35
	v_mov_b32_dpp v145, v134 row_shr:1 row_mask:0xf bank_mask:0xf
	v_mul_f32_e32 v143, v191, v143
	v_mul_f32_e32 v134, v134, v145
	v_mov_b32_e32 v145, 1.0
	v_med3_f32 v181, v181, s30, v218
	v_max_f32_e32 v191, v19, v19
	ds_bpermute_b32 v142, v154, v142
	v_mov_b32_dpp v145, v134 row_shr:2 row_mask:0xf bank_mask:0xf
	v_mul_f32_e32 v181, 0xbfb8aa3b, v181
	v_med3_f32 v191, v191, s30, v218
	v_mul_f32_e32 v134, v134, v145
	v_mov_b32_e32 v145, 1.0
	v_add_f32_e32 v147, 1.0, v146
	v_exp_f32_e32 v181, v181
	v_mul_f32_e32 v191, 0xbfb8aa3b, v191
	v_mov_b32_dpp v145, v134 row_shr:4 row_mask:0xf bank_mask:0xf
	v_rcp_f32_e32 v147, v147
	v_exp_f32_e32 v191, v191
	v_mul_f32_e32 v134, v134, v145
	v_mov_b32_e32 v145, 1.0
	v_mul_f32_e32 v146, v146, v178
	v_add_f32_e32 v193, 1.0, v181
	v_mov_b32_dpp v145, v134 row_shr:8 row_mask:0xf bank_mask:0xf
	v_mul_f32_e32 v145, v134, v145
	s_waitcnt lgkmcnt(0)
	v_mul_f32_e32 v142, v144, v142
	v_fma_f32 v192, v147, v178, v135
	v_rcp_f32_e32 v193, v193
	v_mul_f32_e32 v146, v147, v146
	v_add_f32_e32 v147, 1.0, v191
	v_mul_f32_e32 v144, v142, v145
	ds_bpermute_b32 v134, v154, v145
	v_rcp_f32_e32 v147, v147
	v_rcp_f32_e32 v145, v144
	v_mul_f32_e32 v181, v181, v178
	v_fma_f32 v194, v193, v178, v135
	v_mul_f32_e32 v193, v193, v181
	v_mul_f32_e32 v181, v191, v178
	v_fma_f32 v197, v147, v178, v135
	v_mul_f32_e32 v147, v147, v181
	v_mul_f32_e32 v191, v22, v144
	v_mul_f32_e32 v181, v143, v145
	v_mov_b32_e32 v143, 1.0
	v_mov_b32_e32 v144, 1.0
	v_mov_b32_e32 v145, 1.0
	v_mov_b32_dpp v143, v192 row_shr:1 row_mask:0xf bank_mask:0xf
	v_mul_f32_e32 v143, v192, v143
	s_nop 1
	v_mov_b32_dpp v144, v143 row_shr:2 row_mask:0xf bank_mask:0xf
	v_mul_f32_e32 v143, v143, v144
	v_mov_b32_e32 v144, 1.0
	s_nop 1
	v_mov_b32_dpp v144, v143 row_shr:4 row_mask:0xf bank_mask:0xf
	v_mul_f32_e32 v143, v143, v144
	v_mov_b32_e32 v144, 1.0
	s_nop 1
	v_mov_b32_dpp v144, v143 row_shr:8 row_mask:0xf bank_mask:0xf
	v_mul_f32_e32 v143, v143, v144
	ds_bpermute_b32 v144, v154, v143
	v_mul_f32_e32 v195, v63, v143
	v_rcp_f32_e32 v143, v143
	s_nop 0
	v_mul_f32_e32 v192, v146, v143
	v_mov_b32_e32 v143, 1.0
	s_nop 1
	v_mov_b32_dpp v143, v194 row_shr:1 row_mask:0xf bank_mask:0xf
	v_mul_f32_e32 v143, v194, v143
	s_nop 1
	v_mov_b32_dpp v145, v143 row_shr:2 row_mask:0xf bank_mask:0xf
	v_mul_f32_e32 v143, v143, v145
	v_mov_b32_e32 v145, 1.0
	s_nop 1
	v_mov_b32_dpp v145, v143 row_shr:4 row_mask:0xf bank_mask:0xf
	v_mul_f32_e32 v143, v143, v145
	v_mov_b32_e32 v145, 1.0
	s_nop 1
	v_mov_b32_dpp v145, v143 row_shr:8 row_mask:0xf bank_mask:0xf
	v_mul_f32_e32 v143, v143, v145
	s_waitcnt lgkmcnt(0)
	v_mul_f32_e32 v145, v143, v144
	ds_bpermute_b32 v143, v154, v143
	v_mul_f32_e32 v194, v55, v145
	s_waitcnt lgkmcnt(0)
	v_mul_f32_e32 v143, v144, v143
	v_rcp_f32_e32 v144, v145
	v_mov_b32_e32 v145, 1.0
	v_mul_f32_e32 v196, v193, v144
	v_mov_b32_e32 v144, 1.0
	s_nop 1
	v_mov_b32_dpp v144, v197 row_shr:1 row_mask:0xf bank_mask:0xf
	v_mul_f32_e32 v144, v197, v144
	s_nop 1
	v_mov_b32_dpp v145, v144 row_shr:2 row_mask:0xf bank_mask:0xf
	v_mul_f32_e32 v144, v144, v145
	v_mov_b32_e32 v145, 1.0
	s_nop 1
	v_mov_b32_dpp v145, v144 row_shr:4 row_mask:0xf bank_mask:0xf
	v_mul_f32_e32 v144, v144, v145
	v_mov_b32_e32 v145, 1.0
	s_nop 1
	v_mov_b32_dpp v145, v144 row_shr:8 row_mask:0xf bank_mask:0xf
	v_mul_f32_e32 v144, v144, v145
	v_mul_f32_e32 v145, v143, v144
	ds_bpermute_b32 v144, v154, v144
	v_mul_f32_e32 v197, v39, v145
	s_waitcnt lgkmcnt(0)
; __device__ __forceinline__ float fexp(float x) { return __builtin_amdgcn_exp2f(x * 1.4426950408889634f); }
; __device__ __forceinline__ float frcp(float x) { return __builtin_amdgcn_rcpf(x); }
;     __device__ __forceinline__ void operator()(Acc& acc, const Unit& u, int wr, int wc, int fr, int fq) const {
;     ...
;                     for (int i = 0; i < 4; ++i) {
;                         const float lbv = lb4[n][i], oml = 1.0f - lbv;
;                         float carry = 1.f;
; #pragma unroll
;                         for (int m = 0; m < 4; ++m) {
;                             float x = acc[ai][1][m][n][i]; x = fminf(fmaxf(x, -30.f), 30.f);
;                             const float ex = fexp(-x), s = frcp(1.0f + ex);
;                             const float f = lbv + oml * s, kk = oml * ex * s;
;                             const float p = row16_prefix_mul(f);
;                             const float eb = carry * p;
;                             carry *= __shfl(p, 15, 16);
;                             float qv = acc[ai][0][m][n][i] * eb, kv = kk * frcp(eb);
;                             asm volatile("" : "+v"(qv), "+v"(kv));
;                             acc[ai][0][m][n][i] = qv; acc[ai][1][m][n][i] = kv;
;                         }
	v_mul_f32_e32 v143, v143, v144
	v_rcp_f32_e32 v144, v145
	s_nop 0
	v_mul_f32_e32 v193, v147, v144
	v_max_f32_e32 v144, v7, v7
	v_med3_f32 v144, v144, s30, v218
	v_mul_f32_e32 v144, 0xbfb8aa3b, v144
	v_exp_f32_e32 v144, v144
	s_nop 0
	v_add_f32_e32 v145, 1.0, v144
	v_rcp_f32_e32 v145, v145
	v_mul_f32_e32 v144, v144, v178
	v_fmac_f32_e32 v135, v145, v178
	v_mul_f32_e32 v144, v145, v144
	v_mov_b32_e32 v145, 1.0
	s_nop 1
	v_mov_b32_dpp v145, v135 row_shr:1 row_mask:0xf bank_mask:0xf
	v_mul_f32_e32 v135, v135, v145
	v_mov_b32_e32 v145, 1.0
	s_nop 1
	v_mov_b32_dpp v145, v135 row_shr:2 row_mask:0xf bank_mask:0xf
	v_mul_f32_e32 v135, v135, v145
	v_mov_b32_e32 v145, 1.0
	s_nop 1
	v_mov_b32_dpp v145, v135 row_shr:4 row_mask:0xf bank_mask:0xf
	v_mul_f32_e32 v135, v135, v145
	v_mov_b32_e32 v145, 1.0
	s_nop 1
	v_mov_b32_dpp v145, v135 row_shr:8 row_mask:0xf bank_mask:0xf
	v_mul_f32_e32 v135, v135, v145
	v_mul_f32_e32 v145, v143, v135
	ds_bpermute_b32 v135, v154, v135
	v_mul_f32_e32 v178, v23, v145
	v_rcp_f32_e32 v145, v145
	s_nop 0
	v_mul_f32_e32 v198, v144, v145
	v_max_f32_e32 v144, v40, v40
	v_med3_f32 v144, v144, s30, v218
	v_mul_f32_e32 v144, 0xbfb8aa3b, v144
	v_exp_f32_e32 v144, v144
	v_mov_b32_e32 v145, 1.0
	v_mov_b32_e32 v146, 1.0
	v_mov_b32_e32 v199, 1.0
	v_add_f32_e32 v147, 1.0, v144
	v_rcp_f32_e32 v147, v147
	v_mov_b32_e32 v200, 1.0
	v_mul_f32_e32 v144, v144, v182
	v_max_f32_e32 v207, v25, v25
	v_fma_f32 v201, v147, v182, v128
	v_mul_f32_e32 v144, v147, v144
	v_med3_f32 v207, v207, s30, v218
	v_mov_b32_dpp v145, v201 row_shr:1 row_mask:0xf bank_mask:0xf
	v_mul_f32_e32 v145, v201, v145
	v_max_f32_e32 v219, v9, v9
	v_mul_f32_e32 v207, 0xbfb8aa3b, v207
	v_mov_b32_dpp v146, v145 row_shr:2 row_mask:0xf bank_mask:0xf
	v_mul_f32_e32 v145, v145, v146
	v_max_f32_e32 v146, v24, v24
	v_med3_f32 v146, v146, s30, v218
	v_mul_f32_e32 v146, 0xbfb8aa3b, v146
	v_exp_f32_e32 v146, v146
	v_mov_b32_dpp v199, v145 row_shr:4 row_mask:0xf bank_mask:0xf
	v_mul_f32_e32 v145, v145, v199
	v_med3_f32 v219, v219, s30, v218
	v_exp_f32_e32 v207, v207
	v_mov_b32_dpp v200, v145 row_shr:8 row_mask:0xf bank_mask:0xf
	v_mul_f32_e32 v145, v145, v200
	v_add_f32_e32 v200, 1.0, v146
	v_rcp_f32_e32 v199, v145
	v_rcp_f32_e32 v200, v200
	ds_bpermute_b32 v147, v154, v145
	v_mul_f32_e32 v204, v56, v145
	v_mul_f32_e32 v201, v144, v199
	v_fma_f32 v144, v200, v182, v128
	v_mul_f32_e32 v145, v146, v182
	v_mov_b32_e32 v146, 1.0
	v_max_f32_e32 v199, v8, v8
	v_med3_f32 v199, v199, s30, v218
	v_mov_b32_dpp v146, v144 row_shr:1 row_mask:0xf bank_mask:0xf
	v_mul_f32_e32 v144, v144, v146
	v_mov_b32_e32 v146, 1.0
	v_mul_f32_e32 v199, 0xbfb8aa3b, v199
	v_exp_f32_e32 v199, v199
	v_mov_b32_dpp v146, v144 row_shr:2 row_mask:0xf bank_mask:0xf
	v_mul_f32_e32 v144, v144, v146
	v_mov_b32_e32 v146, 1.0
	v_mul_f32_e32 v145, v200, v145
	v_add_f32_e32 v200, 1.0, v199
	v_mov_b32_dpp v146, v144 row_shr:4 row_mask:0xf bank_mask:0xf
	v_mul_f32_e32 v144, v144, v146
	v_mov_b32_e32 v146, 1.0
	v_rcp_f32_e32 v202, v200
	v_mul_f32_e32 v219, 0xbfb8aa3b, v219
	v_mov_b32_dpp v146, v144 row_shr:8 row_mask:0xf bank_mask:0xf
	v_mul_f32_e32 v144, v144, v146
	ds_bpermute_b32 v146, v154, v144
	s_waitcnt lgkmcnt(1)
	v_mul_f32_e32 v144, v144, v147
	v_mul_f32_e32 v203, v44, v144
	v_exp_f32_e32 v219, v219
	v_add_f32_e32 v220, 1.0, v207
	s_waitcnt lgkmcnt(0)
	v_mul_f32_e32 v146, v147, v146
	v_rcp_f32_e32 v147, v144
	v_fma_f32 v144, v202, v182, v128
	v_rcp_f32_e32 v220, v220
	v_mul_f32_e32 v200, v145, v147
	v_mov_b32_e32 v147, 1.0
	v_mul_f32_e32 v145, v199, v182
	v_mul_f32_e32 v145, v202, v145
	v_mov_b32_dpp v147, v144 row_shr:1 row_mask:0xf bank_mask:0xf
	v_mul_f32_e32 v144, v144, v147
	v_mov_b32_e32 v147, 1.0
	v_fma_f32 v222, v220, v179, v129
	s_nop 0
	v_mov_b32_dpp v147, v144 row_shr:2 row_mask:0xf bank_mask:0xf
	v_mul_f32_e32 v144, v144, v147
	v_mov_b32_e32 v147, 1.0
	s_nop 1
	v_mov_b32_dpp v147, v144 row_shr:4 row_mask:0xf bank_mask:0xf
	v_mul_f32_e32 v144, v144, v147
	v_mov_b32_e32 v147, 1.0
	s_nop 1
	v_mov_b32_dpp v147, v144 row_shr:8 row_mask:0xf bank_mask:0xf
	v_mul_f32_e32 v144, v144, v147
	v_max_f32_e32 v147, v0, v0
	v_med3_f32 v147, v147, s30, v218
	v_mul_f32_e32 v147, 0xbfb8aa3b, v147
	v_exp_f32_e32 v147, v147
	v_mul_f32_e32 v199, v146, v144
	v_rcp_f32_e32 v205, v199
	ds_bpermute_b32 v144, v154, v144
	v_add_f32_e32 v202, 1.0, v147
	v_rcp_f32_e32 v206, v202
	v_mul_f32_e32 v202, v28, v199
	v_mul_f32_e32 v199, v145, v205
	v_mul_f32_e32 v145, v147, v182
	v_fma_f32 v128, v206, v182, v128
	v_max_f32_e32 v182, v41, v41
	v_med3_f32 v182, v182, s30, v218
	v_mul_f32_e32 v182, 0xbfb8aa3b, v182
	v_mov_b32_e32 v147, 1.0
	v_exp_f32_e32 v182, v182
	s_waitcnt lgkmcnt(0)
; __device__ __forceinline__ float fexp(float x) { return __builtin_amdgcn_exp2f(x * 1.4426950408889634f); }
; __device__ __forceinline__ float frcp(float x) { return __builtin_amdgcn_rcpf(x); }
;     __device__ __forceinline__ void operator()(Acc& acc, const Unit& u, int wr, int wc, int fr, int fq) const {
;     ...
;                     for (int i = 0; i < 4; ++i) {
;                         const float lbv = lb4[n][i], oml = 1.0f - lbv;
;                         float carry = 1.f;
; #pragma unroll
;                         for (int m = 0; m < 4; ++m) {
;                             float x = acc[ai][1][m][n][i]; x = fminf(fmaxf(x, -30.f), 30.f);
;                             const float ex = fexp(-x), s = frcp(1.0f + ex);
;                             const float f = lbv + oml * s, kk = oml * ex * s;
;                             const float p = row16_prefix_mul(f);
;                             const float eb = carry * p;
;                             carry *= __shfl(p, 15, 16);
;                             float qv = acc[ai][0][m][n][i] * eb, kv = kk * frcp(eb);
;                             asm volatile("" : "+v"(qv), "+v"(kv));
;                             acc[ai][0][m][n][i] = qv; acc[ai][1][m][n][i] = kv;
;                         }
	v_mul_f32_e32 v144, v146, v144
	v_mov_b32_dpp v147, v128 row_shr:1 row_mask:0xf bank_mask:0xf
	v_mul_f32_e32 v128, v128, v147
	v_mov_b32_e32 v147, 1.0
	v_add_f32_e32 v205, 1.0, v182
	v_rcp_f32_e32 v205, v205
	v_mov_b32_dpp v147, v128 row_shr:2 row_mask:0xf bank_mask:0xf
	v_mul_f32_e32 v128, v128, v147
	v_mov_b32_e32 v147, 1.0
	v_mul_f32_e32 v182, v182, v179
	v_mul_f32_e32 v221, v205, v182
	v_mov_b32_dpp v147, v128 row_shr:4 row_mask:0xf bank_mask:0xf
	v_mul_f32_e32 v128, v128, v147
	v_mov_b32_e32 v147, 1.0
	v_add_f32_e32 v182, 1.0, v219
	v_rcp_f32_e32 v182, v182
	v_mov_b32_dpp v147, v128 row_shr:8 row_mask:0xf bank_mask:0xf
	v_mul_f32_e32 v147, v128, v147
	v_mul_f32_e32 v146, v144, v147
	ds_bpermute_b32 v128, v154, v147
	v_rcp_f32_e32 v147, v146
	v_mul_f32_e32 v145, v206, v145
	v_fma_f32 v206, v205, v179, v129
	v_mul_f32_e32 v205, v207, v179
	v_mul_f32_e32 v207, v220, v205
	v_mul_f32_e32 v205, v219, v179
	v_fma_f32 v223, v182, v179, v129
	v_mul_f32_e32 v224, v182, v205
	v_mul_f32_e32 v205, v12, v146
	v_mul_f32_e32 v182, v145, v147
	v_mov_b32_e32 v145, 1.0
	v_mov_b32_e32 v146, 1.0
	v_mov_b32_e32 v147, 1.0
	v_mov_b32_dpp v145, v206 row_shr:1 row_mask:0xf bank_mask:0xf
	v_mul_f32_e32 v145, v206, v145
	s_nop 1
	v_mov_b32_dpp v146, v145 row_shr:2 row_mask:0xf bank_mask:0xf
	v_mul_f32_e32 v145, v145, v146
	v_mov_b32_e32 v146, 1.0
	s_nop 1
	v_mov_b32_dpp v146, v145 row_shr:4 row_mask:0xf bank_mask:0xf
	v_mul_f32_e32 v145, v145, v146
	v_mov_b32_e32 v146, 1.0
	s_nop 1
	v_mov_b32_dpp v146, v145 row_shr:8 row_mask:0xf bank_mask:0xf
	v_mul_f32_e32 v145, v145, v146
	ds_bpermute_b32 v146, v154, v145
	v_mul_f32_e32 v220, v57, v145
	v_rcp_f32_e32 v145, v145
	s_nop 0
	v_mul_f32_e32 v206, v221, v145
	v_mov_b32_e32 v145, 1.0
	s_nop 1
	v_mov_b32_dpp v145, v222 row_shr:1 row_mask:0xf bank_mask:0xf
	v_mul_f32_e32 v145, v222, v145
	s_nop 1
	v_mov_b32_dpp v147, v145 row_shr:2 row_mask:0xf bank_mask:0xf
	v_mul_f32_e32 v145, v145, v147
	v_mov_b32_e32 v147, 1.0
	s_nop 1
	v_mov_b32_dpp v147, v145 row_shr:4 row_mask:0xf bank_mask:0xf
	v_mul_f32_e32 v145, v145, v147
	v_mov_b32_e32 v147, 1.0
	s_nop 1
	v_mov_b32_dpp v147, v145 row_shr:8 row_mask:0xf bank_mask:0xf
	v_mul_f32_e32 v145, v145, v147
	s_waitcnt lgkmcnt(0)
	v_mul_f32_e32 v147, v145, v146
	ds_bpermute_b32 v145, v154, v145
	v_mul_f32_e32 v219, v45, v147
	s_waitcnt lgkmcnt(0)
	v_mul_f32_e32 v145, v146, v145
	v_rcp_f32_e32 v146, v147
	v_mov_b32_e32 v147, 1.0
	v_mul_f32_e32 v221, v207, v146
	v_mov_b32_e32 v146, 1.0
	s_nop 1
	v_mov_b32_dpp v146, v223 row_shr:1 row_mask:0xf bank_mask:0xf
	v_mul_f32_e32 v146, v223, v146
	s_nop 1
	v_mov_b32_dpp v147, v146 row_shr:2 row_mask:0xf bank_mask:0xf
	v_mul_f32_e32 v146, v146, v147
	v_mov_b32_e32 v147, 1.0
	s_nop 1
	v_mov_b32_dpp v147, v146 row_shr:4 row_mask:0xf bank_mask:0xf
	v_mul_f32_e32 v146, v146, v147
	v_mov_b32_e32 v147, 1.0
	s_nop 1
	v_mov_b32_dpp v147, v146 row_shr:8 row_mask:0xf bank_mask:0xf
	v_mul_f32_e32 v146, v146, v147
	v_mul_f32_e32 v147, v145, v146
	ds_bpermute_b32 v146, v154, v146
	v_mul_f32_e32 v222, v29, v147
	s_waitcnt lgkmcnt(0)
	v_mul_f32_e32 v145, v145, v146
	v_rcp_f32_e32 v146, v147
	s_nop 0
	v_mul_f32_e32 v207, v224, v146
	v_max_f32_e32 v146, v1, v1
	v_med3_f32 v146, v146, s30, v218
	v_mul_f32_e32 v146, 0xbfb8aa3b, v146
	v_exp_f32_e32 v146, v146
	s_nop 0
	v_add_f32_e32 v147, 1.0, v146
	v_rcp_f32_e32 v147, v147
	v_mul_f32_e32 v146, v146, v179
	v_fma_f32 v129, v147, v179, v129
	v_mul_f32_e32 v146, v147, v146
	v_mov_b32_e32 v147, 1.0
	s_nop 1
	v_mov_b32_dpp v147, v129 row_shr:1 row_mask:0xf bank_mask:0xf
	v_mul_f32_e32 v129, v129, v147
	v_mov_b32_e32 v147, 1.0
	s_nop 1
	v_mov_b32_dpp v147, v129 row_shr:2 row_mask:0xf bank_mask:0xf
	v_mul_f32_e32 v129, v129, v147
	v_mov_b32_e32 v147, 1.0
	s_nop 1
	v_mov_b32_dpp v147, v129 row_shr:4 row_mask:0xf bank_mask:0xf
	v_mul_f32_e32 v129, v129, v147
	v_mov_b32_e32 v147, 1.0
	s_nop 1
	v_mov_b32_dpp v147, v129 row_shr:8 row_mask:0xf bank_mask:0xf
	v_mul_f32_e32 v129, v129, v147
	v_mul_f32_e32 v147, v145, v129
	ds_bpermute_b32 v129, v154, v129
	v_mul_f32_e32 v179, v13, v147
	v_rcp_f32_e32 v147, v147
	s_nop 0
	v_mul_f32_e32 v223, v146, v147
	v_max_f32_e32 v146, v42, v42
	v_med3_f32 v146, v146, s30, v218
	v_mul_f32_e32 v146, 0xbfb8aa3b, v146
	v_exp_f32_e32 v146, v146
	v_mov_b32_e32 v147, 1.0
	v_mov_b32_e32 v224, 1.0
	v_mov_b32_e32 v226, 1.0
	v_add_f32_e32 v225, 1.0, v146
	v_rcp_f32_e32 v225, v225
	v_mov_b32_e32 v227, 1.0
	v_mul_f32_e32 v146, v146, v183
	v_max_f32_e32 v235, v27, v27
	v_fma_f32 v229, v225, v183, v130
	v_mul_f32_e32 v146, v225, v146
	v_med3_f32 v235, v235, s30, v218
	v_mov_b32_dpp v147, v229 row_shr:1 row_mask:0xf bank_mask:0xf
	v_mul_f32_e32 v147, v229, v147
	v_mul_f32_e32 v235, 0xbfb8aa3b, v235
	v_exp_f32_e32 v235, v235
	v_mov_b32_dpp v224, v147 row_shr:2 row_mask:0xf bank_mask:0xf
	v_mul_f32_e32 v147, v147, v224
	v_max_f32_e32 v224, v26, v26
	v_med3_f32 v224, v224, s30, v218
	v_mul_f32_e32 v224, 0xbfb8aa3b, v224
	v_exp_f32_e32 v224, v224
	v_mov_b32_dpp v226, v147 row_shr:4 row_mask:0xf bank_mask:0xf
	v_mul_f32_e32 v147, v147, v226
	v_max_f32_e32 v236, v11, v11
	v_med3_f32 v236, v236, s30, v218
	v_mov_b32_dpp v227, v147 row_shr:8 row_mask:0xf bank_mask:0xf
	v_mul_f32_e32 v147, v147, v227
	v_add_f32_e32 v227, 1.0, v224
	v_rcp_f32_e32 v226, v147
	v_rcp_f32_e32 v227, v227
	ds_bpermute_b32 v225, v154, v147
	v_mul_f32_e32 v230, v58, v147
	v_mul_f32_e32 v226, v146, v226
	v_fma_f32 v146, v227, v183, v130
	v_mul_f32_e32 v147, v224, v183
	v_mov_b32_e32 v224, 1.0
	v_mul_f32_e32 v147, v227, v147
	v_max_f32_e32 v227, v10, v10
	v_mov_b32_dpp v224, v146 row_shr:1 row_mask:0xf bank_mask:0xf
	v_mul_f32_e32 v146, v146, v224
	v_mov_b32_e32 v224, 1.0
	v_med3_f32 v227, v227, s30, v218
	v_mul_f32_e32 v227, 0xbfb8aa3b, v227
	v_mov_b32_dpp v224, v146 row_shr:2 row_mask:0xf bank_mask:0xf
	v_mul_f32_e32 v146, v146, v224
	v_mov_b32_e32 v224, 1.0
	v_exp_f32_e32 v227, v227
	v_mul_f32_e32 v236, 0xbfb8aa3b, v236
	v_mov_b32_dpp v224, v146 row_shr:4 row_mask:0xf bank_mask:0xf
	v_mul_f32_e32 v146, v146, v224
	v_mov_b32_e32 v224, 1.0
	v_exp_f32_e32 v236, v236
	v_add_f32_e32 v237, 1.0, v235
	v_mov_b32_dpp v224, v146 row_shr:8 row_mask:0xf bank_mask:0xf
	v_mul_f32_e32 v146, v146, v224
	ds_bpermute_b32 v224, v154, v146
	s_waitcnt lgkmcnt(1)
; __device__ __forceinline__ float fexp(float x) { return __builtin_amdgcn_exp2f(x * 1.4426950408889634f); }
; __device__ __forceinline__ float frcp(float x) { return __builtin_amdgcn_rcpf(x); }
;     __device__ __forceinline__ void operator()(Acc& acc, const Unit& u, int wr, int wc, int fr, int fq) const {
;     ...
;                     for (int i = 0; i < 4; ++i) {
;                         const float lbv = lb4[n][i], oml = 1.0f - lbv;
;                         float carry = 1.f;
; #pragma unroll
;                         for (int m = 0; m < 4; ++m) {
;                             float x = acc[ai][1][m][n][i]; x = fminf(fmaxf(x, -30.f), 30.f);
;                             const float ex = fexp(-x), s = frcp(1.0f + ex);
;                             const float f = lbv + oml * s, kk = oml * ex * s;
;                             const float p = row16_prefix_mul(f);
;                             const float eb = carry * p;
;                             carry *= __shfl(p, 15, 16);
;                             float qv = acc[ai][0][m][n][i] * eb, kv = kk * frcp(eb);
;                             asm volatile("" : "+v"(qv), "+v"(kv));
;                             acc[ai][0][m][n][i] = qv; acc[ai][1][m][n][i] = kv;
;                         }
;                         el[n][i] = carry;
;                         __builtin_amdgcn_sched_barrier(0);
;                     }
;                 if (fr == 0) { float* ep = ELAST + (size_t)(u.pm * 4 + ai * 2 + wr) * 512 + hk0; *(f32x4*)ep = el[0]; *(f32x4*)(ep + 4) = el[1]; }
	v_mul_f32_e32 v146, v146, v225
	v_mul_f32_e32 v229, v46, v146
	v_rcp_f32_e32 v237, v237
	v_mul_f32_e32 v235, v235, v180
	s_waitcnt lgkmcnt(0)
	v_mul_f32_e32 v231, v225, v224
	v_add_f32_e32 v225, 1.0, v227
	v_rcp_f32_e32 v224, v146
	v_rcp_f32_e32 v232, v225
	v_fma_f32 v238, v237, v180, v131
	v_mul_f32_e32 v237, v237, v235
	v_mul_f32_e32 v225, v147, v224
	v_fma_f32 v146, v232, v183, v130
	v_mov_b32_e32 v224, 1.0
	v_mul_f32_e32 v147, v227, v183
	v_mul_f32_e32 v147, v232, v147
	v_mov_b32_dpp v224, v146 row_shr:1 row_mask:0xf bank_mask:0xf
	v_mul_f32_e32 v146, v146, v224
	v_mov_b32_e32 v224, 1.0
	s_nop 1
	v_mov_b32_dpp v224, v146 row_shr:2 row_mask:0xf bank_mask:0xf
	v_mul_f32_e32 v146, v146, v224
	v_mov_b32_e32 v224, 1.0
	s_nop 1
	v_mov_b32_dpp v224, v146 row_shr:4 row_mask:0xf bank_mask:0xf
	v_mul_f32_e32 v146, v146, v224
	v_mov_b32_e32 v224, 1.0
	s_nop 1
	v_mov_b32_dpp v224, v146 row_shr:8 row_mask:0xf bank_mask:0xf
	v_mul_f32_e32 v146, v146, v224
	v_max_f32_e32 v224, v2, v2
	v_med3_f32 v224, v224, s30, v218
	v_mul_f32_e32 v224, 0xbfb8aa3b, v224
	v_exp_f32_e32 v232, v224
	v_mul_f32_e32 v224, v231, v146
	v_rcp_f32_e32 v233, v224
	ds_bpermute_b32 v146, v154, v146
	v_add_f32_e32 v227, 1.0, v232
	v_rcp_f32_e32 v234, v227
	v_mul_f32_e32 v227, v30, v224
	v_mul_f32_e32 v224, v147, v233
	v_mul_f32_e32 v147, v232, v183
	v_max_f32_e32 v232, v43, v43
	v_med3_f32 v232, v232, s30, v218
	v_mul_f32_e32 v232, 0xbfb8aa3b, v232
	v_fma_f32 v130, v234, v183, v130
	v_mov_b32_e32 v183, 1.0
	v_exp_f32_e32 v232, v232
	s_waitcnt lgkmcnt(0)
	v_mul_f32_e32 v146, v231, v146
	v_mov_b32_dpp v183, v130 row_shr:1 row_mask:0xf bank_mask:0xf
	v_mul_f32_e32 v130, v130, v183
	v_mov_b32_e32 v183, 1.0
	v_add_f32_e32 v233, 1.0, v232
	v_rcp_f32_e32 v233, v233
	v_mov_b32_dpp v183, v130 row_shr:2 row_mask:0xf bank_mask:0xf
	v_mul_f32_e32 v130, v130, v183
	v_mov_b32_e32 v183, 1.0
	v_mul_f32_e32 v232, v232, v180
	v_mul_f32_e32 v147, v234, v147
	v_mov_b32_dpp v183, v130 row_shr:4 row_mask:0xf bank_mask:0xf
	v_mul_f32_e32 v130, v130, v183
	v_mov_b32_e32 v183, 1.0
	v_fma_f32 v234, v233, v180, v131
	v_mul_f32_e32 v232, v233, v232
	v_mov_b32_dpp v183, v130 row_shr:8 row_mask:0xf bank_mask:0xf
	v_mul_f32_e32 v183, v130, v183
	ds_bpermute_b32 v130, v154, v183
	v_add_f32_e32 v233, 1.0, v236
	v_mul_f32_e32 v183, v146, v183
	v_rcp_f32_e32 v233, v233
	v_rcp_f32_e32 v235, v183
	v_mul_f32_e32 v231, v236, v180
	v_fma_f32 v239, v233, v180, v131
	v_mul_f32_e32 v233, v233, v231
	v_mul_f32_e32 v231, v14, v183
	v_mul_f32_e32 v183, v147, v235
	v_mov_b32_e32 v147, 1.0
	v_mov_b32_e32 v236, 1.0
	s_nop 0
	v_mov_b32_dpp v147, v234 row_shr:1 row_mask:0xf bank_mask:0xf
	v_mul_f32_e32 v147, v234, v147
	v_mov_b32_e32 v234, 1.0
	s_nop 1
	v_mov_b32_dpp v234, v147 row_shr:2 row_mask:0xf bank_mask:0xf
	v_mul_f32_e32 v147, v147, v234
	v_mov_b32_e32 v234, 1.0
	s_nop 1
	v_mov_b32_dpp v234, v147 row_shr:4 row_mask:0xf bank_mask:0xf
	v_mul_f32_e32 v147, v147, v234
	v_mov_b32_e32 v234, 1.0
	s_nop 1
	v_mov_b32_dpp v234, v147 row_shr:8 row_mask:0xf bank_mask:0xf
	v_mul_f32_e32 v147, v147, v234
	ds_bpermute_b32 v234, v154, v147
	v_mul_f32_e32 v235, v59, v147
	v_rcp_f32_e32 v147, v147
	s_nop 0
	v_mul_f32_e32 v232, v232, v147
	v_mov_b32_e32 v147, 1.0
	s_nop 1
	v_mov_b32_dpp v147, v238 row_shr:1 row_mask:0xf bank_mask:0xf
	v_mul_f32_e32 v147, v238, v147
	v_mov_b32_e32 v238, 1.0
	s_nop 0
	v_mov_b32_dpp v236, v147 row_shr:2 row_mask:0xf bank_mask:0xf
	v_mul_f32_e32 v147, v147, v236
	v_mov_b32_e32 v236, 1.0
	s_nop 1
	v_mov_b32_dpp v236, v147 row_shr:4 row_mask:0xf bank_mask:0xf
	v_mul_f32_e32 v147, v147, v236
	v_mov_b32_e32 v236, 1.0
	s_nop 1
	v_mov_b32_dpp v236, v147 row_shr:8 row_mask:0xf bank_mask:0xf
	v_mul_f32_e32 v147, v147, v236
	s_waitcnt lgkmcnt(0)
	v_mul_f32_e32 v236, v147, v234
	ds_bpermute_b32 v147, v154, v147
	s_waitcnt lgkmcnt(0)
	v_mul_f32_e32 v147, v234, v147
	v_mul_f32_e32 v234, v47, v236
	v_rcp_f32_e32 v236, v236
	s_nop 0
	v_mul_f32_e32 v236, v237, v236
	v_mov_b32_e32 v237, 1.0
	s_nop 1
	v_mov_b32_dpp v237, v239 row_shr:1 row_mask:0xf bank_mask:0xf
	v_mul_f32_e32 v237, v239, v237
	s_nop 1
	v_mov_b32_dpp v238, v237 row_shr:2 row_mask:0xf bank_mask:0xf
	v_mul_f32_e32 v237, v237, v238
	v_mov_b32_e32 v238, 1.0
	s_nop 1
	v_mov_b32_dpp v238, v237 row_shr:4 row_mask:0xf bank_mask:0xf
	v_mul_f32_e32 v237, v237, v238
	v_mov_b32_e32 v238, 1.0
	s_nop 1
	v_mov_b32_dpp v238, v237 row_shr:8 row_mask:0xf bank_mask:0xf
	v_mul_f32_e32 v237, v237, v238
	v_mul_f32_e32 v238, v147, v237
	ds_bpermute_b32 v237, v154, v237
	s_waitcnt lgkmcnt(0)
	v_mul_f32_e32 v147, v147, v237
	v_mul_f32_e32 v237, v31, v238
	v_rcp_f32_e32 v238, v238
	s_nop 0
	v_mul_f32_e32 v233, v233, v238
	v_max_f32_e32 v238, v3, v3
	v_med3_f32 v238, v238, s30, v218
	v_mul_f32_e32 v238, 0xbfb8aa3b, v238
	v_exp_f32_e32 v238, v238
	s_nop 0
	v_add_f32_e32 v239, 1.0, v238
	v_rcp_f32_e32 v239, v239
	s_nop 0
	v_fmac_f32_e32 v131, v239, v180
	v_mul_f32_e32 v180, v238, v180
	v_mov_b32_e32 v238, 1.0
	v_mul_f32_e32 v180, v239, v180
	s_nop 0
	v_mov_b32_dpp v238, v131 row_shr:1 row_mask:0xf bank_mask:0xf
	v_mul_f32_e32 v131, v131, v238
	v_mov_b32_e32 v238, 1.0
	s_nop 1
	v_mov_b32_dpp v238, v131 row_shr:2 row_mask:0xf bank_mask:0xf
	v_mul_f32_e32 v131, v131, v238
	v_mov_b32_e32 v238, 1.0
	s_nop 1
	v_mov_b32_dpp v238, v131 row_shr:4 row_mask:0xf bank_mask:0xf
	v_mul_f32_e32 v131, v131, v238
	v_mov_b32_e32 v238, 1.0
	s_nop 1
	v_mov_b32_dpp v238, v131 row_shr:8 row_mask:0xf bank_mask:0xf
	v_mul_f32_e32 v131, v131, v238
	v_mul_f32_e32 v238, v147, v131
	ds_bpermute_b32 v131, v154, v131
	v_mul_f32_e32 v154, v15, v238
	v_rcp_f32_e32 v238, v238
	s_nop 0
	v_mul_f32_e32 v180, v180, v238
	s_and_saveexec_b64 s[4:5], vcc
	s_cbranch_execz .LBB0_380
	s_lshl_b32 s12, s84, 2
	s_add_i32 s48, s77, s12
	s_ashr_i32 s49, s48, 31
	s_lshl_b64 s[48:49], s[48:49], 11
	s_add_u32 s48, s55, s48
	s_addc_u32 s49, s58, s49
	v_pk_mul_f32 v[134:135], v[142:143], v[134:135]
	v_pk_mul_f32 v[132:133], v[140:141], v[132:133]
	v_lshl_add_u64 v[136:137], v[136:137], 2, s[48:49]
	s_waitcnt lgkmcnt(0)
	v_pk_mul_f32 v[130:131], v[146:147], v[130:131]
	v_pk_mul_f32 v[128:129], v[144:145], v[128:129]
	global_store_dwordx4 v[136:137], v[132:135], off sc1
	global_store_dwordx4 v[136:137], v[128:131], off offset:16 sc1
; __device__ __forceinline__ u32x4 pack8(const f32x4& a, const f32x4& b) { u32x4 w; w.x = cvt_pk_bf16(a[0], a[1]); w.y = cvt_pk_bf16(a[2], a[3]); w.z = cvt_pk_bf16(b[0], b[1]); w.w = cvt_pk_bf16(b[2], b[3]); return w; }
;     __device__ __forceinline__ void operator()(Acc& acc, const Unit& u, int wr, int wc, int fr, int fq) const {
;     ...
; #pragma unroll
;                 for (int m = 0; m < 4; ++m) { const size_t o = (size_t)(row0 + ai * HALF + m * 16) * 512 + hk0;
;                     *(u32x4*)(QT + o) = pack8(acc[ai][0][m][0], acc[ai][0][m][1]); *(u32x4*)(KT + o) = pack8(acc[ai][1][m][0], acc[ai][1][m][1]); }
.LBB0_380:
	s_or_b64 exec, exec, s[4:5]
	v_lshl_add_u64 v[132:133], v[138:139], 0, s[64:65]
	v_cvt_pk_bf16_f32 v128, v153, v175
	v_cvt_pk_bf16_f32 v129, v190, v195
	v_cvt_pk_bf16_f32 v130, v204, v220
	s_waitcnt lgkmcnt(0)
	v_cvt_pk_bf16_f32 v131, v230, v235
	v_lshl_add_u64 v[134:135], s[74:75], 0, v[132:133]
	v_lshl_add_u64 v[132:133], s[0:1], 0, v[132:133]
	global_store_dwordx4 v[134:135], v[128:131], off sc1
	s_nop 1
	v_cvt_pk_bf16_f32 v128, v150, v157
	v_cvt_pk_bf16_f32 v129, v187, v192
	v_cvt_pk_bf16_f32 v130, v201, v206
	v_cvt_pk_bf16_f32 v131, v226, v232
	global_store_dwordx4 v[132:133], v[128:131], off sc1
	v_lshl_add_u64 v[132:133], v[138:139], 0, s[66:67]
	v_lshl_add_u64 v[134:135], s[74:75], 0, v[132:133]
	v_cvt_pk_bf16_f32 v128, v152, v159
	v_cvt_pk_bf16_f32 v129, v189, v194
	v_cvt_pk_bf16_f32 v130, v203, v219
	v_cvt_pk_bf16_f32 v131, v229, v234
	v_lshl_add_u64 v[132:133], s[0:1], 0, v[132:133]
	global_store_dwordx4 v[134:135], v[128:131], off sc1
	s_nop 1
	v_cvt_pk_bf16_f32 v128, v149, v176
	v_cvt_pk_bf16_f32 v129, v186, v196
	v_cvt_pk_bf16_f32 v130, v200, v221
	v_cvt_pk_bf16_f32 v131, v225, v236
	global_store_dwordx4 v[132:133], v[128:131], off sc1
	v_lshl_add_u64 v[132:133], v[138:139], 0, s[36:37]
	v_lshl_add_u64 v[134:135], s[74:75], 0, v[132:133]
	v_cvt_pk_bf16_f32 v128, v151, v177
	v_cvt_pk_bf16_f32 v129, v188, v197
	v_cvt_pk_bf16_f32 v130, v202, v222
	v_cvt_pk_bf16_f32 v131, v227, v237
	v_lshl_add_u64 v[132:133], s[0:1], 0, v[132:133]
	global_store_dwordx4 v[134:135], v[128:131], off sc1
	s_nop 1
	v_cvt_pk_bf16_f32 v128, v148, v158
	v_cvt_pk_bf16_f32 v129, v185, v193
	v_cvt_pk_bf16_f32 v130, v199, v207
	v_cvt_pk_bf16_f32 v131, v224, v233
	global_store_dwordx4 v[132:133], v[128:131], off sc1
	v_lshl_add_u64 v[132:133], v[138:139], 0, s[38:39]
	v_lshl_add_u64 v[134:135], s[74:75], 0, v[132:133]
	v_cvt_pk_bf16_f32 v128, v156, v173
	v_cvt_pk_bf16_f32 v129, v191, v178
	v_cvt_pk_bf16_f32 v130, v205, v179
	v_cvt_pk_bf16_f32 v131, v231, v154
	v_lshl_add_u64 v[132:133], s[0:1], 0, v[132:133]
	global_store_dwordx4 v[134:135], v[128:131], off sc1
	s_nop 1
	v_cvt_pk_bf16_f32 v128, v155, v184
	v_cvt_pk_bf16_f32 v129, v181, v198
	v_cvt_pk_bf16_f32 v130, v182, v223
	v_cvt_pk_bf16_f32 v131, v183, v180
	global_store_dwordx4 v[132:133], v[128:131], off sc1

; #define LAS __attribute__((address_space(3)))
; __device__ __forceinline__ void p0_transpose_item(const float* W, int K, int N, bf16_t* WT, int dest_row0, const float* gain, LAS float* scr, int k0, int n0, int lane) {
;     float wv[32];
; #pragma unroll
;     for (int i = 0; i < 32; ++i) { const int kk = 2 * i + (lane >> 5); wv[i] = W[(size_t)(k0 + kk) * N + n0 + (lane & 31)]; }
;     if (gain) {
; #pragma unroll
;         for (int i = 0; i < 32; ++i) wv[i] *= gain[k0 + 2 * i + (lane >> 5)]; }
; #pragma unroll
;     for (int i = 0; i < 32; ++i) { const int kk = 2 * i + (lane >> 5); scr[kk * 33 + (lane & 31)] = wv[i]; }
;     asm volatile("s_waitcnt lgkmcnt(0)" ::: "memory");
.LBB0_391:
	s_lshl_b32 s8, s11, 6
	v_or_b32_e32 v0, s8, v62
	s_ashr_i32 s11, s10, 31
	v_lshl_add_u64 v[30:31], s[10:11], 2, v[26:27]
	v_or_b32_e32 v34, 2, v0
	v_or_b32_e32 v36, 4, v0
	v_or_b32_e32 v38, 6, v0
	v_or_b32_e32 v40, 8, v0
	v_or_b32_e32 v42, 10, v0
	v_or_b32_e32 v44, 12, v0
	v_or_b32_e32 v46, 14, v0
	v_mad_i64_i32 v[32:33], s[10:11], v0, s26, v[30:31]
	v_mad_i64_i32 v[34:35], s[10:11], v34, s26, v[30:31]
	v_mad_i64_i32 v[36:37], s[10:11], v36, s26, v[30:31]
	v_mad_i64_i32 v[38:39], s[10:11], v38, s26, v[30:31]
	v_mad_i64_i32 v[40:41], s[10:11], v40, s26, v[30:31]
	v_mad_i64_i32 v[42:43], s[10:11], v42, s26, v[30:31]
	v_mad_i64_i32 v[44:45], s[10:11], v44, s26, v[30:31]
	v_mad_i64_i32 v[46:47], s[10:11], v46, s26, v[30:31]
	global_load_dword v48, v[32:33], off
	global_load_dword v49, v[34:35], off
	global_load_dword v50, v[36:37], off
	global_load_dword v51, v[38:39], off
	global_load_dword v52, v[40:41], off
	global_load_dword v53, v[42:43], off
	global_load_dword v54, v[44:45], off
	global_load_dword v55, v[46:47], off
	v_or_b32_e32 v32, 16, v0
	v_or_b32_e32 v34, 18, v0
	v_or_b32_e32 v36, 20, v0
	v_or_b32_e32 v38, 22, v0
	v_or_b32_e32 v40, 24, v0
	v_or_b32_e32 v42, 26, v0
	v_or_b32_e32 v44, 28, v0
	v_or_b32_e32 v46, 30, v0
	v_mad_i64_i32 v[32:33], s[10:11], v32, s26, v[30:31]
	v_mad_i64_i32 v[34:35], s[10:11], v34, s26, v[30:31]
	v_mad_i64_i32 v[36:37], s[10:11], v36, s26, v[30:31]
	v_mad_i64_i32 v[38:39], s[10:11], v38, s26, v[30:31]
	v_mad_i64_i32 v[40:41], s[10:11], v40, s26, v[30:31]
	v_mad_i64_i32 v[42:43], s[10:11], v42, s26, v[30:31]
	v_mad_i64_i32 v[44:45], s[10:11], v44, s26, v[30:31]
	v_mad_i64_i32 v[46:47], s[10:11], v46, s26, v[30:31]
	global_load_dword v56, v[32:33], off
	global_load_dword v57, v[34:35], off
	global_load_dword v58, v[36:37], off
	global_load_dword v59, v[38:39], off
	global_load_dword v60, v[40:41], off
	global_load_dword v61, v[42:43], off
	global_load_dword v77, v[44:45], off
	global_load_dword v78, v[46:47], off
	v_or_b32_e32 v32, 32, v0
	v_or_b32_e32 v34, 34, v0
	v_or_b32_e32 v36, 36, v0
	v_or_b32_e32 v38, 38, v0
	v_or_b32_e32 v40, 40, v0
	v_or_b32_e32 v42, 42, v0
	v_or_b32_e32 v44, 44, v0
	v_or_b32_e32 v46, 46, v0
	v_mad_i64_i32 v[32:33], s[10:11], v32, s26, v[30:31]
	v_mad_i64_i32 v[34:35], s[10:11], v34, s26, v[30:31]
	v_mad_i64_i32 v[36:37], s[10:11], v36, s26, v[30:31]
	v_mad_i64_i32 v[38:39], s[10:11], v38, s26, v[30:31]
	v_mad_i64_i32 v[40:41], s[10:11], v40, s26, v[30:31]
	v_mad_i64_i32 v[42:43], s[10:11], v42, s26, v[30:31]
	v_mad_i64_i32 v[44:45], s[10:11], v44, s26, v[30:31]
	v_mad_i64_i32 v[46:47], s[10:11], v46, s26, v[30:31]
	global_load_dword v79, v[32:33], off
	global_load_dword v80, v[34:35], off
	global_load_dword v81, v[36:37], off
	global_load_dword v82, v[38:39], off
	global_load_dword v83, v[40:41], off
	global_load_dword v84, v[42:43], off
	global_load_dword v85, v[44:45], off
	s_nop 0
	global_load_dword v46, v[46:47], off
	v_or_b32_e32 v32, 48, v0
	v_or_b32_e32 v34, 50, v0
	v_or_b32_e32 v36, 52, v0
	v_or_b32_e32 v38, 54, v0
	v_or_b32_e32 v40, 56, v0
	v_or_b32_e32 v42, 58, v0
	v_or_b32_e32 v44, 60, v0
	v_or_b32_e32 v0, 62, v0
	v_mad_i64_i32 v[32:33], s[10:11], v32, s26, v[30:31]
	v_mad_i64_i32 v[34:35], s[10:11], v34, s26, v[30:31]
	v_mad_i64_i32 v[36:37], s[10:11], v36, s26, v[30:31]
	v_mad_i64_i32 v[38:39], s[10:11], v38, s26, v[30:31]
	v_mad_i64_i32 v[40:41], s[10:11], v40, s26, v[30:31]
	v_mad_i64_i32 v[42:43], s[10:11], v42, s26, v[30:31]
	v_mad_i64_i32 v[44:45], s[10:11], v44, s26, v[30:31]
	v_mad_i64_i32 v[30:31], s[10:11], v0, s26, v[30:31]
	global_load_dword v0, v[32:33], off
	s_nop 0
	global_load_dword v32, v[34:35], off
	global_load_dword v33, v[36:37], off
	s_nop 0
	global_load_dword v34, v[38:39], off
	global_load_dword v35, v[40:41], off
	global_load_dword v36, v[42:43], off
	global_load_dword v37, v[44:45], off
	s_nop 0
	global_load_dword v30, v[30:31], off
	s_waitcnt vmcnt(30)
	ds_write2_b32 v63, v48, v49 offset1:66
	s_waitcnt vmcnt(28)
	ds_write2_b32 v63, v50, v51 offset0:132 offset1:198
	s_waitcnt vmcnt(26)
	ds_write2_b32 v69, v52, v53 offset0:8 offset1:74
	s_waitcnt vmcnt(24)
	ds_write2_b32 v69, v54, v55 offset0:140 offset1:206
	s_waitcnt vmcnt(22)
	ds_write2_b32 v70, v56, v57 offset0:16 offset1:82
	s_waitcnt vmcnt(20)
	ds_write2_b32 v70, v58, v59 offset0:148 offset1:214
	s_waitcnt vmcnt(18)
	ds_write2_b32 v71, v60, v61 offset0:24 offset1:90
	s_waitcnt vmcnt(16)
	ds_write2_b32 v71, v77, v78 offset0:156 offset1:222
	s_waitcnt vmcnt(14)
	ds_write2_b32 v72, v79, v80 offset0:32 offset1:98
	s_waitcnt vmcnt(12)
	ds_write2_b32 v72, v81, v82 offset0:164 offset1:230
	s_waitcnt vmcnt(10)
	ds_write2_b32 v73, v83, v84 offset0:40 offset1:106
	s_waitcnt vmcnt(8)
	ds_write2_b32 v73, v85, v46 offset0:172 offset1:238
	s_waitcnt vmcnt(6)
	ds_write2_b32 v74, v0, v32 offset0:48 offset1:114
	s_waitcnt vmcnt(4)
	ds_write2_b32 v74, v33, v34 offset0:180 offset1:246
	s_waitcnt vmcnt(2)
; #define LAS __attribute__((address_space(3)))
; __device__ __forceinline__ unsigned pk2(float lo, float hi) { return f2bf(lo) | (f2bf(hi) << 16); }
; __device__ __forceinline__ void p0_transpose_item(const float* W, int K, int N, bf16_t* WT, int dest_row0, const float* gain, LAS float* scr, int k0, int n0, int lane) {
;     ...
;     for (int i = 0; i < 32; ++i) { const int kk = 2 * i + (lane >> 5); scr[kk * 33 + (lane & 31)] = wv[i]; }
;     asm volatile("s_waitcnt lgkmcnt(0)" ::: "memory");
;     const int c = lane & 7;
; #pragma unroll
;     for (int j = 0; j < 4; ++j) { const int n = (lane >> 3) + 8 * j; const LAS float* s = scr + (8 * c) * 33 + n;
;         u32x4 o; o.x = pk2(s[0 * 33], s[1 * 33]); o.y = pk2(s[2 * 33], s[3 * 33]); o.z = pk2(s[4 * 33], s[5 * 33]); o.w = pk2(s[6 * 33], s[7 * 33]);
;         *(u32x4*)(WT + (size_t)(dest_row0 + n) * K + k0 + 8 * c) = o; }
;     asm volatile("s_waitcnt lgkmcnt(0)" ::: "memory");
	ds_write2_b32 v75, v35, v36 offset0:56 offset1:122
	s_waitcnt vmcnt(0)
	ds_write2_b32 v75, v37, v30 offset0:188 offset1:254
	s_waitcnt lgkmcnt(0)
	ds_read2_b32 v[34:35], v65 offset1:8
	ds_read2_b32 v[38:39], v65 offset0:33 offset1:41
	ds_read2_b32 v[40:41], v65 offset0:66 offset1:74
	ds_read2_b32 v[42:43], v65 offset0:99 offset1:107
	ds_read2_b32 v[44:45], v65 offset0:132 offset1:140
	s_waitcnt lgkmcnt(4)
	v_bfe_u32 v0, v34, 16, 1
	v_add3_u32 v0, v34, v0, s24
	s_waitcnt lgkmcnt(3)
	v_bfe_u32 v30, v38, 16, 1
	v_lshrrev_b32_e32 v0, 16, v0
	v_add3_u32 v30, v38, v30, s24
	ds_read2_b32 v[46:47], v65 offset0:165 offset1:173
	v_and_or_b32 v30, v30, s25, v0
	s_waitcnt lgkmcnt(3)
	v_bfe_u32 v0, v40, 16, 1
	v_add3_u32 v0, v40, v0, s24
	s_waitcnt lgkmcnt(2)
	v_bfe_u32 v31, v42, 16, 1
	ds_read2_b32 v[48:49], v65 offset0:198 offset1:206
	v_lshrrev_b32_e32 v0, 16, v0
	v_add3_u32 v31, v42, v31, s24
	ds_read2_b32 v[50:51], v65 offset0:231 offset1:239
	v_and_or_b32 v31, v31, s25, v0
	s_waitcnt lgkmcnt(3)
	v_bfe_u32 v0, v44, 16, 1
	v_add3_u32 v0, v44, v0, s24
	s_waitcnt lgkmcnt(2)
	v_bfe_u32 v32, v46, 16, 1
	v_lshrrev_b32_e32 v0, 16, v0
	v_add3_u32 v32, v46, v32, s24
	v_and_or_b32 v32, v32, s25, v0
	s_waitcnt lgkmcnt(1)
	v_bfe_u32 v0, v48, 16, 1
	v_add_u32_e32 v52, s4, v64
	s_ashr_i32 s9, s8, 31
	v_add3_u32 v0, v48, v0, s24
	s_waitcnt lgkmcnt(0)
	v_bfe_u32 v33, v50, 16, 1
	v_ashrrev_i32_e32 v53, 31, v52
	v_lshl_add_u64 v[36:37], s[8:9], 1, v[28:29]
	v_lshrrev_b32_e32 v0, 16, v0
	v_add3_u32 v33, v50, v33, s24
	v_lshlrev_b64 v[52:53], 11, v[52:53]
	v_and_or_b32 v33, v33, s25, v0
	v_lshl_add_u64 v[52:53], v[36:37], 0, v[52:53]
	v_bfe_u32 v0, v35, 16, 1
	global_store_dwordx4 v[52:53], v[30:33], off sc1
	v_add3_u32 v0, v35, v0, s24
	v_lshrrev_b32_e32 v0, 16, v0
	v_bfe_u32 v30, v39, 16, 1
	v_add3_u32 v30, v39, v30, s24
	v_and_or_b32 v30, v30, s25, v0
	v_bfe_u32 v0, v41, 16, 1
	v_add3_u32 v0, v41, v0, s24
	v_bfe_u32 v31, v43, 16, 1
	v_lshrrev_b32_e32 v0, 16, v0
	v_add3_u32 v31, v43, v31, s24
	v_and_or_b32 v31, v31, s25, v0
	v_bfe_u32 v0, v45, 16, 1
	v_add3_u32 v0, v45, v0, s24
	v_bfe_u32 v32, v47, 16, 1
	v_lshrrev_b32_e32 v0, 16, v0
	v_add3_u32 v32, v47, v32, s24
	v_and_or_b32 v32, v32, s25, v0
	v_bfe_u32 v0, v49, 16, 1
	v_add_u32_e32 v34, s4, v66
	v_add3_u32 v0, v49, v0, s24
	v_bfe_u32 v33, v51, 16, 1
	v_ashrrev_i32_e32 v35, 31, v34
	v_lshrrev_b32_e32 v0, 16, v0
	v_add3_u32 v33, v51, v33, s24
	v_lshlrev_b64 v[34:35], 11, v[34:35]
	v_and_or_b32 v33, v33, s25, v0
	ds_read2_b32 v[38:39], v65 offset0:16 offset1:24
	v_lshl_add_u64 v[34:35], v[36:37], 0, v[34:35]
	global_store_dwordx4 v[34:35], v[30:33], off sc1
	ds_read2_b32 v[34:35], v65 offset0:49 offset1:57
	ds_read2_b32 v[40:41], v65 offset0:82 offset1:90
	ds_read2_b32 v[42:43], v65 offset0:115 offset1:123
	s_waitcnt lgkmcnt(3)
	v_bfe_u32 v0, v38, 16, 1
	v_add3_u32 v0, v38, v0, s24
	s_waitcnt lgkmcnt(2)
	v_bfe_u32 v30, v34, 16, 1
	ds_read2_b32 v[44:45], v65 offset0:148 offset1:156
	v_lshrrev_b32_e32 v0, 16, v0
	v_add3_u32 v30, v34, v30, s24
	ds_read2_b32 v[46:47], v65 offset0:181 offset1:189
	v_and_or_b32 v30, v30, s25, v0
	s_waitcnt lgkmcnt(3)
	v_bfe_u32 v0, v40, 16, 1
	v_add3_u32 v0, v40, v0, s24
	s_waitcnt lgkmcnt(2)
	v_bfe_u32 v31, v42, 16, 1
	ds_read2_b32 v[48:49], v65 offset0:214 offset1:222
	v_lshrrev_b32_e32 v0, 16, v0
	v_add3_u32 v31, v42, v31, s24
	ds_read2_b32 v[50:51], v65 offset0:247 offset1:255
	v_and_or_b32 v31, v31, s25, v0
	s_waitcnt lgkmcnt(3)
	v_bfe_u32 v0, v44, 16, 1
	v_add3_u32 v0, v44, v0, s24
	s_waitcnt lgkmcnt(2)
	v_bfe_u32 v32, v46, 16, 1
	v_lshrrev_b32_e32 v0, 16, v0
	v_add3_u32 v32, v46, v32, s24
	v_and_or_b32 v32, v32, s25, v0
	s_waitcnt lgkmcnt(1)
	v_bfe_u32 v0, v48, 16, 1
	v_add_u32_e32 v52, s4, v67
	v_add3_u32 v0, v48, v0, s24
	s_waitcnt lgkmcnt(0)
	v_bfe_u32 v33, v50, 16, 1
	v_ashrrev_i32_e32 v53, 31, v52
	v_lshrrev_b32_e32 v0, 16, v0
	v_add3_u32 v33, v50, v33, s24
	v_lshlrev_b64 v[52:53], 11, v[52:53]
	v_and_or_b32 v33, v33, s25, v0
	v_lshl_add_u64 v[52:53], v[36:37], 0, v[52:53]
	v_bfe_u32 v0, v39, 16, 1
	global_store_dwordx4 v[52:53], v[30:33], off sc1
	v_add3_u32 v0, v39, v0, s24
	v_lshrrev_b32_e32 v0, 16, v0
	v_bfe_u32 v30, v35, 16, 1
	v_add3_u32 v30, v35, v30, s24
	v_and_or_b32 v30, v30, s25, v0
	v_bfe_u32 v0, v41, 16, 1
	v_add3_u32 v0, v41, v0, s24
	v_bfe_u32 v31, v43, 16, 1
	v_lshrrev_b32_e32 v0, 16, v0
	v_add3_u32 v31, v43, v31, s24
	v_and_or_b32 v31, v31, s25, v0
	v_bfe_u32 v0, v45, 16, 1
	v_add3_u32 v0, v45, v0, s24
	v_bfe_u32 v32, v47, 16, 1
	v_lshrrev_b32_e32 v0, 16, v0
	v_add3_u32 v32, v47, v32, s24
	v_and_or_b32 v32, v32, s25, v0
	v_bfe_u32 v0, v49, 16, 1
	v_add_u32_e32 v34, s4, v68
	v_add3_u32 v0, v49, v0, s24
	v_bfe_u32 v33, v51, 16, 1
	v_ashrrev_i32_e32 v35, 31, v34
	v_lshrrev_b32_e32 v0, 16, v0
	v_add3_u32 v33, v51, v33, s24
	v_lshlrev_b64 v[34:35], 11, v[34:35]
	v_and_or_b32 v33, v33, s25, v0
	v_lshl_add_u64 v[34:35], v[36:37], 0, v[34:35]
	global_store_dwordx4 v[34:35], v[30:33], off sc1
	s_waitcnt lgkmcnt(0)

; __device__ __forceinline__ void p0_transpose_item(const float* W, int K, int N, bf16_t* WT, int dest_row0, const float* gain, LAS float* scr, int k0, int n0, int lane) {
;     ...
;     for (int i = 0; i < 32; ++i) { const int kk = 2 * i + (lane >> 5); wv[i] = W[(size_t)(k0 + kk) * N + n0 + (lane & 31)]; }
; __device__ __forceinline__ void transpose_items(Frame& F, int it0, int it1, int gw, int NGW) {
;     ...
;         if (r < I_IN) { const int kb = r / 88, nb = r % 88; p0_transpose_item(F.w_in, D, INW, Win_t, win_dest(32 * nb), nullptr, scr, 64 * kb, 32 * nb, F.lane); continue; } r -= I_IN;
;         if (r < I_KV) { const int kb = r / 32, nb = r % 32; p0_transpose_item(F.wkv, D, D, Wkv_t, 32 * nb, nullptr, scr, 64 * kb, 32 * nb, F.lane); continue; } r -= I_KV;
;         if (r < I_OUT) { const int kb = r / 32, nb = r % 32; p0_transpose_item(F.w_out, D, D, Wout_t, 32 * nb, nullptr, scr, 64 * kb, 32 * nb, F.lane); continue; } r -= I_OUT;
;         if (r < I_Q) { const int kb = r / 16, nb = r % 16; p0_transpose_item(F.wq, D, 512, Wq_t, 32 * nb, F.g2, scr, 64 * kb, 32 * nb, F.lane); continue; } r -= I_Q;
;         if (r < I_O) { const int kb = r / 32, nb = r % 32; p0_transpose_item(F.wo, 512, D, Wo_t, 32 * nb, nullptr, scr, 64 * kb, 32 * nb, F.lane); continue; } r -= I_O;
;         if (r < I_UP) { const int kb = r / 128, nb = r % 128; p0_transpose_item(F.wup, D, FF, Wup_t, 32 * nb, F.g3, scr, 64 * kb, 32 * nb, F.lane); continue; } r -= I_UP;
;         { const int kb = r / 32, nb = r % 32; p0_transpose_item(F.wdn, FF, D, Wdn_t, 32 * nb, nullptr, scr, 64 * kb, 32 * nb, F.lane); }
.LBB0_393:
	s_cmpk_gt_i32 s15, 0x57f
	s_mov_b64 s[8:9], -1
	s_cbranch_scc0 .LBB0_419
	s_cmpk_gt_u32 s15, 0x77f
	s_cbranch_scc0 .LBB0_416
	s_cmpk_gt_u32 s15, 0x97f
	s_cbranch_scc0 .LBB0_413
	s_cmpk_gt_u32 s15, 0xa7f
	s_cbranch_scc0 .LBB0_408
	s_cmpk_gt_u32 s15, 0xb7f
	s_cbranch_scc0 .LBB0_405
	s_cmpk_gt_u32 s15, 0x137f
	s_cbranch_scc0 .LBB0_400
	s_and_b32 s4, s20, 0x7fffffc0
	s_add_i32 s8, s4, 0xffffd900
	s_and_b32 s10, s16, 0x3e0
	v_or_b32_e32 v0, s8, v62
	s_lshl_b32 s4, s10, 2
	v_or_b32_e32 v34, 2, v0
	v_mov_b32_e32 v35, v1
	v_or_b32_e32 v36, 4, v0
	v_mov_b32_e32 v37, v1
	v_or_b32_e32 v38, 6, v0
	v_mov_b32_e32 v39, v1
	v_or_b32_e32 v40, 8, v0
	v_mov_b32_e32 v41, v1
	v_or_b32_e32 v42, 10, v0
	v_mov_b32_e32 v43, v1
	v_or_b32_e32 v44, 12, v0
	v_mov_b32_e32 v45, v1
	v_lshl_add_u64 v[30:31], v[2:3], 0, s[4:5]
	v_lshlrev_b64 v[32:33], 12, v[0:1]
	v_lshlrev_b64 v[34:35], 12, v[34:35]
	v_lshlrev_b64 v[36:37], 12, v[36:37]
	v_lshlrev_b64 v[38:39], 12, v[38:39]
	v_lshlrev_b64 v[40:41], 12, v[40:41]
	v_lshlrev_b64 v[42:43], 12, v[42:43]
	v_lshlrev_b64 v[44:45], 12, v[44:45]
	v_or_b32_e32 v46, 14, v0
	v_mov_b32_e32 v47, v1
	v_lshl_add_u64 v[32:33], v[30:31], 0, v[32:33]
	v_lshl_add_u64 v[34:35], v[30:31], 0, v[34:35]
	v_lshl_add_u64 v[36:37], v[30:31], 0, v[36:37]
	v_lshl_add_u64 v[38:39], v[30:31], 0, v[38:39]
	v_lshl_add_u64 v[40:41], v[30:31], 0, v[40:41]
	v_lshl_add_u64 v[42:43], v[30:31], 0, v[42:43]
	v_lshl_add_u64 v[44:45], v[30:31], 0, v[44:45]
	v_lshlrev_b64 v[46:47], 12, v[46:47]
	v_lshl_add_u64 v[46:47], v[30:31], 0, v[46:47]
	global_load_dword v48, v[32:33], off
	global_load_dword v49, v[34:35], off
	global_load_dword v50, v[36:37], off
	global_load_dword v51, v[38:39], off
	global_load_dword v52, v[40:41], off
	global_load_dword v53, v[42:43], off
	global_load_dword v54, v[44:45], off
	global_load_dword v55, v[46:47], off
	v_or_b32_e32 v32, 16, v0
	v_mov_b32_e32 v33, v1
	v_or_b32_e32 v34, 18, v0
	v_mov_b32_e32 v35, v1
	v_or_b32_e32 v36, 20, v0
	v_mov_b32_e32 v37, v1
	v_or_b32_e32 v38, 22, v0
	v_mov_b32_e32 v39, v1
	v_or_b32_e32 v40, 24, v0
	v_mov_b32_e32 v41, v1
	v_or_b32_e32 v42, 26, v0
	v_mov_b32_e32 v43, v1
	v_or_b32_e32 v44, 28, v0
	v_mov_b32_e32 v45, v1
	v_lshlrev_b64 v[32:33], 12, v[32:33]
	v_lshlrev_b64 v[34:35], 12, v[34:35]
	v_lshlrev_b64 v[36:37], 12, v[36:37]
	v_lshlrev_b64 v[38:39], 12, v[38:39]
	v_lshlrev_b64 v[40:41], 12, v[40:41]
	v_lshlrev_b64 v[42:43], 12, v[42:43]
	v_lshlrev_b64 v[44:45], 12, v[44:45]
	v_or_b32_e32 v46, 30, v0
	v_mov_b32_e32 v47, v1
	v_lshl_add_u64 v[32:33], v[30:31], 0, v[32:33]
	v_lshl_add_u64 v[34:35], v[30:31], 0, v[34:35]
	v_lshl_add_u64 v[36:37], v[30:31], 0, v[36:37]
	v_lshl_add_u64 v[38:39], v[30:31], 0, v[38:39]
	v_lshl_add_u64 v[40:41], v[30:31], 0, v[40:41]
	v_lshl_add_u64 v[42:43], v[30:31], 0, v[42:43]
	v_lshl_add_u64 v[44:45], v[30:31], 0, v[44:45]
	v_lshlrev_b64 v[46:47], 12, v[46:47]
	v_lshl_add_u64 v[46:47], v[30:31], 0, v[46:47]
	global_load_dword v56, v[32:33], off
	global_load_dword v57, v[34:35], off
	global_load_dword v58, v[36:37], off
	global_load_dword v59, v[38:39], off
	global_load_dword v60, v[40:41], off
	global_load_dword v61, v[42:43], off
	global_load_dword v77, v[44:45], off
	global_load_dword v78, v[46:47], off
	v_or_b32_e32 v32, 32, v0
	v_mov_b32_e32 v33, v1
	v_or_b32_e32 v34, 34, v0
	v_mov_b32_e32 v35, v1
	v_or_b32_e32 v36, 36, v0
	v_mov_b32_e32 v37, v1
	v_or_b32_e32 v38, 38, v0
	v_mov_b32_e32 v39, v1
	v_or_b32_e32 v40, 40, v0
	v_mov_b32_e32 v41, v1
	v_or_b32_e32 v42, 42, v0
	v_mov_b32_e32 v43, v1
	v_or_b32_e32 v44, 44, v0
	v_mov_b32_e32 v45, v1
	v_lshlrev_b64 v[32:33], 12, v[32:33]
	v_lshlrev_b64 v[34:35], 12, v[34:35]
	v_lshlrev_b64 v[36:37], 12, v[36:37]
	v_lshlrev_b64 v[38:39], 12, v[38:39]
	v_lshlrev_b64 v[40:41], 12, v[40:41]
	v_lshlrev_b64 v[42:43], 12, v[42:43]
	v_lshlrev_b64 v[44:45], 12, v[44:45]
	v_or_b32_e32 v46, 46, v0
	v_mov_b32_e32 v47, v1
	v_lshl_add_u64 v[32:33], v[30:31], 0, v[32:33]
	v_lshl_add_u64 v[34:35], v[30:31], 0, v[34:35]
	v_lshl_add_u64 v[36:37], v[30:31], 0, v[36:37]
	v_lshl_add_u64 v[38:39], v[30:31], 0, v[38:39]
	v_lshl_add_u64 v[40:41], v[30:31], 0, v[40:41]
	v_lshl_add_u64 v[42:43], v[30:31], 0, v[42:43]
	v_lshl_add_u64 v[44:45], v[30:31], 0, v[44:45]
	v_lshlrev_b64 v[46:47], 12, v[46:47]
	v_lshl_add_u64 v[46:47], v[30:31], 0, v[46:47]
	global_load_dword v79, v[32:33], off
	global_load_dword v80, v[34:35], off
	global_load_dword v81, v[36:37], off
	global_load_dword v82, v[38:39], off
	global_load_dword v83, v[40:41], off
	global_load_dword v84, v[42:43], off
	global_load_dword v85, v[44:45], off
	global_load_dword v86, v[46:47], off
	v_or_b32_e32 v32, 48, v0
	v_mov_b32_e32 v33, v1
	v_or_b32_e32 v34, 50, v0
	v_mov_b32_e32 v35, v1
	v_or_b32_e32 v36, 52, v0
	v_mov_b32_e32 v37, v1
	v_or_b32_e32 v38, 54, v0
	v_mov_b32_e32 v39, v1
	v_or_b32_e32 v40, 56, v0
	v_mov_b32_e32 v41, v1
	v_or_b32_e32 v42, 58, v0
	v_mov_b32_e32 v43, v1
	v_or_b32_e32 v44, 60, v0
	v_mov_b32_e32 v45, v1
	v_or_b32_e32 v0, 62, v0
	v_lshlrev_b64 v[32:33], 12, v[32:33]
	v_lshlrev_b64 v[34:35], 12, v[34:35]
	v_lshlrev_b64 v[36:37], 12, v[36:37]
	v_lshlrev_b64 v[38:39], 12, v[38:39]
	v_lshlrev_b64 v[40:41], 12, v[40:41]
	v_lshlrev_b64 v[42:43], 12, v[42:43]
	v_lshlrev_b64 v[44:45], 12, v[44:45]
	v_lshlrev_b64 v[46:47], 12, v[0:1]
	v_lshl_add_u64 v[32:33], v[30:31], 0, v[32:33]
	v_lshl_add_u64 v[34:35], v[30:31], 0, v[34:35]
	v_lshl_add_u64 v[36:37], v[30:31], 0, v[36:37]
	v_lshl_add_u64 v[38:39], v[30:31], 0, v[38:39]
	v_lshl_add_u64 v[40:41], v[30:31], 0, v[40:41]
	v_lshl_add_u64 v[42:43], v[30:31], 0, v[42:43]
	v_lshl_add_u64 v[44:45], v[30:31], 0, v[44:45]
	v_lshl_add_u64 v[30:31], v[30:31], 0, v[46:47]
	global_load_dword v0, v[32:33], off
	s_nop 0
	global_load_dword v32, v[34:35], off
	global_load_dword v33, v[36:37], off
	s_nop 0
	global_load_dword v34, v[38:39], off
	global_load_dword v35, v[40:41], off
	global_load_dword v36, v[42:43], off
	global_load_dword v37, v[44:45], off
	s_nop 0
	global_load_dword v30, v[30:31], off
	s_waitcnt vmcnt(30)
; #define LAS __attribute__((address_space(3)))
; __device__ __forceinline__ unsigned pk2(float lo, float hi) { return f2bf(lo) | (f2bf(hi) << 16); }
; __device__ __forceinline__ void p0_transpose_item(const float* W, int K, int N, bf16_t* WT, int dest_row0, const float* gain, LAS float* scr, int k0, int n0, int lane) {
;     ...
;     for (int i = 0; i < 32; ++i) { const int kk = 2 * i + (lane >> 5); scr[kk * 33 + (lane & 31)] = wv[i]; }
;     asm volatile("s_waitcnt lgkmcnt(0)" ::: "memory");
;     const int c = lane & 7;
; #pragma unroll
;     for (int j = 0; j < 4; ++j) { const int n = (lane >> 3) + 8 * j; const LAS float* s = scr + (8 * c) * 33 + n;
;         u32x4 o; o.x = pk2(s[0 * 33], s[1 * 33]); o.y = pk2(s[2 * 33], s[3 * 33]); o.z = pk2(s[4 * 33], s[5 * 33]); o.w = pk2(s[6 * 33], s[7 * 33]);
;         *(u32x4*)(WT + (size_t)(dest_row0 + n) * K + k0 + 8 * c) = o; }
;     asm volatile("s_waitcnt lgkmcnt(0)" ::: "memory");
	ds_write2_b32 v63, v48, v49 offset1:66
	s_waitcnt vmcnt(28)
	ds_write2_b32 v63, v50, v51 offset0:132 offset1:198
	s_waitcnt vmcnt(26)
	ds_write2_b32 v69, v52, v53 offset0:8 offset1:74
	s_waitcnt vmcnt(24)
	ds_write2_b32 v69, v54, v55 offset0:140 offset1:206
	s_waitcnt vmcnt(22)
	ds_write2_b32 v70, v56, v57 offset0:16 offset1:82
	s_waitcnt vmcnt(20)
	ds_write2_b32 v70, v58, v59 offset0:148 offset1:214
	s_waitcnt vmcnt(18)
	ds_write2_b32 v71, v60, v61 offset0:24 offset1:90
	s_waitcnt vmcnt(16)
	ds_write2_b32 v71, v77, v78 offset0:156 offset1:222
	s_waitcnt vmcnt(14)
	ds_write2_b32 v72, v79, v80 offset0:32 offset1:98
	s_waitcnt vmcnt(12)
	ds_write2_b32 v72, v81, v82 offset0:164 offset1:230
	s_waitcnt vmcnt(10)
	ds_write2_b32 v73, v83, v84 offset0:40 offset1:106
	s_waitcnt vmcnt(8)
	ds_write2_b32 v73, v85, v86 offset0:172 offset1:238
	s_waitcnt vmcnt(6)
	ds_write2_b32 v74, v0, v32 offset0:48 offset1:114
	s_waitcnt vmcnt(4)
	ds_write2_b32 v74, v33, v34 offset0:180 offset1:246
	s_waitcnt vmcnt(2)
	ds_write2_b32 v75, v35, v36 offset0:56 offset1:122
	s_waitcnt vmcnt(0)
	ds_write2_b32 v75, v37, v30 offset0:188 offset1:254
	s_waitcnt lgkmcnt(0)
	ds_read2_b32 v[34:35], v65 offset1:8
	ds_read2_b32 v[38:39], v65 offset0:33 offset1:41
	ds_read2_b32 v[40:41], v65 offset0:66 offset1:74
	ds_read2_b32 v[42:43], v65 offset0:99 offset1:107
	ds_read2_b32 v[44:45], v65 offset0:132 offset1:140
	s_waitcnt lgkmcnt(4)
	v_bfe_u32 v0, v34, 16, 1
	v_add3_u32 v0, v34, v0, s24
	s_waitcnt lgkmcnt(3)
	v_bfe_u32 v30, v38, 16, 1
	v_lshrrev_b32_e32 v0, 16, v0
	v_add3_u32 v30, v38, v30, s24
	ds_read2_b32 v[46:47], v65 offset0:165 offset1:173
	v_and_or_b32 v30, v30, s25, v0
	s_waitcnt lgkmcnt(3)
	v_bfe_u32 v0, v40, 16, 1
	v_add3_u32 v0, v40, v0, s24
	s_waitcnt lgkmcnt(2)
	v_bfe_u32 v31, v42, 16, 1
	ds_read2_b32 v[48:49], v65 offset0:198 offset1:206
	v_lshrrev_b32_e32 v0, 16, v0
	v_add3_u32 v31, v42, v31, s24
	ds_read2_b32 v[50:51], v65 offset0:231 offset1:239
	v_and_or_b32 v31, v31, s25, v0
	s_waitcnt lgkmcnt(3)
	v_bfe_u32 v0, v44, 16, 1
	v_add3_u32 v0, v44, v0, s24
	s_waitcnt lgkmcnt(2)
	v_bfe_u32 v32, v46, 16, 1
	v_lshrrev_b32_e32 v0, 16, v0
	v_add3_u32 v32, v46, v32, s24
	v_and_or_b32 v32, v32, s25, v0
	s_waitcnt lgkmcnt(1)
	v_bfe_u32 v0, v48, 16, 1
	v_add3_u32 v0, v48, v0, s24
	s_waitcnt lgkmcnt(0)
	v_bfe_u32 v33, v50, 16, 1
	v_lshrrev_b32_e32 v0, 16, v0
	v_add3_u32 v33, v50, v33, s24
	s_mov_b32 s9, s5
	v_and_or_b32 v33, v33, s25, v0
	v_or_b32_e32 v0, s10, v64
	v_lshl_add_u64 v[36:37], s[8:9], 1, v[4:5]
	v_lshlrev_b32_e32 v0, 13, v0
	v_lshl_add_u64 v[52:53], v[36:37], 0, v[0:1]
	v_bfe_u32 v0, v35, 16, 1
	global_store_dwordx4 v[52:53], v[30:33], off sc1
	v_add3_u32 v0, v35, v0, s24
	v_lshrrev_b32_e32 v0, 16, v0
	v_bfe_u32 v30, v39, 16, 1
	v_add3_u32 v30, v39, v30, s24
	v_and_or_b32 v30, v30, s25, v0
	v_bfe_u32 v0, v41, 16, 1
	v_add3_u32 v0, v41, v0, s24
	v_bfe_u32 v31, v43, 16, 1
	v_lshrrev_b32_e32 v0, 16, v0
	v_add3_u32 v31, v43, v31, s24
	v_and_or_b32 v31, v31, s25, v0
	v_bfe_u32 v0, v45, 16, 1
	v_add3_u32 v0, v45, v0, s24
	v_bfe_u32 v32, v47, 16, 1
	v_lshrrev_b32_e32 v0, 16, v0
	v_add3_u32 v32, v47, v32, s24
	v_and_or_b32 v32, v32, s25, v0
	v_bfe_u32 v0, v49, 16, 1
	v_add3_u32 v0, v49, v0, s24
	v_bfe_u32 v33, v51, 16, 1
	v_lshrrev_b32_e32 v0, 16, v0
	v_add3_u32 v33, v51, v33, s24
	v_and_or_b32 v33, v33, s25, v0
	v_or_b32_e32 v0, s10, v66
	v_lshlrev_b32_e32 v0, 13, v0
	ds_read2_b32 v[34:35], v65 offset0:16 offset1:24
	v_lshl_add_u64 v[38:39], v[36:37], 0, v[0:1]
	global_store_dwordx4 v[38:39], v[30:33], off sc1
	ds_read2_b32 v[38:39], v65 offset0:49 offset1:57
	ds_read2_b32 v[40:41], v65 offset0:82 offset1:90
	ds_read2_b32 v[42:43], v65 offset0:115 offset1:123
	s_waitcnt lgkmcnt(3)
	v_bfe_u32 v0, v34, 16, 1
	v_add3_u32 v0, v34, v0, s24
	s_waitcnt lgkmcnt(2)
	v_bfe_u32 v30, v38, 16, 1
	ds_read2_b32 v[44:45], v65 offset0:148 offset1:156
	v_lshrrev_b32_e32 v0, 16, v0
	v_add3_u32 v30, v38, v30, s24
	ds_read2_b32 v[46:47], v65 offset0:181 offset1:189
	v_and_or_b32 v30, v30, s25, v0
	s_waitcnt lgkmcnt(3)
	v_bfe_u32 v0, v40, 16, 1
	v_add3_u32 v0, v40, v0, s24
	s_waitcnt lgkmcnt(2)
	v_bfe_u32 v31, v42, 16, 1
	ds_read2_b32 v[48:49], v65 offset0:214 offset1:222
	v_lshrrev_b32_e32 v0, 16, v0
	v_add3_u32 v31, v42, v31, s24
	ds_read2_b32 v[50:51], v65 offset0:247 offset1:255
	v_and_or_b32 v31, v31, s25, v0
	s_waitcnt lgkmcnt(3)
	v_bfe_u32 v0, v44, 16, 1
	v_add3_u32 v0, v44, v0, s24
	s_waitcnt lgkmcnt(2)
	v_bfe_u32 v32, v46, 16, 1
	v_lshrrev_b32_e32 v0, 16, v0
	v_add3_u32 v32, v46, v32, s24
	v_and_or_b32 v32, v32, s25, v0
	s_waitcnt lgkmcnt(1)
	v_bfe_u32 v0, v48, 16, 1
	v_add3_u32 v0, v48, v0, s24
	s_waitcnt lgkmcnt(0)
	v_bfe_u32 v33, v50, 16, 1
	v_lshrrev_b32_e32 v0, 16, v0
	v_add3_u32 v33, v50, v33, s24
	v_and_or_b32 v33, v33, s25, v0
	v_or_b32_e32 v0, s10, v67
	v_lshlrev_b32_e32 v0, 13, v0
	v_lshl_add_u64 v[52:53], v[36:37], 0, v[0:1]
	v_bfe_u32 v0, v35, 16, 1
	global_store_dwordx4 v[52:53], v[30:33], off sc1
	v_add3_u32 v0, v35, v0, s24
	v_lshrrev_b32_e32 v0, 16, v0
	v_bfe_u32 v30, v39, 16, 1
	v_add3_u32 v30, v39, v30, s24
	v_and_or_b32 v30, v30, s25, v0
	v_bfe_u32 v0, v41, 16, 1
	v_add3_u32 v0, v41, v0, s24
	v_bfe_u32 v31, v43, 16, 1
	v_lshrrev_b32_e32 v0, 16, v0
	v_add3_u32 v31, v43, v31, s24
	v_and_or_b32 v31, v31, s25, v0
	v_bfe_u32 v0, v45, 16, 1
	v_add3_u32 v0, v45, v0, s24
	v_bfe_u32 v32, v47, 16, 1
	v_lshrrev_b32_e32 v0, 16, v0
	v_add3_u32 v32, v47, v32, s24
	v_and_or_b32 v32, v32, s25, v0
	v_bfe_u32 v0, v49, 16, 1
	v_add3_u32 v0, v49, v0, s24
	v_bfe_u32 v33, v51, 16, 1
	v_lshrrev_b32_e32 v0, 16, v0
	v_add3_u32 v33, v51, v33, s24
	v_and_or_b32 v33, v33, s25, v0
	v_or_b32_e32 v0, s10, v68
	v_lshlrev_b32_e32 v0, 13, v0
	v_lshl_add_u64 v[34:35], v[36:37], 0, v[0:1]
	global_store_dwordx4 v[34:35], v[30:33], off sc1
	s_waitcnt lgkmcnt(0)
	s_mov_b64 s[8:9], 0

; #define LAS __attribute__((address_space(3)))
; __device__ __forceinline__ unsigned pk2(float lo, float hi) { return f2bf(lo) | (f2bf(hi) << 16); }
; __device__ __forceinline__ void p0_transpose_item(const float* W, int K, int N, bf16_t* WT, int dest_row0, const float* gain, LAS float* scr, int k0, int n0, int lane) {
;     ...
;     for (int i = 0; i < 32; ++i) { const int kk = 2 * i + (lane >> 5); scr[kk * 33 + (lane & 31)] = wv[i]; }
;     asm volatile("s_waitcnt lgkmcnt(0)" ::: "memory");
;     const int c = lane & 7;
; #pragma unroll
;     for (int j = 0; j < 4; ++j) { const int n = (lane >> 3) + 8 * j; const LAS float* s = scr + (8 * c) * 33 + n;
;         u32x4 o; o.x = pk2(s[0 * 33], s[1 * 33]); o.y = pk2(s[2 * 33], s[3 * 33]); o.z = pk2(s[4 * 33], s[5 * 33]); o.w = pk2(s[6 * 33], s[7 * 33]);
;         *(u32x4*)(WT + (size_t)(dest_row0 + n) * K + k0 + 8 * c) = o; }
;     asm volatile("s_waitcnt lgkmcnt(0)" ::: "memory");
.LBB0_403:
	s_waitcnt vmcnt(30)
	ds_write2_b32 v63, v30, v31 offset1:66
	s_waitcnt vmcnt(28)
	ds_write2_b32 v63, v32, v33 offset0:132 offset1:198
	s_waitcnt vmcnt(26)
	ds_write2_b32 v69, v34, v35 offset0:8 offset1:74
	s_waitcnt vmcnt(24)
	ds_write2_b32 v69, v36, v37 offset0:140 offset1:206
	s_waitcnt vmcnt(22)
	ds_write2_b32 v70, v38, v39 offset0:16 offset1:82
	s_waitcnt vmcnt(20)
	ds_write2_b32 v70, v40, v41 offset0:148 offset1:214
	s_waitcnt vmcnt(18)
	ds_write2_b32 v71, v42, v43 offset0:24 offset1:90
	s_waitcnt vmcnt(16)
	ds_write2_b32 v71, v44, v45 offset0:156 offset1:222
	s_waitcnt vmcnt(14)
	ds_write2_b32 v72, v46, v47 offset0:32 offset1:98
	s_waitcnt vmcnt(12)
	ds_write2_b32 v72, v48, v49 offset0:164 offset1:230
	s_waitcnt vmcnt(10)
	ds_write2_b32 v73, v50, v51 offset0:40 offset1:106
	s_waitcnt vmcnt(8)
	ds_write2_b32 v73, v52, v53 offset0:172 offset1:238
	s_waitcnt vmcnt(6)
	ds_write2_b32 v74, v54, v55 offset0:48 offset1:114
	s_waitcnt vmcnt(4)
	ds_write2_b32 v74, v56, v57 offset0:180 offset1:246
	s_waitcnt vmcnt(2)
	ds_write2_b32 v75, v60, v61 offset0:56 offset1:122
	s_waitcnt vmcnt(0)
	ds_write2_b32 v75, v58, v59 offset0:188 offset1:254
	s_waitcnt lgkmcnt(0)
	ds_read2_b32 v[34:35], v65 offset1:8
	ds_read2_b32 v[38:39], v65 offset0:33 offset1:41
	ds_read2_b32 v[40:41], v65 offset0:66 offset1:74
	ds_read2_b32 v[42:43], v65 offset0:99 offset1:107
	ds_read2_b32 v[44:45], v65 offset0:132 offset1:140
	s_waitcnt lgkmcnt(4)
	v_bfe_u32 v0, v34, 16, 1
	v_add3_u32 v0, v34, v0, s24
	s_waitcnt lgkmcnt(3)
	v_bfe_u32 v30, v38, 16, 1
	v_lshrrev_b32_e32 v0, 16, v0
	v_add3_u32 v30, v38, v30, s24
	ds_read2_b32 v[46:47], v65 offset0:165 offset1:173
	v_and_or_b32 v30, v30, s25, v0
	s_waitcnt lgkmcnt(3)
	v_bfe_u32 v0, v40, 16, 1
	v_add3_u32 v0, v40, v0, s24
	s_waitcnt lgkmcnt(2)
	v_bfe_u32 v31, v42, 16, 1
	ds_read2_b32 v[48:49], v65 offset0:198 offset1:206
	v_lshrrev_b32_e32 v0, 16, v0
	v_add3_u32 v31, v42, v31, s24
	ds_read2_b32 v[50:51], v65 offset0:231 offset1:239
	v_and_or_b32 v31, v31, s25, v0
	s_waitcnt lgkmcnt(3)
	v_bfe_u32 v0, v44, 16, 1
	v_add3_u32 v0, v44, v0, s24
	s_waitcnt lgkmcnt(2)
	v_bfe_u32 v32, v46, 16, 1
	v_lshrrev_b32_e32 v0, 16, v0
	v_add3_u32 v32, v46, v32, s24
	v_and_or_b32 v32, v32, s25, v0
	s_waitcnt lgkmcnt(1)
	v_bfe_u32 v0, v48, 16, 1
	v_add3_u32 v0, v48, v0, s24
	s_waitcnt lgkmcnt(0)
	v_bfe_u32 v33, v50, 16, 1
	v_lshrrev_b32_e32 v0, 16, v0
	v_add3_u32 v33, v50, v33, s24
	s_lshl_b32 s4, s9, 1
	v_and_or_b32 v33, v33, s25, v0
	v_or_b32_e32 v0, s8, v64
	v_lshl_add_u64 v[36:37], v[8:9], 0, s[4:5]
	v_lshlrev_b32_e32 v0, 11, v0
	v_lshl_add_u64 v[52:53], v[36:37], 0, v[0:1]
	v_bfe_u32 v0, v35, 16, 1
	global_store_dwordx4 v[52:53], v[30:33], off sc1
	v_add3_u32 v0, v35, v0, s24
	v_lshrrev_b32_e32 v0, 16, v0
	v_bfe_u32 v30, v39, 16, 1
	v_add3_u32 v30, v39, v30, s24
	v_and_or_b32 v30, v30, s25, v0
	v_bfe_u32 v0, v41, 16, 1
	v_add3_u32 v0, v41, v0, s24
	v_bfe_u32 v31, v43, 16, 1
	v_lshrrev_b32_e32 v0, 16, v0
	v_add3_u32 v31, v43, v31, s24
	v_and_or_b32 v31, v31, s25, v0
	v_bfe_u32 v0, v45, 16, 1
	v_add3_u32 v0, v45, v0, s24
	v_bfe_u32 v32, v47, 16, 1
	v_lshrrev_b32_e32 v0, 16, v0
	v_add3_u32 v32, v47, v32, s24
	v_and_or_b32 v32, v32, s25, v0
	v_bfe_u32 v0, v49, 16, 1
	v_add3_u32 v0, v49, v0, s24
	v_bfe_u32 v33, v51, 16, 1
	v_lshrrev_b32_e32 v0, 16, v0
	v_add3_u32 v33, v51, v33, s24
	v_and_or_b32 v33, v33, s25, v0
	v_or_b32_e32 v0, s8, v66
	v_lshlrev_b32_e32 v0, 11, v0
	ds_read2_b32 v[34:35], v65 offset0:16 offset1:24
	v_lshl_add_u64 v[38:39], v[36:37], 0, v[0:1]
	global_store_dwordx4 v[38:39], v[30:33], off sc1
	ds_read2_b32 v[38:39], v65 offset0:49 offset1:57
	ds_read2_b32 v[40:41], v65 offset0:82 offset1:90
	ds_read2_b32 v[42:43], v65 offset0:115 offset1:123
	s_waitcnt lgkmcnt(3)
	v_bfe_u32 v0, v34, 16, 1
	v_add3_u32 v0, v34, v0, s24
	s_waitcnt lgkmcnt(2)
	v_bfe_u32 v30, v38, 16, 1
	ds_read2_b32 v[44:45], v65 offset0:148 offset1:156
	v_lshrrev_b32_e32 v0, 16, v0
	v_add3_u32 v30, v38, v30, s24
	ds_read2_b32 v[46:47], v65 offset0:181 offset1:189
	v_and_or_b32 v30, v30, s25, v0
	s_waitcnt lgkmcnt(3)
	v_bfe_u32 v0, v40, 16, 1
	v_add3_u32 v0, v40, v0, s24
	s_waitcnt lgkmcnt(2)
	v_bfe_u32 v31, v42, 16, 1
	ds_read2_b32 v[48:49], v65 offset0:214 offset1:222
	v_lshrrev_b32_e32 v0, 16, v0
	v_add3_u32 v31, v42, v31, s24
	ds_read2_b32 v[50:51], v65 offset0:247 offset1:255
	v_and_or_b32 v31, v31, s25, v0
	s_waitcnt lgkmcnt(3)
	v_bfe_u32 v0, v44, 16, 1
	v_add3_u32 v0, v44, v0, s24
	s_waitcnt lgkmcnt(2)
	v_bfe_u32 v32, v46, 16, 1
	v_lshrrev_b32_e32 v0, 16, v0
	v_add3_u32 v32, v46, v32, s24
	v_and_or_b32 v32, v32, s25, v0
	s_waitcnt lgkmcnt(1)
	v_bfe_u32 v0, v48, 16, 1
	v_add3_u32 v0, v48, v0, s24
	s_waitcnt lgkmcnt(0)
	v_bfe_u32 v33, v50, 16, 1
	v_lshrrev_b32_e32 v0, 16, v0
	v_add3_u32 v33, v50, v33, s24
	v_and_or_b32 v33, v33, s25, v0
	v_or_b32_e32 v0, s8, v67
	v_lshlrev_b32_e32 v0, 11, v0
	v_lshl_add_u64 v[52:53], v[36:37], 0, v[0:1]
	v_bfe_u32 v0, v35, 16, 1
	global_store_dwordx4 v[52:53], v[30:33], off sc1
	v_add3_u32 v0, v35, v0, s24
	v_lshrrev_b32_e32 v0, 16, v0
	v_bfe_u32 v30, v39, 16, 1
	v_add3_u32 v30, v39, v30, s24
	v_and_or_b32 v30, v30, s25, v0
	v_bfe_u32 v0, v41, 16, 1
	v_add3_u32 v0, v41, v0, s24
	v_bfe_u32 v31, v43, 16, 1
	v_lshrrev_b32_e32 v0, 16, v0
	v_add3_u32 v31, v43, v31, s24
	v_and_or_b32 v31, v31, s25, v0
	v_bfe_u32 v0, v45, 16, 1
	v_add3_u32 v0, v45, v0, s24
	v_bfe_u32 v32, v47, 16, 1
	v_lshrrev_b32_e32 v0, 16, v0
	v_add3_u32 v32, v47, v32, s24
	v_and_or_b32 v32, v32, s25, v0
	v_bfe_u32 v0, v49, 16, 1
	v_add3_u32 v0, v49, v0, s24
	v_bfe_u32 v33, v51, 16, 1
	v_lshrrev_b32_e32 v0, 16, v0
	v_add3_u32 v33, v51, v33, s24
	v_and_or_b32 v33, v33, s25, v0
	v_or_b32_e32 v0, s8, v68
	v_lshlrev_b32_e32 v0, 11, v0
	v_lshl_add_u64 v[34:35], v[36:37], 0, v[0:1]
	global_store_dwordx4 v[34:35], v[30:33], off sc1
	s_waitcnt lgkmcnt(0)

; #define LAS __attribute__((address_space(3)))
; __device__ __forceinline__ void p0_transpose_item(const float* W, int K, int N, bf16_t* WT, int dest_row0, const float* gain, LAS float* scr, int k0, int n0, int lane) {
;     float wv[32];
; #pragma unroll
;     for (int i = 0; i < 32; ++i) { const int kk = 2 * i + (lane >> 5); wv[i] = W[(size_t)(k0 + kk) * N + n0 + (lane & 31)]; }
;     if (gain) {
; #pragma unroll
;         for (int i = 0; i < 32; ++i) wv[i] *= gain[k0 + 2 * i + (lane >> 5)]; }
; #pragma unroll
;     for (int i = 0; i < 32; ++i) { const int kk = 2 * i + (lane >> 5); scr[kk * 33 + (lane & 31)] = wv[i]; }
; __device__ __forceinline__ void transpose_items(Frame& F, int it0, int it1, int gw, int NGW) {
;     ...
;     for (int it = it0 + gw; it < it1; it += NGW) {
;         int r = it;
;         if (r < I_IN) { const int kb = r / 88, nb = r % 88; p0_transpose_item(F.w_in, D, INW, Win_t, win_dest(32 * nb), nullptr, scr, 64 * kb, 32 * nb, F.lane); continue; } r -= I_IN;
;         if (r < I_KV) { const int kb = r / 32, nb = r % 32; p0_transpose_item(F.wkv, D, D, Wkv_t, 32 * nb, nullptr, scr, 64 * kb, 32 * nb, F.lane); continue; } r -= I_KV;
;         if (r < I_OUT) { const int kb = r / 32, nb = r % 32; p0_transpose_item(F.w_out, D, D, Wout_t, 32 * nb, nullptr, scr, 64 * kb, 32 * nb, F.lane); continue; } r -= I_OUT;
;         if (r < I_Q) { const int kb = r / 16, nb = r % 16; p0_transpose_item(F.wq, D, 512, Wq_t, 32 * nb, F.g2, scr, 64 * kb, 32 * nb, F.lane); continue; } r -= I_Q;
;         if (r < I_O) { const int kb = r / 32, nb = r % 32; p0_transpose_item(F.wo, 512, D, Wo_t, 32 * nb, nullptr, scr, 64 * kb, 32 * nb, F.lane); continue; } r -= I_O;
;         if (r < I_UP) { const int kb = r / 128, nb = r % 128; p0_transpose_item(F.wup, D, FF, Wup_t, 32 * nb, F.g3, scr, 64 * kb, 32 * nb, F.lane); continue; } r -= I_UP;
;         { const int kb = r / 32, nb = r % 32; p0_transpose_item(F.wdn, FF, D, Wdn_t, 32 * nb, nullptr, scr, 64 * kb, 32 * nb, F.lane); }
.LBB0_405:
	s_andn2_b64 vcc, exec, s[8:9]
	s_cbranch_vccnz .LBB0_407
	s_and_b32 s4, s20, 0x1fc0
	s_add_i32 s8, s4, 0xffffeb00
	s_and_b32 s10, s16, 0x3e0
	v_or_b32_e32 v0, s8, v62
	s_lshl_b32 s4, s10, 2
	v_or_b32_e32 v34, 2, v0
	v_mov_b32_e32 v35, v1
	v_or_b32_e32 v36, 4, v0
	v_mov_b32_e32 v37, v1
	v_or_b32_e32 v38, 6, v0
	v_mov_b32_e32 v39, v1
	v_or_b32_e32 v40, 8, v0
	v_mov_b32_e32 v41, v1
	v_or_b32_e32 v42, 10, v0
	v_mov_b32_e32 v43, v1
	v_or_b32_e32 v44, 12, v0
	v_mov_b32_e32 v45, v1
	v_lshl_add_u64 v[30:31], v[10:11], 0, s[4:5]
	v_lshlrev_b64 v[32:33], 12, v[0:1]
	v_lshlrev_b64 v[34:35], 12, v[34:35]
	v_lshlrev_b64 v[36:37], 12, v[36:37]
	v_lshlrev_b64 v[38:39], 12, v[38:39]
	v_lshlrev_b64 v[40:41], 12, v[40:41]
	v_lshlrev_b64 v[42:43], 12, v[42:43]
	v_lshlrev_b64 v[44:45], 12, v[44:45]
	v_or_b32_e32 v46, 14, v0
	v_mov_b32_e32 v47, v1
	v_lshl_add_u64 v[32:33], v[30:31], 0, v[32:33]
	v_lshl_add_u64 v[34:35], v[30:31], 0, v[34:35]
	v_lshl_add_u64 v[36:37], v[30:31], 0, v[36:37]
	v_lshl_add_u64 v[38:39], v[30:31], 0, v[38:39]
	v_lshl_add_u64 v[40:41], v[30:31], 0, v[40:41]
	v_lshl_add_u64 v[42:43], v[30:31], 0, v[42:43]
	v_lshl_add_u64 v[44:45], v[30:31], 0, v[44:45]
	v_lshlrev_b64 v[46:47], 12, v[46:47]
	v_lshl_add_u64 v[46:47], v[30:31], 0, v[46:47]
	global_load_dword v48, v[32:33], off
	global_load_dword v49, v[34:35], off
	global_load_dword v50, v[36:37], off
	global_load_dword v51, v[38:39], off
	global_load_dword v52, v[40:41], off
	global_load_dword v53, v[42:43], off
	global_load_dword v54, v[44:45], off
	global_load_dword v55, v[46:47], off
	v_or_b32_e32 v32, 16, v0
	v_mov_b32_e32 v33, v1
	v_or_b32_e32 v34, 18, v0
	v_mov_b32_e32 v35, v1
	v_or_b32_e32 v36, 20, v0
	v_mov_b32_e32 v37, v1
	v_or_b32_e32 v38, 22, v0
	v_mov_b32_e32 v39, v1
	v_or_b32_e32 v40, 24, v0
	v_mov_b32_e32 v41, v1
	v_or_b32_e32 v42, 26, v0
	v_mov_b32_e32 v43, v1
	v_or_b32_e32 v44, 28, v0
	v_mov_b32_e32 v45, v1
	v_lshlrev_b64 v[32:33], 12, v[32:33]
	v_lshlrev_b64 v[34:35], 12, v[34:35]
	v_lshlrev_b64 v[36:37], 12, v[36:37]
	v_lshlrev_b64 v[38:39], 12, v[38:39]
	v_lshlrev_b64 v[40:41], 12, v[40:41]
	v_lshlrev_b64 v[42:43], 12, v[42:43]
	v_lshlrev_b64 v[44:45], 12, v[44:45]
	v_or_b32_e32 v46, 30, v0
	v_mov_b32_e32 v47, v1
	v_lshl_add_u64 v[32:33], v[30:31], 0, v[32:33]
	v_lshl_add_u64 v[34:35], v[30:31], 0, v[34:35]
	v_lshl_add_u64 v[36:37], v[30:31], 0, v[36:37]
	v_lshl_add_u64 v[38:39], v[30:31], 0, v[38:39]
	v_lshl_add_u64 v[40:41], v[30:31], 0, v[40:41]
	v_lshl_add_u64 v[42:43], v[30:31], 0, v[42:43]
	v_lshl_add_u64 v[44:45], v[30:31], 0, v[44:45]
	v_lshlrev_b64 v[46:47], 12, v[46:47]
	v_lshl_add_u64 v[46:47], v[30:31], 0, v[46:47]
	global_load_dword v56, v[32:33], off
	global_load_dword v57, v[34:35], off
	global_load_dword v58, v[36:37], off
	global_load_dword v59, v[38:39], off
	global_load_dword v60, v[40:41], off
	global_load_dword v61, v[42:43], off
	global_load_dword v77, v[44:45], off
	global_load_dword v78, v[46:47], off
	v_or_b32_e32 v32, 32, v0
	v_mov_b32_e32 v33, v1
	v_or_b32_e32 v34, 34, v0
	v_mov_b32_e32 v35, v1
	v_or_b32_e32 v36, 36, v0
	v_mov_b32_e32 v37, v1
	v_or_b32_e32 v38, 38, v0
	v_mov_b32_e32 v39, v1
	v_or_b32_e32 v40, 40, v0
	v_mov_b32_e32 v41, v1
	v_or_b32_e32 v42, 42, v0
	v_mov_b32_e32 v43, v1
	v_or_b32_e32 v44, 44, v0
	v_mov_b32_e32 v45, v1
	v_lshlrev_b64 v[32:33], 12, v[32:33]
	v_lshlrev_b64 v[34:35], 12, v[34:35]
	v_lshlrev_b64 v[36:37], 12, v[36:37]
	v_lshlrev_b64 v[38:39], 12, v[38:39]
	v_lshlrev_b64 v[40:41], 12, v[40:41]
	v_lshlrev_b64 v[42:43], 12, v[42:43]
	v_lshlrev_b64 v[44:45], 12, v[44:45]
	v_or_b32_e32 v46, 46, v0
	v_mov_b32_e32 v47, v1
	v_lshl_add_u64 v[32:33], v[30:31], 0, v[32:33]
	v_lshl_add_u64 v[34:35], v[30:31], 0, v[34:35]
	v_lshl_add_u64 v[36:37], v[30:31], 0, v[36:37]
	v_lshl_add_u64 v[38:39], v[30:31], 0, v[38:39]
	v_lshl_add_u64 v[40:41], v[30:31], 0, v[40:41]
	v_lshl_add_u64 v[42:43], v[30:31], 0, v[42:43]
	v_lshl_add_u64 v[44:45], v[30:31], 0, v[44:45]
	v_lshlrev_b64 v[46:47], 12, v[46:47]
	v_lshl_add_u64 v[46:47], v[30:31], 0, v[46:47]
	global_load_dword v79, v[32:33], off
	global_load_dword v80, v[34:35], off
	global_load_dword v81, v[36:37], off
	global_load_dword v82, v[38:39], off
	global_load_dword v83, v[40:41], off
	global_load_dword v84, v[42:43], off
	global_load_dword v85, v[44:45], off
	global_load_dword v86, v[46:47], off
	v_or_b32_e32 v32, 48, v0
	v_mov_b32_e32 v33, v1
	v_or_b32_e32 v34, 50, v0
	v_mov_b32_e32 v35, v1
	v_or_b32_e32 v36, 52, v0
	v_mov_b32_e32 v37, v1
	v_or_b32_e32 v38, 54, v0
	v_mov_b32_e32 v39, v1
	v_or_b32_e32 v40, 56, v0
	v_mov_b32_e32 v41, v1
	v_or_b32_e32 v42, 58, v0
	v_mov_b32_e32 v43, v1
	v_or_b32_e32 v44, 60, v0
	v_mov_b32_e32 v45, v1
	v_or_b32_e32 v0, 62, v0
	v_lshlrev_b64 v[32:33], 12, v[32:33]
	v_lshlrev_b64 v[34:35], 12, v[34:35]
	v_lshlrev_b64 v[36:37], 12, v[36:37]
	v_lshlrev_b64 v[38:39], 12, v[38:39]
	v_lshlrev_b64 v[40:41], 12, v[40:41]
	v_lshlrev_b64 v[42:43], 12, v[42:43]
	v_lshlrev_b64 v[44:45], 12, v[44:45]
	v_lshlrev_b64 v[46:47], 12, v[0:1]
	v_lshl_add_u64 v[32:33], v[30:31], 0, v[32:33]
	v_lshl_add_u64 v[34:35], v[30:31], 0, v[34:35]
	v_lshl_add_u64 v[36:37], v[30:31], 0, v[36:37]
	v_lshl_add_u64 v[38:39], v[30:31], 0, v[38:39]
	v_lshl_add_u64 v[40:41], v[30:31], 0, v[40:41]
	v_lshl_add_u64 v[42:43], v[30:31], 0, v[42:43]
	v_lshl_add_u64 v[44:45], v[30:31], 0, v[44:45]
	v_lshl_add_u64 v[30:31], v[30:31], 0, v[46:47]
	global_load_dword v0, v[32:33], off
	s_nop 0
	global_load_dword v32, v[34:35], off
	global_load_dword v33, v[36:37], off
	s_nop 0
	global_load_dword v34, v[38:39], off
	global_load_dword v35, v[40:41], off
	global_load_dword v36, v[42:43], off
	global_load_dword v37, v[44:45], off
	s_nop 0
	global_load_dword v30, v[30:31], off
	s_waitcnt vmcnt(30)
; #define LAS __attribute__((address_space(3)))
; __device__ __forceinline__ unsigned pk2(float lo, float hi) { return f2bf(lo) | (f2bf(hi) << 16); }
; __device__ __forceinline__ void p0_transpose_item(const float* W, int K, int N, bf16_t* WT, int dest_row0, const float* gain, LAS float* scr, int k0, int n0, int lane) {
;     ...
;     for (int i = 0; i < 32; ++i) { const int kk = 2 * i + (lane >> 5); scr[kk * 33 + (lane & 31)] = wv[i]; }
;     asm volatile("s_waitcnt lgkmcnt(0)" ::: "memory");
;     const int c = lane & 7;
; #pragma unroll
;     for (int j = 0; j < 4; ++j) { const int n = (lane >> 3) + 8 * j; const LAS float* s = scr + (8 * c) * 33 + n;
;         u32x4 o; o.x = pk2(s[0 * 33], s[1 * 33]); o.y = pk2(s[2 * 33], s[3 * 33]); o.z = pk2(s[4 * 33], s[5 * 33]); o.w = pk2(s[6 * 33], s[7 * 33]);
;         *(u32x4*)(WT + (size_t)(dest_row0 + n) * K + k0 + 8 * c) = o; }
;     asm volatile("s_waitcnt lgkmcnt(0)" ::: "memory");
	ds_write2_b32 v63, v48, v49 offset1:66
	s_waitcnt vmcnt(28)
	ds_write2_b32 v63, v50, v51 offset0:132 offset1:198
	s_waitcnt vmcnt(26)
	ds_write2_b32 v69, v52, v53 offset0:8 offset1:74
	s_waitcnt vmcnt(24)
	ds_write2_b32 v69, v54, v55 offset0:140 offset1:206
	s_waitcnt vmcnt(22)
	ds_write2_b32 v70, v56, v57 offset0:16 offset1:82
	s_waitcnt vmcnt(20)
	ds_write2_b32 v70, v58, v59 offset0:148 offset1:214
	s_waitcnt vmcnt(18)
	ds_write2_b32 v71, v60, v61 offset0:24 offset1:90
	s_waitcnt vmcnt(16)
	ds_write2_b32 v71, v77, v78 offset0:156 offset1:222
	s_waitcnt vmcnt(14)
	ds_write2_b32 v72, v79, v80 offset0:32 offset1:98
	s_waitcnt vmcnt(12)
	ds_write2_b32 v72, v81, v82 offset0:164 offset1:230
	s_waitcnt vmcnt(10)
	ds_write2_b32 v73, v83, v84 offset0:40 offset1:106
	s_waitcnt vmcnt(8)
	ds_write2_b32 v73, v85, v86 offset0:172 offset1:238
	s_waitcnt vmcnt(6)
	ds_write2_b32 v74, v0, v32 offset0:48 offset1:114
	s_waitcnt vmcnt(4)
	ds_write2_b32 v74, v33, v34 offset0:180 offset1:246
	s_waitcnt vmcnt(2)
	ds_write2_b32 v75, v35, v36 offset0:56 offset1:122
	s_waitcnt vmcnt(0)
	ds_write2_b32 v75, v37, v30 offset0:188 offset1:254
	s_waitcnt lgkmcnt(0)
	ds_read2_b32 v[34:35], v65 offset1:8
	ds_read2_b32 v[38:39], v65 offset0:33 offset1:41
	ds_read2_b32 v[40:41], v65 offset0:66 offset1:74
	ds_read2_b32 v[42:43], v65 offset0:99 offset1:107
	ds_read2_b32 v[44:45], v65 offset0:132 offset1:140
	s_waitcnt lgkmcnt(4)
	v_bfe_u32 v0, v34, 16, 1
	v_add3_u32 v0, v34, v0, s24
	s_waitcnt lgkmcnt(3)
	v_bfe_u32 v30, v38, 16, 1
	v_lshrrev_b32_e32 v0, 16, v0
	v_add3_u32 v30, v38, v30, s24
	ds_read2_b32 v[46:47], v65 offset0:165 offset1:173
	v_and_or_b32 v30, v30, s25, v0
	s_waitcnt lgkmcnt(3)
	v_bfe_u32 v0, v40, 16, 1
	v_add3_u32 v0, v40, v0, s24
	s_waitcnt lgkmcnt(2)
	v_bfe_u32 v31, v42, 16, 1
	ds_read2_b32 v[48:49], v65 offset0:198 offset1:206
	v_lshrrev_b32_e32 v0, 16, v0
	v_add3_u32 v31, v42, v31, s24
	ds_read2_b32 v[50:51], v65 offset0:231 offset1:239
	v_and_or_b32 v31, v31, s25, v0
	s_waitcnt lgkmcnt(3)
	v_bfe_u32 v0, v44, 16, 1
	v_add3_u32 v0, v44, v0, s24
	s_waitcnt lgkmcnt(2)
	v_bfe_u32 v32, v46, 16, 1
	v_lshrrev_b32_e32 v0, 16, v0
	v_add3_u32 v32, v46, v32, s24
	v_and_or_b32 v32, v32, s25, v0
	s_waitcnt lgkmcnt(1)
	v_bfe_u32 v0, v48, 16, 1
	v_add3_u32 v0, v48, v0, s24
	s_waitcnt lgkmcnt(0)
	v_bfe_u32 v33, v50, 16, 1
	v_lshrrev_b32_e32 v0, 16, v0
	v_add3_u32 v33, v50, v33, s24
	s_mov_b32 s9, s5
	v_and_or_b32 v33, v33, s25, v0
	v_or_b32_e32 v0, s10, v64
	v_lshl_add_u64 v[36:37], s[8:9], 1, v[12:13]
	v_lshlrev_b32_e32 v0, 10, v0
	v_lshl_add_u64 v[52:53], v[36:37], 0, v[0:1]
	v_bfe_u32 v0, v35, 16, 1
	global_store_dwordx4 v[52:53], v[30:33], off sc1
	v_add3_u32 v0, v35, v0, s24
	v_lshrrev_b32_e32 v0, 16, v0
	v_bfe_u32 v30, v39, 16, 1
	v_add3_u32 v30, v39, v30, s24
	v_and_or_b32 v30, v30, s25, v0
	v_bfe_u32 v0, v41, 16, 1
	v_add3_u32 v0, v41, v0, s24
	v_bfe_u32 v31, v43, 16, 1
	v_lshrrev_b32_e32 v0, 16, v0
	v_add3_u32 v31, v43, v31, s24
	v_and_or_b32 v31, v31, s25, v0
	v_bfe_u32 v0, v45, 16, 1
	v_add3_u32 v0, v45, v0, s24
	v_bfe_u32 v32, v47, 16, 1
	v_lshrrev_b32_e32 v0, 16, v0
	v_add3_u32 v32, v47, v32, s24
	v_and_or_b32 v32, v32, s25, v0
	v_bfe_u32 v0, v49, 16, 1
	v_add3_u32 v0, v49, v0, s24
	v_bfe_u32 v33, v51, 16, 1
	v_lshrrev_b32_e32 v0, 16, v0
	v_add3_u32 v33, v51, v33, s24
	v_and_or_b32 v33, v33, s25, v0
	v_or_b32_e32 v0, s10, v66
	v_lshlrev_b32_e32 v0, 10, v0
	ds_read2_b32 v[34:35], v65 offset0:16 offset1:24
	v_lshl_add_u64 v[38:39], v[36:37], 0, v[0:1]
	global_store_dwordx4 v[38:39], v[30:33], off sc1
	ds_read2_b32 v[38:39], v65 offset0:49 offset1:57
	ds_read2_b32 v[40:41], v65 offset0:82 offset1:90
	ds_read2_b32 v[42:43], v65 offset0:115 offset1:123
	s_waitcnt lgkmcnt(3)
	v_bfe_u32 v0, v34, 16, 1
	v_add3_u32 v0, v34, v0, s24
	s_waitcnt lgkmcnt(2)
	v_bfe_u32 v30, v38, 16, 1
	ds_read2_b32 v[44:45], v65 offset0:148 offset1:156
	v_lshrrev_b32_e32 v0, 16, v0
	v_add3_u32 v30, v38, v30, s24
	ds_read2_b32 v[46:47], v65 offset0:181 offset1:189
	v_and_or_b32 v30, v30, s25, v0
	s_waitcnt lgkmcnt(3)
	v_bfe_u32 v0, v40, 16, 1
	v_add3_u32 v0, v40, v0, s24
	s_waitcnt lgkmcnt(2)
	v_bfe_u32 v31, v42, 16, 1
	ds_read2_b32 v[48:49], v65 offset0:214 offset1:222
	v_lshrrev_b32_e32 v0, 16, v0
	v_add3_u32 v31, v42, v31, s24
	ds_read2_b32 v[50:51], v65 offset0:247 offset1:255
	v_and_or_b32 v31, v31, s25, v0
	s_waitcnt lgkmcnt(3)
	v_bfe_u32 v0, v44, 16, 1
	v_add3_u32 v0, v44, v0, s24
	s_waitcnt lgkmcnt(2)
	v_bfe_u32 v32, v46, 16, 1
	v_lshrrev_b32_e32 v0, 16, v0
	v_add3_u32 v32, v46, v32, s24
	v_and_or_b32 v32, v32, s25, v0
	s_waitcnt lgkmcnt(1)
	v_bfe_u32 v0, v48, 16, 1
	v_add3_u32 v0, v48, v0, s24
	s_waitcnt lgkmcnt(0)
	v_bfe_u32 v33, v50, 16, 1
	v_lshrrev_b32_e32 v0, 16, v0
	v_add3_u32 v33, v50, v33, s24
	v_and_or_b32 v33, v33, s25, v0
	v_or_b32_e32 v0, s10, v67
	v_lshlrev_b32_e32 v0, 10, v0
	v_lshl_add_u64 v[52:53], v[36:37], 0, v[0:1]
	v_bfe_u32 v0, v35, 16, 1
	global_store_dwordx4 v[52:53], v[30:33], off sc1
	v_add3_u32 v0, v35, v0, s24
	v_lshrrev_b32_e32 v0, 16, v0
	v_bfe_u32 v30, v39, 16, 1
	v_add3_u32 v30, v39, v30, s24
	v_and_or_b32 v30, v30, s25, v0
	v_bfe_u32 v0, v41, 16, 1
	v_add3_u32 v0, v41, v0, s24
	v_bfe_u32 v31, v43, 16, 1
	v_lshrrev_b32_e32 v0, 16, v0
	v_add3_u32 v31, v43, v31, s24
	v_and_or_b32 v31, v31, s25, v0
	v_bfe_u32 v0, v45, 16, 1
	v_add3_u32 v0, v45, v0, s24
	v_bfe_u32 v32, v47, 16, 1
	v_lshrrev_b32_e32 v0, 16, v0
	v_add3_u32 v32, v47, v32, s24
	v_and_or_b32 v32, v32, s25, v0
	v_bfe_u32 v0, v49, 16, 1
	v_add3_u32 v0, v49, v0, s24
	v_bfe_u32 v33, v51, 16, 1
	v_lshrrev_b32_e32 v0, 16, v0
	v_add3_u32 v33, v51, v33, s24
	v_and_or_b32 v33, v33, s25, v0
	v_or_b32_e32 v0, s10, v68
	v_lshlrev_b32_e32 v0, 10, v0
	v_lshl_add_u64 v[34:35], v[36:37], 0, v[0:1]
	global_store_dwordx4 v[34:35], v[30:33], off sc1
	s_waitcnt lgkmcnt(0)

; #define LAS __attribute__((address_space(3)))
; __device__ __forceinline__ unsigned pk2(float lo, float hi) { return f2bf(lo) | (f2bf(hi) << 16); }
; __device__ __forceinline__ void p0_transpose_item(const float* W, int K, int N, bf16_t* WT, int dest_row0, const float* gain, LAS float* scr, int k0, int n0, int lane) {
;     ...
;     for (int i = 0; i < 32; ++i) { const int kk = 2 * i + (lane >> 5); scr[kk * 33 + (lane & 31)] = wv[i]; }
;     asm volatile("s_waitcnt lgkmcnt(0)" ::: "memory");
;     const int c = lane & 7;
; #pragma unroll
;     for (int j = 0; j < 4; ++j) { const int n = (lane >> 3) + 8 * j; const LAS float* s = scr + (8 * c) * 33 + n;
;         u32x4 o; o.x = pk2(s[0 * 33], s[1 * 33]); o.y = pk2(s[2 * 33], s[3 * 33]); o.z = pk2(s[4 * 33], s[5 * 33]); o.w = pk2(s[6 * 33], s[7 * 33]);
;         *(u32x4*)(WT + (size_t)(dest_row0 + n) * K + k0 + 8 * c) = o; }
;     asm volatile("s_waitcnt lgkmcnt(0)" ::: "memory");
.LBB0_411:
	s_waitcnt vmcnt(30)
	ds_write2_b32 v63, v30, v31 offset1:66
	s_waitcnt vmcnt(28)
	ds_write2_b32 v63, v32, v33 offset0:132 offset1:198
	s_waitcnt vmcnt(26)
	ds_write2_b32 v69, v34, v35 offset0:8 offset1:74
	s_waitcnt vmcnt(24)
	ds_write2_b32 v69, v36, v37 offset0:140 offset1:206
	s_waitcnt vmcnt(22)
	ds_write2_b32 v70, v38, v39 offset0:16 offset1:82
	s_waitcnt vmcnt(20)
	ds_write2_b32 v70, v40, v41 offset0:148 offset1:214
	s_waitcnt vmcnt(18)
	ds_write2_b32 v71, v42, v43 offset0:24 offset1:90
	s_waitcnt vmcnt(16)
	ds_write2_b32 v71, v44, v45 offset0:156 offset1:222
	s_waitcnt vmcnt(14)
	ds_write2_b32 v72, v46, v47 offset0:32 offset1:98
	s_waitcnt vmcnt(12)
	ds_write2_b32 v72, v48, v49 offset0:164 offset1:230
	s_waitcnt vmcnt(10)
	ds_write2_b32 v73, v50, v51 offset0:40 offset1:106
	s_waitcnt vmcnt(8)
	ds_write2_b32 v73, v52, v53 offset0:172 offset1:238
	s_waitcnt vmcnt(6)
	ds_write2_b32 v74, v54, v55 offset0:48 offset1:114
	s_waitcnt vmcnt(4)
	ds_write2_b32 v74, v56, v57 offset0:180 offset1:246
	s_waitcnt vmcnt(2)
	ds_write2_b32 v75, v60, v61 offset0:56 offset1:122
	s_waitcnt vmcnt(0)
	ds_write2_b32 v75, v58, v59 offset0:188 offset1:254
	s_waitcnt lgkmcnt(0)
	ds_read2_b32 v[34:35], v65 offset1:8
	ds_read2_b32 v[38:39], v65 offset0:33 offset1:41
	ds_read2_b32 v[40:41], v65 offset0:66 offset1:74
	ds_read2_b32 v[42:43], v65 offset0:99 offset1:107
	ds_read2_b32 v[44:45], v65 offset0:132 offset1:140
	s_waitcnt lgkmcnt(4)
	v_bfe_u32 v0, v34, 16, 1
	v_add3_u32 v0, v34, v0, s24
	s_waitcnt lgkmcnt(3)
	v_bfe_u32 v30, v38, 16, 1
	v_lshrrev_b32_e32 v0, 16, v0
	v_add3_u32 v30, v38, v30, s24
	ds_read2_b32 v[46:47], v65 offset0:165 offset1:173
	v_and_or_b32 v30, v30, s25, v0
	s_waitcnt lgkmcnt(3)
	v_bfe_u32 v0, v40, 16, 1
	v_add3_u32 v0, v40, v0, s24
	s_waitcnt lgkmcnt(2)
	v_bfe_u32 v31, v42, 16, 1
	ds_read2_b32 v[48:49], v65 offset0:198 offset1:206
	v_lshrrev_b32_e32 v0, 16, v0
	v_add3_u32 v31, v42, v31, s24
	ds_read2_b32 v[50:51], v65 offset0:231 offset1:239
	v_and_or_b32 v31, v31, s25, v0
	s_waitcnt lgkmcnt(3)
	v_bfe_u32 v0, v44, 16, 1
	v_add3_u32 v0, v44, v0, s24
	s_waitcnt lgkmcnt(2)
	v_bfe_u32 v32, v46, 16, 1
	v_lshrrev_b32_e32 v0, 16, v0
	v_add3_u32 v32, v46, v32, s24
	v_and_or_b32 v32, v32, s25, v0
	s_waitcnt lgkmcnt(1)
	v_bfe_u32 v0, v48, 16, 1
	v_add3_u32 v0, v48, v0, s24
	s_waitcnt lgkmcnt(0)
	v_bfe_u32 v33, v50, 16, 1
	v_lshrrev_b32_e32 v0, 16, v0
	v_add3_u32 v33, v50, v33, s24
	s_mov_b32 s9, s5
	v_and_or_b32 v33, v33, s25, v0
	v_or_b32_e32 v0, s10, v64
	v_lshl_add_u64 v[36:37], s[8:9], 1, v[16:17]
	v_lshlrev_b32_e32 v0, 11, v0
	v_lshl_add_u64 v[52:53], v[36:37], 0, v[0:1]
	v_bfe_u32 v0, v35, 16, 1
	global_store_dwordx4 v[52:53], v[30:33], off sc1
	v_add3_u32 v0, v35, v0, s24
	v_lshrrev_b32_e32 v0, 16, v0
	v_bfe_u32 v30, v39, 16, 1
	v_add3_u32 v30, v39, v30, s24
	v_and_or_b32 v30, v30, s25, v0
	v_bfe_u32 v0, v41, 16, 1
	v_add3_u32 v0, v41, v0, s24
	v_bfe_u32 v31, v43, 16, 1
	v_lshrrev_b32_e32 v0, 16, v0
	v_add3_u32 v31, v43, v31, s24
	v_and_or_b32 v31, v31, s25, v0
	v_bfe_u32 v0, v45, 16, 1
	v_add3_u32 v0, v45, v0, s24
	v_bfe_u32 v32, v47, 16, 1
	v_lshrrev_b32_e32 v0, 16, v0
	v_add3_u32 v32, v47, v32, s24
	v_and_or_b32 v32, v32, s25, v0
	v_bfe_u32 v0, v49, 16, 1
	v_add3_u32 v0, v49, v0, s24
	v_bfe_u32 v33, v51, 16, 1
	v_lshrrev_b32_e32 v0, 16, v0
	v_add3_u32 v33, v51, v33, s24
	v_and_or_b32 v33, v33, s25, v0
	v_or_b32_e32 v0, s10, v66
	v_lshlrev_b32_e32 v0, 11, v0
	ds_read2_b32 v[34:35], v65 offset0:16 offset1:24
	v_lshl_add_u64 v[38:39], v[36:37], 0, v[0:1]
	global_store_dwordx4 v[38:39], v[30:33], off sc1
	ds_read2_b32 v[38:39], v65 offset0:49 offset1:57
	ds_read2_b32 v[40:41], v65 offset0:82 offset1:90
	ds_read2_b32 v[42:43], v65 offset0:115 offset1:123
	s_waitcnt lgkmcnt(3)
	v_bfe_u32 v0, v34, 16, 1
	v_add3_u32 v0, v34, v0, s24
	s_waitcnt lgkmcnt(2)
	v_bfe_u32 v30, v38, 16, 1
	ds_read2_b32 v[44:45], v65 offset0:148 offset1:156
	v_lshrrev_b32_e32 v0, 16, v0
	v_add3_u32 v30, v38, v30, s24
	ds_read2_b32 v[46:47], v65 offset0:181 offset1:189
	v_and_or_b32 v30, v30, s25, v0
	s_waitcnt lgkmcnt(3)
	v_bfe_u32 v0, v40, 16, 1
	v_add3_u32 v0, v40, v0, s24
	s_waitcnt lgkmcnt(2)
	v_bfe_u32 v31, v42, 16, 1
	ds_read2_b32 v[48:49], v65 offset0:214 offset1:222
	v_lshrrev_b32_e32 v0, 16, v0
	v_add3_u32 v31, v42, v31, s24
	ds_read2_b32 v[50:51], v65 offset0:247 offset1:255
	v_and_or_b32 v31, v31, s25, v0
	s_waitcnt lgkmcnt(3)
	v_bfe_u32 v0, v44, 16, 1
	v_add3_u32 v0, v44, v0, s24
	s_waitcnt lgkmcnt(2)
	v_bfe_u32 v32, v46, 16, 1
	v_lshrrev_b32_e32 v0, 16, v0
	v_add3_u32 v32, v46, v32, s24
	v_and_or_b32 v32, v32, s25, v0
	s_waitcnt lgkmcnt(1)
	v_bfe_u32 v0, v48, 16, 1
	v_add3_u32 v0, v48, v0, s24
	s_waitcnt lgkmcnt(0)
	v_bfe_u32 v33, v50, 16, 1
	v_lshrrev_b32_e32 v0, 16, v0
	v_add3_u32 v33, v50, v33, s24
	v_and_or_b32 v33, v33, s25, v0
	v_or_b32_e32 v0, s10, v67
	v_lshlrev_b32_e32 v0, 11, v0
	v_lshl_add_u64 v[52:53], v[36:37], 0, v[0:1]
	v_bfe_u32 v0, v35, 16, 1
	global_store_dwordx4 v[52:53], v[30:33], off sc1
	v_add3_u32 v0, v35, v0, s24
	v_lshrrev_b32_e32 v0, 16, v0
	v_bfe_u32 v30, v39, 16, 1
	v_add3_u32 v30, v39, v30, s24
	v_and_or_b32 v30, v30, s25, v0
	v_bfe_u32 v0, v41, 16, 1
	v_add3_u32 v0, v41, v0, s24
	v_bfe_u32 v31, v43, 16, 1
	v_lshrrev_b32_e32 v0, 16, v0
	v_add3_u32 v31, v43, v31, s24
	v_and_or_b32 v31, v31, s25, v0
	v_bfe_u32 v0, v45, 16, 1
	v_add3_u32 v0, v45, v0, s24
	v_bfe_u32 v32, v47, 16, 1
	v_lshrrev_b32_e32 v0, 16, v0
	v_add3_u32 v32, v47, v32, s24
	v_and_or_b32 v32, v32, s25, v0
	v_bfe_u32 v0, v49, 16, 1
	v_add3_u32 v0, v49, v0, s24
	v_bfe_u32 v33, v51, 16, 1
	v_lshrrev_b32_e32 v0, 16, v0
	v_add3_u32 v33, v51, v33, s24
	v_and_or_b32 v33, v33, s25, v0
	v_or_b32_e32 v0, s10, v68
	v_lshlrev_b32_e32 v0, 11, v0
	v_lshl_add_u64 v[34:35], v[36:37], 0, v[0:1]
	global_store_dwordx4 v[34:35], v[30:33], off sc1
	s_waitcnt lgkmcnt(0)

; #define LAS __attribute__((address_space(3)))
; __device__ __forceinline__ void p0_transpose_item(const float* W, int K, int N, bf16_t* WT, int dest_row0, const float* gain, LAS float* scr, int k0, int n0, int lane) {
;     float wv[32];
; #pragma unroll
;     for (int i = 0; i < 32; ++i) { const int kk = 2 * i + (lane >> 5); wv[i] = W[(size_t)(k0 + kk) * N + n0 + (lane & 31)]; }
;     if (gain) {
; #pragma unroll
;         for (int i = 0; i < 32; ++i) wv[i] *= gain[k0 + 2 * i + (lane >> 5)]; }
; #pragma unroll
;     for (int i = 0; i < 32; ++i) { const int kk = 2 * i + (lane >> 5); scr[kk * 33 + (lane & 31)] = wv[i]; }
; __device__ __forceinline__ void transpose_items(Frame& F, int it0, int it1, int gw, int NGW) {
;     ...
;     for (int it = it0 + gw; it < it1; it += NGW) {
;         int r = it;
;         if (r < I_IN) { const int kb = r / 88, nb = r % 88; p0_transpose_item(F.w_in, D, INW, Win_t, win_dest(32 * nb), nullptr, scr, 64 * kb, 32 * nb, F.lane); continue; } r -= I_IN;
;         if (r < I_KV) { const int kb = r / 32, nb = r % 32; p0_transpose_item(F.wkv, D, D, Wkv_t, 32 * nb, nullptr, scr, 64 * kb, 32 * nb, F.lane); continue; } r -= I_KV;
;         if (r < I_OUT) { const int kb = r / 32, nb = r % 32; p0_transpose_item(F.w_out, D, D, Wout_t, 32 * nb, nullptr, scr, 64 * kb, 32 * nb, F.lane); continue; } r -= I_OUT;
;         if (r < I_Q) { const int kb = r / 16, nb = r % 16; p0_transpose_item(F.wq, D, 512, Wq_t, 32 * nb, F.g2, scr, 64 * kb, 32 * nb, F.lane); continue; } r -= I_Q;
;         if (r < I_O) { const int kb = r / 32, nb = r % 32; p0_transpose_item(F.wo, 512, D, Wo_t, 32 * nb, nullptr, scr, 64 * kb, 32 * nb, F.lane); continue; } r -= I_O;
;         if (r < I_UP) { const int kb = r / 128, nb = r % 128; p0_transpose_item(F.wup, D, FF, Wup_t, 32 * nb, F.g3, scr, 64 * kb, 32 * nb, F.lane); continue; } r -= I_UP;
;         { const int kb = r / 32, nb = r % 32; p0_transpose_item(F.wdn, FF, D, Wdn_t, 32 * nb, nullptr, scr, 64 * kb, 32 * nb, F.lane); }
.LBB0_413:
	s_andn2_b64 vcc, exec, s[8:9]
	s_cbranch_vccnz .LBB0_415
	s_and_b32 s4, s20, 0x1fc0
	s_add_i32 s8, s4, 0xfffff100
	s_and_b32 s10, s16, 0x3e0
	v_or_b32_e32 v0, s8, v62
	s_lshl_b32 s4, s10, 2
	v_or_b32_e32 v34, 2, v0
	v_mov_b32_e32 v35, v1
	v_or_b32_e32 v36, 4, v0
	v_mov_b32_e32 v37, v1
	v_or_b32_e32 v38, 6, v0
	v_mov_b32_e32 v39, v1
	v_or_b32_e32 v40, 8, v0
	v_mov_b32_e32 v41, v1
	v_or_b32_e32 v42, 10, v0
	v_mov_b32_e32 v43, v1
	v_or_b32_e32 v44, 12, v0
	v_mov_b32_e32 v45, v1
	v_lshl_add_u64 v[30:31], v[18:19], 0, s[4:5]
	v_lshlrev_b64 v[32:33], 12, v[0:1]
	v_lshlrev_b64 v[34:35], 12, v[34:35]
	v_lshlrev_b64 v[36:37], 12, v[36:37]
	v_lshlrev_b64 v[38:39], 12, v[38:39]
	v_lshlrev_b64 v[40:41], 12, v[40:41]
	v_lshlrev_b64 v[42:43], 12, v[42:43]
	v_lshlrev_b64 v[44:45], 12, v[44:45]
	v_or_b32_e32 v46, 14, v0
	v_mov_b32_e32 v47, v1
	v_lshl_add_u64 v[32:33], v[30:31], 0, v[32:33]
	v_lshl_add_u64 v[34:35], v[30:31], 0, v[34:35]
	v_lshl_add_u64 v[36:37], v[30:31], 0, v[36:37]
	v_lshl_add_u64 v[38:39], v[30:31], 0, v[38:39]
	v_lshl_add_u64 v[40:41], v[30:31], 0, v[40:41]
	v_lshl_add_u64 v[42:43], v[30:31], 0, v[42:43]
	v_lshl_add_u64 v[44:45], v[30:31], 0, v[44:45]
	v_lshlrev_b64 v[46:47], 12, v[46:47]
	v_lshl_add_u64 v[46:47], v[30:31], 0, v[46:47]
	global_load_dword v48, v[32:33], off
	global_load_dword v49, v[34:35], off
	global_load_dword v50, v[36:37], off
	global_load_dword v51, v[38:39], off
	global_load_dword v52, v[40:41], off
	global_load_dword v53, v[42:43], off
	global_load_dword v54, v[44:45], off
	global_load_dword v55, v[46:47], off
	v_or_b32_e32 v32, 16, v0
	v_mov_b32_e32 v33, v1
	v_or_b32_e32 v34, 18, v0
	v_mov_b32_e32 v35, v1
	v_or_b32_e32 v36, 20, v0
	v_mov_b32_e32 v37, v1
	v_or_b32_e32 v38, 22, v0
	v_mov_b32_e32 v39, v1
	v_or_b32_e32 v40, 24, v0
	v_mov_b32_e32 v41, v1
	v_or_b32_e32 v42, 26, v0
	v_mov_b32_e32 v43, v1
	v_or_b32_e32 v44, 28, v0
	v_mov_b32_e32 v45, v1
	v_lshlrev_b64 v[32:33], 12, v[32:33]
	v_lshlrev_b64 v[34:35], 12, v[34:35]
	v_lshlrev_b64 v[36:37], 12, v[36:37]
	v_lshlrev_b64 v[38:39], 12, v[38:39]
	v_lshlrev_b64 v[40:41], 12, v[40:41]
	v_lshlrev_b64 v[42:43], 12, v[42:43]
	v_lshlrev_b64 v[44:45], 12, v[44:45]
	v_or_b32_e32 v46, 30, v0
	v_mov_b32_e32 v47, v1
	v_lshl_add_u64 v[32:33], v[30:31], 0, v[32:33]
	v_lshl_add_u64 v[34:35], v[30:31], 0, v[34:35]
	v_lshl_add_u64 v[36:37], v[30:31], 0, v[36:37]
	v_lshl_add_u64 v[38:39], v[30:31], 0, v[38:39]
	v_lshl_add_u64 v[40:41], v[30:31], 0, v[40:41]
	v_lshl_add_u64 v[42:43], v[30:31], 0, v[42:43]
	v_lshl_add_u64 v[44:45], v[30:31], 0, v[44:45]
	v_lshlrev_b64 v[46:47], 12, v[46:47]
	v_lshl_add_u64 v[46:47], v[30:31], 0, v[46:47]
	global_load_dword v56, v[32:33], off
	global_load_dword v57, v[34:35], off
	global_load_dword v58, v[36:37], off
	global_load_dword v59, v[38:39], off
	global_load_dword v60, v[40:41], off
	global_load_dword v61, v[42:43], off
	global_load_dword v77, v[44:45], off
	global_load_dword v78, v[46:47], off
	v_or_b32_e32 v32, 32, v0
	v_mov_b32_e32 v33, v1
	v_or_b32_e32 v34, 34, v0
	v_mov_b32_e32 v35, v1
	v_or_b32_e32 v36, 36, v0
	v_mov_b32_e32 v37, v1
	v_or_b32_e32 v38, 38, v0
	v_mov_b32_e32 v39, v1
	v_or_b32_e32 v40, 40, v0
	v_mov_b32_e32 v41, v1
	v_or_b32_e32 v42, 42, v0
	v_mov_b32_e32 v43, v1
	v_or_b32_e32 v44, 44, v0
	v_mov_b32_e32 v45, v1
	v_lshlrev_b64 v[32:33], 12, v[32:33]
	v_lshlrev_b64 v[34:35], 12, v[34:35]
	v_lshlrev_b64 v[36:37], 12, v[36:37]
	v_lshlrev_b64 v[38:39], 12, v[38:39]
	v_lshlrev_b64 v[40:41], 12, v[40:41]
	v_lshlrev_b64 v[42:43], 12, v[42:43]
	v_lshlrev_b64 v[44:45], 12, v[44:45]
	v_or_b32_e32 v46, 46, v0
	v_mov_b32_e32 v47, v1
	v_lshl_add_u64 v[32:33], v[30:31], 0, v[32:33]
	v_lshl_add_u64 v[34:35], v[30:31], 0, v[34:35]
	v_lshl_add_u64 v[36:37], v[30:31], 0, v[36:37]
	v_lshl_add_u64 v[38:39], v[30:31], 0, v[38:39]
	v_lshl_add_u64 v[40:41], v[30:31], 0, v[40:41]
	v_lshl_add_u64 v[42:43], v[30:31], 0, v[42:43]
	v_lshl_add_u64 v[44:45], v[30:31], 0, v[44:45]
	v_lshlrev_b64 v[46:47], 12, v[46:47]
	v_lshl_add_u64 v[46:47], v[30:31], 0, v[46:47]
	global_load_dword v79, v[32:33], off
	global_load_dword v80, v[34:35], off
	global_load_dword v81, v[36:37], off
	global_load_dword v82, v[38:39], off
	global_load_dword v83, v[40:41], off
	global_load_dword v84, v[42:43], off
	global_load_dword v85, v[44:45], off
	global_load_dword v86, v[46:47], off
	v_or_b32_e32 v32, 48, v0
	v_mov_b32_e32 v33, v1
	v_or_b32_e32 v34, 50, v0
	v_mov_b32_e32 v35, v1
	v_or_b32_e32 v36, 52, v0
	v_mov_b32_e32 v37, v1
	v_or_b32_e32 v38, 54, v0
	v_mov_b32_e32 v39, v1
	v_or_b32_e32 v40, 56, v0
	v_mov_b32_e32 v41, v1
	v_or_b32_e32 v42, 58, v0
	v_mov_b32_e32 v43, v1
	v_or_b32_e32 v44, 60, v0
	v_mov_b32_e32 v45, v1
	v_or_b32_e32 v0, 62, v0
	v_lshlrev_b64 v[32:33], 12, v[32:33]
	v_lshlrev_b64 v[34:35], 12, v[34:35]
	v_lshlrev_b64 v[36:37], 12, v[36:37]
	v_lshlrev_b64 v[38:39], 12, v[38:39]
	v_lshlrev_b64 v[40:41], 12, v[40:41]
	v_lshlrev_b64 v[42:43], 12, v[42:43]
	v_lshlrev_b64 v[44:45], 12, v[44:45]
	v_lshlrev_b64 v[46:47], 12, v[0:1]
	v_lshl_add_u64 v[32:33], v[30:31], 0, v[32:33]
	v_lshl_add_u64 v[34:35], v[30:31], 0, v[34:35]
	v_lshl_add_u64 v[36:37], v[30:31], 0, v[36:37]
	v_lshl_add_u64 v[38:39], v[30:31], 0, v[38:39]
	v_lshl_add_u64 v[40:41], v[30:31], 0, v[40:41]
	v_lshl_add_u64 v[42:43], v[30:31], 0, v[42:43]
	v_lshl_add_u64 v[44:45], v[30:31], 0, v[44:45]
	v_lshl_add_u64 v[30:31], v[30:31], 0, v[46:47]
	global_load_dword v0, v[32:33], off
	s_nop 0
	global_load_dword v32, v[34:35], off
	global_load_dword v33, v[36:37], off
	s_nop 0
	global_load_dword v34, v[38:39], off
	global_load_dword v35, v[40:41], off
	global_load_dword v36, v[42:43], off
	global_load_dword v37, v[44:45], off
	s_nop 0
	global_load_dword v30, v[30:31], off
	s_waitcnt vmcnt(30)
; #define LAS __attribute__((address_space(3)))
; __device__ __forceinline__ unsigned pk2(float lo, float hi) { return f2bf(lo) | (f2bf(hi) << 16); }
; __device__ __forceinline__ void p0_transpose_item(const float* W, int K, int N, bf16_t* WT, int dest_row0, const float* gain, LAS float* scr, int k0, int n0, int lane) {
;     ...
;     for (int i = 0; i < 32; ++i) { const int kk = 2 * i + (lane >> 5); scr[kk * 33 + (lane & 31)] = wv[i]; }
;     asm volatile("s_waitcnt lgkmcnt(0)" ::: "memory");
;     const int c = lane & 7;
; #pragma unroll
;     for (int j = 0; j < 4; ++j) { const int n = (lane >> 3) + 8 * j; const LAS float* s = scr + (8 * c) * 33 + n;
;         u32x4 o; o.x = pk2(s[0 * 33], s[1 * 33]); o.y = pk2(s[2 * 33], s[3 * 33]); o.z = pk2(s[4 * 33], s[5 * 33]); o.w = pk2(s[6 * 33], s[7 * 33]);
;         *(u32x4*)(WT + (size_t)(dest_row0 + n) * K + k0 + 8 * c) = o; }
;     asm volatile("s_waitcnt lgkmcnt(0)" ::: "memory");
	ds_write2_b32 v63, v48, v49 offset1:66
	s_waitcnt vmcnt(28)
	ds_write2_b32 v63, v50, v51 offset0:132 offset1:198
	s_waitcnt vmcnt(26)
	ds_write2_b32 v69, v52, v53 offset0:8 offset1:74
	s_waitcnt vmcnt(24)
	ds_write2_b32 v69, v54, v55 offset0:140 offset1:206
	s_waitcnt vmcnt(22)
	ds_write2_b32 v70, v56, v57 offset0:16 offset1:82
	s_waitcnt vmcnt(20)
	ds_write2_b32 v70, v58, v59 offset0:148 offset1:214
	s_waitcnt vmcnt(18)
	ds_write2_b32 v71, v60, v61 offset0:24 offset1:90
	s_waitcnt vmcnt(16)
	ds_write2_b32 v71, v77, v78 offset0:156 offset1:222
	s_waitcnt vmcnt(14)
	ds_write2_b32 v72, v79, v80 offset0:32 offset1:98
	s_waitcnt vmcnt(12)
	ds_write2_b32 v72, v81, v82 offset0:164 offset1:230
	s_waitcnt vmcnt(10)
	ds_write2_b32 v73, v83, v84 offset0:40 offset1:106
	s_waitcnt vmcnt(8)
	ds_write2_b32 v73, v85, v86 offset0:172 offset1:238
	s_waitcnt vmcnt(6)
	ds_write2_b32 v74, v0, v32 offset0:48 offset1:114
	s_waitcnt vmcnt(4)
	ds_write2_b32 v74, v33, v34 offset0:180 offset1:246
	s_waitcnt vmcnt(2)
	ds_write2_b32 v75, v35, v36 offset0:56 offset1:122
	s_waitcnt vmcnt(0)
	ds_write2_b32 v75, v37, v30 offset0:188 offset1:254
	s_waitcnt lgkmcnt(0)
	ds_read2_b32 v[34:35], v65 offset1:8
	ds_read2_b32 v[38:39], v65 offset0:33 offset1:41
	ds_read2_b32 v[40:41], v65 offset0:66 offset1:74
	ds_read2_b32 v[42:43], v65 offset0:99 offset1:107
	ds_read2_b32 v[44:45], v65 offset0:132 offset1:140
	s_waitcnt lgkmcnt(4)
	v_bfe_u32 v0, v34, 16, 1
	v_add3_u32 v0, v34, v0, s24
	s_waitcnt lgkmcnt(3)
	v_bfe_u32 v30, v38, 16, 1
	v_lshrrev_b32_e32 v0, 16, v0
	v_add3_u32 v30, v38, v30, s24
	ds_read2_b32 v[46:47], v65 offset0:165 offset1:173
	v_and_or_b32 v30, v30, s25, v0
	s_waitcnt lgkmcnt(3)
	v_bfe_u32 v0, v40, 16, 1
	v_add3_u32 v0, v40, v0, s24
	s_waitcnt lgkmcnt(2)
	v_bfe_u32 v31, v42, 16, 1
	ds_read2_b32 v[48:49], v65 offset0:198 offset1:206
	v_lshrrev_b32_e32 v0, 16, v0
	v_add3_u32 v31, v42, v31, s24
	ds_read2_b32 v[50:51], v65 offset0:231 offset1:239
	v_and_or_b32 v31, v31, s25, v0
	s_waitcnt lgkmcnt(3)
	v_bfe_u32 v0, v44, 16, 1
	v_add3_u32 v0, v44, v0, s24
	s_waitcnt lgkmcnt(2)
	v_bfe_u32 v32, v46, 16, 1
	v_lshrrev_b32_e32 v0, 16, v0
	v_add3_u32 v32, v46, v32, s24
	v_and_or_b32 v32, v32, s25, v0
	s_waitcnt lgkmcnt(1)
	v_bfe_u32 v0, v48, 16, 1
	v_add3_u32 v0, v48, v0, s24
	s_waitcnt lgkmcnt(0)
	v_bfe_u32 v33, v50, 16, 1
	v_lshrrev_b32_e32 v0, 16, v0
	v_add3_u32 v33, v50, v33, s24
	s_mov_b32 s9, s5
	v_and_or_b32 v33, v33, s25, v0
	v_or_b32_e32 v0, s10, v64
	v_lshl_add_u64 v[36:37], s[8:9], 1, v[20:21]
	v_lshlrev_b32_e32 v0, 11, v0
	v_lshl_add_u64 v[52:53], v[36:37], 0, v[0:1]
	v_bfe_u32 v0, v35, 16, 1
	global_store_dwordx4 v[52:53], v[30:33], off sc1
	v_add3_u32 v0, v35, v0, s24
	v_lshrrev_b32_e32 v0, 16, v0
	v_bfe_u32 v30, v39, 16, 1
	v_add3_u32 v30, v39, v30, s24
	v_and_or_b32 v30, v30, s25, v0
	v_bfe_u32 v0, v41, 16, 1
	v_add3_u32 v0, v41, v0, s24
	v_bfe_u32 v31, v43, 16, 1
	v_lshrrev_b32_e32 v0, 16, v0
	v_add3_u32 v31, v43, v31, s24
	v_and_or_b32 v31, v31, s25, v0
	v_bfe_u32 v0, v45, 16, 1
	v_add3_u32 v0, v45, v0, s24
	v_bfe_u32 v32, v47, 16, 1
	v_lshrrev_b32_e32 v0, 16, v0
	v_add3_u32 v32, v47, v32, s24
	v_and_or_b32 v32, v32, s25, v0
	v_bfe_u32 v0, v49, 16, 1
	v_add3_u32 v0, v49, v0, s24
	v_bfe_u32 v33, v51, 16, 1
	v_lshrrev_b32_e32 v0, 16, v0
	v_add3_u32 v33, v51, v33, s24
	v_and_or_b32 v33, v33, s25, v0
	v_or_b32_e32 v0, s10, v66
	v_lshlrev_b32_e32 v0, 11, v0
	ds_read2_b32 v[34:35], v65 offset0:16 offset1:24
	v_lshl_add_u64 v[38:39], v[36:37], 0, v[0:1]
	global_store_dwordx4 v[38:39], v[30:33], off sc1
	ds_read2_b32 v[38:39], v65 offset0:49 offset1:57
	ds_read2_b32 v[40:41], v65 offset0:82 offset1:90
	ds_read2_b32 v[42:43], v65 offset0:115 offset1:123
	s_waitcnt lgkmcnt(3)
	v_bfe_u32 v0, v34, 16, 1
	v_add3_u32 v0, v34, v0, s24
	s_waitcnt lgkmcnt(2)
	v_bfe_u32 v30, v38, 16, 1
	ds_read2_b32 v[44:45], v65 offset0:148 offset1:156
	v_lshrrev_b32_e32 v0, 16, v0
	v_add3_u32 v30, v38, v30, s24
	ds_read2_b32 v[46:47], v65 offset0:181 offset1:189
	v_and_or_b32 v30, v30, s25, v0
	s_waitcnt lgkmcnt(3)
	v_bfe_u32 v0, v40, 16, 1
	v_add3_u32 v0, v40, v0, s24
	s_waitcnt lgkmcnt(2)
	v_bfe_u32 v31, v42, 16, 1
	ds_read2_b32 v[48:49], v65 offset0:214 offset1:222
	v_lshrrev_b32_e32 v0, 16, v0
	v_add3_u32 v31, v42, v31, s24
	ds_read2_b32 v[50:51], v65 offset0:247 offset1:255
	v_and_or_b32 v31, v31, s25, v0
	s_waitcnt lgkmcnt(3)
	v_bfe_u32 v0, v44, 16, 1
	v_add3_u32 v0, v44, v0, s24
	s_waitcnt lgkmcnt(2)
	v_bfe_u32 v32, v46, 16, 1
	v_lshrrev_b32_e32 v0, 16, v0
	v_add3_u32 v32, v46, v32, s24
	v_and_or_b32 v32, v32, s25, v0
	s_waitcnt lgkmcnt(1)
	v_bfe_u32 v0, v48, 16, 1
	v_add3_u32 v0, v48, v0, s24
	s_waitcnt lgkmcnt(0)
	v_bfe_u32 v33, v50, 16, 1
	v_lshrrev_b32_e32 v0, 16, v0
	v_add3_u32 v33, v50, v33, s24
	v_and_or_b32 v33, v33, s25, v0
	v_or_b32_e32 v0, s10, v67
	v_lshlrev_b32_e32 v0, 11, v0
	v_lshl_add_u64 v[52:53], v[36:37], 0, v[0:1]
	v_bfe_u32 v0, v35, 16, 1
	global_store_dwordx4 v[52:53], v[30:33], off sc1
	v_add3_u32 v0, v35, v0, s24
	v_lshrrev_b32_e32 v0, 16, v0
	v_bfe_u32 v30, v39, 16, 1
	v_add3_u32 v30, v39, v30, s24
	v_and_or_b32 v30, v30, s25, v0
	v_bfe_u32 v0, v41, 16, 1
	v_add3_u32 v0, v41, v0, s24
	v_bfe_u32 v31, v43, 16, 1
	v_lshrrev_b32_e32 v0, 16, v0
	v_add3_u32 v31, v43, v31, s24
	v_and_or_b32 v31, v31, s25, v0
	v_bfe_u32 v0, v45, 16, 1
	v_add3_u32 v0, v45, v0, s24
	v_bfe_u32 v32, v47, 16, 1
	v_lshrrev_b32_e32 v0, 16, v0
	v_add3_u32 v32, v47, v32, s24
	v_and_or_b32 v32, v32, s25, v0
	v_bfe_u32 v0, v49, 16, 1
	v_add3_u32 v0, v49, v0, s24
	v_bfe_u32 v33, v51, 16, 1
	v_lshrrev_b32_e32 v0, 16, v0
	v_add3_u32 v33, v51, v33, s24
	v_and_or_b32 v33, v33, s25, v0
	v_or_b32_e32 v0, s10, v68
	v_lshlrev_b32_e32 v0, 11, v0
	v_lshl_add_u64 v[34:35], v[36:37], 0, v[0:1]
	global_store_dwordx4 v[34:35], v[30:33], off sc1
	s_waitcnt lgkmcnt(0)

; #define LAS __attribute__((address_space(3)))
; __device__ __forceinline__ void p0_transpose_item(const float* W, int K, int N, bf16_t* WT, int dest_row0, const float* gain, LAS float* scr, int k0, int n0, int lane) {
;     float wv[32];
; #pragma unroll
;     for (int i = 0; i < 32; ++i) { const int kk = 2 * i + (lane >> 5); wv[i] = W[(size_t)(k0 + kk) * N + n0 + (lane & 31)]; }
;     if (gain) {
; #pragma unroll
;         for (int i = 0; i < 32; ++i) wv[i] *= gain[k0 + 2 * i + (lane >> 5)]; }
; #pragma unroll
;     for (int i = 0; i < 32; ++i) { const int kk = 2 * i + (lane >> 5); scr[kk * 33 + (lane & 31)] = wv[i]; }
; __device__ __forceinline__ void transpose_items(Frame& F, int it0, int it1, int gw, int NGW) {
;     ...
;     for (int it = it0 + gw; it < it1; it += NGW) {
;         int r = it;
;         if (r < I_IN) { const int kb = r / 88, nb = r % 88; p0_transpose_item(F.w_in, D, INW, Win_t, win_dest(32 * nb), nullptr, scr, 64 * kb, 32 * nb, F.lane); continue; } r -= I_IN;
;         if (r < I_KV) { const int kb = r / 32, nb = r % 32; p0_transpose_item(F.wkv, D, D, Wkv_t, 32 * nb, nullptr, scr, 64 * kb, 32 * nb, F.lane); continue; } r -= I_KV;
;         if (r < I_OUT) { const int kb = r / 32, nb = r % 32; p0_transpose_item(F.w_out, D, D, Wout_t, 32 * nb, nullptr, scr, 64 * kb, 32 * nb, F.lane); continue; } r -= I_OUT;
;         if (r < I_Q) { const int kb = r / 16, nb = r % 16; p0_transpose_item(F.wq, D, 512, Wq_t, 32 * nb, F.g2, scr, 64 * kb, 32 * nb, F.lane); continue; } r -= I_Q;
;         if (r < I_O) { const int kb = r / 32, nb = r % 32; p0_transpose_item(F.wo, 512, D, Wo_t, 32 * nb, nullptr, scr, 64 * kb, 32 * nb, F.lane); continue; } r -= I_O;
;         if (r < I_UP) { const int kb = r / 128, nb = r % 128; p0_transpose_item(F.wup, D, FF, Wup_t, 32 * nb, F.g3, scr, 64 * kb, 32 * nb, F.lane); continue; } r -= I_UP;
;         { const int kb = r / 32, nb = r % 32; p0_transpose_item(F.wdn, FF, D, Wdn_t, 32 * nb, nullptr, scr, 64 * kb, 32 * nb, F.lane); }
.LBB0_416:
	s_andn2_b64 vcc, exec, s[8:9]
	s_cbranch_vccnz .LBB0_418
	s_and_b32 s4, s20, 0xfc0
	s_add_i32 s8, s4, 0xfffff500
	s_and_b32 s10, s16, 0x3e0
	v_or_b32_e32 v0, s8, v62
	s_lshl_b32 s4, s10, 2
	v_or_b32_e32 v34, 2, v0
	v_mov_b32_e32 v35, v1
	v_or_b32_e32 v36, 4, v0
	v_mov_b32_e32 v37, v1
	v_or_b32_e32 v38, 6, v0
	v_mov_b32_e32 v39, v1
	v_or_b32_e32 v40, 8, v0
	v_mov_b32_e32 v41, v1
	v_or_b32_e32 v42, 10, v0
	v_mov_b32_e32 v43, v1
	v_or_b32_e32 v44, 12, v0
	v_mov_b32_e32 v45, v1
	v_lshl_add_u64 v[30:31], v[22:23], 0, s[4:5]
	v_lshlrev_b64 v[32:33], 12, v[0:1]
	v_lshlrev_b64 v[34:35], 12, v[34:35]
	v_lshlrev_b64 v[36:37], 12, v[36:37]
	v_lshlrev_b64 v[38:39], 12, v[38:39]
	v_lshlrev_b64 v[40:41], 12, v[40:41]
	v_lshlrev_b64 v[42:43], 12, v[42:43]
	v_lshlrev_b64 v[44:45], 12, v[44:45]
	v_or_b32_e32 v46, 14, v0
	v_mov_b32_e32 v47, v1
	v_lshl_add_u64 v[32:33], v[30:31], 0, v[32:33]
	v_lshl_add_u64 v[34:35], v[30:31], 0, v[34:35]
	v_lshl_add_u64 v[36:37], v[30:31], 0, v[36:37]
	v_lshl_add_u64 v[38:39], v[30:31], 0, v[38:39]
	v_lshl_add_u64 v[40:41], v[30:31], 0, v[40:41]
	v_lshl_add_u64 v[42:43], v[30:31], 0, v[42:43]
	v_lshl_add_u64 v[44:45], v[30:31], 0, v[44:45]
	v_lshlrev_b64 v[46:47], 12, v[46:47]
	v_lshl_add_u64 v[46:47], v[30:31], 0, v[46:47]
	global_load_dword v48, v[32:33], off
	global_load_dword v49, v[34:35], off
	global_load_dword v50, v[36:37], off
	global_load_dword v51, v[38:39], off
	global_load_dword v52, v[40:41], off
	global_load_dword v53, v[42:43], off
	global_load_dword v54, v[44:45], off
	global_load_dword v55, v[46:47], off
	v_or_b32_e32 v32, 16, v0
	v_mov_b32_e32 v33, v1
	v_or_b32_e32 v34, 18, v0
	v_mov_b32_e32 v35, v1
	v_or_b32_e32 v36, 20, v0
	v_mov_b32_e32 v37, v1
	v_or_b32_e32 v38, 22, v0
	v_mov_b32_e32 v39, v1
	v_or_b32_e32 v40, 24, v0
	v_mov_b32_e32 v41, v1
	v_or_b32_e32 v42, 26, v0
	v_mov_b32_e32 v43, v1
	v_or_b32_e32 v44, 28, v0
	v_mov_b32_e32 v45, v1
	v_lshlrev_b64 v[32:33], 12, v[32:33]
	v_lshlrev_b64 v[34:35], 12, v[34:35]
	v_lshlrev_b64 v[36:37], 12, v[36:37]
	v_lshlrev_b64 v[38:39], 12, v[38:39]
	v_lshlrev_b64 v[40:41], 12, v[40:41]
	v_lshlrev_b64 v[42:43], 12, v[42:43]
	v_lshlrev_b64 v[44:45], 12, v[44:45]
	v_or_b32_e32 v46, 30, v0
	v_mov_b32_e32 v47, v1
	v_lshl_add_u64 v[32:33], v[30:31], 0, v[32:33]
	v_lshl_add_u64 v[34:35], v[30:31], 0, v[34:35]
	v_lshl_add_u64 v[36:37], v[30:31], 0, v[36:37]
	v_lshl_add_u64 v[38:39], v[30:31], 0, v[38:39]
	v_lshl_add_u64 v[40:41], v[30:31], 0, v[40:41]
	v_lshl_add_u64 v[42:43], v[30:31], 0, v[42:43]
	v_lshl_add_u64 v[44:45], v[30:31], 0, v[44:45]
	v_lshlrev_b64 v[46:47], 12, v[46:47]
	v_lshl_add_u64 v[46:47], v[30:31], 0, v[46:47]
	global_load_dword v56, v[32:33], off
	global_load_dword v57, v[34:35], off
	global_load_dword v58, v[36:37], off
	global_load_dword v59, v[38:39], off
	global_load_dword v60, v[40:41], off
	global_load_dword v61, v[42:43], off
	global_load_dword v77, v[44:45], off
	global_load_dword v78, v[46:47], off
	v_or_b32_e32 v32, 32, v0
	v_mov_b32_e32 v33, v1
	v_or_b32_e32 v34, 34, v0
	v_mov_b32_e32 v35, v1
	v_or_b32_e32 v36, 36, v0
	v_mov_b32_e32 v37, v1
	v_or_b32_e32 v38, 38, v0
	v_mov_b32_e32 v39, v1
	v_or_b32_e32 v40, 40, v0
	v_mov_b32_e32 v41, v1
	v_or_b32_e32 v42, 42, v0
	v_mov_b32_e32 v43, v1
	v_or_b32_e32 v44, 44, v0
	v_mov_b32_e32 v45, v1
	v_lshlrev_b64 v[32:33], 12, v[32:33]
	v_lshlrev_b64 v[34:35], 12, v[34:35]
	v_lshlrev_b64 v[36:37], 12, v[36:37]
	v_lshlrev_b64 v[38:39], 12, v[38:39]
	v_lshlrev_b64 v[40:41], 12, v[40:41]
	v_lshlrev_b64 v[42:43], 12, v[42:43]
	v_lshlrev_b64 v[44:45], 12, v[44:45]
	v_or_b32_e32 v46, 46, v0
	v_mov_b32_e32 v47, v1
	v_lshl_add_u64 v[32:33], v[30:31], 0, v[32:33]
	v_lshl_add_u64 v[34:35], v[30:31], 0, v[34:35]
	v_lshl_add_u64 v[36:37], v[30:31], 0, v[36:37]
	v_lshl_add_u64 v[38:39], v[30:31], 0, v[38:39]
	v_lshl_add_u64 v[40:41], v[30:31], 0, v[40:41]
	v_lshl_add_u64 v[42:43], v[30:31], 0, v[42:43]
	v_lshl_add_u64 v[44:45], v[30:31], 0, v[44:45]
	v_lshlrev_b64 v[46:47], 12, v[46:47]
	v_lshl_add_u64 v[46:47], v[30:31], 0, v[46:47]
	global_load_dword v79, v[32:33], off
	global_load_dword v80, v[34:35], off
	global_load_dword v81, v[36:37], off
	global_load_dword v82, v[38:39], off
	global_load_dword v83, v[40:41], off
	global_load_dword v84, v[42:43], off
	global_load_dword v85, v[44:45], off
	global_load_dword v86, v[46:47], off
	v_or_b32_e32 v32, 48, v0
	v_mov_b32_e32 v33, v1
	v_or_b32_e32 v34, 50, v0
	v_mov_b32_e32 v35, v1
	v_or_b32_e32 v36, 52, v0
	v_mov_b32_e32 v37, v1
	v_or_b32_e32 v38, 54, v0
	v_mov_b32_e32 v39, v1
	v_or_b32_e32 v40, 56, v0
	v_mov_b32_e32 v41, v1
	v_or_b32_e32 v42, 58, v0
	v_mov_b32_e32 v43, v1
	v_or_b32_e32 v44, 60, v0
	v_mov_b32_e32 v45, v1
	v_or_b32_e32 v0, 62, v0
	v_lshlrev_b64 v[32:33], 12, v[32:33]
	v_lshlrev_b64 v[34:35], 12, v[34:35]
	v_lshlrev_b64 v[36:37], 12, v[36:37]
	v_lshlrev_b64 v[38:39], 12, v[38:39]
	v_lshlrev_b64 v[40:41], 12, v[40:41]
	v_lshlrev_b64 v[42:43], 12, v[42:43]
	v_lshlrev_b64 v[44:45], 12, v[44:45]
	v_lshlrev_b64 v[46:47], 12, v[0:1]
	v_lshl_add_u64 v[32:33], v[30:31], 0, v[32:33]
	v_lshl_add_u64 v[34:35], v[30:31], 0, v[34:35]
	v_lshl_add_u64 v[36:37], v[30:31], 0, v[36:37]
	v_lshl_add_u64 v[38:39], v[30:31], 0, v[38:39]
	v_lshl_add_u64 v[40:41], v[30:31], 0, v[40:41]
	v_lshl_add_u64 v[42:43], v[30:31], 0, v[42:43]
	v_lshl_add_u64 v[44:45], v[30:31], 0, v[44:45]
	v_lshl_add_u64 v[30:31], v[30:31], 0, v[46:47]
	global_load_dword v0, v[32:33], off
	s_nop 0
	global_load_dword v32, v[34:35], off
	global_load_dword v33, v[36:37], off
	s_nop 0
	global_load_dword v34, v[38:39], off
	global_load_dword v35, v[40:41], off
	global_load_dword v36, v[42:43], off
	global_load_dword v37, v[44:45], off
	s_nop 0
	global_load_dword v30, v[30:31], off
	s_waitcnt vmcnt(30)
; #define LAS __attribute__((address_space(3)))
; __device__ __forceinline__ unsigned pk2(float lo, float hi) { return f2bf(lo) | (f2bf(hi) << 16); }
; __device__ __forceinline__ void p0_transpose_item(const float* W, int K, int N, bf16_t* WT, int dest_row0, const float* gain, LAS float* scr, int k0, int n0, int lane) {
;     ...
;     for (int i = 0; i < 32; ++i) { const int kk = 2 * i + (lane >> 5); scr[kk * 33 + (lane & 31)] = wv[i]; }
;     asm volatile("s_waitcnt lgkmcnt(0)" ::: "memory");
;     const int c = lane & 7;
; #pragma unroll
;     for (int j = 0; j < 4; ++j) { const int n = (lane >> 3) + 8 * j; const LAS float* s = scr + (8 * c) * 33 + n;
;         u32x4 o; o.x = pk2(s[0 * 33], s[1 * 33]); o.y = pk2(s[2 * 33], s[3 * 33]); o.z = pk2(s[4 * 33], s[5 * 33]); o.w = pk2(s[6 * 33], s[7 * 33]);
;         *(u32x4*)(WT + (size_t)(dest_row0 + n) * K + k0 + 8 * c) = o; }
;     asm volatile("s_waitcnt lgkmcnt(0)" ::: "memory");
	ds_write2_b32 v63, v48, v49 offset1:66
	s_waitcnt vmcnt(28)
	ds_write2_b32 v63, v50, v51 offset0:132 offset1:198
	s_waitcnt vmcnt(26)
	ds_write2_b32 v69, v52, v53 offset0:8 offset1:74
	s_waitcnt vmcnt(24)
	ds_write2_b32 v69, v54, v55 offset0:140 offset1:206
	s_waitcnt vmcnt(22)
	ds_write2_b32 v70, v56, v57 offset0:16 offset1:82
	s_waitcnt vmcnt(20)
	ds_write2_b32 v70, v58, v59 offset0:148 offset1:214
	s_waitcnt vmcnt(18)
	ds_write2_b32 v71, v60, v61 offset0:24 offset1:90
	s_waitcnt vmcnt(16)
	ds_write2_b32 v71, v77, v78 offset0:156 offset1:222
	s_waitcnt vmcnt(14)
	ds_write2_b32 v72, v79, v80 offset0:32 offset1:98
	s_waitcnt vmcnt(12)
	ds_write2_b32 v72, v81, v82 offset0:164 offset1:230
	s_waitcnt vmcnt(10)
	ds_write2_b32 v73, v83, v84 offset0:40 offset1:106
	s_waitcnt vmcnt(8)
	ds_write2_b32 v73, v85, v86 offset0:172 offset1:238
	s_waitcnt vmcnt(6)
	ds_write2_b32 v74, v0, v32 offset0:48 offset1:114
	s_waitcnt vmcnt(4)
	ds_write2_b32 v74, v33, v34 offset0:180 offset1:246
	s_waitcnt vmcnt(2)
	ds_write2_b32 v75, v35, v36 offset0:56 offset1:122
	s_waitcnt vmcnt(0)
	ds_write2_b32 v75, v37, v30 offset0:188 offset1:254
	s_waitcnt lgkmcnt(0)
	ds_read2_b32 v[34:35], v65 offset1:8
	ds_read2_b32 v[38:39], v65 offset0:33 offset1:41
	ds_read2_b32 v[40:41], v65 offset0:66 offset1:74
	ds_read2_b32 v[42:43], v65 offset0:99 offset1:107
	ds_read2_b32 v[44:45], v65 offset0:132 offset1:140
	s_waitcnt lgkmcnt(4)
	v_bfe_u32 v0, v34, 16, 1
	v_add3_u32 v0, v34, v0, s24
	s_waitcnt lgkmcnt(3)
	v_bfe_u32 v30, v38, 16, 1
	v_lshrrev_b32_e32 v0, 16, v0
	v_add3_u32 v30, v38, v30, s24
	ds_read2_b32 v[46:47], v65 offset0:165 offset1:173
	v_and_or_b32 v30, v30, s25, v0
	s_waitcnt lgkmcnt(3)
	v_bfe_u32 v0, v40, 16, 1
	v_add3_u32 v0, v40, v0, s24
	s_waitcnt lgkmcnt(2)
	v_bfe_u32 v31, v42, 16, 1
	ds_read2_b32 v[48:49], v65 offset0:198 offset1:206
	v_lshrrev_b32_e32 v0, 16, v0
	v_add3_u32 v31, v42, v31, s24
	ds_read2_b32 v[50:51], v65 offset0:231 offset1:239
	v_and_or_b32 v31, v31, s25, v0
	s_waitcnt lgkmcnt(3)
	v_bfe_u32 v0, v44, 16, 1
	v_add3_u32 v0, v44, v0, s24
	s_waitcnt lgkmcnt(2)
	v_bfe_u32 v32, v46, 16, 1
	v_lshrrev_b32_e32 v0, 16, v0
	v_add3_u32 v32, v46, v32, s24
	v_and_or_b32 v32, v32, s25, v0
	s_waitcnt lgkmcnt(1)
	v_bfe_u32 v0, v48, 16, 1
	v_add3_u32 v0, v48, v0, s24
	s_waitcnt lgkmcnt(0)
	v_bfe_u32 v33, v50, 16, 1
	v_lshrrev_b32_e32 v0, 16, v0
	v_add3_u32 v33, v50, v33, s24
	s_mov_b32 s9, s5
	v_and_or_b32 v33, v33, s25, v0
	v_or_b32_e32 v0, s10, v64
	v_lshl_add_u64 v[36:37], s[8:9], 1, v[24:25]
	v_lshlrev_b32_e32 v0, 11, v0
	v_lshl_add_u64 v[52:53], v[36:37], 0, v[0:1]
	v_bfe_u32 v0, v35, 16, 1
	global_store_dwordx4 v[52:53], v[30:33], off sc1
	v_add3_u32 v0, v35, v0, s24
	v_lshrrev_b32_e32 v0, 16, v0
	v_bfe_u32 v30, v39, 16, 1
	v_add3_u32 v30, v39, v30, s24
	v_and_or_b32 v30, v30, s25, v0
	v_bfe_u32 v0, v41, 16, 1
	v_add3_u32 v0, v41, v0, s24
	v_bfe_u32 v31, v43, 16, 1
	v_lshrrev_b32_e32 v0, 16, v0
	v_add3_u32 v31, v43, v31, s24
	v_and_or_b32 v31, v31, s25, v0
	v_bfe_u32 v0, v45, 16, 1
	v_add3_u32 v0, v45, v0, s24
	v_bfe_u32 v32, v47, 16, 1
	v_lshrrev_b32_e32 v0, 16, v0
	v_add3_u32 v32, v47, v32, s24
	v_and_or_b32 v32, v32, s25, v0
	v_bfe_u32 v0, v49, 16, 1
	v_add3_u32 v0, v49, v0, s24
	v_bfe_u32 v33, v51, 16, 1
	v_lshrrev_b32_e32 v0, 16, v0
	v_add3_u32 v33, v51, v33, s24
	v_and_or_b32 v33, v33, s25, v0
	v_or_b32_e32 v0, s10, v66
	v_lshlrev_b32_e32 v0, 11, v0
	ds_read2_b32 v[34:35], v65 offset0:16 offset1:24
	v_lshl_add_u64 v[38:39], v[36:37], 0, v[0:1]
	global_store_dwordx4 v[38:39], v[30:33], off sc1
	ds_read2_b32 v[38:39], v65 offset0:49 offset1:57
	ds_read2_b32 v[40:41], v65 offset0:82 offset1:90
	ds_read2_b32 v[42:43], v65 offset0:115 offset1:123
	s_waitcnt lgkmcnt(3)
	v_bfe_u32 v0, v34, 16, 1
	v_add3_u32 v0, v34, v0, s24
	s_waitcnt lgkmcnt(2)
	v_bfe_u32 v30, v38, 16, 1
	ds_read2_b32 v[44:45], v65 offset0:148 offset1:156
	v_lshrrev_b32_e32 v0, 16, v0
	v_add3_u32 v30, v38, v30, s24
	ds_read2_b32 v[46:47], v65 offset0:181 offset1:189
	v_and_or_b32 v30, v30, s25, v0
	s_waitcnt lgkmcnt(3)
	v_bfe_u32 v0, v40, 16, 1
	v_add3_u32 v0, v40, v0, s24
	s_waitcnt lgkmcnt(2)
	v_bfe_u32 v31, v42, 16, 1
	ds_read2_b32 v[48:49], v65 offset0:214 offset1:222
	v_lshrrev_b32_e32 v0, 16, v0
	v_add3_u32 v31, v42, v31, s24
	ds_read2_b32 v[50:51], v65 offset0:247 offset1:255
	v_and_or_b32 v31, v31, s25, v0
	s_waitcnt lgkmcnt(3)
	v_bfe_u32 v0, v44, 16, 1
	v_add3_u32 v0, v44, v0, s24
	s_waitcnt lgkmcnt(2)
	v_bfe_u32 v32, v46, 16, 1
	v_lshrrev_b32_e32 v0, 16, v0
	v_add3_u32 v32, v46, v32, s24
	v_and_or_b32 v32, v32, s25, v0
	s_waitcnt lgkmcnt(1)
	v_bfe_u32 v0, v48, 16, 1
	v_add3_u32 v0, v48, v0, s24
	s_waitcnt lgkmcnt(0)
	v_bfe_u32 v33, v50, 16, 1
	v_lshrrev_b32_e32 v0, 16, v0
	v_add3_u32 v33, v50, v33, s24
	v_and_or_b32 v33, v33, s25, v0
	v_or_b32_e32 v0, s10, v67
	v_lshlrev_b32_e32 v0, 11, v0
	v_lshl_add_u64 v[52:53], v[36:37], 0, v[0:1]
	v_bfe_u32 v0, v35, 16, 1
	global_store_dwordx4 v[52:53], v[30:33], off sc1
	v_add3_u32 v0, v35, v0, s24
	v_lshrrev_b32_e32 v0, 16, v0
	v_bfe_u32 v30, v39, 16, 1
	v_add3_u32 v30, v39, v30, s24
	v_and_or_b32 v30, v30, s25, v0
	v_bfe_u32 v0, v41, 16, 1
	v_add3_u32 v0, v41, v0, s24
	v_bfe_u32 v31, v43, 16, 1
	v_lshrrev_b32_e32 v0, 16, v0
	v_add3_u32 v31, v43, v31, s24
	v_and_or_b32 v31, v31, s25, v0
	v_bfe_u32 v0, v45, 16, 1
	v_add3_u32 v0, v45, v0, s24
	v_bfe_u32 v32, v47, 16, 1
	v_lshrrev_b32_e32 v0, 16, v0
	v_add3_u32 v32, v47, v32, s24
	v_and_or_b32 v32, v32, s25, v0
	v_bfe_u32 v0, v49, 16, 1
	v_add3_u32 v0, v49, v0, s24
	v_bfe_u32 v33, v51, 16, 1
	v_lshrrev_b32_e32 v0, 16, v0
	v_add3_u32 v33, v51, v33, s24
	v_and_or_b32 v33, v33, s25, v0
	v_or_b32_e32 v0, s10, v68
	v_lshlrev_b32_e32 v0, 11, v0
	v_lshl_add_u64 v[34:35], v[36:37], 0, v[0:1]
	global_store_dwordx4 v[34:35], v[30:33], off sc1
	s_waitcnt lgkmcnt(0)
